# stack5 + rolled GEMM K-loops: last LDS-DMA stage of each 6-piece load segment moved into the following 2-piece segment (4/4), covering wait vmcnt(6)
# baseline (speedup 1.0000x reference)
; #define PG8_STAGE(bufoff, gbase, voff) do { _Pragma("unroll") for (int _i = 0; _i < 2; ++_i) \
;         __builtin_amdgcn_global_load_lds((const unsigned*)((const char*)(gbase) + (voff)[_i]), (PG8_LAS unsigned*)(lds + (bufoff) + ldsw + _i * 8192), 16, 0, 0); } while (0)
; #define PG8_LDA(dst, b, h) do { _Pragma("unroll") for (int m = 0; m < 4; ++m) _Pragma("unroll") for (int k = 0; k < 2; ++k) dst[m][k] = *(const PG8_LAS bf16x8*)(lds + PG8_SA(b, h) + aoff + m * 2048 + k * 1024); } while (0)
; #define PG8_LDB(dst, b, h) do { _Pragma("unroll") for (int n = 0; n < 2; ++n) _Pragma("unroll") for (int k = 0; k < 2; ++k) dst[n][k] = *(const PG8_LAS bf16x8*)(lds + PG8_SB(b, h) + boff + n * 2048 + k * 1024); } while (0)
; #define PG8_MMA(ai, bj, At, Bt) do { __builtin_amdgcn_s_setprio(1); _Pragma("unroll") for (int m = 0; m < 4; ++m) _Pragma("unroll") for (int n = 0; n < 2; ++n) _Pragma("unroll") for (int k = 0; k < 2; ++k) \
;         acc[ai][bj][m][n] = __builtin_amdgcn_mfma_f32_16x16x32_bf16(Bt[n][k], At[m][k], acc[ai][bj][m][n], 0, 0, 0); __builtin_amdgcn_s_setprio(0); } while (0)
; #define PG8_WAIT_V(n) asm volatile("s_waitcnt vmcnt(" #n ")" ::: "memory")
; #define PG8_WAIT_L(n) asm volatile("s_waitcnt lgkmcnt(" #n ")" ::: "memory")
; template <class Epi, class Sched, bool ALIGN_EPI = false, bool SP2 = false>
; __device__ __forceinline__ void gemm_phase(PG8_LAS unsigned char* lds, const Gemm g, const Sched& S, const Epi& E) {
;     ...
;             const bool last = (t == nt - 2);
;             const char* a1 = cA + PG8_AK(t + 1);
;             const char* a2 = last ? nA : cA + PG8_AK(t + 2); const char* b2 = last ? nB : cB + (size_t)(t + 2) * kstep;
;             const char* a3 = last ? nA + PG8_AK(1) : cA + PG8_AK(t + 3); const char* b3 = b2 + kstep;
;             if (last && has_next) S.a_ready(nxt);
;             if constexpr (SP2) {
;             PG8_LDB(B0, 0, 0); PG8_LDB(B1, 0, 1); PG8_SCHED; PG8_LDA(At, 0, 0); PG8_STAGE(PG8_SA(1, 1), a1 + hstepA, voffA);
;             PG8_WAIT_V(8); PG8_WAIT_L(0); PG8_BAR; PG8_MMA(0, 0, At, B0); PG8_MMA(0, 1, At, B1); PG8_BAR; PG8_SCHED;
;             PG8_LDA(At, 0, 1); PG8_STAGE(PG8_SB(0, 0), b2, voffB); PG8_STAGE(PG8_SB(0, 1), b2 + hstepB, voffB); PG8_STAGE(PG8_SA(0, 0), a2, voffA);
;             PG8_WAIT_V(8); PG8_WAIT_L(0); PG8_BAR; PG8_MMA(1, 0, At, B0); PG8_MMA(1, 1, At, B1); PG8_BAR; PG8_SCHED;
.LBB0_129:
	ds_read_b128 v[132:135], v172
	ds_read_b128 v[158:161], v172 offset:1024
	ds_read_b128 v[176:179], v172 offset:2048
	ds_read_b128 v[180:183], v172 offset:3072
	ds_read_b128 v[184:187], v173
	ds_read_b128 v[188:191], v173 offset:1024
	ds_read_b128 v[192:195], v173 offset:2048
	ds_read_b128 v[196:199], v173 offset:3072
	s_add_u32 s38, s28, s34
	s_addc_u32 s39, s29, s35
	s_add_u32 s42, s38, 0x100
	s_addc_u32 s43, s39, 0
	s_add_u32 s40, s62, s34
	s_addc_u32 s41, s63, s35
	s_add_u32 s38, s38, 0x180
	s_addc_u32 s39, s39, 0
	s_cmpk_eq_i32 s34, 0x700
	s_cselect_b32 s39, s37, s39
	s_cselect_b32 s38, s31, s38
	s_cselect_b32 s41, s21, s41
	s_cselect_b32 s40, s23, s40
	s_cselect_b32 s43, s3, s43
	s_cselect_b32 s42, s10, s42
	v_lshl_add_u64 v[204:205], v[130:131], 0, s[34:35]
	s_add_i32 m0, s49, 0xc000
	ds_read_b128 v[200:203], v174
	ds_read_b128 v[208:211], v174 offset:1024
	ds_read_b128 v[212:215], v174 offset:2048
	ds_read_b128 v[216:219], v174 offset:3072
	ds_read_b128 v[220:223], v174 offset:4096
	ds_read_b128 v[224:227], v174 offset:5120
	ds_read_b128 v[228:231], v174 offset:6144
	ds_read_b128 v[232:235], v174 offset:7168
	global_load_lds_dwordx4 v[204:205], off
	v_lshl_add_u64 v[204:205], v[128:129], 0, s[34:35]
	s_add_i32 m0, s49, 0xe000
	s_nop 0
	global_load_lds_dwordx4 v[204:205], off
	s_waitcnt vmcnt(8)
	s_waitcnt lgkmcnt(0)
	s_barrier
	s_setprio 1
	v_mfma_f32_16x16x32_bf16 v[124:127], v[132:135], v[200:203], v[124:127]
	v_mfma_f32_16x16x32_bf16 v[120:123], v[176:179], v[200:203], v[120:123]
	v_mfma_f32_16x16x32_bf16 v[108:111], v[132:135], v[212:215], v[108:111]
	v_mfma_f32_16x16x32_bf16 v[104:107], v[176:179], v[212:215], v[104:107]
	v_mfma_f32_16x16x32_bf16 v[92:95], v[132:135], v[220:223], v[92:95]
	v_mfma_f32_16x16x32_bf16 v[88:91], v[176:179], v[220:223], v[88:91]
	v_mfma_f32_16x16x32_bf16 v[76:79], v[132:135], v[228:231], v[76:79]
	v_mfma_f32_16x16x32_bf16 v[72:75], v[176:179], v[228:231], v[72:75]
	v_mfma_f32_16x16x32_bf16 v[124:127], v[158:161], v[208:211], v[124:127]
	v_mfma_f32_16x16x32_bf16 v[120:123], v[180:183], v[208:211], v[120:123]
	v_mfma_f32_16x16x32_bf16 v[108:111], v[158:161], v[216:219], v[108:111]
	v_mfma_f32_16x16x32_bf16 v[104:107], v[180:183], v[216:219], v[104:107]
	v_mfma_f32_16x16x32_bf16 v[92:95], v[158:161], v[224:227], v[92:95]
	v_mfma_f32_16x16x32_bf16 v[88:91], v[180:183], v[224:227], v[88:91]
	v_mfma_f32_16x16x32_bf16 v[76:79], v[158:161], v[232:235], v[76:79]
	v_mfma_f32_16x16x32_bf16 v[72:75], v[180:183], v[232:235], v[72:75]
	v_mfma_f32_16x16x32_bf16 v[116:119], v[184:187], v[200:203], v[116:119]
	v_mfma_f32_16x16x32_bf16 v[112:115], v[192:195], v[200:203], v[112:115]
	v_mfma_f32_16x16x32_bf16 v[100:103], v[184:187], v[212:215], v[100:103]
	v_mfma_f32_16x16x32_bf16 v[96:99], v[192:195], v[212:215], v[96:99]
	v_mfma_f32_16x16x32_bf16 v[84:87], v[184:187], v[220:223], v[84:87]
	v_mfma_f32_16x16x32_bf16 v[80:83], v[192:195], v[220:223], v[80:83]
	v_mfma_f32_16x16x32_bf16 v[68:71], v[184:187], v[228:231], v[68:71]
	v_mfma_f32_16x16x32_bf16 v[64:67], v[192:195], v[228:231], v[64:67]
	v_mfma_f32_16x16x32_bf16 v[116:119], v[188:191], v[208:211], v[116:119]
	v_mfma_f32_16x16x32_bf16 v[112:115], v[196:199], v[208:211], v[112:115]
	v_mfma_f32_16x16x32_bf16 v[100:103], v[188:191], v[216:219], v[100:103]
	v_mfma_f32_16x16x32_bf16 v[96:99], v[196:199], v[216:219], v[96:99]
	v_mfma_f32_16x16x32_bf16 v[84:87], v[188:191], v[224:227], v[84:87]
	v_mfma_f32_16x16x32_bf16 v[80:83], v[196:199], v[224:227], v[80:83]
	v_mfma_f32_16x16x32_bf16 v[68:71], v[188:191], v[232:235], v[68:71]
	v_mfma_f32_16x16x32_bf16 v[64:67], v[196:199], v[232:235], v[64:67]
	s_setprio 0
	s_barrier
	s_add_i32 s65, s58, s48
	v_lshl_add_u64 v[204:205], s[40:41], 0, v[138:139]
	s_mov_b32 m0, s65
	ds_read_b128 v[200:203], v174 offset:16384
	ds_read_b128 v[208:211], v174 offset:17408
	ds_read_b128 v[212:215], v174 offset:18432
	ds_read_b128 v[216:219], v174 offset:19456
	ds_read_b128 v[220:223], v174 offset:20480
	ds_read_b128 v[224:227], v174 offset:21504
	ds_read_b128 v[228:231], v174 offset:22528
	ds_read_b128 v[232:235], v174 offset:23552
	global_load_lds_dwordx4 v[204:205], off
	s_add_i32 m0, s65, 0x2000
	s_add_u32 s66, s40, 0x40000
	v_lshl_add_u64 v[206:207], s[40:41], 0, v[142:143]
	s_addc_u32 s67, s41, 0
	s_add_i32 s65, s59, s48
	global_load_lds_dwordx4 v[206:207], off
	v_lshl_add_u64 v[236:237], s[66:67], 0, v[138:139]
	s_mov_b32 m0, s65
	s_nop 0
	global_load_lds_dwordx4 v[236:237], off
	v_lshl_add_u64 v[236:237], s[66:67], 0, v[142:143]
	s_add_i32 m0, s65, 0x2000
	s_nop 0
	global_load_lds_dwordx4 v[236:237], off
	s_waitcnt vmcnt(6)
	s_waitcnt lgkmcnt(0)
	s_barrier
; #define PG8_STAGE(bufoff, gbase, voff) do { _Pragma("unroll") for (int _i = 0; _i < 2; ++_i) \
;         __builtin_amdgcn_global_load_lds((const unsigned*)((const char*)(gbase) + (voff)[_i]), (PG8_LAS unsigned*)(lds + (bufoff) + ldsw + _i * 8192), 16, 0, 0); } while (0)
; #define PG8_LDA(dst, b, h) do { _Pragma("unroll") for (int m = 0; m < 4; ++m) _Pragma("unroll") for (int k = 0; k < 2; ++k) dst[m][k] = *(const PG8_LAS bf16x8*)(lds + PG8_SA(b, h) + aoff + m * 2048 + k * 1024); } while (0)
; #define PG8_LDB(dst, b, h) do { _Pragma("unroll") for (int n = 0; n < 2; ++n) _Pragma("unroll") for (int k = 0; k < 2; ++k) dst[n][k] = *(const PG8_LAS bf16x8*)(lds + PG8_SB(b, h) + boff + n * 2048 + k * 1024); } while (0)
; #define PG8_MMA(ai, bj, At, Bt) do { __builtin_amdgcn_s_setprio(1); _Pragma("unroll") for (int m = 0; m < 4; ++m) _Pragma("unroll") for (int n = 0; n < 2; ++n) _Pragma("unroll") for (int k = 0; k < 2; ++k) \
;         acc[ai][bj][m][n] = __builtin_amdgcn_mfma_f32_16x16x32_bf16(Bt[n][k], At[m][k], acc[ai][bj][m][n], 0, 0, 0); __builtin_amdgcn_s_setprio(0); } while (0)
; #define PG8_WAIT_V(n) asm volatile("s_waitcnt vmcnt(" #n ")" ::: "memory")
; #define PG8_WAIT_L(n) asm volatile("s_waitcnt lgkmcnt(" #n ")" ::: "memory")
; #define PG8_BAR __builtin_amdgcn_s_barrier()
; #define PG8_SCHED __builtin_amdgcn_sched_barrier(0)
; template <class Epi, class Sched, bool ALIGN_EPI = false, bool SP2 = false>
; __device__ __forceinline__ void gemm_phase(PG8_LAS unsigned char* lds, const Gemm g, const Sched& S, const Epi& E) {
;     ...
;             PG8_WAIT_V(8); PG8_WAIT_L(0); PG8_BAR; PG8_MMA(1, 0, At, B0); PG8_MMA(1, 1, At, B1); PG8_BAR; PG8_SCHED;
;             PG8_LDB(B0, 1, 0); PG8_LDB(B1, 1, 1); PG8_SCHED; PG8_LDA(At, 1, 0); PG8_STAGE(PG8_SA(0, 1), a2 + hstepA, voffA);
;             PG8_WAIT_V(8); PG8_WAIT_L(0); PG8_BAR; PG8_MMA(0, 0, At, B0); PG8_MMA(0, 1, At, B1); PG8_BAR; PG8_SCHED;
	s_setprio 1
	v_mfma_f32_16x16x32_bf16 v[60:63], v[132:135], v[200:203], v[60:63]
	v_mfma_f32_16x16x32_bf16 v[56:59], v[176:179], v[200:203], v[56:59]
	v_mfma_f32_16x16x32_bf16 v[44:47], v[132:135], v[212:215], v[44:47]
	v_mfma_f32_16x16x32_bf16 v[40:43], v[176:179], v[212:215], v[40:43]
	v_mfma_f32_16x16x32_bf16 v[28:31], v[132:135], v[220:223], v[28:31]
	v_mfma_f32_16x16x32_bf16 v[24:27], v[176:179], v[220:223], v[24:27]
	v_mfma_f32_16x16x32_bf16 v[12:15], v[132:135], v[228:231], v[12:15]
	v_mfma_f32_16x16x32_bf16 v[8:11], v[176:179], v[228:231], v[8:11]
	v_mfma_f32_16x16x32_bf16 v[60:63], v[158:161], v[208:211], v[60:63]
	v_mfma_f32_16x16x32_bf16 v[56:59], v[180:183], v[208:211], v[56:59]
	v_mfma_f32_16x16x32_bf16 v[44:47], v[158:161], v[216:219], v[44:47]
	v_mfma_f32_16x16x32_bf16 v[40:43], v[180:183], v[216:219], v[40:43]
	v_mfma_f32_16x16x32_bf16 v[28:31], v[158:161], v[224:227], v[28:31]
	v_mfma_f32_16x16x32_bf16 v[24:27], v[180:183], v[224:227], v[24:27]
	v_mfma_f32_16x16x32_bf16 v[12:15], v[158:161], v[232:235], v[12:15]
	v_mfma_f32_16x16x32_bf16 v[8:11], v[180:183], v[232:235], v[8:11]
	v_mfma_f32_16x16x32_bf16 v[52:55], v[184:187], v[200:203], v[52:55]
	v_mfma_f32_16x16x32_bf16 v[48:51], v[192:195], v[200:203], v[48:51]
	v_mfma_f32_16x16x32_bf16 v[36:39], v[184:187], v[212:215], v[36:39]
	v_mfma_f32_16x16x32_bf16 v[32:35], v[192:195], v[212:215], v[32:35]
	v_mfma_f32_16x16x32_bf16 v[20:23], v[184:187], v[220:223], v[20:23]
	v_mfma_f32_16x16x32_bf16 v[16:19], v[192:195], v[220:223], v[16:19]
	v_mfma_f32_16x16x32_bf16 v[4:7], v[184:187], v[228:231], v[4:7]
	v_mfma_f32_16x16x32_bf16 v[0:3], v[192:195], v[228:231], v[0:3]
	v_mfma_f32_16x16x32_bf16 v[52:55], v[188:191], v[208:211], v[52:55]
	v_mfma_f32_16x16x32_bf16 v[48:51], v[196:199], v[208:211], v[48:51]
	v_mfma_f32_16x16x32_bf16 v[36:39], v[188:191], v[216:219], v[36:39]
	v_mfma_f32_16x16x32_bf16 v[32:35], v[196:199], v[216:219], v[32:35]
	v_mfma_f32_16x16x32_bf16 v[20:23], v[188:191], v[224:227], v[20:23]
	v_mfma_f32_16x16x32_bf16 v[16:19], v[196:199], v[224:227], v[16:19]
	v_mfma_f32_16x16x32_bf16 v[4:7], v[188:191], v[232:235], v[4:7]
	v_mfma_f32_16x16x32_bf16 v[0:3], v[196:199], v[232:235], v[0:3]
	s_setprio 0
	s_barrier
	s_add_i32 s65, 0, 0x18000
	v_add_u32_e32 v144, s65, v163
	s_add_i32 s66, 0, 0x1c000
	ds_read_b128 v[132:135], v144
	ds_read_b128 v[158:161], v144 offset:1024
	ds_read_b128 v[176:179], v144 offset:2048
	ds_read_b128 v[180:183], v144 offset:3072
	v_add_u32_e32 v144, s66, v163
	ds_read_b128 v[184:187], v144
	ds_read_b128 v[188:191], v144 offset:1024
	ds_read_b128 v[192:195], v144 offset:2048
	ds_read_b128 v[196:199], v144 offset:3072
	v_lshl_add_u64 v[236:237], s[42:43], 0, v[136:137]
	s_mov_b32 m0, s49
	s_nop 0
	global_load_lds_dwordx4 v[236:237], off
	v_lshl_add_u64 v[236:237], s[42:43], 0, v[140:141]
	s_mov_b32 m0, s50
	s_nop 0
	global_load_lds_dwordx4 v[236:237], off
	s_add_u32 s42, s42, 0x40000
	s_addc_u32 s43, s43, 0
	s_mov_b32 m0, s51
	v_lshl_add_u64 v[236:237], s[42:43], 0, v[136:137]
	ds_read_b128 v[200:203], v174 offset:32768
	ds_read_b128 v[208:211], v174 offset:33792
	ds_read_b128 v[212:215], v174 offset:34816
	ds_read_b128 v[216:219], v174 offset:35840
	ds_read_b128 v[220:223], v174 offset:36864
	ds_read_b128 v[224:227], v174 offset:37888
	ds_read_b128 v[228:231], v174 offset:38912
	ds_read_b128 v[232:235], v174 offset:39936
	global_load_lds_dwordx4 v[236:237], off
	v_lshl_add_u64 v[236:237], s[42:43], 0, v[140:141]
	s_mov_b32 m0, s52
	s_nop 0
	global_load_lds_dwordx4 v[236:237], off
	s_waitcnt vmcnt(8)
	s_waitcnt lgkmcnt(0)
	s_barrier
	s_setprio 1
	v_mfma_f32_16x16x32_bf16 v[124:127], v[132:135], v[200:203], v[124:127]
	v_mfma_f32_16x16x32_bf16 v[120:123], v[176:179], v[200:203], v[120:123]
	v_mfma_f32_16x16x32_bf16 v[108:111], v[132:135], v[212:215], v[108:111]
	v_mfma_f32_16x16x32_bf16 v[104:107], v[176:179], v[212:215], v[104:107]
	v_mfma_f32_16x16x32_bf16 v[92:95], v[132:135], v[220:223], v[92:95]
	v_mfma_f32_16x16x32_bf16 v[88:91], v[176:179], v[220:223], v[88:91]
	v_mfma_f32_16x16x32_bf16 v[76:79], v[132:135], v[228:231], v[76:79]
	v_mfma_f32_16x16x32_bf16 v[72:75], v[176:179], v[228:231], v[72:75]
	v_mfma_f32_16x16x32_bf16 v[124:127], v[158:161], v[208:211], v[124:127]
	v_mfma_f32_16x16x32_bf16 v[120:123], v[180:183], v[208:211], v[120:123]
	v_mfma_f32_16x16x32_bf16 v[108:111], v[158:161], v[216:219], v[108:111]
	v_mfma_f32_16x16x32_bf16 v[104:107], v[180:183], v[216:219], v[104:107]
	v_mfma_f32_16x16x32_bf16 v[92:95], v[158:161], v[224:227], v[92:95]
	v_mfma_f32_16x16x32_bf16 v[88:91], v[180:183], v[224:227], v[88:91]
	v_mfma_f32_16x16x32_bf16 v[76:79], v[158:161], v[232:235], v[76:79]
	v_mfma_f32_16x16x32_bf16 v[72:75], v[180:183], v[232:235], v[72:75]
	v_mfma_f32_16x16x32_bf16 v[116:119], v[184:187], v[200:203], v[116:119]
	v_mfma_f32_16x16x32_bf16 v[112:115], v[192:195], v[200:203], v[112:115]
	v_mfma_f32_16x16x32_bf16 v[100:103], v[184:187], v[212:215], v[100:103]
	v_mfma_f32_16x16x32_bf16 v[96:99], v[192:195], v[212:215], v[96:99]
	v_mfma_f32_16x16x32_bf16 v[84:87], v[184:187], v[220:223], v[84:87]
	v_mfma_f32_16x16x32_bf16 v[80:83], v[192:195], v[220:223], v[80:83]
	v_mfma_f32_16x16x32_bf16 v[68:71], v[184:187], v[228:231], v[68:71]
	v_mfma_f32_16x16x32_bf16 v[64:67], v[192:195], v[228:231], v[64:67]
	v_mfma_f32_16x16x32_bf16 v[116:119], v[188:191], v[208:211], v[116:119]
	v_mfma_f32_16x16x32_bf16 v[112:115], v[196:199], v[208:211], v[112:115]
	v_mfma_f32_16x16x32_bf16 v[100:103], v[188:191], v[216:219], v[100:103]
	v_mfma_f32_16x16x32_bf16 v[96:99], v[196:199], v[216:219], v[96:99]
	v_mfma_f32_16x16x32_bf16 v[84:87], v[188:191], v[224:227], v[84:87]
	v_mfma_f32_16x16x32_bf16 v[80:83], v[196:199], v[224:227], v[80:83]
	v_mfma_f32_16x16x32_bf16 v[68:71], v[188:191], v[232:235], v[68:71]
	v_mfma_f32_16x16x32_bf16 v[64:67], v[196:199], v[232:235], v[64:67]
	s_setprio 0
	s_barrier
; #define PG8_STAGE(bufoff, gbase, voff) do { _Pragma("unroll") for (int _i = 0; _i < 2; ++_i) \
;         __builtin_amdgcn_global_load_lds((const unsigned*)((const char*)(gbase) + (voff)[_i]), (PG8_LAS unsigned*)(lds + (bufoff) + ldsw + _i * 8192), 16, 0, 0); } while (0)
; #define PG8_LDA(dst, b, h) do { _Pragma("unroll") for (int m = 0; m < 4; ++m) _Pragma("unroll") for (int k = 0; k < 2; ++k) dst[m][k] = *(const PG8_LAS bf16x8*)(lds + PG8_SA(b, h) + aoff + m * 2048 + k * 1024); } while (0)
; #define PG8_MMA(ai, bj, At, Bt) do { __builtin_amdgcn_s_setprio(1); _Pragma("unroll") for (int m = 0; m < 4; ++m) _Pragma("unroll") for (int n = 0; n < 2; ++n) _Pragma("unroll") for (int k = 0; k < 2; ++k) \
;         acc[ai][bj][m][n] = __builtin_amdgcn_mfma_f32_16x16x32_bf16(Bt[n][k], At[m][k], acc[ai][bj][m][n], 0, 0, 0); __builtin_amdgcn_s_setprio(0); } while (0)
; #define PG8_WAIT_V(n) asm volatile("s_waitcnt vmcnt(" #n ")" ::: "memory")
; #define PG8_WAIT_L(n) asm volatile("s_waitcnt lgkmcnt(" #n ")" ::: "memory")
; #define PG8_BAR __builtin_amdgcn_s_barrier()
; #define PG8_SCHED __builtin_amdgcn_sched_barrier(0)
; template <class Epi, class Sched, bool ALIGN_EPI = false, bool SP2 = false>
; __device__ __forceinline__ void gemm_phase(PG8_LAS unsigned char* lds, const Gemm g, const Sched& S, const Epi& E) {
;     ...
;             PG8_LDA(At, 1, 1); PG8_STAGE(PG8_SB(1, 0), b3, voffB); PG8_STAGE(PG8_SB(1, 1), b3 + hstepB, voffB); PG8_STAGE(PG8_SA(1, 0), a3, voffA);
;             PG8_WAIT_V(8); PG8_WAIT_L(0); PG8_BAR; PG8_MMA(1, 0, At, B0); PG8_MMA(1, 1, At, B1); PG8_BAR; PG8_SCHED;
;     ...
;         if constexpr (ALIGN_EPI) { if (wr == 0) PG8_BAR; }
;         if constexpr (!Epi::AFTER_DRAIN) { E(acc, cur, wr, wc, fr, fq); S.done(cur); }
;         if (!has_next) break;
	s_add_i32 s42, s65, s48
	v_lshl_add_u64 v[204:205], v[204:205], 0, s[14:15]
	s_mov_b32 m0, s42
	ds_read_b128 v[200:203], v174 offset:49152
	ds_read_b128 v[208:211], v174 offset:50176
	ds_read_b128 v[212:215], v174 offset:51200
	ds_read_b128 v[216:219], v174 offset:52224
	ds_read_b128 v[220:223], v174 offset:53248
	ds_read_b128 v[224:227], v174 offset:54272
	ds_read_b128 v[228:231], v174 offset:55296
	ds_read_b128 v[232:235], v174 offset:56320
	global_load_lds_dwordx4 v[204:205], off
	s_add_i32 m0, s42, 0x2000
	s_add_u32 s40, s40, 0x40080
	v_lshl_add_u64 v[204:205], v[206:207], 0, s[14:15]
	s_addc_u32 s41, s41, 0
	s_add_i32 s42, s66, s48
	global_load_lds_dwordx4 v[204:205], off
	v_lshl_add_u64 v[204:205], s[40:41], 0, v[138:139]
	s_mov_b32 m0, s42
	s_nop 0
	global_load_lds_dwordx4 v[204:205], off
	v_lshl_add_u64 v[204:205], s[40:41], 0, v[142:143]
	s_add_i32 m0, s42, 0x2000
	s_nop 0
	global_load_lds_dwordx4 v[204:205], off
	v_lshl_add_u64 v[204:205], s[38:39], 0, v[136:137]
	s_mov_b32 m0, s53
	s_nop 0
	global_load_lds_dwordx4 v[204:205], off
	v_lshl_add_u64 v[204:205], s[38:39], 0, v[140:141]
	s_mov_b32 m0, s54
	s_nop 0
	global_load_lds_dwordx4 v[204:205], off
	s_waitcnt vmcnt(8)
	s_waitcnt lgkmcnt(0)
	s_barrier
	s_setprio 1
	v_mfma_f32_16x16x32_bf16 v[60:63], v[132:135], v[200:203], v[60:63]
	v_mfma_f32_16x16x32_bf16 v[56:59], v[176:179], v[200:203], v[56:59]
	v_mfma_f32_16x16x32_bf16 v[44:47], v[132:135], v[212:215], v[44:47]
	v_mfma_f32_16x16x32_bf16 v[40:43], v[176:179], v[212:215], v[40:43]
	v_mfma_f32_16x16x32_bf16 v[28:31], v[132:135], v[220:223], v[28:31]
	v_mfma_f32_16x16x32_bf16 v[24:27], v[176:179], v[220:223], v[24:27]
	v_mfma_f32_16x16x32_bf16 v[12:15], v[132:135], v[228:231], v[12:15]
	v_mfma_f32_16x16x32_bf16 v[8:11], v[176:179], v[228:231], v[8:11]
	v_mfma_f32_16x16x32_bf16 v[60:63], v[158:161], v[208:211], v[60:63]
	v_mfma_f32_16x16x32_bf16 v[56:59], v[180:183], v[208:211], v[56:59]
	v_mfma_f32_16x16x32_bf16 v[44:47], v[158:161], v[216:219], v[44:47]
	v_mfma_f32_16x16x32_bf16 v[40:43], v[180:183], v[216:219], v[40:43]
	v_mfma_f32_16x16x32_bf16 v[28:31], v[158:161], v[224:227], v[28:31]
	v_mfma_f32_16x16x32_bf16 v[24:27], v[180:183], v[224:227], v[24:27]
	v_mfma_f32_16x16x32_bf16 v[12:15], v[158:161], v[232:235], v[12:15]
	v_mfma_f32_16x16x32_bf16 v[8:11], v[180:183], v[232:235], v[8:11]
	v_mfma_f32_16x16x32_bf16 v[52:55], v[184:187], v[200:203], v[52:55]
	v_mfma_f32_16x16x32_bf16 v[48:51], v[192:195], v[200:203], v[48:51]
	v_mfma_f32_16x16x32_bf16 v[36:39], v[184:187], v[212:215], v[36:39]
	v_mfma_f32_16x16x32_bf16 v[32:35], v[192:195], v[212:215], v[32:35]
	v_mfma_f32_16x16x32_bf16 v[20:23], v[184:187], v[220:223], v[20:23]
	v_mfma_f32_16x16x32_bf16 v[16:19], v[192:195], v[220:223], v[16:19]
	v_mfma_f32_16x16x32_bf16 v[4:7], v[184:187], v[228:231], v[4:7]
	v_mfma_f32_16x16x32_bf16 v[0:3], v[192:195], v[228:231], v[0:3]
	v_mfma_f32_16x16x32_bf16 v[52:55], v[188:191], v[208:211], v[52:55]
	v_mfma_f32_16x16x32_bf16 v[48:51], v[196:199], v[208:211], v[48:51]
	v_mfma_f32_16x16x32_bf16 v[36:39], v[188:191], v[216:219], v[36:39]
	v_mfma_f32_16x16x32_bf16 v[32:35], v[196:199], v[216:219], v[32:35]
	v_mfma_f32_16x16x32_bf16 v[20:23], v[188:191], v[224:227], v[20:23]
	v_mfma_f32_16x16x32_bf16 v[16:19], v[196:199], v[224:227], v[16:19]
	v_mfma_f32_16x16x32_bf16 v[4:7], v[188:191], v[232:235], v[4:7]
	v_mfma_f32_16x16x32_bf16 v[0:3], v[196:199], v[232:235], v[0:3]
	s_setprio 0
	s_barrier
	s_add_i32 s64, s64, 2
	s_add_u32 s34, s34, 0x100
	s_addc_u32 s35, s35, 0
	s_cmp_gt_u32 s64, 13
	s_cbranch_scc0 .LBB0_129
	s_and_b64 vcc, exec, s[16:17]
	s_cbranch_vccz .LBB0_134
	s_barrier
	s_cmp_gt_i32 s30, 3
	s_mov_b64 s[28:29], -1
	s_cbranch_scc1 .LBB0_135

; #define PG8_STAGE(bufoff, gbase, voff) do { _Pragma("unroll") for (int _i = 0; _i < 2; ++_i) \
;         __builtin_amdgcn_global_load_lds((const unsigned*)((const char*)(gbase) + (voff)[_i]), (PG8_LAS unsigned*)(lds + (bufoff) + ldsw + _i * 8192), 16, 0, 0); } while (0)
; #define PG8_LDA(dst, b, h) do { _Pragma("unroll") for (int m = 0; m < 4; ++m) _Pragma("unroll") for (int k = 0; k < 2; ++k) dst[m][k] = *(const PG8_LAS bf16x8*)(lds + PG8_SA(b, h) + aoff + m * 2048 + k * 1024); } while (0)
; #define PG8_LDB(dst, b, h) do { _Pragma("unroll") for (int n = 0; n < 2; ++n) _Pragma("unroll") for (int k = 0; k < 2; ++k) dst[n][k] = *(const PG8_LAS bf16x8*)(lds + PG8_SB(b, h) + boff + n * 2048 + k * 1024); } while (0)
; #define PG8_MMA(ai, bj, At, Bt) do { __builtin_amdgcn_s_setprio(1); _Pragma("unroll") for (int m = 0; m < 4; ++m) _Pragma("unroll") for (int n = 0; n < 2; ++n) _Pragma("unroll") for (int k = 0; k < 2; ++k) \
;         acc[ai][bj][m][n] = __builtin_amdgcn_mfma_f32_16x16x32_bf16(Bt[n][k], At[m][k], acc[ai][bj][m][n], 0, 0, 0); __builtin_amdgcn_s_setprio(0); } while (0)
; #define PG8_WAIT_V(n) asm volatile("s_waitcnt vmcnt(" #n ")" ::: "memory")
; #define PG8_WAIT_L(n) asm volatile("s_waitcnt lgkmcnt(" #n ")" ::: "memory")
; template <class Epi, class Sched, bool ALIGN_EPI = false, bool SP2 = false>
; __device__ __forceinline__ void gemm_phase(PG8_LAS unsigned char* lds, const Gemm g, const Sched& S, const Epi& E) {
;     ...
;             const bool last = (t == nt - 2);
;             const char* a1 = cA + PG8_AK(t + 1);
;             const char* a2 = last ? nA : cA + PG8_AK(t + 2); const char* b2 = last ? nB : cB + (size_t)(t + 2) * kstep;
;             const char* a3 = last ? nA + PG8_AK(1) : cA + PG8_AK(t + 3); const char* b3 = b2 + kstep;
;             if (last && has_next) S.a_ready(nxt);
;             if constexpr (SP2) {
;             PG8_LDB(B0, 0, 0); PG8_LDB(B1, 0, 1); PG8_SCHED; PG8_LDA(At, 0, 0); PG8_STAGE(PG8_SA(1, 1), a1 + hstepA, voffA);
;             PG8_WAIT_V(8); PG8_WAIT_L(0); PG8_BAR; PG8_MMA(0, 0, At, B0); PG8_MMA(0, 1, At, B1); PG8_BAR; PG8_SCHED;
;             PG8_LDA(At, 0, 1); PG8_STAGE(PG8_SB(0, 0), b2, voffB); PG8_STAGE(PG8_SB(0, 1), b2 + hstepB, voffB); PG8_STAGE(PG8_SA(0, 0), a2, voffA);
;             PG8_WAIT_V(8); PG8_WAIT_L(0); PG8_BAR; PG8_MMA(1, 0, At, B0); PG8_MMA(1, 1, At, B1); PG8_BAR; PG8_SCHED;
.LBB0_332:
	ds_read_b128 v[180:183], v147
	ds_read_b128 v[184:187], v147 offset:1024
	ds_read_b128 v[188:191], v147 offset:2048
	ds_read_b128 v[192:195], v147 offset:3072
	ds_read_b128 v[196:199], v149
	ds_read_b128 v[200:203], v149 offset:1024
	ds_read_b128 v[208:211], v149 offset:2048
	ds_read_b128 v[212:215], v149 offset:3072
	s_add_u32 s42, s38, s40
	s_addc_u32 s43, s39, s41
	s_add_u32 s46, s42, 0x100
	s_addc_u32 s47, s43, 0
	s_add_u32 s44, s79, s40
	s_addc_u32 s45, s80, s41
	s_add_u32 s42, s42, 0x180
	s_addc_u32 s43, s43, 0
	s_cmpk_eq_i32 s40, 0x700
	s_cselect_b32 s43, s78, s43
	s_cselect_b32 s42, s69, s42
	s_cselect_b32 s45, s27, s45
	s_cselect_b32 s44, s37, s44
	s_cselect_b32 s47, s3, s47
	s_cselect_b32 s46, s29, s46
	v_lshl_add_u64 v[204:205], v[178:179], 0, s[40:41]
	s_add_i32 m0, s54, 0xc000
	ds_read_b128 v[216:219], v143
	ds_read_b128 v[220:223], v143 offset:1024
	ds_read_b128 v[224:227], v143 offset:2048
	ds_read_b128 v[228:231], v143 offset:3072
	ds_read_b128 v[232:235], v143 offset:4096
	ds_read_b128 v[236:239], v143 offset:5120
	ds_read_b128 v[240:243], v143 offset:6144
	ds_read_b128 v[244:247], v143 offset:7168
	global_load_lds_dwordx4 v[204:205], off
	v_lshl_add_u64 v[204:205], v[176:177], 0, s[40:41]
	s_add_i32 m0, s54, 0xe000
	s_nop 0
	global_load_lds_dwordx4 v[204:205], off
	s_waitcnt vmcnt(8)
	s_waitcnt lgkmcnt(0)
	s_barrier
	s_setprio 1
	v_mfma_f32_16x16x32_bf16 v[124:127], v[180:183], v[216:219], v[124:127]
	v_mfma_f32_16x16x32_bf16 v[120:123], v[188:191], v[216:219], v[120:123]
	v_mfma_f32_16x16x32_bf16 v[116:119], v[180:183], v[224:227], v[116:119]
	v_mfma_f32_16x16x32_bf16 v[112:115], v[188:191], v[224:227], v[112:115]
	v_mfma_f32_16x16x32_bf16 v[108:111], v[180:183], v[232:235], v[108:111]
	v_mfma_f32_16x16x32_bf16 v[104:107], v[188:191], v[232:235], v[104:107]
	v_mfma_f32_16x16x32_bf16 v[100:103], v[180:183], v[240:243], v[100:103]
	v_mfma_f32_16x16x32_bf16 v[96:99], v[188:191], v[240:243], v[96:99]
	v_mfma_f32_16x16x32_bf16 v[124:127], v[184:187], v[220:223], v[124:127]
	v_mfma_f32_16x16x32_bf16 v[120:123], v[192:195], v[220:223], v[120:123]
	v_mfma_f32_16x16x32_bf16 v[116:119], v[184:187], v[228:231], v[116:119]
	v_mfma_f32_16x16x32_bf16 v[112:115], v[192:195], v[228:231], v[112:115]
	v_mfma_f32_16x16x32_bf16 v[108:111], v[184:187], v[236:239], v[108:111]
	v_mfma_f32_16x16x32_bf16 v[104:107], v[192:195], v[236:239], v[104:107]
	v_mfma_f32_16x16x32_bf16 v[100:103], v[184:187], v[244:247], v[100:103]
	v_mfma_f32_16x16x32_bf16 v[96:99], v[192:195], v[244:247], v[96:99]
	v_mfma_f32_16x16x32_bf16 v[64:67], v[196:199], v[216:219], v[64:67]
	v_mfma_f32_16x16x32_bf16 v[56:59], v[208:211], v[216:219], v[56:59]
	v_mfma_f32_16x16x32_bf16 v[52:55], v[196:199], v[224:227], v[52:55]
	v_mfma_f32_16x16x32_bf16 v[48:51], v[208:211], v[224:227], v[48:51]
	v_mfma_f32_16x16x32_bf16 v[44:47], v[196:199], v[232:235], v[44:47]
	v_mfma_f32_16x16x32_bf16 v[40:43], v[208:211], v[232:235], v[40:43]
	v_mfma_f32_16x16x32_bf16 v[36:39], v[196:199], v[240:243], v[36:39]
	v_mfma_f32_16x16x32_bf16 v[32:35], v[208:211], v[240:243], v[32:35]
	v_mfma_f32_16x16x32_bf16 v[64:67], v[200:203], v[220:223], v[64:67]
	v_mfma_f32_16x16x32_bf16 v[56:59], v[212:215], v[220:223], v[56:59]
	v_mfma_f32_16x16x32_bf16 v[52:55], v[200:203], v[228:231], v[52:55]
	v_mfma_f32_16x16x32_bf16 v[48:51], v[212:215], v[228:231], v[48:51]
	v_mfma_f32_16x16x32_bf16 v[44:47], v[200:203], v[236:239], v[44:47]
	v_mfma_f32_16x16x32_bf16 v[40:43], v[212:215], v[236:239], v[40:43]
	v_mfma_f32_16x16x32_bf16 v[36:39], v[200:203], v[244:247], v[36:39]
	v_mfma_f32_16x16x32_bf16 v[32:35], v[212:215], v[244:247], v[32:35]
	s_setprio 0
	s_barrier
	s_add_i32 s70, s66, s53
	v_lshl_add_u64 v[204:205], s[44:45], 0, v[130:131]
	s_mov_b32 m0, s70
	ds_read_b128 v[216:219], v143 offset:16384
	ds_read_b128 v[220:223], v143 offset:17408
	ds_read_b128 v[224:227], v143 offset:18432
	ds_read_b128 v[228:231], v143 offset:19456
	ds_read_b128 v[232:235], v143 offset:20480
	ds_read_b128 v[236:239], v143 offset:21504
	ds_read_b128 v[240:243], v143 offset:22528
	ds_read_b128 v[244:247], v143 offset:23552
	global_load_lds_dwordx4 v[204:205], off
	s_add_i32 m0, s70, 0x2000
	s_add_u32 s70, s44, 0x40000
	v_lshl_add_u64 v[206:207], s[44:45], 0, v[134:135]
	s_addc_u32 s71, s45, 0
	s_add_i32 s82, s67, s53
	global_load_lds_dwordx4 v[206:207], off
	v_lshl_add_u64 v[248:249], s[70:71], 0, v[130:131]
	s_mov_b32 m0, s82
	s_nop 0
	global_load_lds_dwordx4 v[248:249], off
	v_lshl_add_u64 v[248:249], s[70:71], 0, v[134:135]
	s_add_i32 m0, s82, 0x2000
	s_nop 0
	global_load_lds_dwordx4 v[248:249], off
	s_waitcnt vmcnt(6)
	s_waitcnt lgkmcnt(0)
	s_barrier
; #define PG8_STAGE(bufoff, gbase, voff) do { _Pragma("unroll") for (int _i = 0; _i < 2; ++_i) \
;         __builtin_amdgcn_global_load_lds((const unsigned*)((const char*)(gbase) + (voff)[_i]), (PG8_LAS unsigned*)(lds + (bufoff) + ldsw + _i * 8192), 16, 0, 0); } while (0)
; #define PG8_LDA(dst, b, h) do { _Pragma("unroll") for (int m = 0; m < 4; ++m) _Pragma("unroll") for (int k = 0; k < 2; ++k) dst[m][k] = *(const PG8_LAS bf16x8*)(lds + PG8_SA(b, h) + aoff + m * 2048 + k * 1024); } while (0)
; #define PG8_LDB(dst, b, h) do { _Pragma("unroll") for (int n = 0; n < 2; ++n) _Pragma("unroll") for (int k = 0; k < 2; ++k) dst[n][k] = *(const PG8_LAS bf16x8*)(lds + PG8_SB(b, h) + boff + n * 2048 + k * 1024); } while (0)
; #define PG8_MMA(ai, bj, At, Bt) do { __builtin_amdgcn_s_setprio(1); _Pragma("unroll") for (int m = 0; m < 4; ++m) _Pragma("unroll") for (int n = 0; n < 2; ++n) _Pragma("unroll") for (int k = 0; k < 2; ++k) \
;         acc[ai][bj][m][n] = __builtin_amdgcn_mfma_f32_16x16x32_bf16(Bt[n][k], At[m][k], acc[ai][bj][m][n], 0, 0, 0); __builtin_amdgcn_s_setprio(0); } while (0)
; #define PG8_WAIT_V(n) asm volatile("s_waitcnt vmcnt(" #n ")" ::: "memory")
; #define PG8_WAIT_L(n) asm volatile("s_waitcnt lgkmcnt(" #n ")" ::: "memory")
; #define PG8_BAR __builtin_amdgcn_s_barrier()
; #define PG8_SCHED __builtin_amdgcn_sched_barrier(0)
; template <class Epi, class Sched, bool ALIGN_EPI = false, bool SP2 = false>
; __device__ __forceinline__ void gemm_phase(PG8_LAS unsigned char* lds, const Gemm g, const Sched& S, const Epi& E) {
;     ...
;             PG8_WAIT_V(8); PG8_WAIT_L(0); PG8_BAR; PG8_MMA(1, 0, At, B0); PG8_MMA(1, 1, At, B1); PG8_BAR; PG8_SCHED;
;             PG8_LDB(B0, 1, 0); PG8_LDB(B1, 1, 1); PG8_SCHED; PG8_LDA(At, 1, 0); PG8_STAGE(PG8_SA(0, 1), a2 + hstepA, voffA);
;             PG8_WAIT_V(8); PG8_WAIT_L(0); PG8_BAR; PG8_MMA(0, 0, At, B0); PG8_MMA(0, 1, At, B1); PG8_BAR; PG8_SCHED;
	s_setprio 1
	v_mfma_f32_16x16x32_bf16 v[92:95], v[180:183], v[216:219], v[92:95]
	v_mfma_f32_16x16x32_bf16 v[88:91], v[188:191], v[216:219], v[88:91]
	v_mfma_f32_16x16x32_bf16 v[84:87], v[180:183], v[224:227], v[84:87]
	v_mfma_f32_16x16x32_bf16 v[80:83], v[188:191], v[224:227], v[80:83]
	v_mfma_f32_16x16x32_bf16 v[76:79], v[180:183], v[232:235], v[76:79]
	v_mfma_f32_16x16x32_bf16 v[72:75], v[188:191], v[232:235], v[72:75]
	v_mfma_f32_16x16x32_bf16 v[68:71], v[180:183], v[240:243], v[68:71]
	v_mfma_f32_16x16x32_bf16 v[60:63], v[188:191], v[240:243], v[60:63]
	v_mfma_f32_16x16x32_bf16 v[92:95], v[184:187], v[220:223], v[92:95]
	v_mfma_f32_16x16x32_bf16 v[88:91], v[192:195], v[220:223], v[88:91]
	v_mfma_f32_16x16x32_bf16 v[84:87], v[184:187], v[228:231], v[84:87]
	v_mfma_f32_16x16x32_bf16 v[80:83], v[192:195], v[228:231], v[80:83]
	v_mfma_f32_16x16x32_bf16 v[76:79], v[184:187], v[236:239], v[76:79]
	v_mfma_f32_16x16x32_bf16 v[72:75], v[192:195], v[236:239], v[72:75]
	v_mfma_f32_16x16x32_bf16 v[68:71], v[184:187], v[244:247], v[68:71]
	v_mfma_f32_16x16x32_bf16 v[60:63], v[192:195], v[244:247], v[60:63]
	v_mfma_f32_16x16x32_bf16 v[28:31], v[196:199], v[216:219], v[28:31]
	v_mfma_f32_16x16x32_bf16 v[24:27], v[208:211], v[216:219], v[24:27]
	v_mfma_f32_16x16x32_bf16 v[20:23], v[196:199], v[224:227], v[20:23]
	v_mfma_f32_16x16x32_bf16 v[16:19], v[208:211], v[224:227], v[16:19]
	v_mfma_f32_16x16x32_bf16 v[12:15], v[196:199], v[232:235], v[12:15]
	v_mfma_f32_16x16x32_bf16 v[8:11], v[208:211], v[232:235], v[8:11]
	v_mfma_f32_16x16x32_bf16 v[4:7], v[196:199], v[240:243], v[4:7]
	v_mfma_f32_16x16x32_bf16 v[0:3], v[208:211], v[240:243], v[0:3]
	v_mfma_f32_16x16x32_bf16 v[28:31], v[200:203], v[220:223], v[28:31]
	v_mfma_f32_16x16x32_bf16 v[24:27], v[212:215], v[220:223], v[24:27]
	v_mfma_f32_16x16x32_bf16 v[20:23], v[200:203], v[228:231], v[20:23]
	v_mfma_f32_16x16x32_bf16 v[16:19], v[212:215], v[228:231], v[16:19]
	v_mfma_f32_16x16x32_bf16 v[12:15], v[200:203], v[236:239], v[12:15]
	v_mfma_f32_16x16x32_bf16 v[8:11], v[212:215], v[236:239], v[8:11]
	v_mfma_f32_16x16x32_bf16 v[4:7], v[200:203], v[244:247], v[4:7]
	v_mfma_f32_16x16x32_bf16 v[0:3], v[212:215], v[244:247], v[0:3]
	s_setprio 0
	s_barrier
	s_add_i32 s70, 0, 0x18000
	v_add_u32_e32 v137, s70, v141
	s_add_i32 s71, 0, 0x1c000
	ds_read_b128 v[180:183], v137
	ds_read_b128 v[184:187], v137 offset:1024
	ds_read_b128 v[188:191], v137 offset:2048
	ds_read_b128 v[192:195], v137 offset:3072
	v_add_u32_e32 v137, s71, v141
	ds_read_b128 v[196:199], v137
	ds_read_b128 v[200:203], v137 offset:1024
	ds_read_b128 v[208:211], v137 offset:2048
	ds_read_b128 v[212:215], v137 offset:3072
	v_lshl_add_u64 v[248:249], s[46:47], 0, v[128:129]
	s_mov_b32 m0, s54
	s_nop 0
	global_load_lds_dwordx4 v[248:249], off
	v_lshl_add_u64 v[248:249], s[46:47], 0, v[132:133]
	s_mov_b32 m0, s55
	s_nop 0
	global_load_lds_dwordx4 v[248:249], off
	s_add_u32 s46, s46, 0x40000
	s_addc_u32 s47, s47, 0
	s_mov_b32 m0, s56
	v_lshl_add_u64 v[248:249], s[46:47], 0, v[128:129]
	ds_read_b128 v[216:219], v143 offset:32768
	ds_read_b128 v[220:223], v143 offset:33792
	ds_read_b128 v[224:227], v143 offset:34816
	ds_read_b128 v[228:231], v143 offset:35840
	ds_read_b128 v[232:235], v143 offset:36864
	ds_read_b128 v[236:239], v143 offset:37888
	ds_read_b128 v[240:243], v143 offset:38912
	ds_read_b128 v[244:247], v143 offset:39936
	global_load_lds_dwordx4 v[248:249], off
	v_lshl_add_u64 v[248:249], s[46:47], 0, v[132:133]
	s_mov_b32 m0, s57
	s_nop 0
	global_load_lds_dwordx4 v[248:249], off
	s_waitcnt vmcnt(8)
	s_waitcnt lgkmcnt(0)
	s_barrier
	s_setprio 1
	v_mfma_f32_16x16x32_bf16 v[124:127], v[180:183], v[216:219], v[124:127]
	v_mfma_f32_16x16x32_bf16 v[120:123], v[188:191], v[216:219], v[120:123]
	v_mfma_f32_16x16x32_bf16 v[116:119], v[180:183], v[224:227], v[116:119]
	v_mfma_f32_16x16x32_bf16 v[112:115], v[188:191], v[224:227], v[112:115]
	v_mfma_f32_16x16x32_bf16 v[108:111], v[180:183], v[232:235], v[108:111]
	v_mfma_f32_16x16x32_bf16 v[104:107], v[188:191], v[232:235], v[104:107]
	v_mfma_f32_16x16x32_bf16 v[100:103], v[180:183], v[240:243], v[100:103]
	v_mfma_f32_16x16x32_bf16 v[96:99], v[188:191], v[240:243], v[96:99]
	v_mfma_f32_16x16x32_bf16 v[124:127], v[184:187], v[220:223], v[124:127]
	v_mfma_f32_16x16x32_bf16 v[120:123], v[192:195], v[220:223], v[120:123]
	v_mfma_f32_16x16x32_bf16 v[116:119], v[184:187], v[228:231], v[116:119]
	v_mfma_f32_16x16x32_bf16 v[112:115], v[192:195], v[228:231], v[112:115]
	v_mfma_f32_16x16x32_bf16 v[108:111], v[184:187], v[236:239], v[108:111]
	v_mfma_f32_16x16x32_bf16 v[104:107], v[192:195], v[236:239], v[104:107]
	v_mfma_f32_16x16x32_bf16 v[100:103], v[184:187], v[244:247], v[100:103]
	v_mfma_f32_16x16x32_bf16 v[96:99], v[192:195], v[244:247], v[96:99]
	v_mfma_f32_16x16x32_bf16 v[64:67], v[196:199], v[216:219], v[64:67]
	v_mfma_f32_16x16x32_bf16 v[56:59], v[208:211], v[216:219], v[56:59]
	v_mfma_f32_16x16x32_bf16 v[52:55], v[196:199], v[224:227], v[52:55]
	v_mfma_f32_16x16x32_bf16 v[48:51], v[208:211], v[224:227], v[48:51]
	v_mfma_f32_16x16x32_bf16 v[44:47], v[196:199], v[232:235], v[44:47]
	v_mfma_f32_16x16x32_bf16 v[40:43], v[208:211], v[232:235], v[40:43]
	v_mfma_f32_16x16x32_bf16 v[36:39], v[196:199], v[240:243], v[36:39]
	v_mfma_f32_16x16x32_bf16 v[32:35], v[208:211], v[240:243], v[32:35]
	v_mfma_f32_16x16x32_bf16 v[64:67], v[200:203], v[220:223], v[64:67]
	v_mfma_f32_16x16x32_bf16 v[56:59], v[212:215], v[220:223], v[56:59]
	v_mfma_f32_16x16x32_bf16 v[52:55], v[200:203], v[228:231], v[52:55]
	v_mfma_f32_16x16x32_bf16 v[48:51], v[212:215], v[228:231], v[48:51]
	v_mfma_f32_16x16x32_bf16 v[44:47], v[200:203], v[236:239], v[44:47]
	v_mfma_f32_16x16x32_bf16 v[40:43], v[212:215], v[236:239], v[40:43]
	v_mfma_f32_16x16x32_bf16 v[36:39], v[200:203], v[244:247], v[36:39]
	v_mfma_f32_16x16x32_bf16 v[32:35], v[212:215], v[244:247], v[32:35]
	s_setprio 0
	s_barrier
; #define PG8_STAGE(bufoff, gbase, voff) do { _Pragma("unroll") for (int _i = 0; _i < 2; ++_i) \
;         __builtin_amdgcn_global_load_lds((const unsigned*)((const char*)(gbase) + (voff)[_i]), (PG8_LAS unsigned*)(lds + (bufoff) + ldsw + _i * 8192), 16, 0, 0); } while (0)
; #define PG8_LDA(dst, b, h) do { _Pragma("unroll") for (int m = 0; m < 4; ++m) _Pragma("unroll") for (int k = 0; k < 2; ++k) dst[m][k] = *(const PG8_LAS bf16x8*)(lds + PG8_SA(b, h) + aoff + m * 2048 + k * 1024); } while (0)
; #define PG8_MMA(ai, bj, At, Bt) do { __builtin_amdgcn_s_setprio(1); _Pragma("unroll") for (int m = 0; m < 4; ++m) _Pragma("unroll") for (int n = 0; n < 2; ++n) _Pragma("unroll") for (int k = 0; k < 2; ++k) \
;         acc[ai][bj][m][n] = __builtin_amdgcn_mfma_f32_16x16x32_bf16(Bt[n][k], At[m][k], acc[ai][bj][m][n], 0, 0, 0); __builtin_amdgcn_s_setprio(0); } while (0)
; #define PG8_WAIT_V(n) asm volatile("s_waitcnt vmcnt(" #n ")" ::: "memory")
; #define PG8_WAIT_L(n) asm volatile("s_waitcnt lgkmcnt(" #n ")" ::: "memory")
; #define PG8_BAR __builtin_amdgcn_s_barrier()
; #define PG8_SCHED __builtin_amdgcn_sched_barrier(0)
; template <class Epi, class Sched, bool ALIGN_EPI = false, bool SP2 = false>
; __device__ __forceinline__ void gemm_phase(PG8_LAS unsigned char* lds, const Gemm g, const Sched& S, const Epi& E) {
;     ...
;             PG8_LDA(At, 1, 1); PG8_STAGE(PG8_SB(1, 0), b3, voffB); PG8_STAGE(PG8_SB(1, 1), b3 + hstepB, voffB); PG8_STAGE(PG8_SA(1, 0), a3, voffA);
;             PG8_WAIT_V(8); PG8_WAIT_L(0); PG8_BAR; PG8_MMA(1, 0, At, B0); PG8_MMA(1, 1, At, B1); PG8_BAR; PG8_SCHED;
;     ...
;         if constexpr (ALIGN_EPI) { if (wr == 0) PG8_BAR; }
;         if constexpr (!Epi::AFTER_DRAIN) { E(acc, cur, wr, wc, fr, fq); S.done(cur); }
;         if (!has_next) break;
	s_add_i32 s46, s70, s53
	v_lshl_add_u64 v[204:205], v[204:205], 0, s[20:21]
	s_mov_b32 m0, s46
	ds_read_b128 v[216:219], v143 offset:49152
	ds_read_b128 v[220:223], v143 offset:50176
	ds_read_b128 v[224:227], v143 offset:51200
	ds_read_b128 v[228:231], v143 offset:52224
	ds_read_b128 v[232:235], v143 offset:53248
	ds_read_b128 v[236:239], v143 offset:54272
	ds_read_b128 v[240:243], v143 offset:55296
	ds_read_b128 v[244:247], v143 offset:56320
	global_load_lds_dwordx4 v[204:205], off
	s_add_i32 m0, s46, 0x2000
	s_add_u32 s44, s44, 0x40080
	v_lshl_add_u64 v[204:205], v[206:207], 0, s[20:21]
	s_addc_u32 s45, s45, 0
	s_add_i32 s46, s71, s53
	global_load_lds_dwordx4 v[204:205], off
	v_lshl_add_u64 v[204:205], s[44:45], 0, v[130:131]
	s_mov_b32 m0, s46
	s_nop 0
	global_load_lds_dwordx4 v[204:205], off
	v_lshl_add_u64 v[204:205], s[44:45], 0, v[134:135]
	s_add_i32 m0, s46, 0x2000
	s_nop 0
	global_load_lds_dwordx4 v[204:205], off
	v_lshl_add_u64 v[204:205], s[42:43], 0, v[128:129]
	s_mov_b32 m0, s62
	s_nop 0
	global_load_lds_dwordx4 v[204:205], off
	v_lshl_add_u64 v[204:205], s[42:43], 0, v[132:133]
	s_mov_b32 m0, s63
	s_nop 0
	global_load_lds_dwordx4 v[204:205], off
	s_waitcnt vmcnt(8)
	s_waitcnt lgkmcnt(0)
	s_barrier
	s_setprio 1
	v_mfma_f32_16x16x32_bf16 v[92:95], v[180:183], v[216:219], v[92:95]
	v_mfma_f32_16x16x32_bf16 v[88:91], v[188:191], v[216:219], v[88:91]
	v_mfma_f32_16x16x32_bf16 v[84:87], v[180:183], v[224:227], v[84:87]
	v_mfma_f32_16x16x32_bf16 v[80:83], v[188:191], v[224:227], v[80:83]
	v_mfma_f32_16x16x32_bf16 v[76:79], v[180:183], v[232:235], v[76:79]
	v_mfma_f32_16x16x32_bf16 v[72:75], v[188:191], v[232:235], v[72:75]
	v_mfma_f32_16x16x32_bf16 v[68:71], v[180:183], v[240:243], v[68:71]
	v_mfma_f32_16x16x32_bf16 v[60:63], v[188:191], v[240:243], v[60:63]
	v_mfma_f32_16x16x32_bf16 v[92:95], v[184:187], v[220:223], v[92:95]
	v_mfma_f32_16x16x32_bf16 v[88:91], v[192:195], v[220:223], v[88:91]
	v_mfma_f32_16x16x32_bf16 v[84:87], v[184:187], v[228:231], v[84:87]
	v_mfma_f32_16x16x32_bf16 v[80:83], v[192:195], v[228:231], v[80:83]
	v_mfma_f32_16x16x32_bf16 v[76:79], v[184:187], v[236:239], v[76:79]
	v_mfma_f32_16x16x32_bf16 v[72:75], v[192:195], v[236:239], v[72:75]
	v_mfma_f32_16x16x32_bf16 v[68:71], v[184:187], v[244:247], v[68:71]
	v_mfma_f32_16x16x32_bf16 v[60:63], v[192:195], v[244:247], v[60:63]
	v_mfma_f32_16x16x32_bf16 v[28:31], v[196:199], v[216:219], v[28:31]
	v_mfma_f32_16x16x32_bf16 v[24:27], v[208:211], v[216:219], v[24:27]
	v_mfma_f32_16x16x32_bf16 v[20:23], v[196:199], v[224:227], v[20:23]
	v_mfma_f32_16x16x32_bf16 v[16:19], v[208:211], v[224:227], v[16:19]
	v_mfma_f32_16x16x32_bf16 v[12:15], v[196:199], v[232:235], v[12:15]
	v_mfma_f32_16x16x32_bf16 v[8:11], v[208:211], v[232:235], v[8:11]
	v_mfma_f32_16x16x32_bf16 v[4:7], v[196:199], v[240:243], v[4:7]
	v_mfma_f32_16x16x32_bf16 v[0:3], v[208:211], v[240:243], v[0:3]
	v_mfma_f32_16x16x32_bf16 v[28:31], v[200:203], v[220:223], v[28:31]
	v_mfma_f32_16x16x32_bf16 v[24:27], v[212:215], v[220:223], v[24:27]
	v_mfma_f32_16x16x32_bf16 v[20:23], v[200:203], v[228:231], v[20:23]
	v_mfma_f32_16x16x32_bf16 v[16:19], v[212:215], v[228:231], v[16:19]
	v_mfma_f32_16x16x32_bf16 v[12:15], v[200:203], v[236:239], v[12:15]
	v_mfma_f32_16x16x32_bf16 v[8:11], v[212:215], v[236:239], v[8:11]
	v_mfma_f32_16x16x32_bf16 v[4:7], v[200:203], v[244:247], v[4:7]
	v_mfma_f32_16x16x32_bf16 v[0:3], v[212:215], v[244:247], v[0:3]
	s_setprio 0
	s_barrier
	s_add_i32 s81, s81, 2
	s_add_u32 s40, s40, 0x100
	s_addc_u32 s41, s41, 0
	s_cmp_gt_u32 s81, 13
	s_cbranch_scc0 .LBB0_332
	s_and_b64 vcc, exec, s[22:23]
	s_cbranch_vccz .LBB0_335
	s_barrier

; #define PG8_STAGE(bufoff, gbase, voff) do { _Pragma("unroll") for (int _i = 0; _i < 2; ++_i) \
;         __builtin_amdgcn_global_load_lds((const unsigned*)((const char*)(gbase) + (voff)[_i]), (PG8_LAS unsigned*)(lds + (bufoff) + ldsw + _i * 8192), 16, 0, 0); } while (0)
; #define PG8_LDA(dst, b, h) do { _Pragma("unroll") for (int m = 0; m < 4; ++m) _Pragma("unroll") for (int k = 0; k < 2; ++k) dst[m][k] = *(const PG8_LAS bf16x8*)(lds + PG8_SA(b, h) + aoff + m * 2048 + k * 1024); } while (0)
; #define PG8_LDB(dst, b, h) do { _Pragma("unroll") for (int n = 0; n < 2; ++n) _Pragma("unroll") for (int k = 0; k < 2; ++k) dst[n][k] = *(const PG8_LAS bf16x8*)(lds + PG8_SB(b, h) + boff + n * 2048 + k * 1024); } while (0)
; #define PG8_MMA(ai, bj, At, Bt) do { __builtin_amdgcn_s_setprio(1); _Pragma("unroll") for (int m = 0; m < 4; ++m) _Pragma("unroll") for (int n = 0; n < 2; ++n) _Pragma("unroll") for (int k = 0; k < 2; ++k) \
;         acc[ai][bj][m][n] = __builtin_amdgcn_mfma_f32_16x16x32_bf16(Bt[n][k], At[m][k], acc[ai][bj][m][n], 0, 0, 0); __builtin_amdgcn_s_setprio(0); } while (0)
; #define PG8_WAIT_V(n) asm volatile("s_waitcnt vmcnt(" #n ")" ::: "memory")
; #define PG8_WAIT_L(n) asm volatile("s_waitcnt lgkmcnt(" #n ")" ::: "memory")
; template <class Epi, class Sched, bool ALIGN_EPI = false, bool SP2 = false>
; __device__ __forceinline__ void gemm_phase(PG8_LAS unsigned char* lds, const Gemm g, const Sched& S, const Epi& E) {
;     ...
;             const bool last = (t == nt - 2);
;             const char* a1 = cA + PG8_AK(t + 1);
;             const char* a2 = last ? nA : cA + PG8_AK(t + 2); const char* b2 = last ? nB : cB + (size_t)(t + 2) * kstep;
;             const char* a3 = last ? nA + PG8_AK(1) : cA + PG8_AK(t + 3); const char* b3 = b2 + kstep;
;             if (last && has_next) S.a_ready(nxt);
;             if constexpr (SP2) {
;             PG8_LDB(B0, 0, 0); PG8_LDB(B1, 0, 1); PG8_SCHED; PG8_LDA(At, 0, 0); PG8_STAGE(PG8_SA(1, 1), a1 + hstepA, voffA);
;             PG8_WAIT_V(8); PG8_WAIT_L(0); PG8_BAR; PG8_MMA(0, 0, At, B0); PG8_MMA(0, 1, At, B1); PG8_BAR; PG8_SCHED;
;             PG8_LDA(At, 0, 1); PG8_STAGE(PG8_SB(0, 0), b2, voffB); PG8_STAGE(PG8_SB(0, 1), b2 + hstepB, voffB); PG8_STAGE(PG8_SA(0, 0), a2, voffA);
;             PG8_WAIT_V(8); PG8_WAIT_L(0); PG8_BAR; PG8_MMA(1, 0, At, B0); PG8_MMA(1, 1, At, B1); PG8_BAR; PG8_SCHED;
.LBB0_416:
	ds_read_b128 v[132:135], v171
	ds_read_b128 v[136:139], v171 offset:1024
	ds_read_b128 v[140:143], v171 offset:2048
	ds_read_b128 v[178:181], v171 offset:3072
	ds_read_b128 v[182:185], v173
	ds_read_b128 v[186:189], v173 offset:1024
	ds_read_b128 v[190:193], v173 offset:2048
	ds_read_b128 v[194:197], v173 offset:3072
	s_add_u32 s38, s34, s36
	s_addc_u32 s39, s35, s37
	s_add_u32 s42, s38, 0x100
	s_addc_u32 s43, s39, 0
	s_add_u32 s40, s66, s36
	s_addc_u32 s41, s67, s37
	s_add_u32 s38, s38, 0x180
	s_addc_u32 s39, s39, 0
	s_cmpk_eq_i32 s36, 0x700
	s_cselect_b32 s39, s65, s39
	s_cselect_b32 s38, s64, s38
	s_cselect_b32 s41, s23, s41
	s_cselect_b32 s40, s63, s40
	s_cselect_b32 s43, s3, s43
	s_cselect_b32 s42, s25, s42
	v_lshl_add_u64 v[206:207], v[130:131], 0, s[36:37]
	s_add_i32 m0, s31, 0xc000
	ds_read_b128 v[198:201], v175
	ds_read_b128 v[202:205], v175 offset:1024
	ds_read_b128 v[208:211], v175 offset:2048
	ds_read_b128 v[212:215], v175 offset:3072
	ds_read_b128 v[216:219], v175 offset:4096
	ds_read_b128 v[220:223], v175 offset:5120
	ds_read_b128 v[224:227], v175 offset:6144
	ds_read_b128 v[228:231], v175 offset:7168
	global_load_lds_dwordx4 v[206:207], off
	v_lshl_add_u64 v[206:207], v[128:129], 0, s[36:37]
	s_add_i32 m0, s31, 0xe000
	s_nop 0
	global_load_lds_dwordx4 v[206:207], off
	s_waitcnt vmcnt(8)
	s_waitcnt lgkmcnt(0)
	s_barrier
	s_setprio 1
	v_mfma_f32_16x16x32_bf16 v[124:127], v[132:135], v[198:201], v[124:127]
	v_mfma_f32_16x16x32_bf16 v[120:123], v[140:143], v[198:201], v[120:123]
	v_mfma_f32_16x16x32_bf16 v[116:119], v[132:135], v[208:211], v[116:119]
	v_mfma_f32_16x16x32_bf16 v[112:115], v[140:143], v[208:211], v[112:115]
	v_mfma_f32_16x16x32_bf16 v[108:111], v[132:135], v[216:219], v[108:111]
	v_mfma_f32_16x16x32_bf16 v[104:107], v[140:143], v[216:219], v[104:107]
	v_mfma_f32_16x16x32_bf16 v[100:103], v[132:135], v[224:227], v[100:103]
	v_mfma_f32_16x16x32_bf16 v[96:99], v[140:143], v[224:227], v[96:99]
	v_mfma_f32_16x16x32_bf16 v[124:127], v[136:139], v[202:205], v[124:127]
	v_mfma_f32_16x16x32_bf16 v[120:123], v[178:181], v[202:205], v[120:123]
	v_mfma_f32_16x16x32_bf16 v[116:119], v[136:139], v[212:215], v[116:119]
	v_mfma_f32_16x16x32_bf16 v[112:115], v[178:181], v[212:215], v[112:115]
	v_mfma_f32_16x16x32_bf16 v[108:111], v[136:139], v[220:223], v[108:111]
	v_mfma_f32_16x16x32_bf16 v[104:107], v[178:181], v[220:223], v[104:107]
	v_mfma_f32_16x16x32_bf16 v[100:103], v[136:139], v[228:231], v[100:103]
	v_mfma_f32_16x16x32_bf16 v[96:99], v[178:181], v[228:231], v[96:99]
	v_mfma_f32_16x16x32_bf16 v[64:67], v[182:185], v[198:201], v[64:67]
	v_mfma_f32_16x16x32_bf16 v[56:59], v[190:193], v[198:201], v[56:59]
	v_mfma_f32_16x16x32_bf16 v[52:55], v[182:185], v[208:211], v[52:55]
	v_mfma_f32_16x16x32_bf16 v[48:51], v[190:193], v[208:211], v[48:51]
	v_mfma_f32_16x16x32_bf16 v[44:47], v[182:185], v[216:219], v[44:47]
	v_mfma_f32_16x16x32_bf16 v[40:43], v[190:193], v[216:219], v[40:43]
	v_mfma_f32_16x16x32_bf16 v[36:39], v[182:185], v[224:227], v[36:39]
	v_mfma_f32_16x16x32_bf16 v[32:35], v[190:193], v[224:227], v[32:35]
	v_mfma_f32_16x16x32_bf16 v[64:67], v[186:189], v[202:205], v[64:67]
	v_mfma_f32_16x16x32_bf16 v[56:59], v[194:197], v[202:205], v[56:59]
	v_mfma_f32_16x16x32_bf16 v[52:55], v[186:189], v[212:215], v[52:55]
	v_mfma_f32_16x16x32_bf16 v[48:51], v[194:197], v[212:215], v[48:51]
	v_mfma_f32_16x16x32_bf16 v[44:47], v[186:189], v[220:223], v[44:47]
	v_mfma_f32_16x16x32_bf16 v[40:43], v[194:197], v[220:223], v[40:43]
	v_mfma_f32_16x16x32_bf16 v[36:39], v[186:189], v[228:231], v[36:39]
	v_mfma_f32_16x16x32_bf16 v[32:35], v[194:197], v[228:231], v[32:35]
	s_setprio 0
	s_barrier
	s_add_i32 s69, s59, s49
	v_lshl_add_u64 v[206:207], s[40:41], 0, v[148:149]
	s_mov_b32 m0, s69
	ds_read_b128 v[198:201], v175 offset:16384
	ds_read_b128 v[202:205], v175 offset:17408
	ds_read_b128 v[208:211], v175 offset:18432
	ds_read_b128 v[212:215], v175 offset:19456
	ds_read_b128 v[216:219], v175 offset:20480
	ds_read_b128 v[220:223], v175 offset:21504
	ds_read_b128 v[224:227], v175 offset:22528
	ds_read_b128 v[228:231], v175 offset:23552
	global_load_lds_dwordx4 v[206:207], off
	s_add_i32 m0, s69, 0x2000
	s_add_u32 s70, s40, 0x40000
	v_lshl_add_u64 v[232:233], s[40:41], 0, v[144:145]
	s_addc_u32 s71, s41, 0
	s_add_i32 s69, s60, s49
	global_load_lds_dwordx4 v[232:233], off
	v_lshl_add_u64 v[234:235], s[70:71], 0, v[148:149]
	s_mov_b32 m0, s69
	s_nop 0
	global_load_lds_dwordx4 v[234:235], off
	v_lshl_add_u64 v[234:235], s[70:71], 0, v[144:145]
	s_add_i32 m0, s69, 0x2000
	s_nop 0
	global_load_lds_dwordx4 v[234:235], off
	s_waitcnt vmcnt(6)
	s_waitcnt lgkmcnt(0)
	s_barrier
; #define PG8_STAGE(bufoff, gbase, voff) do { _Pragma("unroll") for (int _i = 0; _i < 2; ++_i) \
;         __builtin_amdgcn_global_load_lds((const unsigned*)((const char*)(gbase) + (voff)[_i]), (PG8_LAS unsigned*)(lds + (bufoff) + ldsw + _i * 8192), 16, 0, 0); } while (0)
; #define PG8_LDA(dst, b, h) do { _Pragma("unroll") for (int m = 0; m < 4; ++m) _Pragma("unroll") for (int k = 0; k < 2; ++k) dst[m][k] = *(const PG8_LAS bf16x8*)(lds + PG8_SA(b, h) + aoff + m * 2048 + k * 1024); } while (0)
; #define PG8_LDB(dst, b, h) do { _Pragma("unroll") for (int n = 0; n < 2; ++n) _Pragma("unroll") for (int k = 0; k < 2; ++k) dst[n][k] = *(const PG8_LAS bf16x8*)(lds + PG8_SB(b, h) + boff + n * 2048 + k * 1024); } while (0)
; #define PG8_MMA(ai, bj, At, Bt) do { __builtin_amdgcn_s_setprio(1); _Pragma("unroll") for (int m = 0; m < 4; ++m) _Pragma("unroll") for (int n = 0; n < 2; ++n) _Pragma("unroll") for (int k = 0; k < 2; ++k) \
;         acc[ai][bj][m][n] = __builtin_amdgcn_mfma_f32_16x16x32_bf16(Bt[n][k], At[m][k], acc[ai][bj][m][n], 0, 0, 0); __builtin_amdgcn_s_setprio(0); } while (0)
; #define PG8_WAIT_V(n) asm volatile("s_waitcnt vmcnt(" #n ")" ::: "memory")
; #define PG8_WAIT_L(n) asm volatile("s_waitcnt lgkmcnt(" #n ")" ::: "memory")
; #define PG8_BAR __builtin_amdgcn_s_barrier()
; #define PG8_SCHED __builtin_amdgcn_sched_barrier(0)
; template <class Epi, class Sched, bool ALIGN_EPI = false, bool SP2 = false>
; __device__ __forceinline__ void gemm_phase(PG8_LAS unsigned char* lds, const Gemm g, const Sched& S, const Epi& E) {
;     ...
;             PG8_WAIT_V(8); PG8_WAIT_L(0); PG8_BAR; PG8_MMA(1, 0, At, B0); PG8_MMA(1, 1, At, B1); PG8_BAR; PG8_SCHED;
;             PG8_LDB(B0, 1, 0); PG8_LDB(B1, 1, 1); PG8_SCHED; PG8_LDA(At, 1, 0); PG8_STAGE(PG8_SA(0, 1), a2 + hstepA, voffA);
;             PG8_WAIT_V(8); PG8_WAIT_L(0); PG8_BAR; PG8_MMA(0, 0, At, B0); PG8_MMA(0, 1, At, B1); PG8_BAR; PG8_SCHED;
	s_setprio 1
	v_mfma_f32_16x16x32_bf16 v[92:95], v[132:135], v[198:201], v[92:95]
	v_mfma_f32_16x16x32_bf16 v[88:91], v[140:143], v[198:201], v[88:91]
	v_mfma_f32_16x16x32_bf16 v[84:87], v[132:135], v[208:211], v[84:87]
	v_mfma_f32_16x16x32_bf16 v[80:83], v[140:143], v[208:211], v[80:83]
	v_mfma_f32_16x16x32_bf16 v[76:79], v[132:135], v[216:219], v[76:79]
	v_mfma_f32_16x16x32_bf16 v[72:75], v[140:143], v[216:219], v[72:75]
	v_mfma_f32_16x16x32_bf16 v[68:71], v[132:135], v[224:227], v[68:71]
	v_mfma_f32_16x16x32_bf16 v[60:63], v[140:143], v[224:227], v[60:63]
	v_mfma_f32_16x16x32_bf16 v[92:95], v[136:139], v[202:205], v[92:95]
	v_mfma_f32_16x16x32_bf16 v[88:91], v[178:181], v[202:205], v[88:91]
	v_mfma_f32_16x16x32_bf16 v[84:87], v[136:139], v[212:215], v[84:87]
	v_mfma_f32_16x16x32_bf16 v[80:83], v[178:181], v[212:215], v[80:83]
	v_mfma_f32_16x16x32_bf16 v[76:79], v[136:139], v[220:223], v[76:79]
	v_mfma_f32_16x16x32_bf16 v[72:75], v[178:181], v[220:223], v[72:75]
	v_mfma_f32_16x16x32_bf16 v[68:71], v[136:139], v[228:231], v[68:71]
	v_mfma_f32_16x16x32_bf16 v[60:63], v[178:181], v[228:231], v[60:63]
	v_mfma_f32_16x16x32_bf16 v[28:31], v[182:185], v[198:201], v[28:31]
	v_mfma_f32_16x16x32_bf16 v[24:27], v[190:193], v[198:201], v[24:27]
	v_mfma_f32_16x16x32_bf16 v[20:23], v[182:185], v[208:211], v[20:23]
	v_mfma_f32_16x16x32_bf16 v[16:19], v[190:193], v[208:211], v[16:19]
	v_mfma_f32_16x16x32_bf16 v[12:15], v[182:185], v[216:219], v[12:15]
	v_mfma_f32_16x16x32_bf16 v[8:11], v[190:193], v[216:219], v[8:11]
	v_mfma_f32_16x16x32_bf16 v[4:7], v[182:185], v[224:227], v[4:7]
	v_mfma_f32_16x16x32_bf16 v[0:3], v[190:193], v[224:227], v[0:3]
	v_mfma_f32_16x16x32_bf16 v[28:31], v[186:189], v[202:205], v[28:31]
	v_mfma_f32_16x16x32_bf16 v[24:27], v[194:197], v[202:205], v[24:27]
	v_mfma_f32_16x16x32_bf16 v[20:23], v[186:189], v[212:215], v[20:23]
	v_mfma_f32_16x16x32_bf16 v[16:19], v[194:197], v[212:215], v[16:19]
	v_mfma_f32_16x16x32_bf16 v[12:15], v[186:189], v[220:223], v[12:15]
	v_mfma_f32_16x16x32_bf16 v[8:11], v[194:197], v[220:223], v[8:11]
	v_mfma_f32_16x16x32_bf16 v[4:7], v[186:189], v[228:231], v[4:7]
	v_mfma_f32_16x16x32_bf16 v[0:3], v[194:197], v[228:231], v[0:3]
	s_setprio 0
	s_barrier
	s_add_i32 s69, 0, 0x18000
	v_add_u32_e32 v160, s69, v163
	s_add_i32 s70, 0, 0x1c000
	ds_read_b128 v[132:135], v160
	ds_read_b128 v[136:139], v160 offset:1024
	ds_read_b128 v[140:143], v160 offset:2048
	ds_read_b128 v[178:181], v160 offset:3072
	v_add_u32_e32 v160, s70, v163
	ds_read_b128 v[182:185], v160
	ds_read_b128 v[186:189], v160 offset:1024
	ds_read_b128 v[190:193], v160 offset:2048
	ds_read_b128 v[194:197], v160 offset:3072
	v_lshl_add_u64 v[234:235], s[42:43], 0, v[150:151]
	s_mov_b32 m0, s31
	s_nop 0
	global_load_lds_dwordx4 v[234:235], off
	v_lshl_add_u64 v[234:235], s[42:43], 0, v[146:147]
	s_mov_b32 m0, s52
	s_nop 0
	global_load_lds_dwordx4 v[234:235], off
	s_add_u32 s42, s42, 0x40000
	s_addc_u32 s43, s43, 0
	s_mov_b32 m0, s53
	v_lshl_add_u64 v[234:235], s[42:43], 0, v[150:151]
	ds_read_b128 v[198:201], v175 offset:32768
	ds_read_b128 v[202:205], v175 offset:33792
	ds_read_b128 v[208:211], v175 offset:34816
	ds_read_b128 v[212:215], v175 offset:35840
	ds_read_b128 v[216:219], v175 offset:36864
	ds_read_b128 v[220:223], v175 offset:37888
	ds_read_b128 v[224:227], v175 offset:38912
	ds_read_b128 v[228:231], v175 offset:39936
	global_load_lds_dwordx4 v[234:235], off
	v_lshl_add_u64 v[234:235], s[42:43], 0, v[146:147]
	s_mov_b32 m0, s54
	s_nop 0
	global_load_lds_dwordx4 v[234:235], off
	s_waitcnt vmcnt(8)
	s_waitcnt lgkmcnt(0)
	s_barrier
	s_setprio 1
	v_mfma_f32_16x16x32_bf16 v[124:127], v[132:135], v[198:201], v[124:127]
	v_mfma_f32_16x16x32_bf16 v[120:123], v[140:143], v[198:201], v[120:123]
	v_mfma_f32_16x16x32_bf16 v[116:119], v[132:135], v[208:211], v[116:119]
	v_mfma_f32_16x16x32_bf16 v[112:115], v[140:143], v[208:211], v[112:115]
	v_mfma_f32_16x16x32_bf16 v[108:111], v[132:135], v[216:219], v[108:111]
	v_mfma_f32_16x16x32_bf16 v[104:107], v[140:143], v[216:219], v[104:107]
	v_mfma_f32_16x16x32_bf16 v[100:103], v[132:135], v[224:227], v[100:103]
	v_mfma_f32_16x16x32_bf16 v[96:99], v[140:143], v[224:227], v[96:99]
	v_mfma_f32_16x16x32_bf16 v[124:127], v[136:139], v[202:205], v[124:127]
	v_mfma_f32_16x16x32_bf16 v[120:123], v[178:181], v[202:205], v[120:123]
	v_mfma_f32_16x16x32_bf16 v[116:119], v[136:139], v[212:215], v[116:119]
	v_mfma_f32_16x16x32_bf16 v[112:115], v[178:181], v[212:215], v[112:115]
	v_mfma_f32_16x16x32_bf16 v[108:111], v[136:139], v[220:223], v[108:111]
	v_mfma_f32_16x16x32_bf16 v[104:107], v[178:181], v[220:223], v[104:107]
	v_mfma_f32_16x16x32_bf16 v[100:103], v[136:139], v[228:231], v[100:103]
	v_mfma_f32_16x16x32_bf16 v[96:99], v[178:181], v[228:231], v[96:99]
	v_mfma_f32_16x16x32_bf16 v[64:67], v[182:185], v[198:201], v[64:67]
	v_mfma_f32_16x16x32_bf16 v[56:59], v[190:193], v[198:201], v[56:59]
	v_mfma_f32_16x16x32_bf16 v[52:55], v[182:185], v[208:211], v[52:55]
	v_mfma_f32_16x16x32_bf16 v[48:51], v[190:193], v[208:211], v[48:51]
	v_mfma_f32_16x16x32_bf16 v[44:47], v[182:185], v[216:219], v[44:47]
	v_mfma_f32_16x16x32_bf16 v[40:43], v[190:193], v[216:219], v[40:43]
	v_mfma_f32_16x16x32_bf16 v[36:39], v[182:185], v[224:227], v[36:39]
	v_mfma_f32_16x16x32_bf16 v[32:35], v[190:193], v[224:227], v[32:35]
	v_mfma_f32_16x16x32_bf16 v[64:67], v[186:189], v[202:205], v[64:67]
	v_mfma_f32_16x16x32_bf16 v[56:59], v[194:197], v[202:205], v[56:59]
	v_mfma_f32_16x16x32_bf16 v[52:55], v[186:189], v[212:215], v[52:55]
	v_mfma_f32_16x16x32_bf16 v[48:51], v[194:197], v[212:215], v[48:51]
	v_mfma_f32_16x16x32_bf16 v[44:47], v[186:189], v[220:223], v[44:47]
	v_mfma_f32_16x16x32_bf16 v[40:43], v[194:197], v[220:223], v[40:43]
	v_mfma_f32_16x16x32_bf16 v[36:39], v[186:189], v[228:231], v[36:39]
	v_mfma_f32_16x16x32_bf16 v[32:35], v[194:197], v[228:231], v[32:35]
	s_setprio 0
	s_barrier
; #define PG8_STAGE(bufoff, gbase, voff) do { _Pragma("unroll") for (int _i = 0; _i < 2; ++_i) \
;         __builtin_amdgcn_global_load_lds((const unsigned*)((const char*)(gbase) + (voff)[_i]), (PG8_LAS unsigned*)(lds + (bufoff) + ldsw + _i * 8192), 16, 0, 0); } while (0)
; #define PG8_LDA(dst, b, h) do { _Pragma("unroll") for (int m = 0; m < 4; ++m) _Pragma("unroll") for (int k = 0; k < 2; ++k) dst[m][k] = *(const PG8_LAS bf16x8*)(lds + PG8_SA(b, h) + aoff + m * 2048 + k * 1024); } while (0)
; #define PG8_MMA(ai, bj, At, Bt) do { __builtin_amdgcn_s_setprio(1); _Pragma("unroll") for (int m = 0; m < 4; ++m) _Pragma("unroll") for (int n = 0; n < 2; ++n) _Pragma("unroll") for (int k = 0; k < 2; ++k) \
;         acc[ai][bj][m][n] = __builtin_amdgcn_mfma_f32_16x16x32_bf16(Bt[n][k], At[m][k], acc[ai][bj][m][n], 0, 0, 0); __builtin_amdgcn_s_setprio(0); } while (0)
; #define PG8_WAIT_V(n) asm volatile("s_waitcnt vmcnt(" #n ")" ::: "memory")
; #define PG8_WAIT_L(n) asm volatile("s_waitcnt lgkmcnt(" #n ")" ::: "memory")
; #define PG8_BAR __builtin_amdgcn_s_barrier()
; #define PG8_SCHED __builtin_amdgcn_sched_barrier(0)
; template <class Epi, class Sched, bool ALIGN_EPI = false, bool SP2 = false>
; __device__ __forceinline__ void gemm_phase(PG8_LAS unsigned char* lds, const Gemm g, const Sched& S, const Epi& E) {
;     ...
;             PG8_LDA(At, 1, 1); PG8_STAGE(PG8_SB(1, 0), b3, voffB); PG8_STAGE(PG8_SB(1, 1), b3 + hstepB, voffB); PG8_STAGE(PG8_SA(1, 0), a3, voffA);
;             PG8_WAIT_V(8); PG8_WAIT_L(0); PG8_BAR; PG8_MMA(1, 0, At, B0); PG8_MMA(1, 1, At, B1); PG8_BAR; PG8_SCHED;
;     ...
;         if constexpr (ALIGN_EPI) { if (wr == 0) PG8_BAR; }
;         if constexpr (!Epi::AFTER_DRAIN) { E(acc, cur, wr, wc, fr, fq); S.done(cur); }
;         if (!has_next) break;
	s_add_i32 s42, s69, s49
	v_lshl_add_u64 v[206:207], v[206:207], 0, s[16:17]
	s_mov_b32 m0, s42
	ds_read_b128 v[198:201], v175 offset:49152
	ds_read_b128 v[202:205], v175 offset:50176
	ds_read_b128 v[208:211], v175 offset:51200
	ds_read_b128 v[212:215], v175 offset:52224
	ds_read_b128 v[216:219], v175 offset:53248
	ds_read_b128 v[220:223], v175 offset:54272
	ds_read_b128 v[224:227], v175 offset:55296
	ds_read_b128 v[228:231], v175 offset:56320
	global_load_lds_dwordx4 v[206:207], off
	s_add_i32 m0, s42, 0x2000
	s_add_u32 s40, s40, 0x40080
	v_lshl_add_u64 v[206:207], v[232:233], 0, s[16:17]
	s_addc_u32 s41, s41, 0
	s_add_i32 s42, s70, s49
	global_load_lds_dwordx4 v[206:207], off
	v_lshl_add_u64 v[206:207], s[40:41], 0, v[148:149]
	s_mov_b32 m0, s42
	s_nop 0
	global_load_lds_dwordx4 v[206:207], off
	v_lshl_add_u64 v[206:207], s[40:41], 0, v[144:145]
	s_add_i32 m0, s42, 0x2000
	s_nop 0
	global_load_lds_dwordx4 v[206:207], off
	v_lshl_add_u64 v[206:207], s[38:39], 0, v[150:151]
	s_mov_b32 m0, s56
	s_nop 0
	global_load_lds_dwordx4 v[206:207], off
	v_lshl_add_u64 v[206:207], s[38:39], 0, v[146:147]
	s_mov_b32 m0, s57
	s_nop 0
	global_load_lds_dwordx4 v[206:207], off
	s_waitcnt vmcnt(8)
	s_waitcnt lgkmcnt(0)
	s_barrier
	s_setprio 1
	v_mfma_f32_16x16x32_bf16 v[92:95], v[132:135], v[198:201], v[92:95]
	v_mfma_f32_16x16x32_bf16 v[88:91], v[140:143], v[198:201], v[88:91]
	v_mfma_f32_16x16x32_bf16 v[84:87], v[132:135], v[208:211], v[84:87]
	v_mfma_f32_16x16x32_bf16 v[80:83], v[140:143], v[208:211], v[80:83]
	v_mfma_f32_16x16x32_bf16 v[76:79], v[132:135], v[216:219], v[76:79]
	v_mfma_f32_16x16x32_bf16 v[72:75], v[140:143], v[216:219], v[72:75]
	v_mfma_f32_16x16x32_bf16 v[68:71], v[132:135], v[224:227], v[68:71]
	v_mfma_f32_16x16x32_bf16 v[60:63], v[140:143], v[224:227], v[60:63]
	v_mfma_f32_16x16x32_bf16 v[92:95], v[136:139], v[202:205], v[92:95]
	v_mfma_f32_16x16x32_bf16 v[88:91], v[178:181], v[202:205], v[88:91]
	v_mfma_f32_16x16x32_bf16 v[84:87], v[136:139], v[212:215], v[84:87]
	v_mfma_f32_16x16x32_bf16 v[80:83], v[178:181], v[212:215], v[80:83]
	v_mfma_f32_16x16x32_bf16 v[76:79], v[136:139], v[220:223], v[76:79]
	v_mfma_f32_16x16x32_bf16 v[72:75], v[178:181], v[220:223], v[72:75]
	v_mfma_f32_16x16x32_bf16 v[68:71], v[136:139], v[228:231], v[68:71]
	v_mfma_f32_16x16x32_bf16 v[60:63], v[178:181], v[228:231], v[60:63]
	v_mfma_f32_16x16x32_bf16 v[28:31], v[182:185], v[198:201], v[28:31]
	v_mfma_f32_16x16x32_bf16 v[24:27], v[190:193], v[198:201], v[24:27]
	v_mfma_f32_16x16x32_bf16 v[20:23], v[182:185], v[208:211], v[20:23]
	v_mfma_f32_16x16x32_bf16 v[16:19], v[190:193], v[208:211], v[16:19]
	v_mfma_f32_16x16x32_bf16 v[12:15], v[182:185], v[216:219], v[12:15]
	v_mfma_f32_16x16x32_bf16 v[8:11], v[190:193], v[216:219], v[8:11]
	v_mfma_f32_16x16x32_bf16 v[4:7], v[182:185], v[224:227], v[4:7]
	v_mfma_f32_16x16x32_bf16 v[0:3], v[190:193], v[224:227], v[0:3]
	v_mfma_f32_16x16x32_bf16 v[28:31], v[186:189], v[202:205], v[28:31]
	v_mfma_f32_16x16x32_bf16 v[24:27], v[194:197], v[202:205], v[24:27]
	v_mfma_f32_16x16x32_bf16 v[20:23], v[186:189], v[212:215], v[20:23]
	v_mfma_f32_16x16x32_bf16 v[16:19], v[194:197], v[212:215], v[16:19]
	v_mfma_f32_16x16x32_bf16 v[12:15], v[186:189], v[220:223], v[12:15]
	v_mfma_f32_16x16x32_bf16 v[8:11], v[194:197], v[220:223], v[8:11]
	v_mfma_f32_16x16x32_bf16 v[4:7], v[186:189], v[228:231], v[4:7]
	v_mfma_f32_16x16x32_bf16 v[0:3], v[194:197], v[228:231], v[0:3]
	s_setprio 0
	s_barrier
	s_add_i32 s68, s68, 2
	s_add_u32 s36, s36, 0x100
	s_addc_u32 s37, s37, 0
	s_cmp_gt_u32 s68, 13
	s_cbranch_scc0 .LBB0_416
	s_and_b64 vcc, exec, s[18:19]
	s_cbranch_vccz .LBB0_419
	s_barrier

; #define PG8_STAGE(bufoff, gbase, voff) do { _Pragma("unroll") for (int _i = 0; _i < 2; ++_i) \
;         __builtin_amdgcn_global_load_lds((const unsigned*)((const char*)(gbase) + (voff)[_i]), (PG8_LAS unsigned*)(lds + (bufoff) + ldsw + _i * 8192), 16, 0, 0); } while (0)
; #define PG8_LDA(dst, b, h) do { _Pragma("unroll") for (int m = 0; m < 4; ++m) _Pragma("unroll") for (int k = 0; k < 2; ++k) dst[m][k] = *(const PG8_LAS bf16x8*)(lds + PG8_SA(b, h) + aoff + m * 2048 + k * 1024); } while (0)
; #define PG8_LDB(dst, b, h) do { _Pragma("unroll") for (int n = 0; n < 2; ++n) _Pragma("unroll") for (int k = 0; k < 2; ++k) dst[n][k] = *(const PG8_LAS bf16x8*)(lds + PG8_SB(b, h) + boff + n * 2048 + k * 1024); } while (0)
; #define PG8_MMA(ai, bj, At, Bt) do { __builtin_amdgcn_s_setprio(1); _Pragma("unroll") for (int m = 0; m < 4; ++m) _Pragma("unroll") for (int n = 0; n < 2; ++n) _Pragma("unroll") for (int k = 0; k < 2; ++k) \
;         acc[ai][bj][m][n] = __builtin_amdgcn_mfma_f32_16x16x32_bf16(Bt[n][k], At[m][k], acc[ai][bj][m][n], 0, 0, 0); __builtin_amdgcn_s_setprio(0); } while (0)
; #define PG8_WAIT_V(n) asm volatile("s_waitcnt vmcnt(" #n ")" ::: "memory")
; #define PG8_WAIT_L(n) asm volatile("s_waitcnt lgkmcnt(" #n ")" ::: "memory")
; template <class Epi, class Sched, bool ALIGN_EPI = false, bool SP2 = false>
; __device__ __forceinline__ void gemm_phase(PG8_LAS unsigned char* lds, const Gemm g, const Sched& S, const Epi& E) {
;     ...
;             const bool last = (t == nt - 2);
;             const char* a1 = cA + PG8_AK(t + 1);
;             const char* a2 = last ? nA : cA + PG8_AK(t + 2); const char* b2 = last ? nB : cB + (size_t)(t + 2) * kstep;
;             const char* a3 = last ? nA + PG8_AK(1) : cA + PG8_AK(t + 3); const char* b3 = b2 + kstep;
;             if (last && has_next) S.a_ready(nxt);
;             if constexpr (SP2) {
;             PG8_LDB(B0, 0, 0); PG8_LDB(B1, 0, 1); PG8_SCHED; PG8_LDA(At, 0, 0); PG8_STAGE(PG8_SA(1, 1), a1 + hstepA, voffA);
;             PG8_WAIT_V(8); PG8_WAIT_L(0); PG8_BAR; PG8_MMA(0, 0, At, B0); PG8_MMA(0, 1, At, B1); PG8_BAR; PG8_SCHED;
;             PG8_LDA(At, 0, 1); PG8_STAGE(PG8_SB(0, 0), b2, voffB); PG8_STAGE(PG8_SB(0, 1), b2 + hstepB, voffB); PG8_STAGE(PG8_SA(0, 0), a2, voffA);
;             PG8_WAIT_V(8); PG8_WAIT_L(0); PG8_BAR; PG8_MMA(1, 0, At, B0); PG8_MMA(1, 1, At, B1); PG8_BAR; PG8_SCHED;
.LBB0_520:
	ds_read_b128 v[124:127], v210
	ds_read_b128 v[128:131], v210 offset:1024
	ds_read_b128 v[132:135], v210 offset:2048
	ds_read_b128 v[144:147], v210 offset:3072
	ds_read_b128 v[148:151], v211
	ds_read_b128 v[170:173], v211 offset:1024
	ds_read_b128 v[174:177], v211 offset:2048
	ds_read_b128 v[178:181], v211 offset:3072
	s_add_u32 s42, s38, s40
	s_addc_u32 s43, s39, s41
	s_add_u32 s46, s42, 0x100
	s_addc_u32 s47, s43, 0
	s_add_u32 s44, s79, s40
	s_addc_u32 s45, s83, s41
	s_add_u32 s42, s42, 0x180
	s_addc_u32 s43, s43, 0
	s_cmpk_eq_i32 s40, 0x1500
	s_cselect_b32 s43, s78, s43
	s_cselect_b32 s42, s3, s42
	s_cselect_b32 s45, s37, s45
	s_cselect_b32 s44, s36, s44
	s_cselect_b32 s47, s9, s47
	s_cselect_b32 s46, s8, s46
	v_lshl_add_u64 v[206:207], v[122:123], 0, s[40:41]
	s_add_i32 m0, s53, 0xc000
	ds_read_b128 v[212:215], v191
	ds_read_b128 v[216:219], v191 offset:1024
	ds_read_b128 v[220:223], v191 offset:2048
	ds_read_b128 v[224:227], v191 offset:3072
	ds_read_b128 v[228:231], v191 offset:4096
	ds_read_b128 v[232:235], v191 offset:5120
	ds_read_b128 v[236:239], v191 offset:6144
	ds_read_b128 v[240:243], v191 offset:7168
	global_load_lds_dwordx4 v[206:207], off
	v_lshl_add_u64 v[206:207], v[120:121], 0, s[40:41]
	s_add_i32 m0, s53, 0xe000
	s_nop 0
	global_load_lds_dwordx4 v[206:207], off
	s_waitcnt vmcnt(8)
	s_waitcnt lgkmcnt(0)
	s_barrier
	s_setprio 1
	v_mfma_f32_16x16x32_bf16 v[140:143], v[124:127], v[212:215], v[140:143]
	v_mfma_f32_16x16x32_bf16 v[136:139], v[132:135], v[212:215], v[136:139]
	v_mfma_f32_16x16x32_bf16 v[116:119], v[124:127], v[220:223], v[116:119]
	v_mfma_f32_16x16x32_bf16 v[112:115], v[132:135], v[220:223], v[112:115]
	v_mfma_f32_16x16x32_bf16 v[108:111], v[124:127], v[228:231], v[108:111]
	v_mfma_f32_16x16x32_bf16 v[104:107], v[132:135], v[228:231], v[104:107]
	v_mfma_f32_16x16x32_bf16 v[100:103], v[124:127], v[236:239], v[100:103]
	v_mfma_f32_16x16x32_bf16 v[96:99], v[132:135], v[236:239], v[96:99]
	v_mfma_f32_16x16x32_bf16 v[140:143], v[128:131], v[216:219], v[140:143]
	v_mfma_f32_16x16x32_bf16 v[136:139], v[144:147], v[216:219], v[136:139]
	v_mfma_f32_16x16x32_bf16 v[116:119], v[128:131], v[224:227], v[116:119]
	v_mfma_f32_16x16x32_bf16 v[112:115], v[144:147], v[224:227], v[112:115]
	v_mfma_f32_16x16x32_bf16 v[108:111], v[128:131], v[232:235], v[108:111]
	v_mfma_f32_16x16x32_bf16 v[104:107], v[144:147], v[232:235], v[104:107]
	v_mfma_f32_16x16x32_bf16 v[100:103], v[128:131], v[240:243], v[100:103]
	v_mfma_f32_16x16x32_bf16 v[96:99], v[144:147], v[240:243], v[96:99]
	v_mfma_f32_16x16x32_bf16 v[60:63], v[148:151], v[212:215], v[60:63]
	v_mfma_f32_16x16x32_bf16 v[56:59], v[174:177], v[212:215], v[56:59]
	v_mfma_f32_16x16x32_bf16 v[52:55], v[148:151], v[220:223], v[52:55]
	v_mfma_f32_16x16x32_bf16 v[48:51], v[174:177], v[220:223], v[48:51]
	v_mfma_f32_16x16x32_bf16 v[44:47], v[148:151], v[228:231], v[44:47]
	v_mfma_f32_16x16x32_bf16 v[40:43], v[174:177], v[228:231], v[40:43]
	v_mfma_f32_16x16x32_bf16 v[36:39], v[148:151], v[236:239], v[36:39]
	v_mfma_f32_16x16x32_bf16 v[32:35], v[174:177], v[236:239], v[32:35]
	v_mfma_f32_16x16x32_bf16 v[60:63], v[170:173], v[216:219], v[60:63]
	v_mfma_f32_16x16x32_bf16 v[56:59], v[178:181], v[216:219], v[56:59]
	v_mfma_f32_16x16x32_bf16 v[52:55], v[170:173], v[224:227], v[52:55]
	v_mfma_f32_16x16x32_bf16 v[48:51], v[178:181], v[224:227], v[48:51]
	v_mfma_f32_16x16x32_bf16 v[44:47], v[170:173], v[232:235], v[44:47]
	v_mfma_f32_16x16x32_bf16 v[40:43], v[178:181], v[232:235], v[40:43]
	v_mfma_f32_16x16x32_bf16 v[36:39], v[170:173], v[240:243], v[36:39]
	v_mfma_f32_16x16x32_bf16 v[32:35], v[178:181], v[240:243], v[32:35]
	s_setprio 0
	s_barrier
	s_add_i32 s70, s67, s52
	v_lshl_add_u64 v[206:207], s[44:45], 0, v[154:155]
	s_mov_b32 m0, s70
	ds_read_b128 v[212:215], v191 offset:16384
	ds_read_b128 v[216:219], v191 offset:17408
	ds_read_b128 v[220:223], v191 offset:18432
	ds_read_b128 v[224:227], v191 offset:19456
	ds_read_b128 v[228:231], v191 offset:20480
	ds_read_b128 v[232:235], v191 offset:21504
	ds_read_b128 v[236:239], v191 offset:22528
	ds_read_b128 v[240:243], v191 offset:23552
	global_load_lds_dwordx4 v[206:207], off
	s_add_i32 m0, s70, 0x2000
	s_add_u32 s70, s44, 0xb0000
	v_lshl_add_u64 v[244:245], s[44:45], 0, v[158:159]
	s_addc_u32 s71, s45, 0
	s_add_i32 s85, s68, s52
	global_load_lds_dwordx4 v[244:245], off
	v_lshl_add_u64 v[246:247], s[70:71], 0, v[154:155]
	s_mov_b32 m0, s85
	s_nop 0
	global_load_lds_dwordx4 v[246:247], off
	v_lshl_add_u64 v[246:247], s[70:71], 0, v[158:159]
	s_add_i32 m0, s85, 0x2000
	s_nop 0
	global_load_lds_dwordx4 v[246:247], off
	s_waitcnt vmcnt(6)
	s_waitcnt lgkmcnt(0)
	s_barrier
; #define PG8_STAGE(bufoff, gbase, voff) do { _Pragma("unroll") for (int _i = 0; _i < 2; ++_i) \
;         __builtin_amdgcn_global_load_lds((const unsigned*)((const char*)(gbase) + (voff)[_i]), (PG8_LAS unsigned*)(lds + (bufoff) + ldsw + _i * 8192), 16, 0, 0); } while (0)
; #define PG8_LDA(dst, b, h) do { _Pragma("unroll") for (int m = 0; m < 4; ++m) _Pragma("unroll") for (int k = 0; k < 2; ++k) dst[m][k] = *(const PG8_LAS bf16x8*)(lds + PG8_SA(b, h) + aoff + m * 2048 + k * 1024); } while (0)
; #define PG8_LDB(dst, b, h) do { _Pragma("unroll") for (int n = 0; n < 2; ++n) _Pragma("unroll") for (int k = 0; k < 2; ++k) dst[n][k] = *(const PG8_LAS bf16x8*)(lds + PG8_SB(b, h) + boff + n * 2048 + k * 1024); } while (0)
; #define PG8_MMA(ai, bj, At, Bt) do { __builtin_amdgcn_s_setprio(1); _Pragma("unroll") for (int m = 0; m < 4; ++m) _Pragma("unroll") for (int n = 0; n < 2; ++n) _Pragma("unroll") for (int k = 0; k < 2; ++k) \
;         acc[ai][bj][m][n] = __builtin_amdgcn_mfma_f32_16x16x32_bf16(Bt[n][k], At[m][k], acc[ai][bj][m][n], 0, 0, 0); __builtin_amdgcn_s_setprio(0); } while (0)
; #define PG8_WAIT_V(n) asm volatile("s_waitcnt vmcnt(" #n ")" ::: "memory")
; #define PG8_WAIT_L(n) asm volatile("s_waitcnt lgkmcnt(" #n ")" ::: "memory")
; #define PG8_BAR __builtin_amdgcn_s_barrier()
; #define PG8_SCHED __builtin_amdgcn_sched_barrier(0)
; template <class Epi, class Sched, bool ALIGN_EPI = false, bool SP2 = false>
; __device__ __forceinline__ void gemm_phase(PG8_LAS unsigned char* lds, const Gemm g, const Sched& S, const Epi& E) {
;     ...
;             PG8_WAIT_V(8); PG8_WAIT_L(0); PG8_BAR; PG8_MMA(1, 0, At, B0); PG8_MMA(1, 1, At, B1); PG8_BAR; PG8_SCHED;
;             PG8_LDB(B0, 1, 0); PG8_LDB(B1, 1, 1); PG8_SCHED; PG8_LDA(At, 1, 0); PG8_STAGE(PG8_SA(0, 1), a2 + hstepA, voffA);
;             PG8_WAIT_V(8); PG8_WAIT_L(0); PG8_BAR; PG8_MMA(0, 0, At, B0); PG8_MMA(0, 1, At, B1); PG8_BAR; PG8_SCHED;
	s_setprio 1
	v_mfma_f32_16x16x32_bf16 v[92:95], v[124:127], v[212:215], v[92:95]
	v_mfma_f32_16x16x32_bf16 v[88:91], v[132:135], v[212:215], v[88:91]
	v_mfma_f32_16x16x32_bf16 v[84:87], v[124:127], v[220:223], v[84:87]
	v_mfma_f32_16x16x32_bf16 v[80:83], v[132:135], v[220:223], v[80:83]
	v_mfma_f32_16x16x32_bf16 v[76:79], v[124:127], v[228:231], v[76:79]
	v_mfma_f32_16x16x32_bf16 v[72:75], v[132:135], v[228:231], v[72:75]
	v_mfma_f32_16x16x32_bf16 v[68:71], v[124:127], v[236:239], v[68:71]
	v_mfma_f32_16x16x32_bf16 v[64:67], v[132:135], v[236:239], v[64:67]
	v_mfma_f32_16x16x32_bf16 v[92:95], v[128:131], v[216:219], v[92:95]
	v_mfma_f32_16x16x32_bf16 v[88:91], v[144:147], v[216:219], v[88:91]
	v_mfma_f32_16x16x32_bf16 v[84:87], v[128:131], v[224:227], v[84:87]
	v_mfma_f32_16x16x32_bf16 v[80:83], v[144:147], v[224:227], v[80:83]
	v_mfma_f32_16x16x32_bf16 v[76:79], v[128:131], v[232:235], v[76:79]
	v_mfma_f32_16x16x32_bf16 v[72:75], v[144:147], v[232:235], v[72:75]
	v_mfma_f32_16x16x32_bf16 v[68:71], v[128:131], v[240:243], v[68:71]
	v_mfma_f32_16x16x32_bf16 v[64:67], v[144:147], v[240:243], v[64:67]
	v_mfma_f32_16x16x32_bf16 v[28:31], v[148:151], v[212:215], v[28:31]
	v_mfma_f32_16x16x32_bf16 v[24:27], v[174:177], v[212:215], v[24:27]
	v_mfma_f32_16x16x32_bf16 v[20:23], v[148:151], v[220:223], v[20:23]
	v_mfma_f32_16x16x32_bf16 v[16:19], v[174:177], v[220:223], v[16:19]
	v_mfma_f32_16x16x32_bf16 v[12:15], v[148:151], v[228:231], v[12:15]
	v_mfma_f32_16x16x32_bf16 v[8:11], v[174:177], v[228:231], v[8:11]
	v_mfma_f32_16x16x32_bf16 v[4:7], v[148:151], v[236:239], v[4:7]
	v_mfma_f32_16x16x32_bf16 v[0:3], v[174:177], v[236:239], v[0:3]
	v_mfma_f32_16x16x32_bf16 v[28:31], v[170:173], v[216:219], v[28:31]
	v_mfma_f32_16x16x32_bf16 v[24:27], v[178:181], v[216:219], v[24:27]
	v_mfma_f32_16x16x32_bf16 v[20:23], v[170:173], v[224:227], v[20:23]
	v_mfma_f32_16x16x32_bf16 v[16:19], v[178:181], v[224:227], v[16:19]
	v_mfma_f32_16x16x32_bf16 v[12:15], v[170:173], v[232:235], v[12:15]
	v_mfma_f32_16x16x32_bf16 v[8:11], v[178:181], v[232:235], v[8:11]
	v_mfma_f32_16x16x32_bf16 v[4:7], v[170:173], v[240:243], v[4:7]
	v_mfma_f32_16x16x32_bf16 v[0:3], v[178:181], v[240:243], v[0:3]
	s_setprio 0
	s_barrier
	s_add_i32 s70, 0, 0x18000
	s_add_i32 s71, 0, 0x1c000
	v_add_u32_e32 v144, s70, v185
	v_add_u32_e32 v161, s71, v185
	ds_read_b128 v[124:127], v144
	ds_read_b128 v[128:131], v144 offset:1024
	ds_read_b128 v[132:135], v144 offset:2048
	ds_read_b128 v[144:147], v144 offset:3072
	ds_read_b128 v[148:151], v161
	ds_read_b128 v[170:173], v161 offset:1024
	ds_read_b128 v[174:177], v161 offset:2048
	ds_read_b128 v[178:181], v161 offset:3072
	v_lshl_add_u64 v[246:247], s[46:47], 0, v[152:153]
	s_mov_b32 m0, s53
	s_nop 0
	global_load_lds_dwordx4 v[246:247], off
	v_lshl_add_u64 v[246:247], s[46:47], 0, v[156:157]
	s_mov_b32 m0, s54
	s_nop 0
	global_load_lds_dwordx4 v[246:247], off
	s_add_u32 s46, s46, 0xb0000
	s_addc_u32 s47, s47, 0
	s_mov_b32 m0, s55
	v_lshl_add_u64 v[246:247], s[46:47], 0, v[152:153]
	ds_read_b128 v[212:215], v191 offset:32768
	ds_read_b128 v[216:219], v191 offset:33792
	ds_read_b128 v[220:223], v191 offset:34816
	ds_read_b128 v[224:227], v191 offset:35840
	ds_read_b128 v[228:231], v191 offset:36864
	ds_read_b128 v[232:235], v191 offset:37888
	ds_read_b128 v[236:239], v191 offset:38912
	ds_read_b128 v[240:243], v191 offset:39936
	global_load_lds_dwordx4 v[246:247], off
	v_lshl_add_u64 v[246:247], s[46:47], 0, v[156:157]
	s_mov_b32 m0, s56
	s_nop 0
	global_load_lds_dwordx4 v[246:247], off
	s_waitcnt vmcnt(8)
	s_waitcnt lgkmcnt(0)
	s_barrier
	s_setprio 1
	v_mfma_f32_16x16x32_bf16 v[140:143], v[124:127], v[212:215], v[140:143]
	v_mfma_f32_16x16x32_bf16 v[136:139], v[132:135], v[212:215], v[136:139]
	v_mfma_f32_16x16x32_bf16 v[116:119], v[124:127], v[220:223], v[116:119]
	v_mfma_f32_16x16x32_bf16 v[112:115], v[132:135], v[220:223], v[112:115]
	v_mfma_f32_16x16x32_bf16 v[108:111], v[124:127], v[228:231], v[108:111]
	v_mfma_f32_16x16x32_bf16 v[104:107], v[132:135], v[228:231], v[104:107]
	v_mfma_f32_16x16x32_bf16 v[100:103], v[124:127], v[236:239], v[100:103]
	v_mfma_f32_16x16x32_bf16 v[96:99], v[132:135], v[236:239], v[96:99]
	v_mfma_f32_16x16x32_bf16 v[140:143], v[128:131], v[216:219], v[140:143]
	v_mfma_f32_16x16x32_bf16 v[136:139], v[144:147], v[216:219], v[136:139]
	v_mfma_f32_16x16x32_bf16 v[116:119], v[128:131], v[224:227], v[116:119]
	v_mfma_f32_16x16x32_bf16 v[112:115], v[144:147], v[224:227], v[112:115]
	v_mfma_f32_16x16x32_bf16 v[108:111], v[128:131], v[232:235], v[108:111]
	v_mfma_f32_16x16x32_bf16 v[104:107], v[144:147], v[232:235], v[104:107]
	v_mfma_f32_16x16x32_bf16 v[100:103], v[128:131], v[240:243], v[100:103]
	v_mfma_f32_16x16x32_bf16 v[96:99], v[144:147], v[240:243], v[96:99]
	v_mfma_f32_16x16x32_bf16 v[60:63], v[148:151], v[212:215], v[60:63]
	v_mfma_f32_16x16x32_bf16 v[56:59], v[174:177], v[212:215], v[56:59]
	v_mfma_f32_16x16x32_bf16 v[52:55], v[148:151], v[220:223], v[52:55]
	v_mfma_f32_16x16x32_bf16 v[48:51], v[174:177], v[220:223], v[48:51]
	v_mfma_f32_16x16x32_bf16 v[44:47], v[148:151], v[228:231], v[44:47]
	v_mfma_f32_16x16x32_bf16 v[40:43], v[174:177], v[228:231], v[40:43]
	v_mfma_f32_16x16x32_bf16 v[36:39], v[148:151], v[236:239], v[36:39]
	v_mfma_f32_16x16x32_bf16 v[32:35], v[174:177], v[236:239], v[32:35]
	v_mfma_f32_16x16x32_bf16 v[60:63], v[170:173], v[216:219], v[60:63]
	v_mfma_f32_16x16x32_bf16 v[56:59], v[178:181], v[216:219], v[56:59]
	v_mfma_f32_16x16x32_bf16 v[52:55], v[170:173], v[224:227], v[52:55]
	v_mfma_f32_16x16x32_bf16 v[48:51], v[178:181], v[224:227], v[48:51]
	v_mfma_f32_16x16x32_bf16 v[44:47], v[170:173], v[232:235], v[44:47]
	v_mfma_f32_16x16x32_bf16 v[40:43], v[178:181], v[232:235], v[40:43]
	v_mfma_f32_16x16x32_bf16 v[36:39], v[170:173], v[240:243], v[36:39]
	v_mfma_f32_16x16x32_bf16 v[32:35], v[178:181], v[240:243], v[32:35]
	s_setprio 0
	s_barrier
; #define PG8_STAGE(bufoff, gbase, voff) do { _Pragma("unroll") for (int _i = 0; _i < 2; ++_i) \
;         __builtin_amdgcn_global_load_lds((const unsigned*)((const char*)(gbase) + (voff)[_i]), (PG8_LAS unsigned*)(lds + (bufoff) + ldsw + _i * 8192), 16, 0, 0); } while (0)
; #define PG8_LDA(dst, b, h) do { _Pragma("unroll") for (int m = 0; m < 4; ++m) _Pragma("unroll") for (int k = 0; k < 2; ++k) dst[m][k] = *(const PG8_LAS bf16x8*)(lds + PG8_SA(b, h) + aoff + m * 2048 + k * 1024); } while (0)
; #define PG8_MMA(ai, bj, At, Bt) do { __builtin_amdgcn_s_setprio(1); _Pragma("unroll") for (int m = 0; m < 4; ++m) _Pragma("unroll") for (int n = 0; n < 2; ++n) _Pragma("unroll") for (int k = 0; k < 2; ++k) \
;         acc[ai][bj][m][n] = __builtin_amdgcn_mfma_f32_16x16x32_bf16(Bt[n][k], At[m][k], acc[ai][bj][m][n], 0, 0, 0); __builtin_amdgcn_s_setprio(0); } while (0)
; #define PG8_WAIT_V(n) asm volatile("s_waitcnt vmcnt(" #n ")" ::: "memory")
; #define PG8_WAIT_L(n) asm volatile("s_waitcnt lgkmcnt(" #n ")" ::: "memory")
; #define PG8_BAR __builtin_amdgcn_s_barrier()
; #define PG8_SCHED __builtin_amdgcn_sched_barrier(0)
; template <class Epi, class Sched, bool ALIGN_EPI = false, bool SP2 = false>
; __device__ __forceinline__ void gemm_phase(PG8_LAS unsigned char* lds, const Gemm g, const Sched& S, const Epi& E) {
;     ...
;             PG8_LDA(At, 1, 1); PG8_STAGE(PG8_SB(1, 0), b3, voffB); PG8_STAGE(PG8_SB(1, 1), b3 + hstepB, voffB); PG8_STAGE(PG8_SA(1, 0), a3, voffA);
;             PG8_WAIT_V(8); PG8_WAIT_L(0); PG8_BAR; PG8_MMA(1, 0, At, B0); PG8_MMA(1, 1, At, B1); PG8_BAR; PG8_SCHED;
;     ...
;         if constexpr (ALIGN_EPI) { if (wr == 0) PG8_BAR; }
;         if constexpr (!Epi::AFTER_DRAIN) { E(acc, cur, wr, wc, fr, fq); S.done(cur); }
;         if (!has_next) break;
	s_add_i32 s46, s70, s52
	v_lshl_add_u64 v[206:207], v[206:207], 0, s[26:27]
	s_mov_b32 m0, s46
	ds_read_b128 v[212:215], v191 offset:49152
	ds_read_b128 v[216:219], v191 offset:50176
	ds_read_b128 v[220:223], v191 offset:51200
	ds_read_b128 v[224:227], v191 offset:52224
	ds_read_b128 v[228:231], v191 offset:53248
	ds_read_b128 v[232:235], v191 offset:54272
	ds_read_b128 v[236:239], v191 offset:55296
	ds_read_b128 v[240:243], v191 offset:56320
	global_load_lds_dwordx4 v[206:207], off
	s_add_i32 m0, s46, 0x2000
	s_add_u32 s44, s44, 0xb0080
	v_lshl_add_u64 v[206:207], v[244:245], 0, s[26:27]
	s_addc_u32 s45, s45, 0
	s_add_i32 s46, s71, s52
	global_load_lds_dwordx4 v[206:207], off
	v_lshl_add_u64 v[206:207], s[44:45], 0, v[154:155]
	s_mov_b32 m0, s46
	s_nop 0
	global_load_lds_dwordx4 v[206:207], off
	v_lshl_add_u64 v[206:207], s[44:45], 0, v[158:159]
	s_add_i32 m0, s46, 0x2000
	s_nop 0
	global_load_lds_dwordx4 v[206:207], off
	v_lshl_add_u64 v[206:207], s[42:43], 0, v[152:153]
	s_mov_b32 m0, s63
	s_nop 0
	global_load_lds_dwordx4 v[206:207], off
	v_lshl_add_u64 v[206:207], s[42:43], 0, v[156:157]
	s_mov_b32 m0, s64
	s_nop 0
	global_load_lds_dwordx4 v[206:207], off
	s_waitcnt vmcnt(8)
	s_waitcnt lgkmcnt(0)
	s_barrier
	s_setprio 1
	v_mfma_f32_16x16x32_bf16 v[92:95], v[124:127], v[212:215], v[92:95]
	v_mfma_f32_16x16x32_bf16 v[88:91], v[132:135], v[212:215], v[88:91]
	v_mfma_f32_16x16x32_bf16 v[84:87], v[124:127], v[220:223], v[84:87]
	v_mfma_f32_16x16x32_bf16 v[80:83], v[132:135], v[220:223], v[80:83]
	v_mfma_f32_16x16x32_bf16 v[76:79], v[124:127], v[228:231], v[76:79]
	v_mfma_f32_16x16x32_bf16 v[72:75], v[132:135], v[228:231], v[72:75]
	v_mfma_f32_16x16x32_bf16 v[68:71], v[124:127], v[236:239], v[68:71]
	v_mfma_f32_16x16x32_bf16 v[64:67], v[132:135], v[236:239], v[64:67]
	v_mfma_f32_16x16x32_bf16 v[92:95], v[128:131], v[216:219], v[92:95]
	v_mfma_f32_16x16x32_bf16 v[88:91], v[144:147], v[216:219], v[88:91]
	v_mfma_f32_16x16x32_bf16 v[84:87], v[128:131], v[224:227], v[84:87]
	v_mfma_f32_16x16x32_bf16 v[80:83], v[144:147], v[224:227], v[80:83]
	v_mfma_f32_16x16x32_bf16 v[76:79], v[128:131], v[232:235], v[76:79]
	v_mfma_f32_16x16x32_bf16 v[72:75], v[144:147], v[232:235], v[72:75]
	v_mfma_f32_16x16x32_bf16 v[68:71], v[128:131], v[240:243], v[68:71]
	v_mfma_f32_16x16x32_bf16 v[64:67], v[144:147], v[240:243], v[64:67]
	v_mfma_f32_16x16x32_bf16 v[28:31], v[148:151], v[212:215], v[28:31]
	v_mfma_f32_16x16x32_bf16 v[24:27], v[174:177], v[212:215], v[24:27]
	v_mfma_f32_16x16x32_bf16 v[20:23], v[148:151], v[220:223], v[20:23]
	v_mfma_f32_16x16x32_bf16 v[16:19], v[174:177], v[220:223], v[16:19]
	v_mfma_f32_16x16x32_bf16 v[12:15], v[148:151], v[228:231], v[12:15]
	v_mfma_f32_16x16x32_bf16 v[8:11], v[174:177], v[228:231], v[8:11]
	v_mfma_f32_16x16x32_bf16 v[4:7], v[148:151], v[236:239], v[4:7]
	v_mfma_f32_16x16x32_bf16 v[0:3], v[174:177], v[236:239], v[0:3]
	v_mfma_f32_16x16x32_bf16 v[28:31], v[170:173], v[216:219], v[28:31]
	v_mfma_f32_16x16x32_bf16 v[24:27], v[178:181], v[216:219], v[24:27]
	v_mfma_f32_16x16x32_bf16 v[20:23], v[170:173], v[224:227], v[20:23]
	v_mfma_f32_16x16x32_bf16 v[16:19], v[178:181], v[224:227], v[16:19]
	v_mfma_f32_16x16x32_bf16 v[12:15], v[170:173], v[232:235], v[12:15]
	v_mfma_f32_16x16x32_bf16 v[8:11], v[178:181], v[232:235], v[8:11]
	v_mfma_f32_16x16x32_bf16 v[4:7], v[170:173], v[240:243], v[4:7]
	v_mfma_f32_16x16x32_bf16 v[0:3], v[178:181], v[240:243], v[0:3]
	s_setprio 0
	s_barrier
	s_add_i32 s84, s84, 2
	s_add_u32 s40, s40, 0x100
	s_addc_u32 s41, s41, 0
	s_cmp_gt_u32 s84, 41
	s_cbranch_scc0 .LBB0_520
	s_and_b64 vcc, exec, s[28:29]
	s_cbranch_vccz .LBB0_523
	s_barrier

; #define PG8_STAGE(bufoff, gbase, voff) do { _Pragma("unroll") for (int _i = 0; _i < 2; ++_i) \
;         __builtin_amdgcn_global_load_lds((const unsigned*)((const char*)(gbase) + (voff)[_i]), (PG8_LAS unsigned*)(lds + (bufoff) + ldsw + _i * 8192), 16, 0, 0); } while (0)
; #define PG8_LDA(dst, b, h) do { _Pragma("unroll") for (int m = 0; m < 4; ++m) _Pragma("unroll") for (int k = 0; k < 2; ++k) dst[m][k] = *(const PG8_LAS bf16x8*)(lds + PG8_SA(b, h) + aoff + m * 2048 + k * 1024); } while (0)
; #define PG8_LDB(dst, b, h) do { _Pragma("unroll") for (int n = 0; n < 2; ++n) _Pragma("unroll") for (int k = 0; k < 2; ++k) dst[n][k] = *(const PG8_LAS bf16x8*)(lds + PG8_SB(b, h) + boff + n * 2048 + k * 1024); } while (0)
; #define PG8_MMA(ai, bj, At, Bt) do { __builtin_amdgcn_s_setprio(1); _Pragma("unroll") for (int m = 0; m < 4; ++m) _Pragma("unroll") for (int n = 0; n < 2; ++n) _Pragma("unroll") for (int k = 0; k < 2; ++k) \
;         acc[ai][bj][m][n] = __builtin_amdgcn_mfma_f32_16x16x32_bf16(Bt[n][k], At[m][k], acc[ai][bj][m][n], 0, 0, 0); __builtin_amdgcn_s_setprio(0); } while (0)
; #define PG8_WAIT_V(n) asm volatile("s_waitcnt vmcnt(" #n ")" ::: "memory")
; #define PG8_WAIT_L(n) asm volatile("s_waitcnt lgkmcnt(" #n ")" ::: "memory")
; template <class Epi, class Sched, bool ALIGN_EPI = false, bool SP2 = false>
; __device__ __forceinline__ void gemm_phase(PG8_LAS unsigned char* lds, const Gemm g, const Sched& S, const Epi& E) {
;     ...
;             const bool last = (t == nt - 2);
;             const char* a1 = cA + PG8_AK(t + 1);
;             const char* a2 = last ? nA : cA + PG8_AK(t + 2); const char* b2 = last ? nB : cB + (size_t)(t + 2) * kstep;
;             const char* a3 = last ? nA + PG8_AK(1) : cA + PG8_AK(t + 3); const char* b3 = b2 + kstep;
;             if (last && has_next) S.a_ready(nxt);
;             if constexpr (SP2) {
;             PG8_LDB(B0, 0, 0); PG8_LDB(B1, 0, 1); PG8_SCHED; PG8_LDA(At, 0, 0); PG8_STAGE(PG8_SA(1, 1), a1 + hstepA, voffA);
;             PG8_WAIT_V(8); PG8_WAIT_L(0); PG8_BAR; PG8_MMA(0, 0, At, B0); PG8_MMA(0, 1, At, B1); PG8_BAR; PG8_SCHED;
;             PG8_LDA(At, 0, 1); PG8_STAGE(PG8_SB(0, 0), b2, voffB); PG8_STAGE(PG8_SB(0, 1), b2 + hstepB, voffB); PG8_STAGE(PG8_SA(0, 0), a2, voffA);
;             PG8_WAIT_V(8); PG8_WAIT_L(0); PG8_BAR; PG8_MMA(1, 0, At, B0); PG8_MMA(1, 1, At, B1); PG8_BAR; PG8_SCHED;
.LBB0_612:
	ds_read_b128 v[100:103], v226
	ds_read_b128 v[104:107], v226 offset:1024
	ds_read_b128 v[108:111], v226 offset:2048
	ds_read_b128 v[120:123], v226 offset:3072
	ds_read_b128 v[124:127], v227
	ds_read_b128 v[128:131], v227 offset:1024
	ds_read_b128 v[132:135], v227 offset:2048
	ds_read_b128 v[160:163], v227 offset:3072
	s_add_u32 s44, s40, s42
	s_addc_u32 s45, s41, s43
	s_add_u32 s48, s44, 0x100
	s_addc_u32 s49, s45, 0
	s_add_u32 s46, s83, s42
	s_addc_u32 s47, s84, s43
	s_add_u32 s44, s44, 0x180
	s_addc_u32 s45, s45, 0
	s_cmpk_eq_i32 s42, 0x700
	s_cselect_b32 s45, s82, s45
	s_cselect_b32 s44, s79, s44
	s_cselect_b32 s47, s29, s47
	s_cselect_b32 s46, s78, s46
	s_cselect_b32 s49, s3, s49
	s_cselect_b32 s48, s31, s48
	v_lshl_add_u64 v[236:237], v[98:99], 0, s[42:43]
	s_add_i32 m0, s57, 0xc000
	ds_read_b128 v[164:167], v209
	ds_read_b128 v[168:171], v209 offset:1024
	ds_read_b128 v[192:195], v209 offset:2048
	ds_read_b128 v[196:199], v209 offset:3072
	ds_read_b128 v[200:203], v209 offset:4096
	ds_read_b128 v[204:207], v209 offset:5120
	ds_read_b128 v[228:231], v209 offset:6144
	ds_read_b128 v[232:235], v209 offset:7168
	global_load_lds_dwordx4 v[236:237], off
	v_lshl_add_u64 v[236:237], v[96:97], 0, s[42:43]
	s_add_i32 m0, s57, 0xe000
	s_nop 0
	global_load_lds_dwordx4 v[236:237], off
	s_waitcnt vmcnt(8)
	s_waitcnt lgkmcnt(0)
	s_barrier
	s_setprio 1
	v_mfma_f32_16x16x32_bf16 v[156:159], v[100:103], v[164:167], v[156:159]
	v_mfma_f32_16x16x32_bf16 v[152:155], v[108:111], v[164:167], v[152:155]
	v_mfma_f32_16x16x32_bf16 v[148:151], v[100:103], v[192:195], v[148:151]
	v_mfma_f32_16x16x32_bf16 v[144:147], v[108:111], v[192:195], v[144:147]
	v_mfma_f32_16x16x32_bf16 v[140:143], v[100:103], v[200:203], v[140:143]
	v_mfma_f32_16x16x32_bf16 v[136:139], v[108:111], v[200:203], v[136:139]
	v_mfma_f32_16x16x32_bf16 v[116:119], v[100:103], v[228:231], v[116:119]
	v_mfma_f32_16x16x32_bf16 v[112:115], v[108:111], v[228:231], v[112:115]
	v_mfma_f32_16x16x32_bf16 v[156:159], v[104:107], v[168:171], v[156:159]
	v_mfma_f32_16x16x32_bf16 v[152:155], v[120:123], v[168:171], v[152:155]
	v_mfma_f32_16x16x32_bf16 v[148:151], v[104:107], v[196:199], v[148:151]
	v_mfma_f32_16x16x32_bf16 v[144:147], v[120:123], v[196:199], v[144:147]
	v_mfma_f32_16x16x32_bf16 v[140:143], v[104:107], v[204:207], v[140:143]
	v_mfma_f32_16x16x32_bf16 v[136:139], v[120:123], v[204:207], v[136:139]
	v_mfma_f32_16x16x32_bf16 v[116:119], v[104:107], v[232:235], v[116:119]
	v_mfma_f32_16x16x32_bf16 v[112:115], v[120:123], v[232:235], v[112:115]
	v_mfma_f32_16x16x32_bf16 v[60:63], v[124:127], v[164:167], v[60:63]
	v_mfma_f32_16x16x32_bf16 v[56:59], v[132:135], v[164:167], v[56:59]
	v_mfma_f32_16x16x32_bf16 v[52:55], v[124:127], v[192:195], v[52:55]
	v_mfma_f32_16x16x32_bf16 v[48:51], v[132:135], v[192:195], v[48:51]
	v_mfma_f32_16x16x32_bf16 v[44:47], v[124:127], v[200:203], v[44:47]
	v_mfma_f32_16x16x32_bf16 v[40:43], v[132:135], v[200:203], v[40:43]
	v_mfma_f32_16x16x32_bf16 v[36:39], v[124:127], v[228:231], v[36:39]
	v_mfma_f32_16x16x32_bf16 v[32:35], v[132:135], v[228:231], v[32:35]
	v_mfma_f32_16x16x32_bf16 v[60:63], v[128:131], v[168:171], v[60:63]
	v_mfma_f32_16x16x32_bf16 v[56:59], v[160:163], v[168:171], v[56:59]
	v_mfma_f32_16x16x32_bf16 v[52:55], v[128:131], v[196:199], v[52:55]
	v_mfma_f32_16x16x32_bf16 v[48:51], v[160:163], v[196:199], v[48:51]
	v_mfma_f32_16x16x32_bf16 v[44:47], v[128:131], v[204:207], v[44:47]
	v_mfma_f32_16x16x32_bf16 v[40:43], v[160:163], v[204:207], v[40:43]
	v_mfma_f32_16x16x32_bf16 v[36:39], v[128:131], v[232:235], v[36:39]
	v_mfma_f32_16x16x32_bf16 v[32:35], v[160:163], v[232:235], v[32:35]
	s_setprio 0
	s_barrier
	s_add_i32 s70, s69, s56
	v_lshl_add_u64 v[236:237], s[46:47], 0, v[174:175]
	s_mov_b32 m0, s70
	ds_read_b128 v[164:167], v209 offset:16384
	ds_read_b128 v[168:171], v209 offset:17408
	ds_read_b128 v[192:195], v209 offset:18432
	ds_read_b128 v[196:199], v209 offset:19456
	ds_read_b128 v[200:203], v209 offset:20480
	ds_read_b128 v[204:207], v209 offset:21504
	ds_read_b128 v[228:231], v209 offset:22528
	ds_read_b128 v[232:235], v209 offset:23552
	global_load_lds_dwordx4 v[236:237], off
	s_add_i32 m0, s70, 0x2000
	s_add_u32 s70, s46, 0x40000
	v_lshl_add_u64 v[238:239], s[46:47], 0, v[178:179]
	s_addc_u32 s71, s47, 0
	s_add_i32 s86, s80, s56
	global_load_lds_dwordx4 v[238:239], off
	v_lshl_add_u64 v[240:241], s[70:71], 0, v[174:175]
	s_mov_b32 m0, s86
	s_nop 0
	global_load_lds_dwordx4 v[240:241], off
	v_lshl_add_u64 v[240:241], s[70:71], 0, v[178:179]
	s_add_i32 m0, s86, 0x2000
	s_nop 0
	global_load_lds_dwordx4 v[240:241], off
	s_waitcnt vmcnt(6)
	s_waitcnt lgkmcnt(0)
	s_barrier
; #define PG8_STAGE(bufoff, gbase, voff) do { _Pragma("unroll") for (int _i = 0; _i < 2; ++_i) \
;         __builtin_amdgcn_global_load_lds((const unsigned*)((const char*)(gbase) + (voff)[_i]), (PG8_LAS unsigned*)(lds + (bufoff) + ldsw + _i * 8192), 16, 0, 0); } while (0)
; #define PG8_LDA(dst, b, h) do { _Pragma("unroll") for (int m = 0; m < 4; ++m) _Pragma("unroll") for (int k = 0; k < 2; ++k) dst[m][k] = *(const PG8_LAS bf16x8*)(lds + PG8_SA(b, h) + aoff + m * 2048 + k * 1024); } while (0)
; #define PG8_LDB(dst, b, h) do { _Pragma("unroll") for (int n = 0; n < 2; ++n) _Pragma("unroll") for (int k = 0; k < 2; ++k) dst[n][k] = *(const PG8_LAS bf16x8*)(lds + PG8_SB(b, h) + boff + n * 2048 + k * 1024); } while (0)
; #define PG8_MMA(ai, bj, At, Bt) do { __builtin_amdgcn_s_setprio(1); _Pragma("unroll") for (int m = 0; m < 4; ++m) _Pragma("unroll") for (int n = 0; n < 2; ++n) _Pragma("unroll") for (int k = 0; k < 2; ++k) \
;         acc[ai][bj][m][n] = __builtin_amdgcn_mfma_f32_16x16x32_bf16(Bt[n][k], At[m][k], acc[ai][bj][m][n], 0, 0, 0); __builtin_amdgcn_s_setprio(0); } while (0)
; #define PG8_WAIT_V(n) asm volatile("s_waitcnt vmcnt(" #n ")" ::: "memory")
; #define PG8_WAIT_L(n) asm volatile("s_waitcnt lgkmcnt(" #n ")" ::: "memory")
; #define PG8_BAR __builtin_amdgcn_s_barrier()
; #define PG8_SCHED __builtin_amdgcn_sched_barrier(0)
; template <class Epi, class Sched, bool ALIGN_EPI = false, bool SP2 = false>
; __device__ __forceinline__ void gemm_phase(PG8_LAS unsigned char* lds, const Gemm g, const Sched& S, const Epi& E) {
;     ...
;             PG8_WAIT_V(8); PG8_WAIT_L(0); PG8_BAR; PG8_MMA(1, 0, At, B0); PG8_MMA(1, 1, At, B1); PG8_BAR; PG8_SCHED;
;             PG8_LDB(B0, 1, 0); PG8_LDB(B1, 1, 1); PG8_SCHED; PG8_LDA(At, 1, 0); PG8_STAGE(PG8_SA(0, 1), a2 + hstepA, voffA);
;             PG8_WAIT_V(8); PG8_WAIT_L(0); PG8_BAR; PG8_MMA(0, 0, At, B0); PG8_MMA(0, 1, At, B1); PG8_BAR; PG8_SCHED;
	s_setprio 1
	v_mfma_f32_16x16x32_bf16 v[92:95], v[100:103], v[164:167], v[92:95]
	v_mfma_f32_16x16x32_bf16 v[88:91], v[108:111], v[164:167], v[88:91]
	v_mfma_f32_16x16x32_bf16 v[84:87], v[100:103], v[192:195], v[84:87]
	v_mfma_f32_16x16x32_bf16 v[80:83], v[108:111], v[192:195], v[80:83]
	v_mfma_f32_16x16x32_bf16 v[76:79], v[100:103], v[200:203], v[76:79]
	v_mfma_f32_16x16x32_bf16 v[72:75], v[108:111], v[200:203], v[72:75]
	v_mfma_f32_16x16x32_bf16 v[68:71], v[100:103], v[228:231], v[68:71]
	v_mfma_f32_16x16x32_bf16 v[64:67], v[108:111], v[228:231], v[64:67]
	v_mfma_f32_16x16x32_bf16 v[92:95], v[104:107], v[168:171], v[92:95]
	v_mfma_f32_16x16x32_bf16 v[88:91], v[120:123], v[168:171], v[88:91]
	v_mfma_f32_16x16x32_bf16 v[84:87], v[104:107], v[196:199], v[84:87]
	v_mfma_f32_16x16x32_bf16 v[80:83], v[120:123], v[196:199], v[80:83]
	v_mfma_f32_16x16x32_bf16 v[76:79], v[104:107], v[204:207], v[76:79]
	v_mfma_f32_16x16x32_bf16 v[72:75], v[120:123], v[204:207], v[72:75]
	v_mfma_f32_16x16x32_bf16 v[68:71], v[104:107], v[232:235], v[68:71]
	v_mfma_f32_16x16x32_bf16 v[64:67], v[120:123], v[232:235], v[64:67]
	v_mfma_f32_16x16x32_bf16 v[28:31], v[124:127], v[164:167], v[28:31]
	v_mfma_f32_16x16x32_bf16 v[24:27], v[132:135], v[164:167], v[24:27]
	v_mfma_f32_16x16x32_bf16 v[20:23], v[124:127], v[192:195], v[20:23]
	v_mfma_f32_16x16x32_bf16 v[16:19], v[132:135], v[192:195], v[16:19]
	v_mfma_f32_16x16x32_bf16 v[12:15], v[124:127], v[200:203], v[12:15]
	v_mfma_f32_16x16x32_bf16 v[8:11], v[132:135], v[200:203], v[8:11]
	v_mfma_f32_16x16x32_bf16 v[4:7], v[124:127], v[228:231], v[4:7]
	v_mfma_f32_16x16x32_bf16 v[0:3], v[132:135], v[228:231], v[0:3]
	v_mfma_f32_16x16x32_bf16 v[28:31], v[128:131], v[168:171], v[28:31]
	v_mfma_f32_16x16x32_bf16 v[24:27], v[160:163], v[168:171], v[24:27]
	v_mfma_f32_16x16x32_bf16 v[20:23], v[128:131], v[196:199], v[20:23]
	v_mfma_f32_16x16x32_bf16 v[16:19], v[160:163], v[196:199], v[16:19]
	v_mfma_f32_16x16x32_bf16 v[12:15], v[128:131], v[204:207], v[12:15]
	v_mfma_f32_16x16x32_bf16 v[8:11], v[160:163], v[204:207], v[8:11]
	v_mfma_f32_16x16x32_bf16 v[4:7], v[128:131], v[232:235], v[4:7]
	v_mfma_f32_16x16x32_bf16 v[0:3], v[160:163], v[232:235], v[0:3]
	s_setprio 0
	s_barrier
	s_add_i32 s70, 0, 0x18000
	s_add_i32 s71, 0, 0x1c000
	v_add_u32_e32 v120, s70, v189
	v_add_u32_e32 v160, s71, v189
	ds_read_b128 v[100:103], v120
	ds_read_b128 v[104:107], v120 offset:1024
	ds_read_b128 v[108:111], v120 offset:2048
	ds_read_b128 v[120:123], v120 offset:3072
	ds_read_b128 v[124:127], v160
	ds_read_b128 v[128:131], v160 offset:1024
	ds_read_b128 v[132:135], v160 offset:2048
	ds_read_b128 v[160:163], v160 offset:3072
	v_lshl_add_u64 v[240:241], s[48:49], 0, v[172:173]
	s_mov_b32 m0, s57
	s_nop 0
	global_load_lds_dwordx4 v[240:241], off
	v_lshl_add_u64 v[240:241], s[48:49], 0, v[176:177]
	s_mov_b32 m0, s58
	s_nop 0
	global_load_lds_dwordx4 v[240:241], off
	s_add_u32 s48, s48, 0x40000
	s_addc_u32 s49, s49, 0
	s_mov_b32 m0, s59
	v_lshl_add_u64 v[240:241], s[48:49], 0, v[172:173]
	ds_read_b128 v[164:167], v209 offset:32768
	ds_read_b128 v[168:171], v209 offset:33792
	ds_read_b128 v[192:195], v209 offset:34816
	ds_read_b128 v[196:199], v209 offset:35840
	ds_read_b128 v[200:203], v209 offset:36864
	ds_read_b128 v[204:207], v209 offset:37888
	ds_read_b128 v[228:231], v209 offset:38912
	ds_read_b128 v[232:235], v209 offset:39936
	global_load_lds_dwordx4 v[240:241], off
	v_lshl_add_u64 v[240:241], s[48:49], 0, v[176:177]
	s_mov_b32 m0, s60
	s_nop 0
	global_load_lds_dwordx4 v[240:241], off
	s_waitcnt vmcnt(8)
	s_waitcnt lgkmcnt(0)
	s_barrier
	s_setprio 1
	v_mfma_f32_16x16x32_bf16 v[156:159], v[100:103], v[164:167], v[156:159]
	v_mfma_f32_16x16x32_bf16 v[152:155], v[108:111], v[164:167], v[152:155]
	v_mfma_f32_16x16x32_bf16 v[148:151], v[100:103], v[192:195], v[148:151]
	v_mfma_f32_16x16x32_bf16 v[144:147], v[108:111], v[192:195], v[144:147]
	v_mfma_f32_16x16x32_bf16 v[140:143], v[100:103], v[200:203], v[140:143]
	v_mfma_f32_16x16x32_bf16 v[136:139], v[108:111], v[200:203], v[136:139]
	v_mfma_f32_16x16x32_bf16 v[116:119], v[100:103], v[228:231], v[116:119]
	v_mfma_f32_16x16x32_bf16 v[112:115], v[108:111], v[228:231], v[112:115]
	v_mfma_f32_16x16x32_bf16 v[156:159], v[104:107], v[168:171], v[156:159]
	v_mfma_f32_16x16x32_bf16 v[152:155], v[120:123], v[168:171], v[152:155]
	v_mfma_f32_16x16x32_bf16 v[148:151], v[104:107], v[196:199], v[148:151]
	v_mfma_f32_16x16x32_bf16 v[144:147], v[120:123], v[196:199], v[144:147]
	v_mfma_f32_16x16x32_bf16 v[140:143], v[104:107], v[204:207], v[140:143]
	v_mfma_f32_16x16x32_bf16 v[136:139], v[120:123], v[204:207], v[136:139]
	v_mfma_f32_16x16x32_bf16 v[116:119], v[104:107], v[232:235], v[116:119]
	v_mfma_f32_16x16x32_bf16 v[112:115], v[120:123], v[232:235], v[112:115]
	v_mfma_f32_16x16x32_bf16 v[60:63], v[124:127], v[164:167], v[60:63]
	v_mfma_f32_16x16x32_bf16 v[56:59], v[132:135], v[164:167], v[56:59]
	v_mfma_f32_16x16x32_bf16 v[52:55], v[124:127], v[192:195], v[52:55]
	v_mfma_f32_16x16x32_bf16 v[48:51], v[132:135], v[192:195], v[48:51]
	v_mfma_f32_16x16x32_bf16 v[44:47], v[124:127], v[200:203], v[44:47]
	v_mfma_f32_16x16x32_bf16 v[40:43], v[132:135], v[200:203], v[40:43]
	v_mfma_f32_16x16x32_bf16 v[36:39], v[124:127], v[228:231], v[36:39]
	v_mfma_f32_16x16x32_bf16 v[32:35], v[132:135], v[228:231], v[32:35]
	v_mfma_f32_16x16x32_bf16 v[60:63], v[128:131], v[168:171], v[60:63]
	v_mfma_f32_16x16x32_bf16 v[56:59], v[160:163], v[168:171], v[56:59]
	v_mfma_f32_16x16x32_bf16 v[52:55], v[128:131], v[196:199], v[52:55]
	v_mfma_f32_16x16x32_bf16 v[48:51], v[160:163], v[196:199], v[48:51]
	v_mfma_f32_16x16x32_bf16 v[44:47], v[128:131], v[204:207], v[44:47]
	v_mfma_f32_16x16x32_bf16 v[40:43], v[160:163], v[204:207], v[40:43]
	v_mfma_f32_16x16x32_bf16 v[36:39], v[128:131], v[232:235], v[36:39]
	v_mfma_f32_16x16x32_bf16 v[32:35], v[160:163], v[232:235], v[32:35]
	s_setprio 0
	s_barrier
; #define PG8_STAGE(bufoff, gbase, voff) do { _Pragma("unroll") for (int _i = 0; _i < 2; ++_i) \
;         __builtin_amdgcn_global_load_lds((const unsigned*)((const char*)(gbase) + (voff)[_i]), (PG8_LAS unsigned*)(lds + (bufoff) + ldsw + _i * 8192), 16, 0, 0); } while (0)
; #define PG8_LDA(dst, b, h) do { _Pragma("unroll") for (int m = 0; m < 4; ++m) _Pragma("unroll") for (int k = 0; k < 2; ++k) dst[m][k] = *(const PG8_LAS bf16x8*)(lds + PG8_SA(b, h) + aoff + m * 2048 + k * 1024); } while (0)
; #define PG8_MMA(ai, bj, At, Bt) do { __builtin_amdgcn_s_setprio(1); _Pragma("unroll") for (int m = 0; m < 4; ++m) _Pragma("unroll") for (int n = 0; n < 2; ++n) _Pragma("unroll") for (int k = 0; k < 2; ++k) \
;         acc[ai][bj][m][n] = __builtin_amdgcn_mfma_f32_16x16x32_bf16(Bt[n][k], At[m][k], acc[ai][bj][m][n], 0, 0, 0); __builtin_amdgcn_s_setprio(0); } while (0)
; #define PG8_WAIT_V(n) asm volatile("s_waitcnt vmcnt(" #n ")" ::: "memory")
; #define PG8_WAIT_L(n) asm volatile("s_waitcnt lgkmcnt(" #n ")" ::: "memory")
; #define PG8_BAR __builtin_amdgcn_s_barrier()
; #define PG8_SCHED __builtin_amdgcn_sched_barrier(0)
; template <class Epi, class Sched, bool ALIGN_EPI = false, bool SP2 = false>
; __device__ __forceinline__ void gemm_phase(PG8_LAS unsigned char* lds, const Gemm g, const Sched& S, const Epi& E) {
;     ...
;             PG8_LDA(At, 1, 1); PG8_STAGE(PG8_SB(1, 0), b3, voffB); PG8_STAGE(PG8_SB(1, 1), b3 + hstepB, voffB); PG8_STAGE(PG8_SA(1, 0), a3, voffA);
;             PG8_WAIT_V(8); PG8_WAIT_L(0); PG8_BAR; PG8_MMA(1, 0, At, B0); PG8_MMA(1, 1, At, B1); PG8_BAR; PG8_SCHED;
;     ...
;         if constexpr (ALIGN_EPI) { if (wr == 0) PG8_BAR; }
;         if constexpr (!Epi::AFTER_DRAIN) { E(acc, cur, wr, wc, fr, fq); S.done(cur); }
;         if (!has_next) break;
	s_add_i32 s48, s70, s56
	v_lshl_add_u64 v[236:237], v[236:237], 0, s[10:11]
	s_mov_b32 m0, s48
	ds_read_b128 v[164:167], v209 offset:49152
	ds_read_b128 v[168:171], v209 offset:50176
	ds_read_b128 v[192:195], v209 offset:51200
	ds_read_b128 v[196:199], v209 offset:52224
	ds_read_b128 v[200:203], v209 offset:53248
	ds_read_b128 v[204:207], v209 offset:54272
	ds_read_b128 v[228:231], v209 offset:55296
	ds_read_b128 v[232:235], v209 offset:56320
	global_load_lds_dwordx4 v[236:237], off
	s_add_i32 m0, s48, 0x2000
	s_add_u32 s46, s46, 0x40080
	v_lshl_add_u64 v[236:237], v[238:239], 0, s[10:11]
	s_addc_u32 s47, s47, 0
	s_add_i32 s48, s71, s56
	global_load_lds_dwordx4 v[236:237], off
	v_lshl_add_u64 v[236:237], s[46:47], 0, v[174:175]
	s_mov_b32 m0, s48
	s_nop 0
	global_load_lds_dwordx4 v[236:237], off
	v_lshl_add_u64 v[236:237], s[46:47], 0, v[178:179]
	s_add_i32 m0, s48, 0x2000
	s_nop 0
	global_load_lds_dwordx4 v[236:237], off
	v_lshl_add_u64 v[236:237], s[44:45], 0, v[172:173]
	s_mov_b32 m0, s66
	s_nop 0
	global_load_lds_dwordx4 v[236:237], off
	v_lshl_add_u64 v[236:237], s[44:45], 0, v[176:177]
	s_mov_b32 m0, s67
	s_nop 0
	global_load_lds_dwordx4 v[236:237], off
	s_waitcnt vmcnt(8)
	s_waitcnt lgkmcnt(0)
	s_barrier
	s_setprio 1
	v_mfma_f32_16x16x32_bf16 v[92:95], v[100:103], v[164:167], v[92:95]
	v_mfma_f32_16x16x32_bf16 v[88:91], v[108:111], v[164:167], v[88:91]
	v_mfma_f32_16x16x32_bf16 v[84:87], v[100:103], v[192:195], v[84:87]
	v_mfma_f32_16x16x32_bf16 v[80:83], v[108:111], v[192:195], v[80:83]
	v_mfma_f32_16x16x32_bf16 v[76:79], v[100:103], v[200:203], v[76:79]
	v_mfma_f32_16x16x32_bf16 v[72:75], v[108:111], v[200:203], v[72:75]
	v_mfma_f32_16x16x32_bf16 v[68:71], v[100:103], v[228:231], v[68:71]
	v_mfma_f32_16x16x32_bf16 v[64:67], v[108:111], v[228:231], v[64:67]
	v_mfma_f32_16x16x32_bf16 v[92:95], v[104:107], v[168:171], v[92:95]
	v_mfma_f32_16x16x32_bf16 v[88:91], v[120:123], v[168:171], v[88:91]
	v_mfma_f32_16x16x32_bf16 v[84:87], v[104:107], v[196:199], v[84:87]
	v_mfma_f32_16x16x32_bf16 v[80:83], v[120:123], v[196:199], v[80:83]
	v_mfma_f32_16x16x32_bf16 v[76:79], v[104:107], v[204:207], v[76:79]
	v_mfma_f32_16x16x32_bf16 v[72:75], v[120:123], v[204:207], v[72:75]
	v_mfma_f32_16x16x32_bf16 v[68:71], v[104:107], v[232:235], v[68:71]
	v_mfma_f32_16x16x32_bf16 v[64:67], v[120:123], v[232:235], v[64:67]
	v_mfma_f32_16x16x32_bf16 v[28:31], v[124:127], v[164:167], v[28:31]
	v_mfma_f32_16x16x32_bf16 v[24:27], v[132:135], v[164:167], v[24:27]
	v_mfma_f32_16x16x32_bf16 v[20:23], v[124:127], v[192:195], v[20:23]
	v_mfma_f32_16x16x32_bf16 v[16:19], v[132:135], v[192:195], v[16:19]
	v_mfma_f32_16x16x32_bf16 v[12:15], v[124:127], v[200:203], v[12:15]
	v_mfma_f32_16x16x32_bf16 v[8:11], v[132:135], v[200:203], v[8:11]
	v_mfma_f32_16x16x32_bf16 v[4:7], v[124:127], v[228:231], v[4:7]
	v_mfma_f32_16x16x32_bf16 v[0:3], v[132:135], v[228:231], v[0:3]
	v_mfma_f32_16x16x32_bf16 v[28:31], v[128:131], v[168:171], v[28:31]
	v_mfma_f32_16x16x32_bf16 v[24:27], v[160:163], v[168:171], v[24:27]
	v_mfma_f32_16x16x32_bf16 v[20:23], v[128:131], v[196:199], v[20:23]
	v_mfma_f32_16x16x32_bf16 v[16:19], v[160:163], v[196:199], v[16:19]
	v_mfma_f32_16x16x32_bf16 v[12:15], v[128:131], v[204:207], v[12:15]
	v_mfma_f32_16x16x32_bf16 v[8:11], v[160:163], v[204:207], v[8:11]
	v_mfma_f32_16x16x32_bf16 v[4:7], v[128:131], v[232:235], v[4:7]
	v_mfma_f32_16x16x32_bf16 v[0:3], v[160:163], v[232:235], v[0:3]
	s_setprio 0
	s_barrier
	s_add_i32 s85, s85, 2
	s_add_u32 s42, s42, 0x100
	s_addc_u32 s43, s43, 0
	s_cmp_gt_u32 s85, 13
	s_cbranch_scc0 .LBB0_612
	s_and_b64 vcc, exec, s[24:25]
	s_cbranch_vccz .LBB0_615
	s_barrier

; #define PG8_STAGE(bufoff, gbase, voff) do { _Pragma("unroll") for (int _i = 0; _i < 2; ++_i) \
;         __builtin_amdgcn_global_load_lds((const unsigned*)((const char*)(gbase) + (voff)[_i]), (PG8_LAS unsigned*)(lds + (bufoff) + ldsw + _i * 8192), 16, 0, 0); } while (0)
; #define PG8_LDA(dst, b, h) do { _Pragma("unroll") for (int m = 0; m < 4; ++m) _Pragma("unroll") for (int k = 0; k < 2; ++k) dst[m][k] = *(const PG8_LAS bf16x8*)(lds + PG8_SA(b, h) + aoff + m * 2048 + k * 1024); } while (0)
; #define PG8_LDB(dst, b, h) do { _Pragma("unroll") for (int n = 0; n < 2; ++n) _Pragma("unroll") for (int k = 0; k < 2; ++k) dst[n][k] = *(const PG8_LAS bf16x8*)(lds + PG8_SB(b, h) + boff + n * 2048 + k * 1024); } while (0)
; #define PG8_MMA(ai, bj, At, Bt) do { __builtin_amdgcn_s_setprio(1); _Pragma("unroll") for (int m = 0; m < 4; ++m) _Pragma("unroll") for (int n = 0; n < 2; ++n) _Pragma("unroll") for (int k = 0; k < 2; ++k) \
;         acc[ai][bj][m][n] = __builtin_amdgcn_mfma_f32_16x16x32_bf16(Bt[n][k], At[m][k], acc[ai][bj][m][n], 0, 0, 0); __builtin_amdgcn_s_setprio(0); } while (0)
; #define PG8_WAIT_V(n) asm volatile("s_waitcnt vmcnt(" #n ")" ::: "memory")
; #define PG8_WAIT_L(n) asm volatile("s_waitcnt lgkmcnt(" #n ")" ::: "memory")
; template <class Epi, class Sched, bool ALIGN_EPI = false, bool SP2 = false>
; __device__ __forceinline__ void gemm_phase(PG8_LAS unsigned char* lds, const Gemm g, const Sched& S, const Epi& E) {
;     ...
;             const bool last = (t == nt - 2);
;             const char* a1 = cA + PG8_AK(t + 1);
;             const char* a2 = last ? nA : cA + PG8_AK(t + 2); const char* b2 = last ? nB : cB + (size_t)(t + 2) * kstep;
;             const char* a3 = last ? nA + PG8_AK(1) : cA + PG8_AK(t + 3); const char* b3 = b2 + kstep;
;             if (last && has_next) S.a_ready(nxt);
;             if constexpr (SP2) {
;             PG8_LDB(B0, 0, 0); PG8_LDB(B1, 0, 1); PG8_SCHED; PG8_LDA(At, 0, 0); PG8_STAGE(PG8_SA(1, 1), a1 + hstepA, voffA);
;             PG8_WAIT_V(8); PG8_WAIT_L(0); PG8_BAR; PG8_MMA(0, 0, At, B0); PG8_MMA(0, 1, At, B1); PG8_BAR; PG8_SCHED;
;             PG8_LDA(At, 0, 1); PG8_STAGE(PG8_SB(0, 0), b2, voffB); PG8_STAGE(PG8_SB(0, 1), b2 + hstepB, voffB); PG8_STAGE(PG8_SA(0, 0), a2, voffA);
;             PG8_WAIT_V(8); PG8_WAIT_L(0); PG8_BAR; PG8_MMA(1, 0, At, B0); PG8_MMA(1, 1, At, B1); PG8_BAR; PG8_SCHED;
.LBB0_782:
	ds_read_b128 v[100:103], v167
	ds_read_b128 v[154:157], v167 offset:1024
	ds_read_b128 v[158:161], v167 offset:2048
	ds_read_b128 v[170:173], v167 offset:3072
	ds_read_b128 v[174:177], v168
	ds_read_b128 v[178:181], v168 offset:1024
	ds_read_b128 v[182:185], v168 offset:2048
	ds_read_b128 v[186:189], v168 offset:3072
	s_add_u32 s36, s6, s34
	s_addc_u32 s37, s7, s35
	s_add_u32 s40, s36, 0x100
	s_addc_u32 s41, s37, 0
	s_add_u32 s38, s62, s34
	s_addc_u32 s39, s63, s35
	s_add_u32 s36, s36, 0x180
	s_addc_u32 s37, s37, 0
	s_cmpk_eq_i32 s34, 0x700
	s_cselect_b32 s37, s61, s37
	s_cselect_b32 s36, s31, s36
	s_cselect_b32 s39, s23, s39
	s_cselect_b32 s38, s25, s38
	s_cselect_b32 s41, s3, s41
	s_cselect_b32 s40, s9, s40
	v_lshl_add_u64 v[162:163], v[98:99], 0, s[34:35]
	s_add_i32 m0, s47, 0xc000
	ds_read_b128 v[190:193], v169
	ds_read_b128 v[194:197], v169 offset:1024
	ds_read_b128 v[198:201], v169 offset:2048
	ds_read_b128 v[202:205], v169 offset:3072
	ds_read_b128 v[206:209], v169 offset:4096
	ds_read_b128 v[210:213], v169 offset:5120
	ds_read_b128 v[214:217], v169 offset:6144
	ds_read_b128 v[218:221], v169 offset:7168
	global_load_lds_dwordx4 v[162:163], off
	v_lshl_add_u64 v[162:163], v[96:97], 0, s[34:35]
	s_add_i32 m0, s47, 0xe000
	s_nop 0
	global_load_lds_dwordx4 v[162:163], off
	s_waitcnt vmcnt(8)
	s_waitcnt lgkmcnt(0)
	s_barrier
	s_setprio 1
	v_mfma_f32_16x16x32_bf16 v[132:135], v[100:103], v[190:193], v[132:135]
	v_mfma_f32_16x16x32_bf16 v[128:131], v[158:161], v[190:193], v[128:131]
	v_mfma_f32_16x16x32_bf16 v[124:127], v[100:103], v[198:201], v[124:127]
	v_mfma_f32_16x16x32_bf16 v[120:123], v[158:161], v[198:201], v[120:123]
	v_mfma_f32_16x16x32_bf16 v[116:119], v[100:103], v[206:209], v[116:119]
	v_mfma_f32_16x16x32_bf16 v[112:115], v[158:161], v[206:209], v[112:115]
	v_mfma_f32_16x16x32_bf16 v[108:111], v[100:103], v[214:217], v[108:111]
	v_mfma_f32_16x16x32_bf16 v[104:107], v[158:161], v[214:217], v[104:107]
	v_mfma_f32_16x16x32_bf16 v[132:135], v[154:157], v[194:197], v[132:135]
	v_mfma_f32_16x16x32_bf16 v[128:131], v[170:173], v[194:197], v[128:131]
	v_mfma_f32_16x16x32_bf16 v[124:127], v[154:157], v[202:205], v[124:127]
	v_mfma_f32_16x16x32_bf16 v[120:123], v[170:173], v[202:205], v[120:123]
	v_mfma_f32_16x16x32_bf16 v[116:119], v[154:157], v[210:213], v[116:119]
	v_mfma_f32_16x16x32_bf16 v[112:115], v[170:173], v[210:213], v[112:115]
	v_mfma_f32_16x16x32_bf16 v[108:111], v[154:157], v[218:221], v[108:111]
	v_mfma_f32_16x16x32_bf16 v[104:107], v[170:173], v[218:221], v[104:107]
	v_mfma_f32_16x16x32_bf16 v[60:63], v[174:177], v[190:193], v[60:63]
	v_mfma_f32_16x16x32_bf16 v[56:59], v[182:185], v[190:193], v[56:59]
	v_mfma_f32_16x16x32_bf16 v[52:55], v[174:177], v[198:201], v[52:55]
	v_mfma_f32_16x16x32_bf16 v[48:51], v[182:185], v[198:201], v[48:51]
	v_mfma_f32_16x16x32_bf16 v[44:47], v[174:177], v[206:209], v[44:47]
	v_mfma_f32_16x16x32_bf16 v[40:43], v[182:185], v[206:209], v[40:43]
	v_mfma_f32_16x16x32_bf16 v[36:39], v[174:177], v[214:217], v[36:39]
	v_mfma_f32_16x16x32_bf16 v[32:35], v[182:185], v[214:217], v[32:35]
	v_mfma_f32_16x16x32_bf16 v[60:63], v[178:181], v[194:197], v[60:63]
	v_mfma_f32_16x16x32_bf16 v[56:59], v[186:189], v[194:197], v[56:59]
	v_mfma_f32_16x16x32_bf16 v[52:55], v[178:181], v[202:205], v[52:55]
	v_mfma_f32_16x16x32_bf16 v[48:51], v[186:189], v[202:205], v[48:51]
	v_mfma_f32_16x16x32_bf16 v[44:47], v[178:181], v[210:213], v[44:47]
	v_mfma_f32_16x16x32_bf16 v[40:43], v[186:189], v[210:213], v[40:43]
	v_mfma_f32_16x16x32_bf16 v[36:39], v[178:181], v[218:221], v[36:39]
	v_mfma_f32_16x16x32_bf16 v[32:35], v[186:189], v[218:221], v[32:35]
	s_setprio 0
	s_barrier
	s_add_i32 s65, s58, s46
	v_lshl_add_u64 v[162:163], s[38:39], 0, v[138:139]
	s_mov_b32 m0, s65
	ds_read_b128 v[190:193], v169 offset:16384
	ds_read_b128 v[194:197], v169 offset:17408
	ds_read_b128 v[198:201], v169 offset:18432
	ds_read_b128 v[202:205], v169 offset:19456
	ds_read_b128 v[206:209], v169 offset:20480
	ds_read_b128 v[210:213], v169 offset:21504
	ds_read_b128 v[214:217], v169 offset:22528
	ds_read_b128 v[218:221], v169 offset:23552
	global_load_lds_dwordx4 v[162:163], off
	s_add_i32 m0, s65, 0x2000
	s_add_u32 s66, s38, 0x40000
	v_lshl_add_u64 v[222:223], s[38:39], 0, v[142:143]
	s_addc_u32 s67, s39, 0
	s_add_i32 s65, s59, s46
	global_load_lds_dwordx4 v[222:223], off
	v_lshl_add_u64 v[224:225], s[66:67], 0, v[138:139]
	s_mov_b32 m0, s65
	s_nop 0
	global_load_lds_dwordx4 v[224:225], off
	v_lshl_add_u64 v[224:225], s[66:67], 0, v[142:143]
	s_add_i32 m0, s65, 0x2000
	s_nop 0
	global_load_lds_dwordx4 v[224:225], off
	s_waitcnt vmcnt(6)
	s_waitcnt lgkmcnt(0)
	s_barrier
; #define PG8_STAGE(bufoff, gbase, voff) do { _Pragma("unroll") for (int _i = 0; _i < 2; ++_i) \
;         __builtin_amdgcn_global_load_lds((const unsigned*)((const char*)(gbase) + (voff)[_i]), (PG8_LAS unsigned*)(lds + (bufoff) + ldsw + _i * 8192), 16, 0, 0); } while (0)
; #define PG8_LDA(dst, b, h) do { _Pragma("unroll") for (int m = 0; m < 4; ++m) _Pragma("unroll") for (int k = 0; k < 2; ++k) dst[m][k] = *(const PG8_LAS bf16x8*)(lds + PG8_SA(b, h) + aoff + m * 2048 + k * 1024); } while (0)
; #define PG8_LDB(dst, b, h) do { _Pragma("unroll") for (int n = 0; n < 2; ++n) _Pragma("unroll") for (int k = 0; k < 2; ++k) dst[n][k] = *(const PG8_LAS bf16x8*)(lds + PG8_SB(b, h) + boff + n * 2048 + k * 1024); } while (0)
; #define PG8_MMA(ai, bj, At, Bt) do { __builtin_amdgcn_s_setprio(1); _Pragma("unroll") for (int m = 0; m < 4; ++m) _Pragma("unroll") for (int n = 0; n < 2; ++n) _Pragma("unroll") for (int k = 0; k < 2; ++k) \
;         acc[ai][bj][m][n] = __builtin_amdgcn_mfma_f32_16x16x32_bf16(Bt[n][k], At[m][k], acc[ai][bj][m][n], 0, 0, 0); __builtin_amdgcn_s_setprio(0); } while (0)
; #define PG8_WAIT_V(n) asm volatile("s_waitcnt vmcnt(" #n ")" ::: "memory")
; #define PG8_WAIT_L(n) asm volatile("s_waitcnt lgkmcnt(" #n ")" ::: "memory")
; #define PG8_BAR __builtin_amdgcn_s_barrier()
; #define PG8_SCHED __builtin_amdgcn_sched_barrier(0)
; template <class Epi, class Sched, bool ALIGN_EPI = false, bool SP2 = false>
; __device__ __forceinline__ void gemm_phase(PG8_LAS unsigned char* lds, const Gemm g, const Sched& S, const Epi& E) {
;     ...
;             PG8_WAIT_V(8); PG8_WAIT_L(0); PG8_BAR; PG8_MMA(1, 0, At, B0); PG8_MMA(1, 1, At, B1); PG8_BAR; PG8_SCHED;
;             PG8_LDB(B0, 1, 0); PG8_LDB(B1, 1, 1); PG8_SCHED; PG8_LDA(At, 1, 0); PG8_STAGE(PG8_SA(0, 1), a2 + hstepA, voffA);
;             PG8_WAIT_V(8); PG8_WAIT_L(0); PG8_BAR; PG8_MMA(0, 0, At, B0); PG8_MMA(0, 1, At, B1); PG8_BAR; PG8_SCHED;
	s_setprio 1
	v_mfma_f32_16x16x32_bf16 v[92:95], v[100:103], v[190:193], v[92:95]
	v_mfma_f32_16x16x32_bf16 v[88:91], v[158:161], v[190:193], v[88:91]
	v_mfma_f32_16x16x32_bf16 v[84:87], v[100:103], v[198:201], v[84:87]
	v_mfma_f32_16x16x32_bf16 v[80:83], v[158:161], v[198:201], v[80:83]
	v_mfma_f32_16x16x32_bf16 v[76:79], v[100:103], v[206:209], v[76:79]
	v_mfma_f32_16x16x32_bf16 v[72:75], v[158:161], v[206:209], v[72:75]
	v_mfma_f32_16x16x32_bf16 v[68:71], v[100:103], v[214:217], v[68:71]
	v_mfma_f32_16x16x32_bf16 v[64:67], v[158:161], v[214:217], v[64:67]
	v_mfma_f32_16x16x32_bf16 v[92:95], v[154:157], v[194:197], v[92:95]
	v_mfma_f32_16x16x32_bf16 v[88:91], v[170:173], v[194:197], v[88:91]
	v_mfma_f32_16x16x32_bf16 v[84:87], v[154:157], v[202:205], v[84:87]
	v_mfma_f32_16x16x32_bf16 v[80:83], v[170:173], v[202:205], v[80:83]
	v_mfma_f32_16x16x32_bf16 v[76:79], v[154:157], v[210:213], v[76:79]
	v_mfma_f32_16x16x32_bf16 v[72:75], v[170:173], v[210:213], v[72:75]
	v_mfma_f32_16x16x32_bf16 v[68:71], v[154:157], v[218:221], v[68:71]
	v_mfma_f32_16x16x32_bf16 v[64:67], v[170:173], v[218:221], v[64:67]
	v_mfma_f32_16x16x32_bf16 v[28:31], v[174:177], v[190:193], v[28:31]
	v_mfma_f32_16x16x32_bf16 v[24:27], v[182:185], v[190:193], v[24:27]
	v_mfma_f32_16x16x32_bf16 v[20:23], v[174:177], v[198:201], v[20:23]
	v_mfma_f32_16x16x32_bf16 v[16:19], v[182:185], v[198:201], v[16:19]
	v_mfma_f32_16x16x32_bf16 v[12:15], v[174:177], v[206:209], v[12:15]
	v_mfma_f32_16x16x32_bf16 v[8:11], v[182:185], v[206:209], v[8:11]
	v_mfma_f32_16x16x32_bf16 v[4:7], v[174:177], v[214:217], v[4:7]
	v_mfma_f32_16x16x32_bf16 v[0:3], v[182:185], v[214:217], v[0:3]
	v_mfma_f32_16x16x32_bf16 v[28:31], v[178:181], v[194:197], v[28:31]
	v_mfma_f32_16x16x32_bf16 v[24:27], v[186:189], v[194:197], v[24:27]
	v_mfma_f32_16x16x32_bf16 v[20:23], v[178:181], v[202:205], v[20:23]
	v_mfma_f32_16x16x32_bf16 v[16:19], v[186:189], v[202:205], v[16:19]
	v_mfma_f32_16x16x32_bf16 v[12:15], v[178:181], v[210:213], v[12:15]
	v_mfma_f32_16x16x32_bf16 v[8:11], v[186:189], v[210:213], v[8:11]
	v_mfma_f32_16x16x32_bf16 v[4:7], v[178:181], v[218:221], v[4:7]
	v_mfma_f32_16x16x32_bf16 v[0:3], v[186:189], v[218:221], v[0:3]
	s_setprio 0
	s_barrier
	s_add_i32 s65, 0, 0x18000
	s_add_i32 s66, 0, 0x1c000
	v_add_u32_e32 v170, s65, v165
	v_add_u32_e32 v186, s66, v165
	ds_read_b128 v[100:103], v170
	ds_read_b128 v[154:157], v170 offset:1024
	ds_read_b128 v[158:161], v170 offset:2048
	ds_read_b128 v[170:173], v170 offset:3072
	ds_read_b128 v[174:177], v186
	ds_read_b128 v[178:181], v186 offset:1024
	ds_read_b128 v[182:185], v186 offset:2048
	ds_read_b128 v[186:189], v186 offset:3072
	v_lshl_add_u64 v[224:225], s[40:41], 0, v[136:137]
	s_mov_b32 m0, s47
	s_nop 0
	global_load_lds_dwordx4 v[224:225], off
	v_lshl_add_u64 v[224:225], s[40:41], 0, v[140:141]
	s_mov_b32 m0, s48
	s_nop 0
	global_load_lds_dwordx4 v[224:225], off
	s_add_u32 s40, s40, 0x40000
	s_addc_u32 s41, s41, 0
	s_mov_b32 m0, s49
	v_lshl_add_u64 v[224:225], s[40:41], 0, v[136:137]
	ds_read_b128 v[190:193], v169 offset:32768
	ds_read_b128 v[194:197], v169 offset:33792
	ds_read_b128 v[198:201], v169 offset:34816
	ds_read_b128 v[202:205], v169 offset:35840
	ds_read_b128 v[206:209], v169 offset:36864
	ds_read_b128 v[210:213], v169 offset:37888
	ds_read_b128 v[214:217], v169 offset:38912
	ds_read_b128 v[218:221], v169 offset:39936
	global_load_lds_dwordx4 v[224:225], off
	v_lshl_add_u64 v[224:225], s[40:41], 0, v[140:141]
	s_mov_b32 m0, s50
	s_nop 0
	global_load_lds_dwordx4 v[224:225], off
	s_waitcnt vmcnt(8)
	s_waitcnt lgkmcnt(0)
	s_barrier
	s_setprio 1
	v_mfma_f32_16x16x32_bf16 v[132:135], v[100:103], v[190:193], v[132:135]
	v_mfma_f32_16x16x32_bf16 v[128:131], v[158:161], v[190:193], v[128:131]
	v_mfma_f32_16x16x32_bf16 v[124:127], v[100:103], v[198:201], v[124:127]
	v_mfma_f32_16x16x32_bf16 v[120:123], v[158:161], v[198:201], v[120:123]
	v_mfma_f32_16x16x32_bf16 v[116:119], v[100:103], v[206:209], v[116:119]
	v_mfma_f32_16x16x32_bf16 v[112:115], v[158:161], v[206:209], v[112:115]
	v_mfma_f32_16x16x32_bf16 v[108:111], v[100:103], v[214:217], v[108:111]
	v_mfma_f32_16x16x32_bf16 v[104:107], v[158:161], v[214:217], v[104:107]
	v_mfma_f32_16x16x32_bf16 v[132:135], v[154:157], v[194:197], v[132:135]
	v_mfma_f32_16x16x32_bf16 v[128:131], v[170:173], v[194:197], v[128:131]
	v_mfma_f32_16x16x32_bf16 v[124:127], v[154:157], v[202:205], v[124:127]
	v_mfma_f32_16x16x32_bf16 v[120:123], v[170:173], v[202:205], v[120:123]
	v_mfma_f32_16x16x32_bf16 v[116:119], v[154:157], v[210:213], v[116:119]
	v_mfma_f32_16x16x32_bf16 v[112:115], v[170:173], v[210:213], v[112:115]
	v_mfma_f32_16x16x32_bf16 v[108:111], v[154:157], v[218:221], v[108:111]
	v_mfma_f32_16x16x32_bf16 v[104:107], v[170:173], v[218:221], v[104:107]
	v_mfma_f32_16x16x32_bf16 v[60:63], v[174:177], v[190:193], v[60:63]
	v_mfma_f32_16x16x32_bf16 v[56:59], v[182:185], v[190:193], v[56:59]
	v_mfma_f32_16x16x32_bf16 v[52:55], v[174:177], v[198:201], v[52:55]
	v_mfma_f32_16x16x32_bf16 v[48:51], v[182:185], v[198:201], v[48:51]
	v_mfma_f32_16x16x32_bf16 v[44:47], v[174:177], v[206:209], v[44:47]
	v_mfma_f32_16x16x32_bf16 v[40:43], v[182:185], v[206:209], v[40:43]
	v_mfma_f32_16x16x32_bf16 v[36:39], v[174:177], v[214:217], v[36:39]
	v_mfma_f32_16x16x32_bf16 v[32:35], v[182:185], v[214:217], v[32:35]
	v_mfma_f32_16x16x32_bf16 v[60:63], v[178:181], v[194:197], v[60:63]
	v_mfma_f32_16x16x32_bf16 v[56:59], v[186:189], v[194:197], v[56:59]
	v_mfma_f32_16x16x32_bf16 v[52:55], v[178:181], v[202:205], v[52:55]
	v_mfma_f32_16x16x32_bf16 v[48:51], v[186:189], v[202:205], v[48:51]
	v_mfma_f32_16x16x32_bf16 v[44:47], v[178:181], v[210:213], v[44:47]
	v_mfma_f32_16x16x32_bf16 v[40:43], v[186:189], v[210:213], v[40:43]
	v_mfma_f32_16x16x32_bf16 v[36:39], v[178:181], v[218:221], v[36:39]
	v_mfma_f32_16x16x32_bf16 v[32:35], v[186:189], v[218:221], v[32:35]
	s_setprio 0
	s_barrier
; #define PG8_STAGE(bufoff, gbase, voff) do { _Pragma("unroll") for (int _i = 0; _i < 2; ++_i) \
;         __builtin_amdgcn_global_load_lds((const unsigned*)((const char*)(gbase) + (voff)[_i]), (PG8_LAS unsigned*)(lds + (bufoff) + ldsw + _i * 8192), 16, 0, 0); } while (0)
; #define PG8_LDA(dst, b, h) do { _Pragma("unroll") for (int m = 0; m < 4; ++m) _Pragma("unroll") for (int k = 0; k < 2; ++k) dst[m][k] = *(const PG8_LAS bf16x8*)(lds + PG8_SA(b, h) + aoff + m * 2048 + k * 1024); } while (0)
; #define PG8_MMA(ai, bj, At, Bt) do { __builtin_amdgcn_s_setprio(1); _Pragma("unroll") for (int m = 0; m < 4; ++m) _Pragma("unroll") for (int n = 0; n < 2; ++n) _Pragma("unroll") for (int k = 0; k < 2; ++k) \
;         acc[ai][bj][m][n] = __builtin_amdgcn_mfma_f32_16x16x32_bf16(Bt[n][k], At[m][k], acc[ai][bj][m][n], 0, 0, 0); __builtin_amdgcn_s_setprio(0); } while (0)
; #define PG8_WAIT_V(n) asm volatile("s_waitcnt vmcnt(" #n ")" ::: "memory")
; #define PG8_WAIT_L(n) asm volatile("s_waitcnt lgkmcnt(" #n ")" ::: "memory")
; #define PG8_BAR __builtin_amdgcn_s_barrier()
; #define PG8_SCHED __builtin_amdgcn_sched_barrier(0)
; template <class Epi, class Sched, bool ALIGN_EPI = false, bool SP2 = false>
; __device__ __forceinline__ void gemm_phase(PG8_LAS unsigned char* lds, const Gemm g, const Sched& S, const Epi& E) {
;     ...
;             PG8_LDA(At, 1, 1); PG8_STAGE(PG8_SB(1, 0), b3, voffB); PG8_STAGE(PG8_SB(1, 1), b3 + hstepB, voffB); PG8_STAGE(PG8_SA(1, 0), a3, voffA);
;             PG8_WAIT_V(8); PG8_WAIT_L(0); PG8_BAR; PG8_MMA(1, 0, At, B0); PG8_MMA(1, 1, At, B1); PG8_BAR; PG8_SCHED;
;     ...
;         if constexpr (ALIGN_EPI) { if (wr == 0) PG8_BAR; }
;         if constexpr (!Epi::AFTER_DRAIN) { E(acc, cur, wr, wc, fr, fq); S.done(cur); }
;         if (!has_next) break;
	s_add_i32 s40, s65, s46
	v_lshl_add_u64 v[162:163], v[162:163], 0, s[18:19]
	s_mov_b32 m0, s40
	ds_read_b128 v[190:193], v169 offset:49152
	ds_read_b128 v[194:197], v169 offset:50176
	ds_read_b128 v[198:201], v169 offset:51200
	ds_read_b128 v[202:205], v169 offset:52224
	ds_read_b128 v[206:209], v169 offset:53248
	ds_read_b128 v[210:213], v169 offset:54272
	ds_read_b128 v[214:217], v169 offset:55296
	ds_read_b128 v[218:221], v169 offset:56320
	global_load_lds_dwordx4 v[162:163], off
	s_add_i32 m0, s40, 0x2000
	s_add_u32 s38, s38, 0x40080
	v_lshl_add_u64 v[162:163], v[222:223], 0, s[18:19]
	s_addc_u32 s39, s39, 0
	s_add_i32 s40, s66, s46
	global_load_lds_dwordx4 v[162:163], off
	v_lshl_add_u64 v[162:163], s[38:39], 0, v[138:139]
	s_mov_b32 m0, s40
	s_nop 0
	global_load_lds_dwordx4 v[162:163], off
	v_lshl_add_u64 v[162:163], s[38:39], 0, v[142:143]
	s_add_i32 m0, s40, 0x2000
	s_nop 0
	global_load_lds_dwordx4 v[162:163], off
	v_lshl_add_u64 v[162:163], s[36:37], 0, v[136:137]
	s_mov_b32 m0, s53
	s_nop 0
	global_load_lds_dwordx4 v[162:163], off
	v_lshl_add_u64 v[162:163], s[36:37], 0, v[140:141]
	s_mov_b32 m0, s54
	s_nop 0
	global_load_lds_dwordx4 v[162:163], off
	s_waitcnt vmcnt(8)
	s_waitcnt lgkmcnt(0)
	s_barrier
	s_setprio 1
	v_mfma_f32_16x16x32_bf16 v[92:95], v[100:103], v[190:193], v[92:95]
	v_mfma_f32_16x16x32_bf16 v[88:91], v[158:161], v[190:193], v[88:91]
	v_mfma_f32_16x16x32_bf16 v[84:87], v[100:103], v[198:201], v[84:87]
	v_mfma_f32_16x16x32_bf16 v[80:83], v[158:161], v[198:201], v[80:83]
	v_mfma_f32_16x16x32_bf16 v[76:79], v[100:103], v[206:209], v[76:79]
	v_mfma_f32_16x16x32_bf16 v[72:75], v[158:161], v[206:209], v[72:75]
	v_mfma_f32_16x16x32_bf16 v[68:71], v[100:103], v[214:217], v[68:71]
	v_mfma_f32_16x16x32_bf16 v[64:67], v[158:161], v[214:217], v[64:67]
	v_mfma_f32_16x16x32_bf16 v[92:95], v[154:157], v[194:197], v[92:95]
	v_mfma_f32_16x16x32_bf16 v[88:91], v[170:173], v[194:197], v[88:91]
	v_mfma_f32_16x16x32_bf16 v[84:87], v[154:157], v[202:205], v[84:87]
	v_mfma_f32_16x16x32_bf16 v[80:83], v[170:173], v[202:205], v[80:83]
	v_mfma_f32_16x16x32_bf16 v[76:79], v[154:157], v[210:213], v[76:79]
	v_mfma_f32_16x16x32_bf16 v[72:75], v[170:173], v[210:213], v[72:75]
	v_mfma_f32_16x16x32_bf16 v[68:71], v[154:157], v[218:221], v[68:71]
	v_mfma_f32_16x16x32_bf16 v[64:67], v[170:173], v[218:221], v[64:67]
	v_mfma_f32_16x16x32_bf16 v[28:31], v[174:177], v[190:193], v[28:31]
	v_mfma_f32_16x16x32_bf16 v[24:27], v[182:185], v[190:193], v[24:27]
	v_mfma_f32_16x16x32_bf16 v[20:23], v[174:177], v[198:201], v[20:23]
	v_mfma_f32_16x16x32_bf16 v[16:19], v[182:185], v[198:201], v[16:19]
	v_mfma_f32_16x16x32_bf16 v[12:15], v[174:177], v[206:209], v[12:15]
	v_mfma_f32_16x16x32_bf16 v[8:11], v[182:185], v[206:209], v[8:11]
	v_mfma_f32_16x16x32_bf16 v[4:7], v[174:177], v[214:217], v[4:7]
	v_mfma_f32_16x16x32_bf16 v[0:3], v[182:185], v[214:217], v[0:3]
	v_mfma_f32_16x16x32_bf16 v[28:31], v[178:181], v[194:197], v[28:31]
	v_mfma_f32_16x16x32_bf16 v[24:27], v[186:189], v[194:197], v[24:27]
	v_mfma_f32_16x16x32_bf16 v[20:23], v[178:181], v[202:205], v[20:23]
	v_mfma_f32_16x16x32_bf16 v[16:19], v[186:189], v[202:205], v[16:19]
	v_mfma_f32_16x16x32_bf16 v[12:15], v[178:181], v[210:213], v[12:15]
	v_mfma_f32_16x16x32_bf16 v[8:11], v[186:189], v[210:213], v[8:11]
	v_mfma_f32_16x16x32_bf16 v[4:7], v[178:181], v[218:221], v[4:7]
	v_mfma_f32_16x16x32_bf16 v[0:3], v[186:189], v[218:221], v[0:3]
	s_setprio 0
	s_barrier
	s_add_i32 s64, s64, 2
	s_add_u32 s34, s34, 0x100
	s_addc_u32 s35, s35, 0
	s_cmp_gt_u32 s64, 13
	s_cbranch_scc0 .LBB0_782
	s_and_b64 vcc, exec, s[20:21]
	s_cbranch_vccz .LBB0_785
	s_barrier

; #define PG8_STAGE(bufoff, gbase, voff) do { _Pragma("unroll") for (int _i = 0; _i < 2; ++_i) \
;         __builtin_amdgcn_global_load_lds((const unsigned*)((const char*)(gbase) + (voff)[_i]), (PG8_LAS unsigned*)(lds + (bufoff) + ldsw + _i * 8192), 16, 0, 0); } while (0)
; #define PG8_LDA(dst, b, h) do { _Pragma("unroll") for (int m = 0; m < 4; ++m) _Pragma("unroll") for (int k = 0; k < 2; ++k) dst[m][k] = *(const PG8_LAS bf16x8*)(lds + PG8_SA(b, h) + aoff + m * 2048 + k * 1024); } while (0)
; #define PG8_LDB(dst, b, h) do { _Pragma("unroll") for (int n = 0; n < 2; ++n) _Pragma("unroll") for (int k = 0; k < 2; ++k) dst[n][k] = *(const PG8_LAS bf16x8*)(lds + PG8_SB(b, h) + boff + n * 2048 + k * 1024); } while (0)
; #define PG8_WAIT_V(n) asm volatile("s_waitcnt vmcnt(" #n ")" ::: "memory")
; #define PG8_WAIT_L(n) asm volatile("s_waitcnt lgkmcnt(" #n ")" ::: "memory")
; #define PG8_BAR __builtin_amdgcn_s_barrier()
; #define PG8_SCHED __builtin_amdgcn_sched_barrier(0)
; template <class Epi, class Sched, bool ALIGN_EPI = false, bool SP2 = false>
; __device__ __forceinline__ void gemm_phase(PG8_LAS unsigned char* lds, const Gemm g, const Sched& S, const Epi& E) {
;     ...
;             const bool last = (t == nt - 2);
;             const char* a1 = cA + PG8_AK(t + 1);
;             const char* a2 = last ? nA : cA + PG8_AK(t + 2); const char* b2 = last ? nB : cB + (size_t)(t + 2) * kstep;
;             const char* a3 = last ? nA + PG8_AK(1) : cA + PG8_AK(t + 3); const char* b3 = b2 + kstep;
;             if (last && has_next) S.a_ready(nxt);
;             if constexpr (SP2) {
;             PG8_LDB(B0, 0, 0); PG8_LDB(B1, 0, 1); PG8_SCHED; PG8_LDA(At, 0, 0); PG8_STAGE(PG8_SA(1, 1), a1 + hstepA, voffA);
;             PG8_WAIT_V(8); PG8_WAIT_L(0); PG8_BAR; PG8_MMA(0, 0, At, B0); PG8_MMA(0, 1, At, B1); PG8_BAR; PG8_SCHED;
;             PG8_LDA(At, 0, 1); PG8_STAGE(PG8_SB(0, 0), b2, voffB); PG8_STAGE(PG8_SB(0, 1), b2 + hstepB, voffB); PG8_STAGE(PG8_SA(0, 0), a2, voffA);
;             PG8_WAIT_V(8); PG8_WAIT_L(0); PG8_BAR; PG8_MMA(1, 0, At, B0); PG8_MMA(1, 1, At, B1); PG8_BAR; PG8_SCHED;
;             PG8_LDB(B0, 1, 0); PG8_LDB(B1, 1, 1); PG8_SCHED; PG8_LDA(At, 1, 0); PG8_STAGE(PG8_SA(0, 1), a2 + hstepA, voffA);
;             PG8_WAIT_V(8); PG8_WAIT_L(0); PG8_BAR; PG8_MMA(0, 0, At, B0); PG8_MMA(0, 1, At, B1); PG8_BAR; PG8_SCHED;
.LBB0_1191:
	ds_read_b128 v[128:131], v191
	ds_read_b128 v[132:135], v191 offset:1024
	ds_read_b128 v[136:139], v191 offset:2048
	ds_read_b128 v[140:143], v191 offset:3072
	ds_read_b128 v[162:165], v192
	ds_read_b128 v[166:169], v192 offset:1024
	ds_read_b128 v[194:197], v192 offset:2048
	ds_read_b128 v[198:201], v192 offset:3072
	s_add_u32 s38, s36, 0x800000
	s_addc_u32 s39, s37, 0
	s_cmp_eq_u32 s67, 12
	s_cselect_b32 s43, s3, s39
	s_cselect_b32 s42, s27, s38
	s_cselect_b32 s41, s25, s66
	s_cselect_b32 s40, s35, s65
	v_lshl_add_u64 v[170:171], s[36:37], 0, v[156:157]
	s_add_i32 m0, s50, 0xc000
	ds_read_b128 v[202:205], v174
	ds_read_b128 v[206:209], v174 offset:1024
	ds_read_b128 v[210:213], v174 offset:2048
	ds_read_b128 v[214:217], v174 offset:3072
	ds_read_b128 v[218:221], v174 offset:4096
	ds_read_b128 v[222:225], v174 offset:5120
	ds_read_b128 v[226:229], v174 offset:6144
	ds_read_b128 v[230:233], v174 offset:7168
	global_load_lds_dwordx4 v[170:171], off
	v_lshl_add_u64 v[170:171], s[36:37], 0, v[154:155]
	s_add_i32 m0, s50, 0xe000
	s_nop 0
	global_load_lds_dwordx4 v[170:171], off
	s_waitcnt vmcnt(8)
	s_waitcnt lgkmcnt(0)
	s_barrier
	s_setprio 1
	v_mfma_f32_16x16x32_bf16 v[124:127], v[128:131], v[202:205], v[124:127]
	v_mfma_f32_16x16x32_bf16 v[120:123], v[136:139], v[202:205], v[120:123]
	v_mfma_f32_16x16x32_bf16 v[116:119], v[128:131], v[210:213], v[116:119]
	v_mfma_f32_16x16x32_bf16 v[112:115], v[136:139], v[210:213], v[112:115]
	v_mfma_f32_16x16x32_bf16 v[108:111], v[128:131], v[218:221], v[108:111]
	v_mfma_f32_16x16x32_bf16 v[104:107], v[136:139], v[218:221], v[104:107]
	v_mfma_f32_16x16x32_bf16 v[100:103], v[128:131], v[226:229], v[100:103]
	v_mfma_f32_16x16x32_bf16 v[96:99], v[136:139], v[226:229], v[96:99]
	v_mfma_f32_16x16x32_bf16 v[124:127], v[132:135], v[206:209], v[124:127]
	v_mfma_f32_16x16x32_bf16 v[120:123], v[140:143], v[206:209], v[120:123]
	v_mfma_f32_16x16x32_bf16 v[116:119], v[132:135], v[214:217], v[116:119]
	v_mfma_f32_16x16x32_bf16 v[112:115], v[140:143], v[214:217], v[112:115]
	v_mfma_f32_16x16x32_bf16 v[108:111], v[132:135], v[222:225], v[108:111]
	v_mfma_f32_16x16x32_bf16 v[104:107], v[140:143], v[222:225], v[104:107]
	v_mfma_f32_16x16x32_bf16 v[100:103], v[132:135], v[230:233], v[100:103]
	v_mfma_f32_16x16x32_bf16 v[96:99], v[140:143], v[230:233], v[96:99]
	v_mfma_f32_16x16x32_bf16 v[60:63], v[162:165], v[202:205], v[60:63]
	v_mfma_f32_16x16x32_bf16 v[56:59], v[194:197], v[202:205], v[56:59]
	v_mfma_f32_16x16x32_bf16 v[52:55], v[162:165], v[210:213], v[52:55]
	v_mfma_f32_16x16x32_bf16 v[48:51], v[194:197], v[210:213], v[48:51]
	v_mfma_f32_16x16x32_bf16 v[44:47], v[162:165], v[218:221], v[44:47]
	v_mfma_f32_16x16x32_bf16 v[40:43], v[194:197], v[218:221], v[40:43]
	v_mfma_f32_16x16x32_bf16 v[36:39], v[162:165], v[226:229], v[36:39]
	v_mfma_f32_16x16x32_bf16 v[32:35], v[194:197], v[226:229], v[32:35]
	v_mfma_f32_16x16x32_bf16 v[60:63], v[166:169], v[206:209], v[60:63]
	v_mfma_f32_16x16x32_bf16 v[56:59], v[198:201], v[206:209], v[56:59]
	v_mfma_f32_16x16x32_bf16 v[52:55], v[166:169], v[214:217], v[52:55]
	v_mfma_f32_16x16x32_bf16 v[48:51], v[198:201], v[214:217], v[48:51]
	v_mfma_f32_16x16x32_bf16 v[44:47], v[166:169], v[222:225], v[44:47]
	v_mfma_f32_16x16x32_bf16 v[40:43], v[198:201], v[222:225], v[40:43]
	v_mfma_f32_16x16x32_bf16 v[36:39], v[166:169], v[230:233], v[36:39]
	v_mfma_f32_16x16x32_bf16 v[32:35], v[198:201], v[230:233], v[32:35]
	s_setprio 0
	s_barrier
	s_add_i32 s36, s62, s49
	v_lshl_add_u64 v[170:171], s[40:41], 0, v[146:147]
	s_mov_b32 m0, s36
	ds_read_b128 v[202:205], v174 offset:16384
	ds_read_b128 v[206:209], v174 offset:17408
	ds_read_b128 v[210:213], v174 offset:18432
	ds_read_b128 v[214:217], v174 offset:19456
	ds_read_b128 v[218:221], v174 offset:20480
	ds_read_b128 v[222:225], v174 offset:21504
	ds_read_b128 v[226:229], v174 offset:22528
	ds_read_b128 v[230:233], v174 offset:23552
	global_load_lds_dwordx4 v[170:171], off
	s_add_i32 m0, s36, 0x2000
	s_add_u32 s36, s40, 0x40000
	v_lshl_add_u64 v[234:235], s[40:41], 0, v[150:151]
	s_addc_u32 s37, s41, 0
	s_add_i32 s68, s63, s49
	global_load_lds_dwordx4 v[234:235], off
	v_lshl_add_u64 v[236:237], s[36:37], 0, v[146:147]
	s_mov_b32 m0, s68
	v_lshl_add_u64 v[238:239], s[42:43], 0, v[148:149]
	global_load_lds_dwordx4 v[236:237], off
	v_lshl_add_u64 v[236:237], s[36:37], 0, v[150:151]
	s_add_i32 m0, s68, 0x2000
	s_nop 0
	global_load_lds_dwordx4 v[236:237], off
	s_waitcnt vmcnt(6)
	s_waitcnt lgkmcnt(0)
	s_barrier
	s_setprio 1
	v_mfma_f32_16x16x32_bf16 v[92:95], v[128:131], v[202:205], v[92:95]
	v_mfma_f32_16x16x32_bf16 v[88:91], v[136:139], v[202:205], v[88:91]
	v_mfma_f32_16x16x32_bf16 v[84:87], v[128:131], v[210:213], v[84:87]
	v_mfma_f32_16x16x32_bf16 v[80:83], v[136:139], v[210:213], v[80:83]
	v_mfma_f32_16x16x32_bf16 v[76:79], v[128:131], v[218:221], v[76:79]
	v_mfma_f32_16x16x32_bf16 v[72:75], v[136:139], v[218:221], v[72:75]
	v_mfma_f32_16x16x32_bf16 v[68:71], v[128:131], v[226:229], v[68:71]
	v_mfma_f32_16x16x32_bf16 v[64:67], v[136:139], v[226:229], v[64:67]
	v_mfma_f32_16x16x32_bf16 v[92:95], v[132:135], v[206:209], v[92:95]
	v_mfma_f32_16x16x32_bf16 v[88:91], v[140:143], v[206:209], v[88:91]
	v_mfma_f32_16x16x32_bf16 v[84:87], v[132:135], v[214:217], v[84:87]
	v_mfma_f32_16x16x32_bf16 v[80:83], v[140:143], v[214:217], v[80:83]
	v_mfma_f32_16x16x32_bf16 v[76:79], v[132:135], v[222:225], v[76:79]
	v_mfma_f32_16x16x32_bf16 v[72:75], v[140:143], v[222:225], v[72:75]
	v_mfma_f32_16x16x32_bf16 v[68:71], v[132:135], v[230:233], v[68:71]
	v_mfma_f32_16x16x32_bf16 v[64:67], v[140:143], v[230:233], v[64:67]
	v_mfma_f32_16x16x32_bf16 v[28:31], v[162:165], v[202:205], v[28:31]
	v_mfma_f32_16x16x32_bf16 v[24:27], v[194:197], v[202:205], v[24:27]
	v_mfma_f32_16x16x32_bf16 v[20:23], v[162:165], v[210:213], v[20:23]
	v_mfma_f32_16x16x32_bf16 v[16:19], v[194:197], v[210:213], v[16:19]
	v_mfma_f32_16x16x32_bf16 v[12:15], v[162:165], v[218:221], v[12:15]
	v_mfma_f32_16x16x32_bf16 v[8:11], v[194:197], v[218:221], v[8:11]
	v_mfma_f32_16x16x32_bf16 v[4:7], v[162:165], v[226:229], v[4:7]
	v_mfma_f32_16x16x32_bf16 v[0:3], v[194:197], v[226:229], v[0:3]
	v_mfma_f32_16x16x32_bf16 v[28:31], v[166:169], v[206:209], v[28:31]
	v_mfma_f32_16x16x32_bf16 v[24:27], v[198:201], v[206:209], v[24:27]
	v_mfma_f32_16x16x32_bf16 v[20:23], v[166:169], v[214:217], v[20:23]
	v_mfma_f32_16x16x32_bf16 v[16:19], v[198:201], v[214:217], v[16:19]
	v_mfma_f32_16x16x32_bf16 v[12:15], v[166:169], v[222:225], v[12:15]
	v_mfma_f32_16x16x32_bf16 v[8:11], v[198:201], v[222:225], v[8:11]
	v_mfma_f32_16x16x32_bf16 v[4:7], v[166:169], v[230:233], v[4:7]
	v_mfma_f32_16x16x32_bf16 v[0:3], v[198:201], v[230:233], v[0:3]
	s_setprio 0
	s_barrier
; #define PG8_STAGE(bufoff, gbase, voff) do { _Pragma("unroll") for (int _i = 0; _i < 2; ++_i) \
;         __builtin_amdgcn_global_load_lds((const unsigned*)((const char*)(gbase) + (voff)[_i]), (PG8_LAS unsigned*)(lds + (bufoff) + ldsw + _i * 8192), 16, 0, 0); } while (0)
; #define PG8_LDA(dst, b, h) do { _Pragma("unroll") for (int m = 0; m < 4; ++m) _Pragma("unroll") for (int k = 0; k < 2; ++k) dst[m][k] = *(const PG8_LAS bf16x8*)(lds + PG8_SA(b, h) + aoff + m * 2048 + k * 1024); } while (0)
; #define PG8_LDB(dst, b, h) do { _Pragma("unroll") for (int n = 0; n < 2; ++n) _Pragma("unroll") for (int k = 0; k < 2; ++k) dst[n][k] = *(const PG8_LAS bf16x8*)(lds + PG8_SB(b, h) + boff + n * 2048 + k * 1024); } while (0)
; #define PG8_MMA(ai, bj, At, Bt) do { __builtin_amdgcn_s_setprio(1); _Pragma("unroll") for (int m = 0; m < 4; ++m) _Pragma("unroll") for (int n = 0; n < 2; ++n) _Pragma("unroll") for (int k = 0; k < 2; ++k) \
;         acc[ai][bj][m][n] = __builtin_amdgcn_mfma_f32_16x16x32_bf16(Bt[n][k], At[m][k], acc[ai][bj][m][n], 0, 0, 0); __builtin_amdgcn_s_setprio(0); } while (0)
; #define PG8_WAIT_V(n) asm volatile("s_waitcnt vmcnt(" #n ")" ::: "memory")
; #define PG8_WAIT_L(n) asm volatile("s_waitcnt lgkmcnt(" #n ")" ::: "memory")
; #define PG8_BAR __builtin_amdgcn_s_barrier()
; #define PG8_SCHED __builtin_amdgcn_sched_barrier(0)
; template <class Epi, class Sched, bool ALIGN_EPI = false, bool SP2 = false>
; __device__ __forceinline__ void gemm_phase(PG8_LAS unsigned char* lds, const Gemm g, const Sched& S, const Epi& E) {
;     ...
;             PG8_LDB(B0, 1, 0); PG8_LDB(B1, 1, 1); PG8_SCHED; PG8_LDA(At, 1, 0); PG8_STAGE(PG8_SA(0, 1), a2 + hstepA, voffA);
;             PG8_WAIT_V(8); PG8_WAIT_L(0); PG8_BAR; PG8_MMA(0, 0, At, B0); PG8_MMA(0, 1, At, B1); PG8_BAR; PG8_SCHED;
	s_add_i32 s68, 0, 0x18000
	s_add_i32 s69, 0, 0x1c000
	v_add_u32_e32 v140, s68, v173
	v_add_u32_e32 v153, s69, v173
	ds_read_b128 v[128:131], v140
	ds_read_b128 v[132:135], v140 offset:1024
	ds_read_b128 v[136:139], v140 offset:2048
	ds_read_b128 v[140:143], v140 offset:3072
	ds_read_b128 v[162:165], v153
	ds_read_b128 v[166:169], v153 offset:1024
	ds_read_b128 v[194:197], v153 offset:2048
	ds_read_b128 v[198:201], v153 offset:3072
	s_add_u32 s36, s42, 0x8000
	s_addc_u32 s37, s43, 0
	v_lshl_add_u64 v[236:237], s[42:43], 0, v[144:145]
	s_mov_b32 m0, s50
	s_nop 0
	global_load_lds_dwordx4 v[236:237], off
	s_mov_b32 m0, s51
	s_nop 0
	global_load_lds_dwordx4 v[238:239], off
	s_mov_b32 m0, s52
	v_lshl_add_u64 v[240:241], s[36:37], 0, v[144:145]
	ds_read_b128 v[202:205], v174 offset:32768
	ds_read_b128 v[206:209], v174 offset:33792
	ds_read_b128 v[210:213], v174 offset:34816
	ds_read_b128 v[214:217], v174 offset:35840
	ds_read_b128 v[218:221], v174 offset:36864
	ds_read_b128 v[222:225], v174 offset:37888
	ds_read_b128 v[226:229], v174 offset:38912
	ds_read_b128 v[230:233], v174 offset:39936
	global_load_lds_dwordx4 v[240:241], off
	v_lshl_add_u64 v[240:241], s[36:37], 0, v[148:149]
	s_mov_b32 m0, s53
	s_nop 0
	global_load_lds_dwordx4 v[240:241], off
	s_waitcnt vmcnt(8)
	s_waitcnt lgkmcnt(0)
	s_barrier
	s_setprio 1
	v_mfma_f32_16x16x32_bf16 v[124:127], v[128:131], v[202:205], v[124:127]
	v_mfma_f32_16x16x32_bf16 v[120:123], v[136:139], v[202:205], v[120:123]
	v_mfma_f32_16x16x32_bf16 v[116:119], v[128:131], v[210:213], v[116:119]
	v_mfma_f32_16x16x32_bf16 v[112:115], v[136:139], v[210:213], v[112:115]
	v_mfma_f32_16x16x32_bf16 v[108:111], v[128:131], v[218:221], v[108:111]
	v_mfma_f32_16x16x32_bf16 v[104:107], v[136:139], v[218:221], v[104:107]
	v_mfma_f32_16x16x32_bf16 v[100:103], v[128:131], v[226:229], v[100:103]
	v_mfma_f32_16x16x32_bf16 v[96:99], v[136:139], v[226:229], v[96:99]
	v_mfma_f32_16x16x32_bf16 v[124:127], v[132:135], v[206:209], v[124:127]
	v_mfma_f32_16x16x32_bf16 v[120:123], v[140:143], v[206:209], v[120:123]
	v_mfma_f32_16x16x32_bf16 v[116:119], v[132:135], v[214:217], v[116:119]
	v_mfma_f32_16x16x32_bf16 v[112:115], v[140:143], v[214:217], v[112:115]
	v_mfma_f32_16x16x32_bf16 v[108:111], v[132:135], v[222:225], v[108:111]
	v_mfma_f32_16x16x32_bf16 v[104:107], v[140:143], v[222:225], v[104:107]
	v_mfma_f32_16x16x32_bf16 v[100:103], v[132:135], v[230:233], v[100:103]
	v_mfma_f32_16x16x32_bf16 v[96:99], v[140:143], v[230:233], v[96:99]
	v_mfma_f32_16x16x32_bf16 v[60:63], v[162:165], v[202:205], v[60:63]
	v_mfma_f32_16x16x32_bf16 v[56:59], v[194:197], v[202:205], v[56:59]
	v_mfma_f32_16x16x32_bf16 v[52:55], v[162:165], v[210:213], v[52:55]
	v_mfma_f32_16x16x32_bf16 v[48:51], v[194:197], v[210:213], v[48:51]
	v_mfma_f32_16x16x32_bf16 v[44:47], v[162:165], v[218:221], v[44:47]
	v_mfma_f32_16x16x32_bf16 v[40:43], v[194:197], v[218:221], v[40:43]
	v_mfma_f32_16x16x32_bf16 v[36:39], v[162:165], v[226:229], v[36:39]
	v_mfma_f32_16x16x32_bf16 v[32:35], v[194:197], v[226:229], v[32:35]
	v_mfma_f32_16x16x32_bf16 v[60:63], v[166:169], v[206:209], v[60:63]
	v_mfma_f32_16x16x32_bf16 v[56:59], v[198:201], v[206:209], v[56:59]
	v_mfma_f32_16x16x32_bf16 v[52:55], v[166:169], v[214:217], v[52:55]
	v_mfma_f32_16x16x32_bf16 v[48:51], v[198:201], v[214:217], v[48:51]
	v_mfma_f32_16x16x32_bf16 v[44:47], v[166:169], v[222:225], v[44:47]
	v_mfma_f32_16x16x32_bf16 v[40:43], v[198:201], v[222:225], v[40:43]
	v_mfma_f32_16x16x32_bf16 v[36:39], v[166:169], v[230:233], v[36:39]
	v_mfma_f32_16x16x32_bf16 v[32:35], v[198:201], v[230:233], v[32:35]
	s_setprio 0
	s_barrier
; #define PG8_STAGE(bufoff, gbase, voff) do { _Pragma("unroll") for (int _i = 0; _i < 2; ++_i) \
;         __builtin_amdgcn_global_load_lds((const unsigned*)((const char*)(gbase) + (voff)[_i]), (PG8_LAS unsigned*)(lds + (bufoff) + ldsw + _i * 8192), 16, 0, 0); } while (0)
; #define PG8_LDA(dst, b, h) do { _Pragma("unroll") for (int m = 0; m < 4; ++m) _Pragma("unroll") for (int k = 0; k < 2; ++k) dst[m][k] = *(const PG8_LAS bf16x8*)(lds + PG8_SA(b, h) + aoff + m * 2048 + k * 1024); } while (0)
; #define PG8_MMA(ai, bj, At, Bt) do { __builtin_amdgcn_s_setprio(1); _Pragma("unroll") for (int m = 0; m < 4; ++m) _Pragma("unroll") for (int n = 0; n < 2; ++n) _Pragma("unroll") for (int k = 0; k < 2; ++k) \
;         acc[ai][bj][m][n] = __builtin_amdgcn_mfma_f32_16x16x32_bf16(Bt[n][k], At[m][k], acc[ai][bj][m][n], 0, 0, 0); __builtin_amdgcn_s_setprio(0); } while (0)
; #define PG8_WAIT_V(n) asm volatile("s_waitcnt vmcnt(" #n ")" ::: "memory")
; #define PG8_WAIT_L(n) asm volatile("s_waitcnt lgkmcnt(" #n ")" ::: "memory")
; #define PG8_BAR __builtin_amdgcn_s_barrier()
; #define PG8_SCHED __builtin_amdgcn_sched_barrier(0)
; template <class Epi, class Sched, bool ALIGN_EPI = false, bool SP2 = false>
; __device__ __forceinline__ void gemm_phase(PG8_LAS unsigned char* lds, const Gemm g, const Sched& S, const Epi& E) {
;     ...
;             PG8_LDA(At, 1, 1); PG8_STAGE(PG8_SB(1, 0), b3, voffB); PG8_STAGE(PG8_SB(1, 1), b3 + hstepB, voffB); PG8_STAGE(PG8_SA(1, 0), a3, voffA);
;             PG8_WAIT_V(8); PG8_WAIT_L(0); PG8_BAR; PG8_MMA(1, 0, At, B0); PG8_MMA(1, 1, At, B1); PG8_BAR; PG8_SCHED;
;     ...
;         if constexpr (ALIGN_EPI) { if (wr == 0) PG8_BAR; }
;         if constexpr (!Epi::AFTER_DRAIN) { E(acc, cur, wr, wc, fr, fq); S.done(cur); }
;         if (!has_next) break;
	s_add_i32 s36, s68, s49
	v_lshl_add_u64 v[170:171], v[170:171], 0, s[18:19]
	s_mov_b32 m0, s36
	ds_read_b128 v[202:205], v174 offset:49152
	ds_read_b128 v[206:209], v174 offset:50176
	ds_read_b128 v[210:213], v174 offset:51200
	ds_read_b128 v[214:217], v174 offset:52224
	ds_read_b128 v[218:221], v174 offset:53248
	ds_read_b128 v[222:225], v174 offset:54272
	ds_read_b128 v[226:229], v174 offset:55296
	ds_read_b128 v[230:233], v174 offset:56320
	global_load_lds_dwordx4 v[170:171], off
	s_add_i32 m0, s36, 0x2000
	s_add_u32 s36, s40, 0x40080
	v_lshl_add_u64 v[170:171], v[234:235], 0, s[18:19]
	s_addc_u32 s37, s41, 0
	s_add_i32 s40, s69, s49
	global_load_lds_dwordx4 v[170:171], off
	v_lshl_add_u64 v[170:171], s[36:37], 0, v[146:147]
	s_mov_b32 m0, s40
	s_nop 0
	global_load_lds_dwordx4 v[170:171], off
	v_lshl_add_u64 v[170:171], s[36:37], 0, v[150:151]
	s_add_i32 m0, s40, 0x2000
	s_nop 0
	global_load_lds_dwordx4 v[170:171], off
	v_lshl_add_u64 v[170:171], v[236:237], 0, s[18:19]
	s_mov_b32 m0, s58
	s_nop 0
	global_load_lds_dwordx4 v[170:171], off
	v_lshl_add_u64 v[170:171], v[238:239], 0, s[18:19]
	s_mov_b32 m0, s59
	s_nop 0
	global_load_lds_dwordx4 v[170:171], off
	s_waitcnt vmcnt(8)
	s_waitcnt lgkmcnt(0)
	s_barrier
	s_setprio 1
	v_mfma_f32_16x16x32_bf16 v[92:95], v[128:131], v[202:205], v[92:95]
	v_mfma_f32_16x16x32_bf16 v[88:91], v[136:139], v[202:205], v[88:91]
	v_mfma_f32_16x16x32_bf16 v[84:87], v[128:131], v[210:213], v[84:87]
	v_mfma_f32_16x16x32_bf16 v[80:83], v[136:139], v[210:213], v[80:83]
	v_mfma_f32_16x16x32_bf16 v[76:79], v[128:131], v[218:221], v[76:79]
	v_mfma_f32_16x16x32_bf16 v[72:75], v[136:139], v[218:221], v[72:75]
	v_mfma_f32_16x16x32_bf16 v[68:71], v[128:131], v[226:229], v[68:71]
	v_mfma_f32_16x16x32_bf16 v[64:67], v[136:139], v[226:229], v[64:67]
	v_mfma_f32_16x16x32_bf16 v[92:95], v[132:135], v[206:209], v[92:95]
	v_mfma_f32_16x16x32_bf16 v[88:91], v[140:143], v[206:209], v[88:91]
	v_mfma_f32_16x16x32_bf16 v[84:87], v[132:135], v[214:217], v[84:87]
	v_mfma_f32_16x16x32_bf16 v[80:83], v[140:143], v[214:217], v[80:83]
	v_mfma_f32_16x16x32_bf16 v[76:79], v[132:135], v[222:225], v[76:79]
	v_mfma_f32_16x16x32_bf16 v[72:75], v[140:143], v[222:225], v[72:75]
	v_mfma_f32_16x16x32_bf16 v[68:71], v[132:135], v[230:233], v[68:71]
	v_mfma_f32_16x16x32_bf16 v[64:67], v[140:143], v[230:233], v[64:67]
	v_mfma_f32_16x16x32_bf16 v[28:31], v[162:165], v[202:205], v[28:31]
	v_mfma_f32_16x16x32_bf16 v[24:27], v[194:197], v[202:205], v[24:27]
	v_mfma_f32_16x16x32_bf16 v[20:23], v[162:165], v[210:213], v[20:23]
	v_mfma_f32_16x16x32_bf16 v[16:19], v[194:197], v[210:213], v[16:19]
	v_mfma_f32_16x16x32_bf16 v[12:15], v[162:165], v[218:221], v[12:15]
	v_mfma_f32_16x16x32_bf16 v[8:11], v[194:197], v[218:221], v[8:11]
	v_mfma_f32_16x16x32_bf16 v[4:7], v[162:165], v[226:229], v[4:7]
	v_mfma_f32_16x16x32_bf16 v[0:3], v[194:197], v[226:229], v[0:3]
	v_mfma_f32_16x16x32_bf16 v[28:31], v[166:169], v[206:209], v[28:31]
	v_mfma_f32_16x16x32_bf16 v[24:27], v[198:201], v[206:209], v[24:27]
	v_mfma_f32_16x16x32_bf16 v[20:23], v[166:169], v[214:217], v[20:23]
	v_mfma_f32_16x16x32_bf16 v[16:19], v[198:201], v[214:217], v[16:19]
	v_mfma_f32_16x16x32_bf16 v[12:15], v[166:169], v[222:225], v[12:15]
	v_mfma_f32_16x16x32_bf16 v[8:11], v[198:201], v[222:225], v[8:11]
	v_mfma_f32_16x16x32_bf16 v[4:7], v[166:169], v[230:233], v[4:7]
	v_mfma_f32_16x16x32_bf16 v[0:3], v[198:201], v[230:233], v[0:3]
	s_setprio 0
	s_barrier
	s_add_i32 s67, s67, 2
	s_add_u32 s65, s65, 0x100
	s_addc_u32 s66, s66, 0
	s_cmp_gt_u32 s67, 13
	s_mov_b64 s[36:37], s[38:39]
	s_cbranch_scc0 .LBB0_1191
	s_and_b64 vcc, exec, s[20:21]
	s_cbranch_vccz .LBB0_1194
	s_barrier

; #define PG8_STAGE(bufoff, gbase, voff) do { _Pragma("unroll") for (int _i = 0; _i < 2; ++_i) \
;         __builtin_amdgcn_global_load_lds((const unsigned*)((const char*)(gbase) + (voff)[_i]), (PG8_LAS unsigned*)(lds + (bufoff) + ldsw + _i * 8192), 16, 0, 0); } while (0)
; #define PG8_LDA(dst, b, h) do { _Pragma("unroll") for (int m = 0; m < 4; ++m) _Pragma("unroll") for (int k = 0; k < 2; ++k) dst[m][k] = *(const PG8_LAS bf16x8*)(lds + PG8_SA(b, h) + aoff + m * 2048 + k * 1024); } while (0)
; #define PG8_LDB(dst, b, h) do { _Pragma("unroll") for (int n = 0; n < 2; ++n) _Pragma("unroll") for (int k = 0; k < 2; ++k) dst[n][k] = *(const PG8_LAS bf16x8*)(lds + PG8_SB(b, h) + boff + n * 2048 + k * 1024); } while (0)
; #define PG8_MMA(ai, bj, At, Bt) do { __builtin_amdgcn_s_setprio(1); _Pragma("unroll") for (int m = 0; m < 4; ++m) _Pragma("unroll") for (int n = 0; n < 2; ++n) _Pragma("unroll") for (int k = 0; k < 2; ++k) \
;         acc[ai][bj][m][n] = __builtin_amdgcn_mfma_f32_16x16x32_bf16(Bt[n][k], At[m][k], acc[ai][bj][m][n], 0, 0, 0); __builtin_amdgcn_s_setprio(0); } while (0)
; #define PG8_WAIT_V(n) asm volatile("s_waitcnt vmcnt(" #n ")" ::: "memory")
; #define PG8_WAIT_L(n) asm volatile("s_waitcnt lgkmcnt(" #n ")" ::: "memory")
; template <class Epi, class Sched, bool ALIGN_EPI = false, bool SP2 = false>
; __device__ __forceinline__ void gemm_phase(PG8_LAS unsigned char* lds, const Gemm g, const Sched& S, const Epi& E) {
;     ...
;             const bool last = (t == nt - 2);
;             const char* a1 = cA + PG8_AK(t + 1);
;             const char* a2 = last ? nA : cA + PG8_AK(t + 2); const char* b2 = last ? nB : cB + (size_t)(t + 2) * kstep;
;             const char* a3 = last ? nA + PG8_AK(1) : cA + PG8_AK(t + 3); const char* b3 = b2 + kstep;
;             if (last && has_next) S.a_ready(nxt);
;             if constexpr (SP2) {
;             PG8_LDB(B0, 0, 0); PG8_LDB(B1, 0, 1); PG8_SCHED; PG8_LDA(At, 0, 0); PG8_STAGE(PG8_SA(1, 1), a1 + hstepA, voffA);
;             PG8_WAIT_V(8); PG8_WAIT_L(0); PG8_BAR; PG8_MMA(0, 0, At, B0); PG8_MMA(0, 1, At, B1); PG8_BAR; PG8_SCHED;
;             PG8_LDA(At, 0, 1); PG8_STAGE(PG8_SB(0, 0), b2, voffB); PG8_STAGE(PG8_SB(0, 1), b2 + hstepB, voffB); PG8_STAGE(PG8_SA(0, 0), a2, voffA);
;             PG8_WAIT_V(8); PG8_WAIT_L(0); PG8_BAR; PG8_MMA(1, 0, At, B0); PG8_MMA(1, 1, At, B1); PG8_BAR; PG8_SCHED;
.LBB0_1275:
	ds_read_b128 v[132:135], v171
	ds_read_b128 v[136:139], v171 offset:1024
	ds_read_b128 v[140:143], v171 offset:2048
	ds_read_b128 v[178:181], v171 offset:3072
	ds_read_b128 v[182:185], v173
	ds_read_b128 v[186:189], v173 offset:1024
	ds_read_b128 v[190:193], v173 offset:2048
	ds_read_b128 v[194:197], v173 offset:3072
	s_add_u32 s38, s34, s36
	s_addc_u32 s39, s35, s37
	s_add_u32 s42, s38, 0x100
	s_addc_u32 s43, s39, 0
	s_add_u32 s40, s66, s36
	s_addc_u32 s41, s67, s37
	s_add_u32 s38, s38, 0x180
	s_addc_u32 s39, s39, 0
	s_cmpk_eq_i32 s36, 0x700
	s_cselect_b32 s39, s65, s39
	s_cselect_b32 s38, s64, s38
	s_cselect_b32 s41, s23, s41
	s_cselect_b32 s40, s63, s40
	s_cselect_b32 s43, s3, s43
	s_cselect_b32 s42, s25, s42
	v_lshl_add_u64 v[230:231], v[130:131], 0, s[36:37]
	s_add_i32 m0, s31, 0xc000
	ds_read_b128 v[198:201], v175
	ds_read_b128 v[202:205], v175 offset:1024
	ds_read_b128 v[206:209], v175 offset:2048
	ds_read_b128 v[210:213], v175 offset:3072
	ds_read_b128 v[214:217], v175 offset:4096
	ds_read_b128 v[218:221], v175 offset:5120
	ds_read_b128 v[222:225], v175 offset:6144
	ds_read_b128 v[226:229], v175 offset:7168
	global_load_lds_dwordx4 v[230:231], off
	v_lshl_add_u64 v[230:231], v[128:129], 0, s[36:37]
	s_add_i32 m0, s31, 0xe000
	s_nop 0
	global_load_lds_dwordx4 v[230:231], off
	s_waitcnt vmcnt(8)
	s_waitcnt lgkmcnt(0)
	s_barrier
	s_setprio 1
	v_mfma_f32_16x16x32_bf16 v[124:127], v[132:135], v[198:201], v[124:127]
	v_mfma_f32_16x16x32_bf16 v[120:123], v[140:143], v[198:201], v[120:123]
	v_mfma_f32_16x16x32_bf16 v[116:119], v[132:135], v[206:209], v[116:119]
	v_mfma_f32_16x16x32_bf16 v[112:115], v[140:143], v[206:209], v[112:115]
	v_mfma_f32_16x16x32_bf16 v[108:111], v[132:135], v[214:217], v[108:111]
	v_mfma_f32_16x16x32_bf16 v[104:107], v[140:143], v[214:217], v[104:107]
	v_mfma_f32_16x16x32_bf16 v[100:103], v[132:135], v[222:225], v[100:103]
	v_mfma_f32_16x16x32_bf16 v[96:99], v[140:143], v[222:225], v[96:99]
	v_mfma_f32_16x16x32_bf16 v[124:127], v[136:139], v[202:205], v[124:127]
	v_mfma_f32_16x16x32_bf16 v[120:123], v[178:181], v[202:205], v[120:123]
	v_mfma_f32_16x16x32_bf16 v[116:119], v[136:139], v[210:213], v[116:119]
	v_mfma_f32_16x16x32_bf16 v[112:115], v[178:181], v[210:213], v[112:115]
	v_mfma_f32_16x16x32_bf16 v[108:111], v[136:139], v[218:221], v[108:111]
	v_mfma_f32_16x16x32_bf16 v[104:107], v[178:181], v[218:221], v[104:107]
	v_mfma_f32_16x16x32_bf16 v[100:103], v[136:139], v[226:229], v[100:103]
	v_mfma_f32_16x16x32_bf16 v[96:99], v[178:181], v[226:229], v[96:99]
	v_mfma_f32_16x16x32_bf16 v[64:67], v[182:185], v[198:201], v[64:67]
	v_mfma_f32_16x16x32_bf16 v[56:59], v[190:193], v[198:201], v[56:59]
	v_mfma_f32_16x16x32_bf16 v[52:55], v[182:185], v[206:209], v[52:55]
	v_mfma_f32_16x16x32_bf16 v[48:51], v[190:193], v[206:209], v[48:51]
	v_mfma_f32_16x16x32_bf16 v[44:47], v[182:185], v[214:217], v[44:47]
	v_mfma_f32_16x16x32_bf16 v[40:43], v[190:193], v[214:217], v[40:43]
	v_mfma_f32_16x16x32_bf16 v[36:39], v[182:185], v[222:225], v[36:39]
	v_mfma_f32_16x16x32_bf16 v[32:35], v[190:193], v[222:225], v[32:35]
	v_mfma_f32_16x16x32_bf16 v[64:67], v[186:189], v[202:205], v[64:67]
	v_mfma_f32_16x16x32_bf16 v[56:59], v[194:197], v[202:205], v[56:59]
	v_mfma_f32_16x16x32_bf16 v[52:55], v[186:189], v[210:213], v[52:55]
	v_mfma_f32_16x16x32_bf16 v[48:51], v[194:197], v[210:213], v[48:51]
	v_mfma_f32_16x16x32_bf16 v[44:47], v[186:189], v[218:221], v[44:47]
	v_mfma_f32_16x16x32_bf16 v[40:43], v[194:197], v[218:221], v[40:43]
	v_mfma_f32_16x16x32_bf16 v[36:39], v[186:189], v[226:229], v[36:39]
	v_mfma_f32_16x16x32_bf16 v[32:35], v[194:197], v[226:229], v[32:35]
	s_setprio 0
	s_barrier
	s_add_i32 s69, s59, s49
	v_lshl_add_u64 v[230:231], s[40:41], 0, v[148:149]
	s_mov_b32 m0, s69
	ds_read_b128 v[198:201], v175 offset:16384
	ds_read_b128 v[202:205], v175 offset:17408
	ds_read_b128 v[206:209], v175 offset:18432
	ds_read_b128 v[210:213], v175 offset:19456
	ds_read_b128 v[214:217], v175 offset:20480
	ds_read_b128 v[218:221], v175 offset:21504
	ds_read_b128 v[222:225], v175 offset:22528
	ds_read_b128 v[226:229], v175 offset:23552
	global_load_lds_dwordx4 v[230:231], off
	s_add_i32 m0, s69, 0x2000
	s_add_u32 s70, s40, 0x40000
	v_lshl_add_u64 v[232:233], s[40:41], 0, v[144:145]
	s_addc_u32 s71, s41, 0
	s_add_i32 s69, s60, s49
	global_load_lds_dwordx4 v[232:233], off
	v_lshl_add_u64 v[234:235], s[70:71], 0, v[148:149]
	s_mov_b32 m0, s69
	s_nop 0
	global_load_lds_dwordx4 v[234:235], off
	v_lshl_add_u64 v[234:235], s[70:71], 0, v[144:145]
	s_add_i32 m0, s69, 0x2000
	s_nop 0
	global_load_lds_dwordx4 v[234:235], off
	s_waitcnt vmcnt(6)
	s_waitcnt lgkmcnt(0)
	s_barrier
; #define PG8_STAGE(bufoff, gbase, voff) do { _Pragma("unroll") for (int _i = 0; _i < 2; ++_i) \
;         __builtin_amdgcn_global_load_lds((const unsigned*)((const char*)(gbase) + (voff)[_i]), (PG8_LAS unsigned*)(lds + (bufoff) + ldsw + _i * 8192), 16, 0, 0); } while (0)
; #define PG8_LDA(dst, b, h) do { _Pragma("unroll") for (int m = 0; m < 4; ++m) _Pragma("unroll") for (int k = 0; k < 2; ++k) dst[m][k] = *(const PG8_LAS bf16x8*)(lds + PG8_SA(b, h) + aoff + m * 2048 + k * 1024); } while (0)
; #define PG8_LDB(dst, b, h) do { _Pragma("unroll") for (int n = 0; n < 2; ++n) _Pragma("unroll") for (int k = 0; k < 2; ++k) dst[n][k] = *(const PG8_LAS bf16x8*)(lds + PG8_SB(b, h) + boff + n * 2048 + k * 1024); } while (0)
; #define PG8_MMA(ai, bj, At, Bt) do { __builtin_amdgcn_s_setprio(1); _Pragma("unroll") for (int m = 0; m < 4; ++m) _Pragma("unroll") for (int n = 0; n < 2; ++n) _Pragma("unroll") for (int k = 0; k < 2; ++k) \
;         acc[ai][bj][m][n] = __builtin_amdgcn_mfma_f32_16x16x32_bf16(Bt[n][k], At[m][k], acc[ai][bj][m][n], 0, 0, 0); __builtin_amdgcn_s_setprio(0); } while (0)
; #define PG8_WAIT_V(n) asm volatile("s_waitcnt vmcnt(" #n ")" ::: "memory")
; #define PG8_WAIT_L(n) asm volatile("s_waitcnt lgkmcnt(" #n ")" ::: "memory")
; #define PG8_BAR __builtin_amdgcn_s_barrier()
; #define PG8_SCHED __builtin_amdgcn_sched_barrier(0)
; template <class Epi, class Sched, bool ALIGN_EPI = false, bool SP2 = false>
; __device__ __forceinline__ void gemm_phase(PG8_LAS unsigned char* lds, const Gemm g, const Sched& S, const Epi& E) {
;     ...
;             PG8_WAIT_V(8); PG8_WAIT_L(0); PG8_BAR; PG8_MMA(1, 0, At, B0); PG8_MMA(1, 1, At, B1); PG8_BAR; PG8_SCHED;
;             PG8_LDB(B0, 1, 0); PG8_LDB(B1, 1, 1); PG8_SCHED; PG8_LDA(At, 1, 0); PG8_STAGE(PG8_SA(0, 1), a2 + hstepA, voffA);
;             PG8_WAIT_V(8); PG8_WAIT_L(0); PG8_BAR; PG8_MMA(0, 0, At, B0); PG8_MMA(0, 1, At, B1); PG8_BAR; PG8_SCHED;
	s_setprio 1
	v_mfma_f32_16x16x32_bf16 v[92:95], v[132:135], v[198:201], v[92:95]
	v_mfma_f32_16x16x32_bf16 v[88:91], v[140:143], v[198:201], v[88:91]
	v_mfma_f32_16x16x32_bf16 v[84:87], v[132:135], v[206:209], v[84:87]
	v_mfma_f32_16x16x32_bf16 v[80:83], v[140:143], v[206:209], v[80:83]
	v_mfma_f32_16x16x32_bf16 v[76:79], v[132:135], v[214:217], v[76:79]
	v_mfma_f32_16x16x32_bf16 v[72:75], v[140:143], v[214:217], v[72:75]
	v_mfma_f32_16x16x32_bf16 v[68:71], v[132:135], v[222:225], v[68:71]
	v_mfma_f32_16x16x32_bf16 v[60:63], v[140:143], v[222:225], v[60:63]
	v_mfma_f32_16x16x32_bf16 v[92:95], v[136:139], v[202:205], v[92:95]
	v_mfma_f32_16x16x32_bf16 v[88:91], v[178:181], v[202:205], v[88:91]
	v_mfma_f32_16x16x32_bf16 v[84:87], v[136:139], v[210:213], v[84:87]
	v_mfma_f32_16x16x32_bf16 v[80:83], v[178:181], v[210:213], v[80:83]
	v_mfma_f32_16x16x32_bf16 v[76:79], v[136:139], v[218:221], v[76:79]
	v_mfma_f32_16x16x32_bf16 v[72:75], v[178:181], v[218:221], v[72:75]
	v_mfma_f32_16x16x32_bf16 v[68:71], v[136:139], v[226:229], v[68:71]
	v_mfma_f32_16x16x32_bf16 v[60:63], v[178:181], v[226:229], v[60:63]
	v_mfma_f32_16x16x32_bf16 v[28:31], v[182:185], v[198:201], v[28:31]
	v_mfma_f32_16x16x32_bf16 v[24:27], v[190:193], v[198:201], v[24:27]
	v_mfma_f32_16x16x32_bf16 v[20:23], v[182:185], v[206:209], v[20:23]
	v_mfma_f32_16x16x32_bf16 v[16:19], v[190:193], v[206:209], v[16:19]
	v_mfma_f32_16x16x32_bf16 v[12:15], v[182:185], v[214:217], v[12:15]
	v_mfma_f32_16x16x32_bf16 v[8:11], v[190:193], v[214:217], v[8:11]
	v_mfma_f32_16x16x32_bf16 v[4:7], v[182:185], v[222:225], v[4:7]
	v_mfma_f32_16x16x32_bf16 v[0:3], v[190:193], v[222:225], v[0:3]
	v_mfma_f32_16x16x32_bf16 v[28:31], v[186:189], v[202:205], v[28:31]
	v_mfma_f32_16x16x32_bf16 v[24:27], v[194:197], v[202:205], v[24:27]
	v_mfma_f32_16x16x32_bf16 v[20:23], v[186:189], v[210:213], v[20:23]
	v_mfma_f32_16x16x32_bf16 v[16:19], v[194:197], v[210:213], v[16:19]
	v_mfma_f32_16x16x32_bf16 v[12:15], v[186:189], v[218:221], v[12:15]
	v_mfma_f32_16x16x32_bf16 v[8:11], v[194:197], v[218:221], v[8:11]
	v_mfma_f32_16x16x32_bf16 v[4:7], v[186:189], v[226:229], v[4:7]
	v_mfma_f32_16x16x32_bf16 v[0:3], v[194:197], v[226:229], v[0:3]
	s_setprio 0
	s_barrier
	s_add_i32 s69, 0, 0x18000
	v_add_u32_e32 v160, s69, v163
	s_add_i32 s70, 0, 0x1c000
	ds_read_b128 v[132:135], v160
	ds_read_b128 v[136:139], v160 offset:1024
	ds_read_b128 v[140:143], v160 offset:2048
	ds_read_b128 v[178:181], v160 offset:3072
	v_add_u32_e32 v160, s70, v163
	ds_read_b128 v[182:185], v160
	ds_read_b128 v[186:189], v160 offset:1024
	ds_read_b128 v[190:193], v160 offset:2048
	ds_read_b128 v[194:197], v160 offset:3072
	v_lshl_add_u64 v[234:235], s[42:43], 0, v[150:151]
	s_mov_b32 m0, s31
	s_nop 0
	global_load_lds_dwordx4 v[234:235], off
	v_lshl_add_u64 v[234:235], s[42:43], 0, v[146:147]
	s_mov_b32 m0, s52
	s_nop 0
	global_load_lds_dwordx4 v[234:235], off
	s_add_u32 s42, s42, 0x40000
	s_addc_u32 s43, s43, 0
	s_mov_b32 m0, s53
	v_lshl_add_u64 v[234:235], s[42:43], 0, v[150:151]
	ds_read_b128 v[198:201], v175 offset:32768
	ds_read_b128 v[202:205], v175 offset:33792
	ds_read_b128 v[206:209], v175 offset:34816
	ds_read_b128 v[210:213], v175 offset:35840
	ds_read_b128 v[214:217], v175 offset:36864
	ds_read_b128 v[218:221], v175 offset:37888
	ds_read_b128 v[222:225], v175 offset:38912
	ds_read_b128 v[226:229], v175 offset:39936
	global_load_lds_dwordx4 v[234:235], off
	v_lshl_add_u64 v[234:235], s[42:43], 0, v[146:147]
	s_mov_b32 m0, s54
	s_nop 0
	global_load_lds_dwordx4 v[234:235], off
	s_waitcnt vmcnt(8)
	s_waitcnt lgkmcnt(0)
	s_barrier
	s_setprio 1
	v_mfma_f32_16x16x32_bf16 v[124:127], v[132:135], v[198:201], v[124:127]
	v_mfma_f32_16x16x32_bf16 v[120:123], v[140:143], v[198:201], v[120:123]
	v_mfma_f32_16x16x32_bf16 v[116:119], v[132:135], v[206:209], v[116:119]
	v_mfma_f32_16x16x32_bf16 v[112:115], v[140:143], v[206:209], v[112:115]
	v_mfma_f32_16x16x32_bf16 v[108:111], v[132:135], v[214:217], v[108:111]
	v_mfma_f32_16x16x32_bf16 v[104:107], v[140:143], v[214:217], v[104:107]
	v_mfma_f32_16x16x32_bf16 v[100:103], v[132:135], v[222:225], v[100:103]
	v_mfma_f32_16x16x32_bf16 v[96:99], v[140:143], v[222:225], v[96:99]
	v_mfma_f32_16x16x32_bf16 v[124:127], v[136:139], v[202:205], v[124:127]
	v_mfma_f32_16x16x32_bf16 v[120:123], v[178:181], v[202:205], v[120:123]
	v_mfma_f32_16x16x32_bf16 v[116:119], v[136:139], v[210:213], v[116:119]
	v_mfma_f32_16x16x32_bf16 v[112:115], v[178:181], v[210:213], v[112:115]
	v_mfma_f32_16x16x32_bf16 v[108:111], v[136:139], v[218:221], v[108:111]
	v_mfma_f32_16x16x32_bf16 v[104:107], v[178:181], v[218:221], v[104:107]
	v_mfma_f32_16x16x32_bf16 v[100:103], v[136:139], v[226:229], v[100:103]
	v_mfma_f32_16x16x32_bf16 v[96:99], v[178:181], v[226:229], v[96:99]
	v_mfma_f32_16x16x32_bf16 v[64:67], v[182:185], v[198:201], v[64:67]
	v_mfma_f32_16x16x32_bf16 v[56:59], v[190:193], v[198:201], v[56:59]
	v_mfma_f32_16x16x32_bf16 v[52:55], v[182:185], v[206:209], v[52:55]
	v_mfma_f32_16x16x32_bf16 v[48:51], v[190:193], v[206:209], v[48:51]
	v_mfma_f32_16x16x32_bf16 v[44:47], v[182:185], v[214:217], v[44:47]
	v_mfma_f32_16x16x32_bf16 v[40:43], v[190:193], v[214:217], v[40:43]
	v_mfma_f32_16x16x32_bf16 v[36:39], v[182:185], v[222:225], v[36:39]
	v_mfma_f32_16x16x32_bf16 v[32:35], v[190:193], v[222:225], v[32:35]
	v_mfma_f32_16x16x32_bf16 v[64:67], v[186:189], v[202:205], v[64:67]
	v_mfma_f32_16x16x32_bf16 v[56:59], v[194:197], v[202:205], v[56:59]
	v_mfma_f32_16x16x32_bf16 v[52:55], v[186:189], v[210:213], v[52:55]
	v_mfma_f32_16x16x32_bf16 v[48:51], v[194:197], v[210:213], v[48:51]
	v_mfma_f32_16x16x32_bf16 v[44:47], v[186:189], v[218:221], v[44:47]
	v_mfma_f32_16x16x32_bf16 v[40:43], v[194:197], v[218:221], v[40:43]
	v_mfma_f32_16x16x32_bf16 v[36:39], v[186:189], v[226:229], v[36:39]
	v_mfma_f32_16x16x32_bf16 v[32:35], v[194:197], v[226:229], v[32:35]
	s_setprio 0
	s_barrier
; #define PG8_STAGE(bufoff, gbase, voff) do { _Pragma("unroll") for (int _i = 0; _i < 2; ++_i) \
;         __builtin_amdgcn_global_load_lds((const unsigned*)((const char*)(gbase) + (voff)[_i]), (PG8_LAS unsigned*)(lds + (bufoff) + ldsw + _i * 8192), 16, 0, 0); } while (0)
; #define PG8_LDA(dst, b, h) do { _Pragma("unroll") for (int m = 0; m < 4; ++m) _Pragma("unroll") for (int k = 0; k < 2; ++k) dst[m][k] = *(const PG8_LAS bf16x8*)(lds + PG8_SA(b, h) + aoff + m * 2048 + k * 1024); } while (0)
; #define PG8_MMA(ai, bj, At, Bt) do { __builtin_amdgcn_s_setprio(1); _Pragma("unroll") for (int m = 0; m < 4; ++m) _Pragma("unroll") for (int n = 0; n < 2; ++n) _Pragma("unroll") for (int k = 0; k < 2; ++k) \
;         acc[ai][bj][m][n] = __builtin_amdgcn_mfma_f32_16x16x32_bf16(Bt[n][k], At[m][k], acc[ai][bj][m][n], 0, 0, 0); __builtin_amdgcn_s_setprio(0); } while (0)
; #define PG8_WAIT_V(n) asm volatile("s_waitcnt vmcnt(" #n ")" ::: "memory")
; #define PG8_WAIT_L(n) asm volatile("s_waitcnt lgkmcnt(" #n ")" ::: "memory")
; #define PG8_BAR __builtin_amdgcn_s_barrier()
; #define PG8_SCHED __builtin_amdgcn_sched_barrier(0)
; template <class Epi, class Sched, bool ALIGN_EPI = false, bool SP2 = false>
; __device__ __forceinline__ void gemm_phase(PG8_LAS unsigned char* lds, const Gemm g, const Sched& S, const Epi& E) {
;     ...
;             PG8_LDA(At, 1, 1); PG8_STAGE(PG8_SB(1, 0), b3, voffB); PG8_STAGE(PG8_SB(1, 1), b3 + hstepB, voffB); PG8_STAGE(PG8_SA(1, 0), a3, voffA);
;             PG8_WAIT_V(8); PG8_WAIT_L(0); PG8_BAR; PG8_MMA(1, 0, At, B0); PG8_MMA(1, 1, At, B1); PG8_BAR; PG8_SCHED;
;     ...
;         if constexpr (ALIGN_EPI) { if (wr == 0) PG8_BAR; }
;         if constexpr (!Epi::AFTER_DRAIN) { E(acc, cur, wr, wc, fr, fq); S.done(cur); }
;         if (!has_next) break;
	s_add_i32 s42, s69, s49
	v_lshl_add_u64 v[230:231], v[230:231], 0, s[16:17]
	s_mov_b32 m0, s42
	ds_read_b128 v[198:201], v175 offset:49152
	ds_read_b128 v[202:205], v175 offset:50176
	ds_read_b128 v[206:209], v175 offset:51200
	ds_read_b128 v[210:213], v175 offset:52224
	ds_read_b128 v[214:217], v175 offset:53248
	ds_read_b128 v[218:221], v175 offset:54272
	ds_read_b128 v[222:225], v175 offset:55296
	ds_read_b128 v[226:229], v175 offset:56320
	global_load_lds_dwordx4 v[230:231], off
	s_add_i32 m0, s42, 0x2000
	s_add_u32 s40, s40, 0x40080
	v_lshl_add_u64 v[230:231], v[232:233], 0, s[16:17]
	s_addc_u32 s41, s41, 0
	s_add_i32 s42, s70, s49
	global_load_lds_dwordx4 v[230:231], off
	v_lshl_add_u64 v[230:231], s[40:41], 0, v[148:149]
	s_mov_b32 m0, s42
	s_nop 0
	global_load_lds_dwordx4 v[230:231], off
	v_lshl_add_u64 v[230:231], s[40:41], 0, v[144:145]
	s_add_i32 m0, s42, 0x2000
	s_nop 0
	global_load_lds_dwordx4 v[230:231], off
	v_lshl_add_u64 v[230:231], s[38:39], 0, v[150:151]
	s_mov_b32 m0, s56
	s_nop 0
	global_load_lds_dwordx4 v[230:231], off
	v_lshl_add_u64 v[230:231], s[38:39], 0, v[146:147]
	s_mov_b32 m0, s57
	s_nop 0
	global_load_lds_dwordx4 v[230:231], off
	s_waitcnt vmcnt(8)
	s_waitcnt lgkmcnt(0)
	s_barrier
	s_setprio 1
	v_mfma_f32_16x16x32_bf16 v[92:95], v[132:135], v[198:201], v[92:95]
	v_mfma_f32_16x16x32_bf16 v[88:91], v[140:143], v[198:201], v[88:91]
	v_mfma_f32_16x16x32_bf16 v[84:87], v[132:135], v[206:209], v[84:87]
	v_mfma_f32_16x16x32_bf16 v[80:83], v[140:143], v[206:209], v[80:83]
	v_mfma_f32_16x16x32_bf16 v[76:79], v[132:135], v[214:217], v[76:79]
	v_mfma_f32_16x16x32_bf16 v[72:75], v[140:143], v[214:217], v[72:75]
	v_mfma_f32_16x16x32_bf16 v[68:71], v[132:135], v[222:225], v[68:71]
	v_mfma_f32_16x16x32_bf16 v[60:63], v[140:143], v[222:225], v[60:63]
	v_mfma_f32_16x16x32_bf16 v[92:95], v[136:139], v[202:205], v[92:95]
	v_mfma_f32_16x16x32_bf16 v[88:91], v[178:181], v[202:205], v[88:91]
	v_mfma_f32_16x16x32_bf16 v[84:87], v[136:139], v[210:213], v[84:87]
	v_mfma_f32_16x16x32_bf16 v[80:83], v[178:181], v[210:213], v[80:83]
	v_mfma_f32_16x16x32_bf16 v[76:79], v[136:139], v[218:221], v[76:79]
	v_mfma_f32_16x16x32_bf16 v[72:75], v[178:181], v[218:221], v[72:75]
	v_mfma_f32_16x16x32_bf16 v[68:71], v[136:139], v[226:229], v[68:71]
	v_mfma_f32_16x16x32_bf16 v[60:63], v[178:181], v[226:229], v[60:63]
	v_mfma_f32_16x16x32_bf16 v[28:31], v[182:185], v[198:201], v[28:31]
	v_mfma_f32_16x16x32_bf16 v[24:27], v[190:193], v[198:201], v[24:27]
	v_mfma_f32_16x16x32_bf16 v[20:23], v[182:185], v[206:209], v[20:23]
	v_mfma_f32_16x16x32_bf16 v[16:19], v[190:193], v[206:209], v[16:19]
	v_mfma_f32_16x16x32_bf16 v[12:15], v[182:185], v[214:217], v[12:15]
	v_mfma_f32_16x16x32_bf16 v[8:11], v[190:193], v[214:217], v[8:11]
	v_mfma_f32_16x16x32_bf16 v[4:7], v[182:185], v[222:225], v[4:7]
	v_mfma_f32_16x16x32_bf16 v[0:3], v[190:193], v[222:225], v[0:3]
	v_mfma_f32_16x16x32_bf16 v[28:31], v[186:189], v[202:205], v[28:31]
	v_mfma_f32_16x16x32_bf16 v[24:27], v[194:197], v[202:205], v[24:27]
	v_mfma_f32_16x16x32_bf16 v[20:23], v[186:189], v[210:213], v[20:23]
	v_mfma_f32_16x16x32_bf16 v[16:19], v[194:197], v[210:213], v[16:19]
	v_mfma_f32_16x16x32_bf16 v[12:15], v[186:189], v[218:221], v[12:15]
	v_mfma_f32_16x16x32_bf16 v[8:11], v[194:197], v[218:221], v[8:11]
	v_mfma_f32_16x16x32_bf16 v[4:7], v[186:189], v[226:229], v[4:7]
	v_mfma_f32_16x16x32_bf16 v[0:3], v[194:197], v[226:229], v[0:3]
	s_setprio 0
	s_barrier
	s_add_i32 s68, s68, 2
	s_add_u32 s36, s36, 0x100
	s_addc_u32 s37, s37, 0
	s_cmp_gt_u32 s68, 13
	s_cbranch_scc0 .LBB0_1275
	s_and_b64 vcc, exec, s[18:19]
	s_cbranch_vccz .LBB0_1278
	s_barrier

; #define PG8_STAGE(bufoff, gbase, voff) do { _Pragma("unroll") for (int _i = 0; _i < 2; ++_i) \
;         __builtin_amdgcn_global_load_lds((const unsigned*)((const char*)(gbase) + (voff)[_i]), (PG8_LAS unsigned*)(lds + (bufoff) + ldsw + _i * 8192), 16, 0, 0); } while (0)
; #define PG8_LDA(dst, b, h) do { _Pragma("unroll") for (int m = 0; m < 4; ++m) _Pragma("unroll") for (int k = 0; k < 2; ++k) dst[m][k] = *(const PG8_LAS bf16x8*)(lds + PG8_SA(b, h) + aoff + m * 2048 + k * 1024); } while (0)
; #define PG8_LDB(dst, b, h) do { _Pragma("unroll") for (int n = 0; n < 2; ++n) _Pragma("unroll") for (int k = 0; k < 2; ++k) dst[n][k] = *(const PG8_LAS bf16x8*)(lds + PG8_SB(b, h) + boff + n * 2048 + k * 1024); } while (0)
; #define PG8_MMA(ai, bj, At, Bt) do { __builtin_amdgcn_s_setprio(1); _Pragma("unroll") for (int m = 0; m < 4; ++m) _Pragma("unroll") for (int n = 0; n < 2; ++n) _Pragma("unroll") for (int k = 0; k < 2; ++k) \
;         acc[ai][bj][m][n] = __builtin_amdgcn_mfma_f32_16x16x32_bf16(Bt[n][k], At[m][k], acc[ai][bj][m][n], 0, 0, 0); __builtin_amdgcn_s_setprio(0); } while (0)
; #define PG8_WAIT_V(n) asm volatile("s_waitcnt vmcnt(" #n ")" ::: "memory")
; #define PG8_WAIT_L(n) asm volatile("s_waitcnt lgkmcnt(" #n ")" ::: "memory")
; template <class Epi, class Sched, bool ALIGN_EPI = false, bool SP2 = false>
; __device__ __forceinline__ void gemm_phase(PG8_LAS unsigned char* lds, const Gemm g, const Sched& S, const Epi& E) {
;     ...
;             const bool last = (t == nt - 2);
;             const char* a1 = cA + PG8_AK(t + 1);
;             const char* a2 = last ? nA : cA + PG8_AK(t + 2); const char* b2 = last ? nB : cB + (size_t)(t + 2) * kstep;
;             const char* a3 = last ? nA + PG8_AK(1) : cA + PG8_AK(t + 3); const char* b3 = b2 + kstep;
;             if (last && has_next) S.a_ready(nxt);
;             if constexpr (SP2) {
;             PG8_LDB(B0, 0, 0); PG8_LDB(B1, 0, 1); PG8_SCHED; PG8_LDA(At, 0, 0); PG8_STAGE(PG8_SA(1, 1), a1 + hstepA, voffA);
;             PG8_WAIT_V(8); PG8_WAIT_L(0); PG8_BAR; PG8_MMA(0, 0, At, B0); PG8_MMA(0, 1, At, B1); PG8_BAR; PG8_SCHED;
;             PG8_LDA(At, 0, 1); PG8_STAGE(PG8_SB(0, 0), b2, voffB); PG8_STAGE(PG8_SB(0, 1), b2 + hstepB, voffB); PG8_STAGE(PG8_SA(0, 0), a2, voffA);
;             PG8_WAIT_V(8); PG8_WAIT_L(0); PG8_BAR; PG8_MMA(1, 0, At, B0); PG8_MMA(1, 1, At, B1); PG8_BAR; PG8_SCHED;
.LBB0_1379:
	ds_read_b128 v[124:127], v210
	ds_read_b128 v[128:131], v210 offset:1024
	ds_read_b128 v[132:135], v210 offset:2048
	ds_read_b128 v[144:147], v210 offset:3072
	ds_read_b128 v[148:151], v211
	ds_read_b128 v[170:173], v211 offset:1024
	ds_read_b128 v[174:177], v211 offset:2048
	ds_read_b128 v[178:181], v211 offset:3072
	s_add_u32 s42, s38, s40
	s_addc_u32 s43, s39, s41
	s_add_u32 s46, s42, 0x100
	s_addc_u32 s47, s43, 0
	s_add_u32 s44, s78, s40
	s_addc_u32 s45, s79, s41
	s_add_u32 s42, s42, 0x180
	s_addc_u32 s43, s43, 0
	s_cmpk_eq_i32 s40, 0x1500
	s_cselect_b32 s43, s10, s43
	s_cselect_b32 s42, s3, s42
	s_cselect_b32 s45, s37, s45
	s_cselect_b32 s44, s36, s44
	s_cselect_b32 s47, s9, s47
	s_cselect_b32 s46, s8, s46
	v_lshl_add_u64 v[206:207], v[122:123], 0, s[40:41]
	s_add_i32 m0, s53, 0xc000
	ds_read_b128 v[212:215], v191
	ds_read_b128 v[216:219], v191 offset:1024
	ds_read_b128 v[220:223], v191 offset:2048
	ds_read_b128 v[224:227], v191 offset:3072
	ds_read_b128 v[228:231], v191 offset:4096
	ds_read_b128 v[232:235], v191 offset:5120
	ds_read_b128 v[236:239], v191 offset:6144
	ds_read_b128 v[240:243], v191 offset:7168
	global_load_lds_dwordx4 v[206:207], off
	v_lshl_add_u64 v[206:207], v[120:121], 0, s[40:41]
	s_add_i32 m0, s53, 0xe000
	s_nop 0
	global_load_lds_dwordx4 v[206:207], off
	s_waitcnt vmcnt(8)
	s_waitcnt lgkmcnt(0)
	s_barrier
	s_setprio 1
	v_mfma_f32_16x16x32_bf16 v[140:143], v[124:127], v[212:215], v[140:143]
	v_mfma_f32_16x16x32_bf16 v[136:139], v[132:135], v[212:215], v[136:139]
	v_mfma_f32_16x16x32_bf16 v[116:119], v[124:127], v[220:223], v[116:119]
	v_mfma_f32_16x16x32_bf16 v[112:115], v[132:135], v[220:223], v[112:115]
	v_mfma_f32_16x16x32_bf16 v[108:111], v[124:127], v[228:231], v[108:111]
	v_mfma_f32_16x16x32_bf16 v[104:107], v[132:135], v[228:231], v[104:107]
	v_mfma_f32_16x16x32_bf16 v[100:103], v[124:127], v[236:239], v[100:103]
	v_mfma_f32_16x16x32_bf16 v[96:99], v[132:135], v[236:239], v[96:99]
	v_mfma_f32_16x16x32_bf16 v[140:143], v[128:131], v[216:219], v[140:143]
	v_mfma_f32_16x16x32_bf16 v[136:139], v[144:147], v[216:219], v[136:139]
	v_mfma_f32_16x16x32_bf16 v[116:119], v[128:131], v[224:227], v[116:119]
	v_mfma_f32_16x16x32_bf16 v[112:115], v[144:147], v[224:227], v[112:115]
	v_mfma_f32_16x16x32_bf16 v[108:111], v[128:131], v[232:235], v[108:111]
	v_mfma_f32_16x16x32_bf16 v[104:107], v[144:147], v[232:235], v[104:107]
	v_mfma_f32_16x16x32_bf16 v[100:103], v[128:131], v[240:243], v[100:103]
	v_mfma_f32_16x16x32_bf16 v[96:99], v[144:147], v[240:243], v[96:99]
	v_mfma_f32_16x16x32_bf16 v[60:63], v[148:151], v[212:215], v[60:63]
	v_mfma_f32_16x16x32_bf16 v[56:59], v[174:177], v[212:215], v[56:59]
	v_mfma_f32_16x16x32_bf16 v[52:55], v[148:151], v[220:223], v[52:55]
	v_mfma_f32_16x16x32_bf16 v[48:51], v[174:177], v[220:223], v[48:51]
	v_mfma_f32_16x16x32_bf16 v[44:47], v[148:151], v[228:231], v[44:47]
	v_mfma_f32_16x16x32_bf16 v[40:43], v[174:177], v[228:231], v[40:43]
	v_mfma_f32_16x16x32_bf16 v[36:39], v[148:151], v[236:239], v[36:39]
	v_mfma_f32_16x16x32_bf16 v[32:35], v[174:177], v[236:239], v[32:35]
	v_mfma_f32_16x16x32_bf16 v[60:63], v[170:173], v[216:219], v[60:63]
	v_mfma_f32_16x16x32_bf16 v[56:59], v[178:181], v[216:219], v[56:59]
	v_mfma_f32_16x16x32_bf16 v[52:55], v[170:173], v[224:227], v[52:55]
	v_mfma_f32_16x16x32_bf16 v[48:51], v[178:181], v[224:227], v[48:51]
	v_mfma_f32_16x16x32_bf16 v[44:47], v[170:173], v[232:235], v[44:47]
	v_mfma_f32_16x16x32_bf16 v[40:43], v[178:181], v[232:235], v[40:43]
	v_mfma_f32_16x16x32_bf16 v[36:39], v[170:173], v[240:243], v[36:39]
	v_mfma_f32_16x16x32_bf16 v[32:35], v[178:181], v[240:243], v[32:35]
	s_setprio 0
	s_barrier
	s_add_i32 s70, s67, s52
	v_lshl_add_u64 v[206:207], s[44:45], 0, v[154:155]
	s_mov_b32 m0, s70
	ds_read_b128 v[212:215], v191 offset:16384
	ds_read_b128 v[216:219], v191 offset:17408
	ds_read_b128 v[220:223], v191 offset:18432
	ds_read_b128 v[224:227], v191 offset:19456
	ds_read_b128 v[228:231], v191 offset:20480
	ds_read_b128 v[232:235], v191 offset:21504
	ds_read_b128 v[236:239], v191 offset:22528
	ds_read_b128 v[240:243], v191 offset:23552
	global_load_lds_dwordx4 v[206:207], off
	s_add_i32 m0, s70, 0x2000
	s_add_u32 s70, s44, 0xb0000
	v_lshl_add_u64 v[244:245], s[44:45], 0, v[158:159]
	s_addc_u32 s71, s45, 0
	s_add_i32 s85, s68, s52
	global_load_lds_dwordx4 v[244:245], off
	v_lshl_add_u64 v[246:247], s[70:71], 0, v[154:155]
	s_mov_b32 m0, s85
	s_nop 0
	global_load_lds_dwordx4 v[246:247], off
	v_lshl_add_u64 v[246:247], s[70:71], 0, v[158:159]
	s_add_i32 m0, s85, 0x2000
	s_nop 0
	global_load_lds_dwordx4 v[246:247], off
	s_waitcnt vmcnt(6)
	s_waitcnt lgkmcnt(0)
	s_barrier
; #define PG8_STAGE(bufoff, gbase, voff) do { _Pragma("unroll") for (int _i = 0; _i < 2; ++_i) \
;         __builtin_amdgcn_global_load_lds((const unsigned*)((const char*)(gbase) + (voff)[_i]), (PG8_LAS unsigned*)(lds + (bufoff) + ldsw + _i * 8192), 16, 0, 0); } while (0)
; #define PG8_LDA(dst, b, h) do { _Pragma("unroll") for (int m = 0; m < 4; ++m) _Pragma("unroll") for (int k = 0; k < 2; ++k) dst[m][k] = *(const PG8_LAS bf16x8*)(lds + PG8_SA(b, h) + aoff + m * 2048 + k * 1024); } while (0)
; #define PG8_LDB(dst, b, h) do { _Pragma("unroll") for (int n = 0; n < 2; ++n) _Pragma("unroll") for (int k = 0; k < 2; ++k) dst[n][k] = *(const PG8_LAS bf16x8*)(lds + PG8_SB(b, h) + boff + n * 2048 + k * 1024); } while (0)
; #define PG8_MMA(ai, bj, At, Bt) do { __builtin_amdgcn_s_setprio(1); _Pragma("unroll") for (int m = 0; m < 4; ++m) _Pragma("unroll") for (int n = 0; n < 2; ++n) _Pragma("unroll") for (int k = 0; k < 2; ++k) \
;         acc[ai][bj][m][n] = __builtin_amdgcn_mfma_f32_16x16x32_bf16(Bt[n][k], At[m][k], acc[ai][bj][m][n], 0, 0, 0); __builtin_amdgcn_s_setprio(0); } while (0)
; #define PG8_WAIT_V(n) asm volatile("s_waitcnt vmcnt(" #n ")" ::: "memory")
; #define PG8_WAIT_L(n) asm volatile("s_waitcnt lgkmcnt(" #n ")" ::: "memory")
; #define PG8_BAR __builtin_amdgcn_s_barrier()
; #define PG8_SCHED __builtin_amdgcn_sched_barrier(0)
; template <class Epi, class Sched, bool ALIGN_EPI = false, bool SP2 = false>
; __device__ __forceinline__ void gemm_phase(PG8_LAS unsigned char* lds, const Gemm g, const Sched& S, const Epi& E) {
;     ...
;             PG8_WAIT_V(8); PG8_WAIT_L(0); PG8_BAR; PG8_MMA(0, 0, At, B0); PG8_MMA(0, 1, At, B1); PG8_BAR; PG8_SCHED;
;             PG8_LDA(At, 0, 1); PG8_STAGE(PG8_SB(0, 0), b2, voffB); PG8_STAGE(PG8_SB(0, 1), b2 + hstepB, voffB); PG8_STAGE(PG8_SA(0, 0), a2, voffA);
;             PG8_WAIT_V(8); PG8_WAIT_L(0); PG8_BAR; PG8_MMA(1, 0, At, B0); PG8_MMA(1, 1, At, B1); PG8_BAR; PG8_SCHED;
;             PG8_LDB(B0, 1, 0); PG8_LDB(B1, 1, 1); PG8_SCHED; PG8_LDA(At, 1, 0); PG8_STAGE(PG8_SA(0, 1), a2 + hstepA, voffA);
;             PG8_WAIT_V(8); PG8_WAIT_L(0); PG8_BAR; PG8_MMA(0, 0, At, B0); PG8_MMA(0, 1, At, B1); PG8_BAR; PG8_SCHED;
	s_setprio 1
	v_mfma_f32_16x16x32_bf16 v[92:95], v[124:127], v[212:215], v[92:95]
	v_mfma_f32_16x16x32_bf16 v[88:91], v[132:135], v[212:215], v[88:91]
	v_mfma_f32_16x16x32_bf16 v[84:87], v[124:127], v[220:223], v[84:87]
	v_mfma_f32_16x16x32_bf16 v[80:83], v[132:135], v[220:223], v[80:83]
	v_mfma_f32_16x16x32_bf16 v[76:79], v[124:127], v[228:231], v[76:79]
	v_mfma_f32_16x16x32_bf16 v[72:75], v[132:135], v[228:231], v[72:75]
	v_mfma_f32_16x16x32_bf16 v[68:71], v[124:127], v[236:239], v[68:71]
	v_mfma_f32_16x16x32_bf16 v[64:67], v[132:135], v[236:239], v[64:67]
	v_mfma_f32_16x16x32_bf16 v[92:95], v[128:131], v[216:219], v[92:95]
	v_mfma_f32_16x16x32_bf16 v[88:91], v[144:147], v[216:219], v[88:91]
	v_mfma_f32_16x16x32_bf16 v[84:87], v[128:131], v[224:227], v[84:87]
	v_mfma_f32_16x16x32_bf16 v[80:83], v[144:147], v[224:227], v[80:83]
	v_mfma_f32_16x16x32_bf16 v[76:79], v[128:131], v[232:235], v[76:79]
	v_mfma_f32_16x16x32_bf16 v[72:75], v[144:147], v[232:235], v[72:75]
	v_mfma_f32_16x16x32_bf16 v[68:71], v[128:131], v[240:243], v[68:71]
	v_mfma_f32_16x16x32_bf16 v[64:67], v[144:147], v[240:243], v[64:67]
	v_mfma_f32_16x16x32_bf16 v[28:31], v[148:151], v[212:215], v[28:31]
	v_mfma_f32_16x16x32_bf16 v[24:27], v[174:177], v[212:215], v[24:27]
	v_mfma_f32_16x16x32_bf16 v[20:23], v[148:151], v[220:223], v[20:23]
	v_mfma_f32_16x16x32_bf16 v[16:19], v[174:177], v[220:223], v[16:19]
	v_mfma_f32_16x16x32_bf16 v[12:15], v[148:151], v[228:231], v[12:15]
	v_mfma_f32_16x16x32_bf16 v[8:11], v[174:177], v[228:231], v[8:11]
	v_mfma_f32_16x16x32_bf16 v[4:7], v[148:151], v[236:239], v[4:7]
	v_mfma_f32_16x16x32_bf16 v[0:3], v[174:177], v[236:239], v[0:3]
	v_mfma_f32_16x16x32_bf16 v[28:31], v[170:173], v[216:219], v[28:31]
	v_mfma_f32_16x16x32_bf16 v[24:27], v[178:181], v[216:219], v[24:27]
	v_mfma_f32_16x16x32_bf16 v[20:23], v[170:173], v[224:227], v[20:23]
	v_mfma_f32_16x16x32_bf16 v[16:19], v[178:181], v[224:227], v[16:19]
	v_mfma_f32_16x16x32_bf16 v[12:15], v[170:173], v[232:235], v[12:15]
	v_mfma_f32_16x16x32_bf16 v[8:11], v[178:181], v[232:235], v[8:11]
	v_mfma_f32_16x16x32_bf16 v[4:7], v[170:173], v[240:243], v[4:7]
	v_mfma_f32_16x16x32_bf16 v[0:3], v[178:181], v[240:243], v[0:3]
	s_setprio 0
	s_barrier
	s_add_i32 s70, 0, 0x18000
	s_add_i32 s71, 0, 0x1c000
	v_add_u32_e32 v144, s70, v185
	v_add_u32_e32 v161, s71, v185
	ds_read_b128 v[124:127], v144
	ds_read_b128 v[128:131], v144 offset:1024
	ds_read_b128 v[132:135], v144 offset:2048
	ds_read_b128 v[144:147], v144 offset:3072
	ds_read_b128 v[148:151], v161
	ds_read_b128 v[170:173], v161 offset:1024
	ds_read_b128 v[174:177], v161 offset:2048
	ds_read_b128 v[178:181], v161 offset:3072
	v_lshl_add_u64 v[246:247], s[46:47], 0, v[152:153]
	s_mov_b32 m0, s53
	s_nop 0
	global_load_lds_dwordx4 v[246:247], off
	v_lshl_add_u64 v[246:247], s[46:47], 0, v[156:157]
	s_mov_b32 m0, s54
	s_nop 0
	global_load_lds_dwordx4 v[246:247], off
	s_add_u32 s46, s46, 0xb0000
	s_addc_u32 s47, s47, 0
	s_mov_b32 m0, s55
	v_lshl_add_u64 v[246:247], s[46:47], 0, v[152:153]
	ds_read_b128 v[212:215], v191 offset:32768
	ds_read_b128 v[216:219], v191 offset:33792
	ds_read_b128 v[220:223], v191 offset:34816
	ds_read_b128 v[224:227], v191 offset:35840
	ds_read_b128 v[228:231], v191 offset:36864
	ds_read_b128 v[232:235], v191 offset:37888
	ds_read_b128 v[236:239], v191 offset:38912
	ds_read_b128 v[240:243], v191 offset:39936
	global_load_lds_dwordx4 v[246:247], off
	v_lshl_add_u64 v[246:247], s[46:47], 0, v[156:157]
	s_mov_b32 m0, s56
	s_nop 0
	global_load_lds_dwordx4 v[246:247], off
	s_waitcnt vmcnt(8)
	s_waitcnt lgkmcnt(0)
	s_barrier
	s_setprio 1
	v_mfma_f32_16x16x32_bf16 v[140:143], v[124:127], v[212:215], v[140:143]
	v_mfma_f32_16x16x32_bf16 v[136:139], v[132:135], v[212:215], v[136:139]
	v_mfma_f32_16x16x32_bf16 v[116:119], v[124:127], v[220:223], v[116:119]
	v_mfma_f32_16x16x32_bf16 v[112:115], v[132:135], v[220:223], v[112:115]
	v_mfma_f32_16x16x32_bf16 v[108:111], v[124:127], v[228:231], v[108:111]
	v_mfma_f32_16x16x32_bf16 v[104:107], v[132:135], v[228:231], v[104:107]
	v_mfma_f32_16x16x32_bf16 v[100:103], v[124:127], v[236:239], v[100:103]
	v_mfma_f32_16x16x32_bf16 v[96:99], v[132:135], v[236:239], v[96:99]
	v_mfma_f32_16x16x32_bf16 v[140:143], v[128:131], v[216:219], v[140:143]
	v_mfma_f32_16x16x32_bf16 v[136:139], v[144:147], v[216:219], v[136:139]
	v_mfma_f32_16x16x32_bf16 v[116:119], v[128:131], v[224:227], v[116:119]
	v_mfma_f32_16x16x32_bf16 v[112:115], v[144:147], v[224:227], v[112:115]
	v_mfma_f32_16x16x32_bf16 v[108:111], v[128:131], v[232:235], v[108:111]
	v_mfma_f32_16x16x32_bf16 v[104:107], v[144:147], v[232:235], v[104:107]
	v_mfma_f32_16x16x32_bf16 v[100:103], v[128:131], v[240:243], v[100:103]
	v_mfma_f32_16x16x32_bf16 v[96:99], v[144:147], v[240:243], v[96:99]
	v_mfma_f32_16x16x32_bf16 v[60:63], v[148:151], v[212:215], v[60:63]
	v_mfma_f32_16x16x32_bf16 v[56:59], v[174:177], v[212:215], v[56:59]
	v_mfma_f32_16x16x32_bf16 v[52:55], v[148:151], v[220:223], v[52:55]
	v_mfma_f32_16x16x32_bf16 v[48:51], v[174:177], v[220:223], v[48:51]
	v_mfma_f32_16x16x32_bf16 v[44:47], v[148:151], v[228:231], v[44:47]
	v_mfma_f32_16x16x32_bf16 v[40:43], v[174:177], v[228:231], v[40:43]
	v_mfma_f32_16x16x32_bf16 v[36:39], v[148:151], v[236:239], v[36:39]
	v_mfma_f32_16x16x32_bf16 v[32:35], v[174:177], v[236:239], v[32:35]
	v_mfma_f32_16x16x32_bf16 v[60:63], v[170:173], v[216:219], v[60:63]
	v_mfma_f32_16x16x32_bf16 v[56:59], v[178:181], v[216:219], v[56:59]
	v_mfma_f32_16x16x32_bf16 v[52:55], v[170:173], v[224:227], v[52:55]
	v_mfma_f32_16x16x32_bf16 v[48:51], v[178:181], v[224:227], v[48:51]
	v_mfma_f32_16x16x32_bf16 v[44:47], v[170:173], v[232:235], v[44:47]
	v_mfma_f32_16x16x32_bf16 v[40:43], v[178:181], v[232:235], v[40:43]
	v_mfma_f32_16x16x32_bf16 v[36:39], v[170:173], v[240:243], v[36:39]
	v_mfma_f32_16x16x32_bf16 v[32:35], v[178:181], v[240:243], v[32:35]
	s_setprio 0
	s_barrier
; #define PG8_STAGE(bufoff, gbase, voff) do { _Pragma("unroll") for (int _i = 0; _i < 2; ++_i) \
;         __builtin_amdgcn_global_load_lds((const unsigned*)((const char*)(gbase) + (voff)[_i]), (PG8_LAS unsigned*)(lds + (bufoff) + ldsw + _i * 8192), 16, 0, 0); } while (0)
; #define PG8_LDA(dst, b, h) do { _Pragma("unroll") for (int m = 0; m < 4; ++m) _Pragma("unroll") for (int k = 0; k < 2; ++k) dst[m][k] = *(const PG8_LAS bf16x8*)(lds + PG8_SA(b, h) + aoff + m * 2048 + k * 1024); } while (0)
; #define PG8_MMA(ai, bj, At, Bt) do { __builtin_amdgcn_s_setprio(1); _Pragma("unroll") for (int m = 0; m < 4; ++m) _Pragma("unroll") for (int n = 0; n < 2; ++n) _Pragma("unroll") for (int k = 0; k < 2; ++k) \
;         acc[ai][bj][m][n] = __builtin_amdgcn_mfma_f32_16x16x32_bf16(Bt[n][k], At[m][k], acc[ai][bj][m][n], 0, 0, 0); __builtin_amdgcn_s_setprio(0); } while (0)
; #define PG8_WAIT_V(n) asm volatile("s_waitcnt vmcnt(" #n ")" ::: "memory")
; #define PG8_WAIT_L(n) asm volatile("s_waitcnt lgkmcnt(" #n ")" ::: "memory")
; #define PG8_BAR __builtin_amdgcn_s_barrier()
; #define PG8_SCHED __builtin_amdgcn_sched_barrier(0)
; template <class Epi, class Sched, bool ALIGN_EPI = false, bool SP2 = false>
; __device__ __forceinline__ void gemm_phase(PG8_LAS unsigned char* lds, const Gemm g, const Sched& S, const Epi& E) {
;     ...
;         for (int t = 0; t < nt; t += 2) {
;     ...
;             PG8_LDA(At, 1, 1); PG8_STAGE(PG8_SB(1, 0), b3, voffB); PG8_STAGE(PG8_SB(1, 1), b3 + hstepB, voffB); PG8_STAGE(PG8_SA(1, 0), a3, voffA);
;             PG8_WAIT_V(8); PG8_WAIT_L(0); PG8_BAR; PG8_MMA(1, 0, At, B0); PG8_MMA(1, 1, At, B1); PG8_BAR; PG8_SCHED;
	s_add_i32 s46, s70, s52
	v_lshl_add_u64 v[206:207], v[206:207], 0, s[26:27]
	s_mov_b32 m0, s46
	ds_read_b128 v[212:215], v191 offset:49152
	ds_read_b128 v[216:219], v191 offset:50176
	ds_read_b128 v[220:223], v191 offset:51200
	ds_read_b128 v[224:227], v191 offset:52224
	ds_read_b128 v[228:231], v191 offset:53248
	ds_read_b128 v[232:235], v191 offset:54272
	ds_read_b128 v[236:239], v191 offset:55296
	ds_read_b128 v[240:243], v191 offset:56320
	global_load_lds_dwordx4 v[206:207], off
	s_add_i32 m0, s46, 0x2000
	s_add_u32 s44, s44, 0xb0080
	v_lshl_add_u64 v[206:207], v[244:245], 0, s[26:27]
	s_addc_u32 s45, s45, 0
	s_add_i32 s46, s71, s52
	global_load_lds_dwordx4 v[206:207], off
	v_lshl_add_u64 v[206:207], s[44:45], 0, v[154:155]
	s_mov_b32 m0, s46
	s_nop 0
	global_load_lds_dwordx4 v[206:207], off
	v_lshl_add_u64 v[206:207], s[44:45], 0, v[158:159]
	s_add_i32 m0, s46, 0x2000
	s_nop 0
	global_load_lds_dwordx4 v[206:207], off
	v_lshl_add_u64 v[206:207], s[42:43], 0, v[152:153]
	s_mov_b32 m0, s63
	s_nop 0
	global_load_lds_dwordx4 v[206:207], off
	v_lshl_add_u64 v[206:207], s[42:43], 0, v[156:157]
	s_mov_b32 m0, s64
	s_nop 0
	global_load_lds_dwordx4 v[206:207], off
	s_waitcnt vmcnt(8)
	s_waitcnt lgkmcnt(0)
	s_barrier
	s_setprio 1
	v_mfma_f32_16x16x32_bf16 v[92:95], v[124:127], v[212:215], v[92:95]
	v_mfma_f32_16x16x32_bf16 v[88:91], v[132:135], v[212:215], v[88:91]
	v_mfma_f32_16x16x32_bf16 v[84:87], v[124:127], v[220:223], v[84:87]
	v_mfma_f32_16x16x32_bf16 v[80:83], v[132:135], v[220:223], v[80:83]
	v_mfma_f32_16x16x32_bf16 v[76:79], v[124:127], v[228:231], v[76:79]
	v_mfma_f32_16x16x32_bf16 v[72:75], v[132:135], v[228:231], v[72:75]
	v_mfma_f32_16x16x32_bf16 v[68:71], v[124:127], v[236:239], v[68:71]
	v_mfma_f32_16x16x32_bf16 v[64:67], v[132:135], v[236:239], v[64:67]
	v_mfma_f32_16x16x32_bf16 v[92:95], v[128:131], v[216:219], v[92:95]
	v_mfma_f32_16x16x32_bf16 v[88:91], v[144:147], v[216:219], v[88:91]
	v_mfma_f32_16x16x32_bf16 v[84:87], v[128:131], v[224:227], v[84:87]
	v_mfma_f32_16x16x32_bf16 v[80:83], v[144:147], v[224:227], v[80:83]
	v_mfma_f32_16x16x32_bf16 v[76:79], v[128:131], v[232:235], v[76:79]
	v_mfma_f32_16x16x32_bf16 v[72:75], v[144:147], v[232:235], v[72:75]
	v_mfma_f32_16x16x32_bf16 v[68:71], v[128:131], v[240:243], v[68:71]
	v_mfma_f32_16x16x32_bf16 v[64:67], v[144:147], v[240:243], v[64:67]
	v_mfma_f32_16x16x32_bf16 v[28:31], v[148:151], v[212:215], v[28:31]
	v_mfma_f32_16x16x32_bf16 v[24:27], v[174:177], v[212:215], v[24:27]
	v_mfma_f32_16x16x32_bf16 v[20:23], v[148:151], v[220:223], v[20:23]
	v_mfma_f32_16x16x32_bf16 v[16:19], v[174:177], v[220:223], v[16:19]
	v_mfma_f32_16x16x32_bf16 v[12:15], v[148:151], v[228:231], v[12:15]
	v_mfma_f32_16x16x32_bf16 v[8:11], v[174:177], v[228:231], v[8:11]
	v_mfma_f32_16x16x32_bf16 v[4:7], v[148:151], v[236:239], v[4:7]
	v_mfma_f32_16x16x32_bf16 v[0:3], v[174:177], v[236:239], v[0:3]
	v_mfma_f32_16x16x32_bf16 v[28:31], v[170:173], v[216:219], v[28:31]
	v_mfma_f32_16x16x32_bf16 v[24:27], v[178:181], v[216:219], v[24:27]
	v_mfma_f32_16x16x32_bf16 v[20:23], v[170:173], v[224:227], v[20:23]
	v_mfma_f32_16x16x32_bf16 v[16:19], v[178:181], v[224:227], v[16:19]
	v_mfma_f32_16x16x32_bf16 v[12:15], v[170:173], v[232:235], v[12:15]
	v_mfma_f32_16x16x32_bf16 v[8:11], v[178:181], v[232:235], v[8:11]
	v_mfma_f32_16x16x32_bf16 v[4:7], v[170:173], v[240:243], v[4:7]
	v_mfma_f32_16x16x32_bf16 v[0:3], v[178:181], v[240:243], v[0:3]
	s_setprio 0
	s_barrier
	s_add_i32 s84, s84, 2
	s_add_u32 s40, s40, 0x100
	s_addc_u32 s41, s41, 0
	s_cmp_gt_u32 s84, 41
	s_cbranch_scc0 .LBB0_1379
	s_and_b64 vcc, exec, s[28:29]
	s_cbranch_vccz .LBB0_1382
	s_barrier

; #define PG8_STAGE(bufoff, gbase, voff) do { _Pragma("unroll") for (int _i = 0; _i < 2; ++_i) \
;         __builtin_amdgcn_global_load_lds((const unsigned*)((const char*)(gbase) + (voff)[_i]), (PG8_LAS unsigned*)(lds + (bufoff) + ldsw + _i * 8192), 16, 0, 0); } while (0)
; #define PG8_LDA(dst, b, h) do { _Pragma("unroll") for (int m = 0; m < 4; ++m) _Pragma("unroll") for (int k = 0; k < 2; ++k) dst[m][k] = *(const PG8_LAS bf16x8*)(lds + PG8_SA(b, h) + aoff + m * 2048 + k * 1024); } while (0)
; #define PG8_LDB(dst, b, h) do { _Pragma("unroll") for (int n = 0; n < 2; ++n) _Pragma("unroll") for (int k = 0; k < 2; ++k) dst[n][k] = *(const PG8_LAS bf16x8*)(lds + PG8_SB(b, h) + boff + n * 2048 + k * 1024); } while (0)
; #define PG8_MMA(ai, bj, At, Bt) do { __builtin_amdgcn_s_setprio(1); _Pragma("unroll") for (int m = 0; m < 4; ++m) _Pragma("unroll") for (int n = 0; n < 2; ++n) _Pragma("unroll") for (int k = 0; k < 2; ++k) \
;         acc[ai][bj][m][n] = __builtin_amdgcn_mfma_f32_16x16x32_bf16(Bt[n][k], At[m][k], acc[ai][bj][m][n], 0, 0, 0); __builtin_amdgcn_s_setprio(0); } while (0)
; #define PG8_WAIT_V(n) asm volatile("s_waitcnt vmcnt(" #n ")" ::: "memory")
; #define PG8_BAR __builtin_amdgcn_s_barrier()
; template <class Epi, class Sched, bool ALIGN_EPI = false, bool SP2 = false>
; __device__ __forceinline__ void gemm_phase(PG8_LAS unsigned char* lds, const Gemm g, const Sched& S, const Epi& E) {
;     ...
;         for (int t = 0; t < nt; t += 2) {
;             const bool last = (t == nt - 2);
;             const char* a1 = cA + PG8_AK(t + 1);
;             const char* a2 = last ? nA : cA + PG8_AK(t + 2); const char* b2 = last ? nB : cB + (size_t)(t + 2) * kstep;
;             const char* a3 = last ? nA + PG8_AK(1) : cA + PG8_AK(t + 3); const char* b3 = b2 + kstep;
;             if (last && has_next) S.a_ready(nxt);
;             if constexpr (SP2) {
;             PG8_LDB(B0, 0, 0); PG8_LDB(B1, 0, 1); PG8_SCHED; PG8_LDA(At, 0, 0); PG8_STAGE(PG8_SA(1, 1), a1 + hstepA, voffA);
;             PG8_WAIT_V(8); PG8_WAIT_L(0); PG8_BAR; PG8_MMA(0, 0, At, B0); PG8_MMA(0, 1, At, B1); PG8_BAR; PG8_SCHED;
;             PG8_LDA(At, 0, 1); PG8_STAGE(PG8_SB(0, 0), b2, voffB); PG8_STAGE(PG8_SB(0, 1), b2 + hstepB, voffB); PG8_STAGE(PG8_SA(0, 0), a2, voffA);
;             PG8_WAIT_V(8); PG8_WAIT_L(0); PG8_BAR; PG8_MMA(1, 0, At, B0); PG8_MMA(1, 1, At, B1); PG8_BAR; PG8_SCHED;
.LBB0_1471:
	ds_read_b128 v[100:103], v222
	ds_read_b128 v[104:107], v222 offset:1024
	ds_read_b128 v[108:111], v222 offset:2048
	ds_read_b128 v[120:123], v222 offset:3072
	ds_read_b128 v[124:127], v223
	ds_read_b128 v[128:131], v223 offset:1024
	ds_read_b128 v[132:135], v223 offset:2048
	ds_read_b128 v[160:163], v223 offset:3072
	s_add_u32 s44, s40, s42
	s_addc_u32 s45, s41, s43
	s_add_u32 s48, s44, 0x100
	s_addc_u32 s49, s45, 0
	s_add_u32 s46, s83, s42
	s_addc_u32 s47, s84, s43
	s_add_u32 s44, s44, 0x180
	s_addc_u32 s45, s45, 0
	s_cmpk_eq_i32 s42, 0x700
	s_cselect_b32 s45, s82, s45
	s_cselect_b32 s44, s79, s44
	s_cselect_b32 s47, s29, s47
	s_cselect_b32 s46, s78, s46
	s_cselect_b32 s49, s3, s49
	s_cselect_b32 s48, s31, s48
	v_lshl_add_u64 v[200:201], v[98:99], 0, s[42:43]
	s_add_i32 m0, s57, 0xc000
	ds_read_b128 v[164:167], v203
	ds_read_b128 v[168:171], v203 offset:1024
	ds_read_b128 v[192:195], v203 offset:2048
	ds_read_b128 v[196:199], v203 offset:3072
	ds_read_b128 v[224:227], v203 offset:4096
	ds_read_b128 v[228:231], v203 offset:5120
	ds_read_b128 v[232:235], v203 offset:6144
	ds_read_b128 v[236:239], v203 offset:7168
	global_load_lds_dwordx4 v[200:201], off
	v_lshl_add_u64 v[200:201], v[96:97], 0, s[42:43]
	s_add_i32 m0, s57, 0xe000
	s_nop 0
	global_load_lds_dwordx4 v[200:201], off
	s_waitcnt vmcnt(8)
	s_waitcnt lgkmcnt(0)
	s_barrier
	s_setprio 1
	v_mfma_f32_16x16x32_bf16 v[156:159], v[100:103], v[164:167], v[156:159]
	v_mfma_f32_16x16x32_bf16 v[152:155], v[108:111], v[164:167], v[152:155]
	v_mfma_f32_16x16x32_bf16 v[148:151], v[100:103], v[192:195], v[148:151]
	v_mfma_f32_16x16x32_bf16 v[144:147], v[108:111], v[192:195], v[144:147]
	v_mfma_f32_16x16x32_bf16 v[140:143], v[100:103], v[224:227], v[140:143]
	v_mfma_f32_16x16x32_bf16 v[136:139], v[108:111], v[224:227], v[136:139]
	v_mfma_f32_16x16x32_bf16 v[116:119], v[100:103], v[232:235], v[116:119]
	v_mfma_f32_16x16x32_bf16 v[112:115], v[108:111], v[232:235], v[112:115]
	v_mfma_f32_16x16x32_bf16 v[156:159], v[104:107], v[168:171], v[156:159]
	v_mfma_f32_16x16x32_bf16 v[152:155], v[120:123], v[168:171], v[152:155]
	v_mfma_f32_16x16x32_bf16 v[148:151], v[104:107], v[196:199], v[148:151]
	v_mfma_f32_16x16x32_bf16 v[144:147], v[120:123], v[196:199], v[144:147]
	v_mfma_f32_16x16x32_bf16 v[140:143], v[104:107], v[228:231], v[140:143]
	v_mfma_f32_16x16x32_bf16 v[136:139], v[120:123], v[228:231], v[136:139]
	v_mfma_f32_16x16x32_bf16 v[116:119], v[104:107], v[236:239], v[116:119]
	v_mfma_f32_16x16x32_bf16 v[112:115], v[120:123], v[236:239], v[112:115]
	v_mfma_f32_16x16x32_bf16 v[60:63], v[124:127], v[164:167], v[60:63]
	v_mfma_f32_16x16x32_bf16 v[56:59], v[132:135], v[164:167], v[56:59]
	v_mfma_f32_16x16x32_bf16 v[52:55], v[124:127], v[192:195], v[52:55]
	v_mfma_f32_16x16x32_bf16 v[48:51], v[132:135], v[192:195], v[48:51]
	v_mfma_f32_16x16x32_bf16 v[44:47], v[124:127], v[224:227], v[44:47]
	v_mfma_f32_16x16x32_bf16 v[40:43], v[132:135], v[224:227], v[40:43]
	v_mfma_f32_16x16x32_bf16 v[36:39], v[124:127], v[232:235], v[36:39]
	v_mfma_f32_16x16x32_bf16 v[32:35], v[132:135], v[232:235], v[32:35]
	v_mfma_f32_16x16x32_bf16 v[60:63], v[128:131], v[168:171], v[60:63]
	v_mfma_f32_16x16x32_bf16 v[56:59], v[160:163], v[168:171], v[56:59]
	v_mfma_f32_16x16x32_bf16 v[52:55], v[128:131], v[196:199], v[52:55]
	v_mfma_f32_16x16x32_bf16 v[48:51], v[160:163], v[196:199], v[48:51]
	v_mfma_f32_16x16x32_bf16 v[44:47], v[128:131], v[228:231], v[44:47]
	v_mfma_f32_16x16x32_bf16 v[40:43], v[160:163], v[228:231], v[40:43]
	v_mfma_f32_16x16x32_bf16 v[36:39], v[128:131], v[236:239], v[36:39]
	v_mfma_f32_16x16x32_bf16 v[32:35], v[160:163], v[236:239], v[32:35]
	s_setprio 0
	s_barrier
	s_add_i32 s70, s69, s56
	v_lshl_add_u64 v[200:201], s[46:47], 0, v[174:175]
	s_mov_b32 m0, s70
	ds_read_b128 v[164:167], v203 offset:16384
	ds_read_b128 v[168:171], v203 offset:17408
	ds_read_b128 v[192:195], v203 offset:18432
	ds_read_b128 v[196:199], v203 offset:19456
	ds_read_b128 v[224:227], v203 offset:20480
	ds_read_b128 v[228:231], v203 offset:21504
	ds_read_b128 v[232:235], v203 offset:22528
	ds_read_b128 v[236:239], v203 offset:23552
	global_load_lds_dwordx4 v[200:201], off
	s_add_i32 m0, s70, 0x2000
	s_add_u32 s70, s46, 0x40000
	v_lshl_add_u64 v[206:207], s[46:47], 0, v[178:179]
	s_addc_u32 s71, s47, 0
	s_add_i32 s86, s80, s56
	global_load_lds_dwordx4 v[206:207], off
	v_lshl_add_u64 v[240:241], s[70:71], 0, v[174:175]
	s_mov_b32 m0, s86
	s_nop 0
	global_load_lds_dwordx4 v[240:241], off
	v_lshl_add_u64 v[240:241], s[70:71], 0, v[178:179]
	s_add_i32 m0, s86, 0x2000
	s_nop 0
	global_load_lds_dwordx4 v[240:241], off
	s_waitcnt vmcnt(6)
	s_waitcnt lgkmcnt(0)
	s_barrier
; #define PG8_STAGE(bufoff, gbase, voff) do { _Pragma("unroll") for (int _i = 0; _i < 2; ++_i) \
;         __builtin_amdgcn_global_load_lds((const unsigned*)((const char*)(gbase) + (voff)[_i]), (PG8_LAS unsigned*)(lds + (bufoff) + ldsw + _i * 8192), 16, 0, 0); } while (0)
; #define PG8_LDA(dst, b, h) do { _Pragma("unroll") for (int m = 0; m < 4; ++m) _Pragma("unroll") for (int k = 0; k < 2; ++k) dst[m][k] = *(const PG8_LAS bf16x8*)(lds + PG8_SA(b, h) + aoff + m * 2048 + k * 1024); } while (0)
; #define PG8_LDB(dst, b, h) do { _Pragma("unroll") for (int n = 0; n < 2; ++n) _Pragma("unroll") for (int k = 0; k < 2; ++k) dst[n][k] = *(const PG8_LAS bf16x8*)(lds + PG8_SB(b, h) + boff + n * 2048 + k * 1024); } while (0)
; #define PG8_MMA(ai, bj, At, Bt) do { __builtin_amdgcn_s_setprio(1); _Pragma("unroll") for (int m = 0; m < 4; ++m) _Pragma("unroll") for (int n = 0; n < 2; ++n) _Pragma("unroll") for (int k = 0; k < 2; ++k) \
;         acc[ai][bj][m][n] = __builtin_amdgcn_mfma_f32_16x16x32_bf16(Bt[n][k], At[m][k], acc[ai][bj][m][n], 0, 0, 0); __builtin_amdgcn_s_setprio(0); } while (0)
; #define PG8_WAIT_V(n) asm volatile("s_waitcnt vmcnt(" #n ")" ::: "memory")
; #define PG8_WAIT_L(n) asm volatile("s_waitcnt lgkmcnt(" #n ")" ::: "memory")
; #define PG8_BAR __builtin_amdgcn_s_barrier()
; #define PG8_SCHED __builtin_amdgcn_sched_barrier(0)
; template <class Epi, class Sched, bool ALIGN_EPI = false, bool SP2 = false>
; __device__ __forceinline__ void gemm_phase(PG8_LAS unsigned char* lds, const Gemm g, const Sched& S, const Epi& E) {
;     ...
;             PG8_WAIT_V(8); PG8_WAIT_L(0); PG8_BAR; PG8_MMA(1, 0, At, B0); PG8_MMA(1, 1, At, B1); PG8_BAR; PG8_SCHED;
;             PG8_LDB(B0, 1, 0); PG8_LDB(B1, 1, 1); PG8_SCHED; PG8_LDA(At, 1, 0); PG8_STAGE(PG8_SA(0, 1), a2 + hstepA, voffA);
;             PG8_WAIT_V(8); PG8_WAIT_L(0); PG8_BAR; PG8_MMA(0, 0, At, B0); PG8_MMA(0, 1, At, B1); PG8_BAR; PG8_SCHED;
	s_setprio 1
	v_mfma_f32_16x16x32_bf16 v[92:95], v[100:103], v[164:167], v[92:95]
	v_mfma_f32_16x16x32_bf16 v[88:91], v[108:111], v[164:167], v[88:91]
	v_mfma_f32_16x16x32_bf16 v[84:87], v[100:103], v[192:195], v[84:87]
	v_mfma_f32_16x16x32_bf16 v[80:83], v[108:111], v[192:195], v[80:83]
	v_mfma_f32_16x16x32_bf16 v[76:79], v[100:103], v[224:227], v[76:79]
	v_mfma_f32_16x16x32_bf16 v[72:75], v[108:111], v[224:227], v[72:75]
	v_mfma_f32_16x16x32_bf16 v[68:71], v[100:103], v[232:235], v[68:71]
	v_mfma_f32_16x16x32_bf16 v[64:67], v[108:111], v[232:235], v[64:67]
	v_mfma_f32_16x16x32_bf16 v[92:95], v[104:107], v[168:171], v[92:95]
	v_mfma_f32_16x16x32_bf16 v[88:91], v[120:123], v[168:171], v[88:91]
	v_mfma_f32_16x16x32_bf16 v[84:87], v[104:107], v[196:199], v[84:87]
	v_mfma_f32_16x16x32_bf16 v[80:83], v[120:123], v[196:199], v[80:83]
	v_mfma_f32_16x16x32_bf16 v[76:79], v[104:107], v[228:231], v[76:79]
	v_mfma_f32_16x16x32_bf16 v[72:75], v[120:123], v[228:231], v[72:75]
	v_mfma_f32_16x16x32_bf16 v[68:71], v[104:107], v[236:239], v[68:71]
	v_mfma_f32_16x16x32_bf16 v[64:67], v[120:123], v[236:239], v[64:67]
	v_mfma_f32_16x16x32_bf16 v[28:31], v[124:127], v[164:167], v[28:31]
	v_mfma_f32_16x16x32_bf16 v[24:27], v[132:135], v[164:167], v[24:27]
	v_mfma_f32_16x16x32_bf16 v[20:23], v[124:127], v[192:195], v[20:23]
	v_mfma_f32_16x16x32_bf16 v[16:19], v[132:135], v[192:195], v[16:19]
	v_mfma_f32_16x16x32_bf16 v[12:15], v[124:127], v[224:227], v[12:15]
	v_mfma_f32_16x16x32_bf16 v[8:11], v[132:135], v[224:227], v[8:11]
	v_mfma_f32_16x16x32_bf16 v[4:7], v[124:127], v[232:235], v[4:7]
	v_mfma_f32_16x16x32_bf16 v[0:3], v[132:135], v[232:235], v[0:3]
	v_mfma_f32_16x16x32_bf16 v[28:31], v[128:131], v[168:171], v[28:31]
	v_mfma_f32_16x16x32_bf16 v[24:27], v[160:163], v[168:171], v[24:27]
	v_mfma_f32_16x16x32_bf16 v[20:23], v[128:131], v[196:199], v[20:23]
	v_mfma_f32_16x16x32_bf16 v[16:19], v[160:163], v[196:199], v[16:19]
	v_mfma_f32_16x16x32_bf16 v[12:15], v[128:131], v[228:231], v[12:15]
	v_mfma_f32_16x16x32_bf16 v[8:11], v[160:163], v[228:231], v[8:11]
	v_mfma_f32_16x16x32_bf16 v[4:7], v[128:131], v[236:239], v[4:7]
	v_mfma_f32_16x16x32_bf16 v[0:3], v[160:163], v[236:239], v[0:3]
	s_setprio 0
	s_barrier
	s_add_i32 s70, 0, 0x18000
	s_add_i32 s71, 0, 0x1c000
	v_add_u32_e32 v120, s70, v189
	v_add_u32_e32 v160, s71, v189
	ds_read_b128 v[100:103], v120
	ds_read_b128 v[104:107], v120 offset:1024
	ds_read_b128 v[108:111], v120 offset:2048
	ds_read_b128 v[120:123], v120 offset:3072
	ds_read_b128 v[124:127], v160
	ds_read_b128 v[128:131], v160 offset:1024
	ds_read_b128 v[132:135], v160 offset:2048
	ds_read_b128 v[160:163], v160 offset:3072
	v_lshl_add_u64 v[240:241], s[48:49], 0, v[172:173]
	s_mov_b32 m0, s57
	s_nop 0
	global_load_lds_dwordx4 v[240:241], off
	v_lshl_add_u64 v[240:241], s[48:49], 0, v[176:177]
	s_mov_b32 m0, s58
	s_nop 0
	global_load_lds_dwordx4 v[240:241], off
	s_add_u32 s48, s48, 0x40000
	s_addc_u32 s49, s49, 0
	s_mov_b32 m0, s59
	v_lshl_add_u64 v[240:241], s[48:49], 0, v[172:173]
	ds_read_b128 v[164:167], v203 offset:32768
	ds_read_b128 v[168:171], v203 offset:33792
	ds_read_b128 v[192:195], v203 offset:34816
	ds_read_b128 v[196:199], v203 offset:35840
	ds_read_b128 v[224:227], v203 offset:36864
	ds_read_b128 v[228:231], v203 offset:37888
	ds_read_b128 v[232:235], v203 offset:38912
	ds_read_b128 v[236:239], v203 offset:39936
	global_load_lds_dwordx4 v[240:241], off
	v_lshl_add_u64 v[240:241], s[48:49], 0, v[176:177]
	s_mov_b32 m0, s60
	s_nop 0
	global_load_lds_dwordx4 v[240:241], off
	s_waitcnt vmcnt(8)
	s_waitcnt lgkmcnt(0)
	s_barrier
	s_setprio 1
	v_mfma_f32_16x16x32_bf16 v[156:159], v[100:103], v[164:167], v[156:159]
	v_mfma_f32_16x16x32_bf16 v[152:155], v[108:111], v[164:167], v[152:155]
	v_mfma_f32_16x16x32_bf16 v[148:151], v[100:103], v[192:195], v[148:151]
	v_mfma_f32_16x16x32_bf16 v[144:147], v[108:111], v[192:195], v[144:147]
	v_mfma_f32_16x16x32_bf16 v[140:143], v[100:103], v[224:227], v[140:143]
	v_mfma_f32_16x16x32_bf16 v[136:139], v[108:111], v[224:227], v[136:139]
	v_mfma_f32_16x16x32_bf16 v[116:119], v[100:103], v[232:235], v[116:119]
	v_mfma_f32_16x16x32_bf16 v[112:115], v[108:111], v[232:235], v[112:115]
	v_mfma_f32_16x16x32_bf16 v[156:159], v[104:107], v[168:171], v[156:159]
	v_mfma_f32_16x16x32_bf16 v[152:155], v[120:123], v[168:171], v[152:155]
	v_mfma_f32_16x16x32_bf16 v[148:151], v[104:107], v[196:199], v[148:151]
	v_mfma_f32_16x16x32_bf16 v[144:147], v[120:123], v[196:199], v[144:147]
	v_mfma_f32_16x16x32_bf16 v[140:143], v[104:107], v[228:231], v[140:143]
	v_mfma_f32_16x16x32_bf16 v[136:139], v[120:123], v[228:231], v[136:139]
	v_mfma_f32_16x16x32_bf16 v[116:119], v[104:107], v[236:239], v[116:119]
	v_mfma_f32_16x16x32_bf16 v[112:115], v[120:123], v[236:239], v[112:115]
	v_mfma_f32_16x16x32_bf16 v[60:63], v[124:127], v[164:167], v[60:63]
	v_mfma_f32_16x16x32_bf16 v[56:59], v[132:135], v[164:167], v[56:59]
	v_mfma_f32_16x16x32_bf16 v[52:55], v[124:127], v[192:195], v[52:55]
	v_mfma_f32_16x16x32_bf16 v[48:51], v[132:135], v[192:195], v[48:51]
	v_mfma_f32_16x16x32_bf16 v[44:47], v[124:127], v[224:227], v[44:47]
	v_mfma_f32_16x16x32_bf16 v[40:43], v[132:135], v[224:227], v[40:43]
	v_mfma_f32_16x16x32_bf16 v[36:39], v[124:127], v[232:235], v[36:39]
	v_mfma_f32_16x16x32_bf16 v[32:35], v[132:135], v[232:235], v[32:35]
	v_mfma_f32_16x16x32_bf16 v[60:63], v[128:131], v[168:171], v[60:63]
	v_mfma_f32_16x16x32_bf16 v[56:59], v[160:163], v[168:171], v[56:59]
	v_mfma_f32_16x16x32_bf16 v[52:55], v[128:131], v[196:199], v[52:55]
	v_mfma_f32_16x16x32_bf16 v[48:51], v[160:163], v[196:199], v[48:51]
	v_mfma_f32_16x16x32_bf16 v[44:47], v[128:131], v[228:231], v[44:47]
	v_mfma_f32_16x16x32_bf16 v[40:43], v[160:163], v[228:231], v[40:43]
	v_mfma_f32_16x16x32_bf16 v[36:39], v[128:131], v[236:239], v[36:39]
	v_mfma_f32_16x16x32_bf16 v[32:35], v[160:163], v[236:239], v[32:35]
	s_setprio 0
	s_barrier
; #define PG8_STAGE(bufoff, gbase, voff) do { _Pragma("unroll") for (int _i = 0; _i < 2; ++_i) \
;         __builtin_amdgcn_global_load_lds((const unsigned*)((const char*)(gbase) + (voff)[_i]), (PG8_LAS unsigned*)(lds + (bufoff) + ldsw + _i * 8192), 16, 0, 0); } while (0)
; #define PG8_LDA(dst, b, h) do { _Pragma("unroll") for (int m = 0; m < 4; ++m) _Pragma("unroll") for (int k = 0; k < 2; ++k) dst[m][k] = *(const PG8_LAS bf16x8*)(lds + PG8_SA(b, h) + aoff + m * 2048 + k * 1024); } while (0)
; #define PG8_MMA(ai, bj, At, Bt) do { __builtin_amdgcn_s_setprio(1); _Pragma("unroll") for (int m = 0; m < 4; ++m) _Pragma("unroll") for (int n = 0; n < 2; ++n) _Pragma("unroll") for (int k = 0; k < 2; ++k) \
;         acc[ai][bj][m][n] = __builtin_amdgcn_mfma_f32_16x16x32_bf16(Bt[n][k], At[m][k], acc[ai][bj][m][n], 0, 0, 0); __builtin_amdgcn_s_setprio(0); } while (0)
; #define PG8_WAIT_V(n) asm volatile("s_waitcnt vmcnt(" #n ")" ::: "memory")
; #define PG8_WAIT_L(n) asm volatile("s_waitcnt lgkmcnt(" #n ")" ::: "memory")
; #define PG8_BAR __builtin_amdgcn_s_barrier()
; #define PG8_SCHED __builtin_amdgcn_sched_barrier(0)
; template <class Epi, class Sched, bool ALIGN_EPI = false, bool SP2 = false>
; __device__ __forceinline__ void gemm_phase(PG8_LAS unsigned char* lds, const Gemm g, const Sched& S, const Epi& E) {
;     ...
;         for (int t = 0; t < nt; t += 2) {
;     ...
;             PG8_LDA(At, 1, 1); PG8_STAGE(PG8_SB(1, 0), b3, voffB); PG8_STAGE(PG8_SB(1, 1), b3 + hstepB, voffB); PG8_STAGE(PG8_SA(1, 0), a3, voffA);
;             PG8_WAIT_V(8); PG8_WAIT_L(0); PG8_BAR; PG8_MMA(1, 0, At, B0); PG8_MMA(1, 1, At, B1); PG8_BAR; PG8_SCHED;
	s_add_i32 s48, s70, s56
	v_lshl_add_u64 v[200:201], v[200:201], 0, s[10:11]
	s_mov_b32 m0, s48
	ds_read_b128 v[164:167], v203 offset:49152
	ds_read_b128 v[168:171], v203 offset:50176
	ds_read_b128 v[192:195], v203 offset:51200
	ds_read_b128 v[196:199], v203 offset:52224
	ds_read_b128 v[224:227], v203 offset:53248
	ds_read_b128 v[228:231], v203 offset:54272
	ds_read_b128 v[232:235], v203 offset:55296
	ds_read_b128 v[236:239], v203 offset:56320
	global_load_lds_dwordx4 v[200:201], off
	s_add_i32 m0, s48, 0x2000
	s_add_u32 s46, s46, 0x40080
	v_lshl_add_u64 v[200:201], v[206:207], 0, s[10:11]
	s_addc_u32 s47, s47, 0
	s_add_i32 s48, s71, s56
	global_load_lds_dwordx4 v[200:201], off
	v_lshl_add_u64 v[200:201], s[46:47], 0, v[174:175]
	s_mov_b32 m0, s48
	s_nop 0
	global_load_lds_dwordx4 v[200:201], off
	v_lshl_add_u64 v[200:201], s[46:47], 0, v[178:179]
	s_add_i32 m0, s48, 0x2000
	s_nop 0
	global_load_lds_dwordx4 v[200:201], off
	v_lshl_add_u64 v[200:201], s[44:45], 0, v[172:173]
	s_mov_b32 m0, s66
	s_nop 0
	global_load_lds_dwordx4 v[200:201], off
	v_lshl_add_u64 v[200:201], s[44:45], 0, v[176:177]
	s_mov_b32 m0, s67
	s_nop 0
	global_load_lds_dwordx4 v[200:201], off
	s_waitcnt vmcnt(8)
	s_waitcnt lgkmcnt(0)
	s_barrier
	s_setprio 1
	v_mfma_f32_16x16x32_bf16 v[92:95], v[100:103], v[164:167], v[92:95]
	v_mfma_f32_16x16x32_bf16 v[88:91], v[108:111], v[164:167], v[88:91]
	v_mfma_f32_16x16x32_bf16 v[84:87], v[100:103], v[192:195], v[84:87]
	v_mfma_f32_16x16x32_bf16 v[80:83], v[108:111], v[192:195], v[80:83]
	v_mfma_f32_16x16x32_bf16 v[76:79], v[100:103], v[224:227], v[76:79]
	v_mfma_f32_16x16x32_bf16 v[72:75], v[108:111], v[224:227], v[72:75]
	v_mfma_f32_16x16x32_bf16 v[68:71], v[100:103], v[232:235], v[68:71]
	v_mfma_f32_16x16x32_bf16 v[64:67], v[108:111], v[232:235], v[64:67]
	v_mfma_f32_16x16x32_bf16 v[92:95], v[104:107], v[168:171], v[92:95]
	v_mfma_f32_16x16x32_bf16 v[88:91], v[120:123], v[168:171], v[88:91]
	v_mfma_f32_16x16x32_bf16 v[84:87], v[104:107], v[196:199], v[84:87]
	v_mfma_f32_16x16x32_bf16 v[80:83], v[120:123], v[196:199], v[80:83]
	v_mfma_f32_16x16x32_bf16 v[76:79], v[104:107], v[228:231], v[76:79]
	v_mfma_f32_16x16x32_bf16 v[72:75], v[120:123], v[228:231], v[72:75]
	v_mfma_f32_16x16x32_bf16 v[68:71], v[104:107], v[236:239], v[68:71]
	v_mfma_f32_16x16x32_bf16 v[64:67], v[120:123], v[236:239], v[64:67]
	v_mfma_f32_16x16x32_bf16 v[28:31], v[124:127], v[164:167], v[28:31]
	v_mfma_f32_16x16x32_bf16 v[24:27], v[132:135], v[164:167], v[24:27]
	v_mfma_f32_16x16x32_bf16 v[20:23], v[124:127], v[192:195], v[20:23]
	v_mfma_f32_16x16x32_bf16 v[16:19], v[132:135], v[192:195], v[16:19]
	v_mfma_f32_16x16x32_bf16 v[12:15], v[124:127], v[224:227], v[12:15]
	v_mfma_f32_16x16x32_bf16 v[8:11], v[132:135], v[224:227], v[8:11]
	v_mfma_f32_16x16x32_bf16 v[4:7], v[124:127], v[232:235], v[4:7]
	v_mfma_f32_16x16x32_bf16 v[0:3], v[132:135], v[232:235], v[0:3]
	v_mfma_f32_16x16x32_bf16 v[28:31], v[128:131], v[168:171], v[28:31]
	v_mfma_f32_16x16x32_bf16 v[24:27], v[160:163], v[168:171], v[24:27]
	v_mfma_f32_16x16x32_bf16 v[20:23], v[128:131], v[196:199], v[20:23]
	v_mfma_f32_16x16x32_bf16 v[16:19], v[160:163], v[196:199], v[16:19]
	v_mfma_f32_16x16x32_bf16 v[12:15], v[128:131], v[228:231], v[12:15]
	v_mfma_f32_16x16x32_bf16 v[8:11], v[160:163], v[228:231], v[8:11]
	v_mfma_f32_16x16x32_bf16 v[4:7], v[128:131], v[236:239], v[4:7]
	v_mfma_f32_16x16x32_bf16 v[0:3], v[160:163], v[236:239], v[0:3]
	s_setprio 0
	s_barrier
	s_add_i32 s85, s85, 2
	s_add_u32 s42, s42, 0x100
	s_addc_u32 s43, s43, 0
	s_cmp_gt_u32 s85, 13
	s_cbranch_scc0 .LBB0_1471
	s_and_b64 vcc, exec, s[24:25]
	s_cbranch_vccz .LBB0_1474
	s_barrier

; #define PG8_STAGE(bufoff, gbase, voff) do { _Pragma("unroll") for (int _i = 0; _i < 2; ++_i) \
;         __builtin_amdgcn_global_load_lds((const unsigned*)((const char*)(gbase) + (voff)[_i]), (PG8_LAS unsigned*)(lds + (bufoff) + ldsw + _i * 8192), 16, 0, 0); } while (0)
; #define PG8_LDA(dst, b, h) do { _Pragma("unroll") for (int m = 0; m < 4; ++m) _Pragma("unroll") for (int k = 0; k < 2; ++k) dst[m][k] = *(const PG8_LAS bf16x8*)(lds + PG8_SA(b, h) + aoff + m * 2048 + k * 1024); } while (0)
; #define PG8_LDB(dst, b, h) do { _Pragma("unroll") for (int n = 0; n < 2; ++n) _Pragma("unroll") for (int k = 0; k < 2; ++k) dst[n][k] = *(const PG8_LAS bf16x8*)(lds + PG8_SB(b, h) + boff + n * 2048 + k * 1024); } while (0)
; #define PG8_MMA(ai, bj, At, Bt) do { __builtin_amdgcn_s_setprio(1); _Pragma("unroll") for (int m = 0; m < 4; ++m) _Pragma("unroll") for (int n = 0; n < 2; ++n) _Pragma("unroll") for (int k = 0; k < 2; ++k) \
;         acc[ai][bj][m][n] = __builtin_amdgcn_mfma_f32_16x16x32_bf16(Bt[n][k], At[m][k], acc[ai][bj][m][n], 0, 0, 0); __builtin_amdgcn_s_setprio(0); } while (0)
; #define PG8_WAIT_V(n) asm volatile("s_waitcnt vmcnt(" #n ")" ::: "memory")
; #define PG8_BAR __builtin_amdgcn_s_barrier()
; template <class Epi, class Sched, bool ALIGN_EPI = false, bool SP2 = false>
; __device__ __forceinline__ void gemm_phase(PG8_LAS unsigned char* lds, const Gemm g, const Sched& S, const Epi& E) {
;     ...
;         for (int t = 0; t < nt; t += 2) {
;             const bool last = (t == nt - 2);
;             const char* a1 = cA + PG8_AK(t + 1);
;             const char* a2 = last ? nA : cA + PG8_AK(t + 2); const char* b2 = last ? nB : cB + (size_t)(t + 2) * kstep;
;             const char* a3 = last ? nA + PG8_AK(1) : cA + PG8_AK(t + 3); const char* b3 = b2 + kstep;
;             if (last && has_next) S.a_ready(nxt);
;             if constexpr (SP2) {
;             PG8_LDB(B0, 0, 0); PG8_LDB(B1, 0, 1); PG8_SCHED; PG8_LDA(At, 0, 0); PG8_STAGE(PG8_SA(1, 1), a1 + hstepA, voffA);
;             PG8_WAIT_V(8); PG8_WAIT_L(0); PG8_BAR; PG8_MMA(0, 0, At, B0); PG8_MMA(0, 1, At, B1); PG8_BAR; PG8_SCHED;
;             PG8_LDA(At, 0, 1); PG8_STAGE(PG8_SB(0, 0), b2, voffB); PG8_STAGE(PG8_SB(0, 1), b2 + hstepB, voffB); PG8_STAGE(PG8_SA(0, 0), a2, voffA);
;             PG8_WAIT_V(8); PG8_WAIT_L(0); PG8_BAR; PG8_MMA(1, 0, At, B0); PG8_MMA(1, 1, At, B1); PG8_BAR; PG8_SCHED;
.LBB0_1638:
	ds_read_b128 v[132:135], v172
	ds_read_b128 v[158:161], v172 offset:1024
	ds_read_b128 v[176:179], v172 offset:2048
	ds_read_b128 v[180:183], v172 offset:3072
	ds_read_b128 v[184:187], v173
	ds_read_b128 v[188:191], v173 offset:1024
	ds_read_b128 v[192:195], v173 offset:2048
	ds_read_b128 v[196:199], v173 offset:3072
	s_add_u32 s38, s28, s34
	s_addc_u32 s39, s29, s35
	s_add_u32 s42, s38, 0x100
	s_addc_u32 s43, s39, 0
	s_add_u32 s40, s62, s34
	s_addc_u32 s41, s63, s35
	s_add_u32 s38, s38, 0x180
	s_addc_u32 s39, s39, 0
	s_cmpk_eq_i32 s34, 0x700
	s_cselect_b32 s39, s37, s39
	s_cselect_b32 s38, s31, s38
	s_cselect_b32 s41, s21, s41
	s_cselect_b32 s40, s23, s40
	s_cselect_b32 s43, s3, s43
	s_cselect_b32 s42, s10, s42
	v_lshl_add_u64 v[232:233], v[130:131], 0, s[34:35]
	s_add_i32 m0, s49, 0xc000
	ds_read_b128 v[200:203], v174
	ds_read_b128 v[204:207], v174 offset:1024
	ds_read_b128 v[208:211], v174 offset:2048
	ds_read_b128 v[212:215], v174 offset:3072
	ds_read_b128 v[216:219], v174 offset:4096
	ds_read_b128 v[220:223], v174 offset:5120
	ds_read_b128 v[224:227], v174 offset:6144
	ds_read_b128 v[228:231], v174 offset:7168
	global_load_lds_dwordx4 v[232:233], off
	v_lshl_add_u64 v[232:233], v[128:129], 0, s[34:35]
	s_add_i32 m0, s49, 0xe000
	s_nop 0
	global_load_lds_dwordx4 v[232:233], off
	s_waitcnt vmcnt(8)
	s_waitcnt lgkmcnt(0)
	s_barrier
	s_setprio 1
	v_mfma_f32_16x16x32_bf16 v[124:127], v[132:135], v[200:203], v[124:127]
	v_mfma_f32_16x16x32_bf16 v[120:123], v[176:179], v[200:203], v[120:123]
	v_mfma_f32_16x16x32_bf16 v[108:111], v[132:135], v[208:211], v[108:111]
	v_mfma_f32_16x16x32_bf16 v[104:107], v[176:179], v[208:211], v[104:107]
	v_mfma_f32_16x16x32_bf16 v[92:95], v[132:135], v[216:219], v[92:95]
	v_mfma_f32_16x16x32_bf16 v[88:91], v[176:179], v[216:219], v[88:91]
	v_mfma_f32_16x16x32_bf16 v[76:79], v[132:135], v[224:227], v[76:79]
	v_mfma_f32_16x16x32_bf16 v[72:75], v[176:179], v[224:227], v[72:75]
	v_mfma_f32_16x16x32_bf16 v[124:127], v[158:161], v[204:207], v[124:127]
	v_mfma_f32_16x16x32_bf16 v[120:123], v[180:183], v[204:207], v[120:123]
	v_mfma_f32_16x16x32_bf16 v[108:111], v[158:161], v[212:215], v[108:111]
	v_mfma_f32_16x16x32_bf16 v[104:107], v[180:183], v[212:215], v[104:107]
	v_mfma_f32_16x16x32_bf16 v[92:95], v[158:161], v[220:223], v[92:95]
	v_mfma_f32_16x16x32_bf16 v[88:91], v[180:183], v[220:223], v[88:91]
	v_mfma_f32_16x16x32_bf16 v[76:79], v[158:161], v[228:231], v[76:79]
	v_mfma_f32_16x16x32_bf16 v[72:75], v[180:183], v[228:231], v[72:75]
	v_mfma_f32_16x16x32_bf16 v[116:119], v[184:187], v[200:203], v[116:119]
	v_mfma_f32_16x16x32_bf16 v[112:115], v[192:195], v[200:203], v[112:115]
	v_mfma_f32_16x16x32_bf16 v[100:103], v[184:187], v[208:211], v[100:103]
	v_mfma_f32_16x16x32_bf16 v[96:99], v[192:195], v[208:211], v[96:99]
	v_mfma_f32_16x16x32_bf16 v[84:87], v[184:187], v[216:219], v[84:87]
	v_mfma_f32_16x16x32_bf16 v[80:83], v[192:195], v[216:219], v[80:83]
	v_mfma_f32_16x16x32_bf16 v[68:71], v[184:187], v[224:227], v[68:71]
	v_mfma_f32_16x16x32_bf16 v[64:67], v[192:195], v[224:227], v[64:67]
	v_mfma_f32_16x16x32_bf16 v[116:119], v[188:191], v[204:207], v[116:119]
	v_mfma_f32_16x16x32_bf16 v[112:115], v[196:199], v[204:207], v[112:115]
	v_mfma_f32_16x16x32_bf16 v[100:103], v[188:191], v[212:215], v[100:103]
	v_mfma_f32_16x16x32_bf16 v[96:99], v[196:199], v[212:215], v[96:99]
	v_mfma_f32_16x16x32_bf16 v[84:87], v[188:191], v[220:223], v[84:87]
	v_mfma_f32_16x16x32_bf16 v[80:83], v[196:199], v[220:223], v[80:83]
	v_mfma_f32_16x16x32_bf16 v[68:71], v[188:191], v[228:231], v[68:71]
	v_mfma_f32_16x16x32_bf16 v[64:67], v[196:199], v[228:231], v[64:67]
	s_setprio 0
	s_barrier
	s_add_i32 s65, s58, s48
	v_lshl_add_u64 v[232:233], s[40:41], 0, v[138:139]
	s_mov_b32 m0, s65
	ds_read_b128 v[200:203], v174 offset:16384
	ds_read_b128 v[204:207], v174 offset:17408
	ds_read_b128 v[208:211], v174 offset:18432
	ds_read_b128 v[212:215], v174 offset:19456
	ds_read_b128 v[216:219], v174 offset:20480
	ds_read_b128 v[220:223], v174 offset:21504
	ds_read_b128 v[224:227], v174 offset:22528
	ds_read_b128 v[228:231], v174 offset:23552
	global_load_lds_dwordx4 v[232:233], off
	s_add_i32 m0, s65, 0x2000
	s_add_u32 s66, s40, 0x40000
	v_lshl_add_u64 v[234:235], s[40:41], 0, v[142:143]
	s_addc_u32 s67, s41, 0
	s_add_i32 s65, s59, s48
	global_load_lds_dwordx4 v[234:235], off
	v_lshl_add_u64 v[236:237], s[66:67], 0, v[138:139]
	s_mov_b32 m0, s65
	s_nop 0
	global_load_lds_dwordx4 v[236:237], off
	v_lshl_add_u64 v[236:237], s[66:67], 0, v[142:143]
	s_add_i32 m0, s65, 0x2000
	s_nop 0
	global_load_lds_dwordx4 v[236:237], off
	s_waitcnt vmcnt(6)
	s_waitcnt lgkmcnt(0)
	s_barrier
; #define PG8_STAGE(bufoff, gbase, voff) do { _Pragma("unroll") for (int _i = 0; _i < 2; ++_i) \
;         __builtin_amdgcn_global_load_lds((const unsigned*)((const char*)(gbase) + (voff)[_i]), (PG8_LAS unsigned*)(lds + (bufoff) + ldsw + _i * 8192), 16, 0, 0); } while (0)
; #define PG8_LDA(dst, b, h) do { _Pragma("unroll") for (int m = 0; m < 4; ++m) _Pragma("unroll") for (int k = 0; k < 2; ++k) dst[m][k] = *(const PG8_LAS bf16x8*)(lds + PG8_SA(b, h) + aoff + m * 2048 + k * 1024); } while (0)
; #define PG8_LDB(dst, b, h) do { _Pragma("unroll") for (int n = 0; n < 2; ++n) _Pragma("unroll") for (int k = 0; k < 2; ++k) dst[n][k] = *(const PG8_LAS bf16x8*)(lds + PG8_SB(b, h) + boff + n * 2048 + k * 1024); } while (0)
; #define PG8_MMA(ai, bj, At, Bt) do { __builtin_amdgcn_s_setprio(1); _Pragma("unroll") for (int m = 0; m < 4; ++m) _Pragma("unroll") for (int n = 0; n < 2; ++n) _Pragma("unroll") for (int k = 0; k < 2; ++k) \
;         acc[ai][bj][m][n] = __builtin_amdgcn_mfma_f32_16x16x32_bf16(Bt[n][k], At[m][k], acc[ai][bj][m][n], 0, 0, 0); __builtin_amdgcn_s_setprio(0); } while (0)
; #define PG8_WAIT_V(n) asm volatile("s_waitcnt vmcnt(" #n ")" ::: "memory")
; #define PG8_WAIT_L(n) asm volatile("s_waitcnt lgkmcnt(" #n ")" ::: "memory")
; #define PG8_BAR __builtin_amdgcn_s_barrier()
; #define PG8_SCHED __builtin_amdgcn_sched_barrier(0)
; template <class Epi, class Sched, bool ALIGN_EPI = false, bool SP2 = false>
; __device__ __forceinline__ void gemm_phase(PG8_LAS unsigned char* lds, const Gemm g, const Sched& S, const Epi& E) {
;     ...
;             PG8_WAIT_V(8); PG8_WAIT_L(0); PG8_BAR; PG8_MMA(1, 0, At, B0); PG8_MMA(1, 1, At, B1); PG8_BAR; PG8_SCHED;
;             PG8_LDB(B0, 1, 0); PG8_LDB(B1, 1, 1); PG8_SCHED; PG8_LDA(At, 1, 0); PG8_STAGE(PG8_SA(0, 1), a2 + hstepA, voffA);
;             PG8_WAIT_V(8); PG8_WAIT_L(0); PG8_BAR; PG8_MMA(0, 0, At, B0); PG8_MMA(0, 1, At, B1); PG8_BAR; PG8_SCHED;
	s_setprio 1
	v_mfma_f32_16x16x32_bf16 v[60:63], v[132:135], v[200:203], v[60:63]
	v_mfma_f32_16x16x32_bf16 v[56:59], v[176:179], v[200:203], v[56:59]
	v_mfma_f32_16x16x32_bf16 v[44:47], v[132:135], v[208:211], v[44:47]
	v_mfma_f32_16x16x32_bf16 v[40:43], v[176:179], v[208:211], v[40:43]
	v_mfma_f32_16x16x32_bf16 v[28:31], v[132:135], v[216:219], v[28:31]
	v_mfma_f32_16x16x32_bf16 v[24:27], v[176:179], v[216:219], v[24:27]
	v_mfma_f32_16x16x32_bf16 v[12:15], v[132:135], v[224:227], v[12:15]
	v_mfma_f32_16x16x32_bf16 v[8:11], v[176:179], v[224:227], v[8:11]
	v_mfma_f32_16x16x32_bf16 v[60:63], v[158:161], v[204:207], v[60:63]
	v_mfma_f32_16x16x32_bf16 v[56:59], v[180:183], v[204:207], v[56:59]
	v_mfma_f32_16x16x32_bf16 v[44:47], v[158:161], v[212:215], v[44:47]
	v_mfma_f32_16x16x32_bf16 v[40:43], v[180:183], v[212:215], v[40:43]
	v_mfma_f32_16x16x32_bf16 v[28:31], v[158:161], v[220:223], v[28:31]
	v_mfma_f32_16x16x32_bf16 v[24:27], v[180:183], v[220:223], v[24:27]
	v_mfma_f32_16x16x32_bf16 v[12:15], v[158:161], v[228:231], v[12:15]
	v_mfma_f32_16x16x32_bf16 v[8:11], v[180:183], v[228:231], v[8:11]
	v_mfma_f32_16x16x32_bf16 v[52:55], v[184:187], v[200:203], v[52:55]
	v_mfma_f32_16x16x32_bf16 v[48:51], v[192:195], v[200:203], v[48:51]
	v_mfma_f32_16x16x32_bf16 v[36:39], v[184:187], v[208:211], v[36:39]
	v_mfma_f32_16x16x32_bf16 v[32:35], v[192:195], v[208:211], v[32:35]
	v_mfma_f32_16x16x32_bf16 v[20:23], v[184:187], v[216:219], v[20:23]
	v_mfma_f32_16x16x32_bf16 v[16:19], v[192:195], v[216:219], v[16:19]
	v_mfma_f32_16x16x32_bf16 v[4:7], v[184:187], v[224:227], v[4:7]
	v_mfma_f32_16x16x32_bf16 v[0:3], v[192:195], v[224:227], v[0:3]
	v_mfma_f32_16x16x32_bf16 v[52:55], v[188:191], v[204:207], v[52:55]
	v_mfma_f32_16x16x32_bf16 v[48:51], v[196:199], v[204:207], v[48:51]
	v_mfma_f32_16x16x32_bf16 v[36:39], v[188:191], v[212:215], v[36:39]
	v_mfma_f32_16x16x32_bf16 v[32:35], v[196:199], v[212:215], v[32:35]
	v_mfma_f32_16x16x32_bf16 v[20:23], v[188:191], v[220:223], v[20:23]
	v_mfma_f32_16x16x32_bf16 v[16:19], v[196:199], v[220:223], v[16:19]
	v_mfma_f32_16x16x32_bf16 v[4:7], v[188:191], v[228:231], v[4:7]
	v_mfma_f32_16x16x32_bf16 v[0:3], v[196:199], v[228:231], v[0:3]
	s_setprio 0
	s_barrier
	s_add_i32 s65, 0, 0x18000
	v_add_u32_e32 v144, s65, v163
	s_add_i32 s66, 0, 0x1c000
	ds_read_b128 v[132:135], v144
	ds_read_b128 v[158:161], v144 offset:1024
	ds_read_b128 v[176:179], v144 offset:2048
	ds_read_b128 v[180:183], v144 offset:3072
	v_add_u32_e32 v144, s66, v163
	ds_read_b128 v[184:187], v144
	ds_read_b128 v[188:191], v144 offset:1024
	ds_read_b128 v[192:195], v144 offset:2048
	ds_read_b128 v[196:199], v144 offset:3072
	v_lshl_add_u64 v[236:237], s[42:43], 0, v[136:137]
	s_mov_b32 m0, s49
	s_nop 0
	global_load_lds_dwordx4 v[236:237], off
	v_lshl_add_u64 v[236:237], s[42:43], 0, v[140:141]
	s_mov_b32 m0, s50
	s_nop 0
	global_load_lds_dwordx4 v[236:237], off
	s_add_u32 s42, s42, 0x40000
	s_addc_u32 s43, s43, 0
	s_mov_b32 m0, s51
	v_lshl_add_u64 v[236:237], s[42:43], 0, v[136:137]
	ds_read_b128 v[200:203], v174 offset:32768
	ds_read_b128 v[204:207], v174 offset:33792
	ds_read_b128 v[208:211], v174 offset:34816
	ds_read_b128 v[212:215], v174 offset:35840
	ds_read_b128 v[216:219], v174 offset:36864
	ds_read_b128 v[220:223], v174 offset:37888
	ds_read_b128 v[224:227], v174 offset:38912
	ds_read_b128 v[228:231], v174 offset:39936
	global_load_lds_dwordx4 v[236:237], off
	v_lshl_add_u64 v[236:237], s[42:43], 0, v[140:141]
	s_mov_b32 m0, s52
	s_nop 0
	global_load_lds_dwordx4 v[236:237], off
	s_waitcnt vmcnt(8)
	s_waitcnt lgkmcnt(0)
	s_barrier
	s_setprio 1
	v_mfma_f32_16x16x32_bf16 v[124:127], v[132:135], v[200:203], v[124:127]
	v_mfma_f32_16x16x32_bf16 v[120:123], v[176:179], v[200:203], v[120:123]
	v_mfma_f32_16x16x32_bf16 v[108:111], v[132:135], v[208:211], v[108:111]
	v_mfma_f32_16x16x32_bf16 v[104:107], v[176:179], v[208:211], v[104:107]
	v_mfma_f32_16x16x32_bf16 v[92:95], v[132:135], v[216:219], v[92:95]
	v_mfma_f32_16x16x32_bf16 v[88:91], v[176:179], v[216:219], v[88:91]
	v_mfma_f32_16x16x32_bf16 v[76:79], v[132:135], v[224:227], v[76:79]
	v_mfma_f32_16x16x32_bf16 v[72:75], v[176:179], v[224:227], v[72:75]
	v_mfma_f32_16x16x32_bf16 v[124:127], v[158:161], v[204:207], v[124:127]
	v_mfma_f32_16x16x32_bf16 v[120:123], v[180:183], v[204:207], v[120:123]
	v_mfma_f32_16x16x32_bf16 v[108:111], v[158:161], v[212:215], v[108:111]
	v_mfma_f32_16x16x32_bf16 v[104:107], v[180:183], v[212:215], v[104:107]
	v_mfma_f32_16x16x32_bf16 v[92:95], v[158:161], v[220:223], v[92:95]
	v_mfma_f32_16x16x32_bf16 v[88:91], v[180:183], v[220:223], v[88:91]
	v_mfma_f32_16x16x32_bf16 v[76:79], v[158:161], v[228:231], v[76:79]
	v_mfma_f32_16x16x32_bf16 v[72:75], v[180:183], v[228:231], v[72:75]
	v_mfma_f32_16x16x32_bf16 v[116:119], v[184:187], v[200:203], v[116:119]
	v_mfma_f32_16x16x32_bf16 v[112:115], v[192:195], v[200:203], v[112:115]
	v_mfma_f32_16x16x32_bf16 v[100:103], v[184:187], v[208:211], v[100:103]
	v_mfma_f32_16x16x32_bf16 v[96:99], v[192:195], v[208:211], v[96:99]
	v_mfma_f32_16x16x32_bf16 v[84:87], v[184:187], v[216:219], v[84:87]
	v_mfma_f32_16x16x32_bf16 v[80:83], v[192:195], v[216:219], v[80:83]
	v_mfma_f32_16x16x32_bf16 v[68:71], v[184:187], v[224:227], v[68:71]
	v_mfma_f32_16x16x32_bf16 v[64:67], v[192:195], v[224:227], v[64:67]
	v_mfma_f32_16x16x32_bf16 v[116:119], v[188:191], v[204:207], v[116:119]
	v_mfma_f32_16x16x32_bf16 v[112:115], v[196:199], v[204:207], v[112:115]
	v_mfma_f32_16x16x32_bf16 v[100:103], v[188:191], v[212:215], v[100:103]
	v_mfma_f32_16x16x32_bf16 v[96:99], v[196:199], v[212:215], v[96:99]
	v_mfma_f32_16x16x32_bf16 v[84:87], v[188:191], v[220:223], v[84:87]
	v_mfma_f32_16x16x32_bf16 v[80:83], v[196:199], v[220:223], v[80:83]
	v_mfma_f32_16x16x32_bf16 v[68:71], v[188:191], v[228:231], v[68:71]
	v_mfma_f32_16x16x32_bf16 v[64:67], v[196:199], v[228:231], v[64:67]
	s_setprio 0
	s_barrier
; #define PG8_STAGE(bufoff, gbase, voff) do { _Pragma("unroll") for (int _i = 0; _i < 2; ++_i) \
;         __builtin_amdgcn_global_load_lds((const unsigned*)((const char*)(gbase) + (voff)[_i]), (PG8_LAS unsigned*)(lds + (bufoff) + ldsw + _i * 8192), 16, 0, 0); } while (0)
; #define PG8_LDA(dst, b, h) do { _Pragma("unroll") for (int m = 0; m < 4; ++m) _Pragma("unroll") for (int k = 0; k < 2; ++k) dst[m][k] = *(const PG8_LAS bf16x8*)(lds + PG8_SA(b, h) + aoff + m * 2048 + k * 1024); } while (0)
; #define PG8_MMA(ai, bj, At, Bt) do { __builtin_amdgcn_s_setprio(1); _Pragma("unroll") for (int m = 0; m < 4; ++m) _Pragma("unroll") for (int n = 0; n < 2; ++n) _Pragma("unroll") for (int k = 0; k < 2; ++k) \
;         acc[ai][bj][m][n] = __builtin_amdgcn_mfma_f32_16x16x32_bf16(Bt[n][k], At[m][k], acc[ai][bj][m][n], 0, 0, 0); __builtin_amdgcn_s_setprio(0); } while (0)
; #define PG8_WAIT_V(n) asm volatile("s_waitcnt vmcnt(" #n ")" ::: "memory")
; #define PG8_WAIT_L(n) asm volatile("s_waitcnt lgkmcnt(" #n ")" ::: "memory")
; #define PG8_BAR __builtin_amdgcn_s_barrier()
; #define PG8_SCHED __builtin_amdgcn_sched_barrier(0)
; template <class Epi, class Sched, bool ALIGN_EPI = false, bool SP2 = false>
; __device__ __forceinline__ void gemm_phase(PG8_LAS unsigned char* lds, const Gemm g, const Sched& S, const Epi& E) {
;     ...
;         for (int t = 0; t < nt; t += 2) {
;     ...
;             PG8_LDA(At, 1, 1); PG8_STAGE(PG8_SB(1, 0), b3, voffB); PG8_STAGE(PG8_SB(1, 1), b3 + hstepB, voffB); PG8_STAGE(PG8_SA(1, 0), a3, voffA);
;             PG8_WAIT_V(8); PG8_WAIT_L(0); PG8_BAR; PG8_MMA(1, 0, At, B0); PG8_MMA(1, 1, At, B1); PG8_BAR; PG8_SCHED;
	s_add_i32 s42, s65, s48
	v_lshl_add_u64 v[232:233], v[232:233], 0, s[14:15]
	s_mov_b32 m0, s42
	ds_read_b128 v[200:203], v174 offset:49152
	ds_read_b128 v[204:207], v174 offset:50176
	ds_read_b128 v[208:211], v174 offset:51200
	ds_read_b128 v[212:215], v174 offset:52224
	ds_read_b128 v[216:219], v174 offset:53248
	ds_read_b128 v[220:223], v174 offset:54272
	ds_read_b128 v[224:227], v174 offset:55296
	ds_read_b128 v[228:231], v174 offset:56320
	global_load_lds_dwordx4 v[232:233], off
	s_add_i32 m0, s42, 0x2000
	s_add_u32 s40, s40, 0x40080
	v_lshl_add_u64 v[232:233], v[234:235], 0, s[14:15]
	s_addc_u32 s41, s41, 0
	s_add_i32 s42, s66, s48
	global_load_lds_dwordx4 v[232:233], off
	v_lshl_add_u64 v[232:233], s[40:41], 0, v[138:139]
	s_mov_b32 m0, s42
	s_nop 0
	global_load_lds_dwordx4 v[232:233], off
	v_lshl_add_u64 v[232:233], s[40:41], 0, v[142:143]
	s_add_i32 m0, s42, 0x2000
	s_nop 0
	global_load_lds_dwordx4 v[232:233], off
	v_lshl_add_u64 v[232:233], s[38:39], 0, v[136:137]
	s_mov_b32 m0, s53
	s_nop 0
	global_load_lds_dwordx4 v[232:233], off
	v_lshl_add_u64 v[232:233], s[38:39], 0, v[140:141]
	s_mov_b32 m0, s54
	s_nop 0
	global_load_lds_dwordx4 v[232:233], off
	s_waitcnt vmcnt(8)
	s_waitcnt lgkmcnt(0)
	s_barrier
	s_setprio 1
	v_mfma_f32_16x16x32_bf16 v[60:63], v[132:135], v[200:203], v[60:63]
	v_mfma_f32_16x16x32_bf16 v[56:59], v[176:179], v[200:203], v[56:59]
	v_mfma_f32_16x16x32_bf16 v[44:47], v[132:135], v[208:211], v[44:47]
	v_mfma_f32_16x16x32_bf16 v[40:43], v[176:179], v[208:211], v[40:43]
	v_mfma_f32_16x16x32_bf16 v[28:31], v[132:135], v[216:219], v[28:31]
	v_mfma_f32_16x16x32_bf16 v[24:27], v[176:179], v[216:219], v[24:27]
	v_mfma_f32_16x16x32_bf16 v[12:15], v[132:135], v[224:227], v[12:15]
	v_mfma_f32_16x16x32_bf16 v[8:11], v[176:179], v[224:227], v[8:11]
	v_mfma_f32_16x16x32_bf16 v[60:63], v[158:161], v[204:207], v[60:63]
	v_mfma_f32_16x16x32_bf16 v[56:59], v[180:183], v[204:207], v[56:59]
	v_mfma_f32_16x16x32_bf16 v[44:47], v[158:161], v[212:215], v[44:47]
	v_mfma_f32_16x16x32_bf16 v[40:43], v[180:183], v[212:215], v[40:43]
	v_mfma_f32_16x16x32_bf16 v[28:31], v[158:161], v[220:223], v[28:31]
	v_mfma_f32_16x16x32_bf16 v[24:27], v[180:183], v[220:223], v[24:27]
	v_mfma_f32_16x16x32_bf16 v[12:15], v[158:161], v[228:231], v[12:15]
	v_mfma_f32_16x16x32_bf16 v[8:11], v[180:183], v[228:231], v[8:11]
	v_mfma_f32_16x16x32_bf16 v[52:55], v[184:187], v[200:203], v[52:55]
	v_mfma_f32_16x16x32_bf16 v[48:51], v[192:195], v[200:203], v[48:51]
	v_mfma_f32_16x16x32_bf16 v[36:39], v[184:187], v[208:211], v[36:39]
	v_mfma_f32_16x16x32_bf16 v[32:35], v[192:195], v[208:211], v[32:35]
	v_mfma_f32_16x16x32_bf16 v[20:23], v[184:187], v[216:219], v[20:23]
	v_mfma_f32_16x16x32_bf16 v[16:19], v[192:195], v[216:219], v[16:19]
	v_mfma_f32_16x16x32_bf16 v[4:7], v[184:187], v[224:227], v[4:7]
	v_mfma_f32_16x16x32_bf16 v[0:3], v[192:195], v[224:227], v[0:3]
	v_mfma_f32_16x16x32_bf16 v[52:55], v[188:191], v[204:207], v[52:55]
	v_mfma_f32_16x16x32_bf16 v[48:51], v[196:199], v[204:207], v[48:51]
	v_mfma_f32_16x16x32_bf16 v[36:39], v[188:191], v[212:215], v[36:39]
	v_mfma_f32_16x16x32_bf16 v[32:35], v[196:199], v[212:215], v[32:35]
	v_mfma_f32_16x16x32_bf16 v[20:23], v[188:191], v[220:223], v[20:23]
	v_mfma_f32_16x16x32_bf16 v[16:19], v[196:199], v[220:223], v[16:19]
	v_mfma_f32_16x16x32_bf16 v[4:7], v[188:191], v[228:231], v[4:7]
	v_mfma_f32_16x16x32_bf16 v[0:3], v[196:199], v[228:231], v[0:3]
	s_setprio 0
	s_barrier
	s_add_i32 s64, s64, 2
	s_add_u32 s34, s34, 0x100
	s_addc_u32 s35, s35, 0
	s_cmp_gt_u32 s64, 13
	s_cbranch_scc0 .LBB0_1638
	s_and_b64 vcc, exec, s[16:17]
	s_cbranch_vccz .LBB0_1643
	s_barrier
	s_cmp_gt_i32 s30, 3
	s_mov_b64 s[28:29], -1
	s_cbranch_scc1 .LBB0_1644

; #define PG8_STAGE(bufoff, gbase, voff) do { _Pragma("unroll") for (int _i = 0; _i < 2; ++_i) \
;         __builtin_amdgcn_global_load_lds((const unsigned*)((const char*)(gbase) + (voff)[_i]), (PG8_LAS unsigned*)(lds + (bufoff) + ldsw + _i * 8192), 16, 0, 0); } while (0)
; #define PG8_LDA(dst, b, h) do { _Pragma("unroll") for (int m = 0; m < 4; ++m) _Pragma("unroll") for (int k = 0; k < 2; ++k) dst[m][k] = *(const PG8_LAS bf16x8*)(lds + PG8_SA(b, h) + aoff + m * 2048 + k * 1024); } while (0)
; #define PG8_LDB(dst, b, h) do { _Pragma("unroll") for (int n = 0; n < 2; ++n) _Pragma("unroll") for (int k = 0; k < 2; ++k) dst[n][k] = *(const PG8_LAS bf16x8*)(lds + PG8_SB(b, h) + boff + n * 2048 + k * 1024); } while (0)
; #define PG8_MMA(ai, bj, At, Bt) do { __builtin_amdgcn_s_setprio(1); _Pragma("unroll") for (int m = 0; m < 4; ++m) _Pragma("unroll") for (int n = 0; n < 2; ++n) _Pragma("unroll") for (int k = 0; k < 2; ++k) \
;         acc[ai][bj][m][n] = __builtin_amdgcn_mfma_f32_16x16x32_bf16(Bt[n][k], At[m][k], acc[ai][bj][m][n], 0, 0, 0); __builtin_amdgcn_s_setprio(0); } while (0)
; #define PG8_WAIT_V(n) asm volatile("s_waitcnt vmcnt(" #n ")" ::: "memory")
; #define PG8_BAR __builtin_amdgcn_s_barrier()
; template <class Epi, class Sched, bool ALIGN_EPI = false, bool SP2 = false>
; __device__ __forceinline__ void gemm_phase(PG8_LAS unsigned char* lds, const Gemm g, const Sched& S, const Epi& E) {
;     ...
;         for (int t = 0; t < nt; t += 2) {
;             const bool last = (t == nt - 2);
;             const char* a1 = cA + PG8_AK(t + 1);
;             const char* a2 = last ? nA : cA + PG8_AK(t + 2); const char* b2 = last ? nB : cB + (size_t)(t + 2) * kstep;
;             const char* a3 = last ? nA + PG8_AK(1) : cA + PG8_AK(t + 3); const char* b3 = b2 + kstep;
;             if (last && has_next) S.a_ready(nxt);
;             if constexpr (SP2) {
;             PG8_LDB(B0, 0, 0); PG8_LDB(B1, 0, 1); PG8_SCHED; PG8_LDA(At, 0, 0); PG8_STAGE(PG8_SA(1, 1), a1 + hstepA, voffA);
;             PG8_WAIT_V(8); PG8_WAIT_L(0); PG8_BAR; PG8_MMA(0, 0, At, B0); PG8_MMA(0, 1, At, B1); PG8_BAR; PG8_SCHED;
;             PG8_LDA(At, 0, 1); PG8_STAGE(PG8_SB(0, 0), b2, voffB); PG8_STAGE(PG8_SB(0, 1), b2 + hstepB, voffB); PG8_STAGE(PG8_SA(0, 0), a2, voffA);
;             PG8_WAIT_V(8); PG8_WAIT_L(0); PG8_BAR; PG8_MMA(1, 0, At, B0); PG8_MMA(1, 1, At, B1); PG8_BAR; PG8_SCHED;
.LBB0_1841:
	ds_read_b128 v[132:135], v191
	ds_read_b128 v[136:139], v191 offset:1024
	ds_read_b128 v[140:143], v191 offset:2048
	ds_read_b128 v[162:165], v191 offset:3072
	ds_read_b128 v[166:169], v192
	ds_read_b128 v[194:197], v192 offset:1024
	ds_read_b128 v[198:201], v192 offset:2048
	ds_read_b128 v[202:205], v192 offset:3072
	s_add_u32 s40, s36, s38
	s_addc_u32 s41, s37, s39
	s_add_u32 s42, s40, 0x100
	s_addc_u32 s43, s41, 0
	s_add_u32 s70, s69, s38
	s_addc_u32 s71, s78, s39
	s_add_u32 s40, s40, 0x180
	s_addc_u32 s41, s41, 0
	s_cmpk_eq_i32 s38, 0x700
	s_cselect_b32 s45, s3, s43
	s_cselect_b32 s44, s27, s42
	s_cselect_b32 s43, s25, s71
	s_cselect_b32 s42, s35, s70
	s_cselect_b32 s41, s68, s41
	s_cselect_b32 s40, s67, s40
	v_lshl_add_u64 v[170:171], v[130:131], 0, s[38:39]
	s_add_i32 m0, s52, 0xc000
	ds_read_b128 v[206:209], v174
	ds_read_b128 v[210:213], v174 offset:1024
	ds_read_b128 v[214:217], v174 offset:2048
	ds_read_b128 v[218:221], v174 offset:3072
	ds_read_b128 v[222:225], v174 offset:4096
	ds_read_b128 v[226:229], v174 offset:5120
	ds_read_b128 v[230:233], v174 offset:6144
	ds_read_b128 v[234:237], v174 offset:7168
	global_load_lds_dwordx4 v[170:171], off
	v_lshl_add_u64 v[170:171], v[128:129], 0, s[38:39]
	s_add_i32 m0, s52, 0xe000
	s_nop 0
	global_load_lds_dwordx4 v[170:171], off
	s_waitcnt vmcnt(8)
	s_waitcnt lgkmcnt(0)
	s_barrier
	s_setprio 1
	v_mfma_f32_16x16x32_bf16 v[124:127], v[132:135], v[206:209], v[124:127]
	v_mfma_f32_16x16x32_bf16 v[120:123], v[140:143], v[206:209], v[120:123]
	v_mfma_f32_16x16x32_bf16 v[116:119], v[132:135], v[214:217], v[116:119]
	v_mfma_f32_16x16x32_bf16 v[112:115], v[140:143], v[214:217], v[112:115]
	v_mfma_f32_16x16x32_bf16 v[108:111], v[132:135], v[222:225], v[108:111]
	v_mfma_f32_16x16x32_bf16 v[104:107], v[140:143], v[222:225], v[104:107]
	v_mfma_f32_16x16x32_bf16 v[100:103], v[132:135], v[230:233], v[100:103]
	v_mfma_f32_16x16x32_bf16 v[96:99], v[140:143], v[230:233], v[96:99]
	v_mfma_f32_16x16x32_bf16 v[124:127], v[136:139], v[210:213], v[124:127]
	v_mfma_f32_16x16x32_bf16 v[120:123], v[162:165], v[210:213], v[120:123]
	v_mfma_f32_16x16x32_bf16 v[116:119], v[136:139], v[218:221], v[116:119]
	v_mfma_f32_16x16x32_bf16 v[112:115], v[162:165], v[218:221], v[112:115]
	v_mfma_f32_16x16x32_bf16 v[108:111], v[136:139], v[226:229], v[108:111]
	v_mfma_f32_16x16x32_bf16 v[104:107], v[162:165], v[226:229], v[104:107]
	v_mfma_f32_16x16x32_bf16 v[100:103], v[136:139], v[234:237], v[100:103]
	v_mfma_f32_16x16x32_bf16 v[96:99], v[162:165], v[234:237], v[96:99]
	v_mfma_f32_16x16x32_bf16 v[60:63], v[166:169], v[206:209], v[60:63]
	v_mfma_f32_16x16x32_bf16 v[56:59], v[198:201], v[206:209], v[56:59]
	v_mfma_f32_16x16x32_bf16 v[52:55], v[166:169], v[214:217], v[52:55]
	v_mfma_f32_16x16x32_bf16 v[48:51], v[198:201], v[214:217], v[48:51]
	v_mfma_f32_16x16x32_bf16 v[44:47], v[166:169], v[222:225], v[44:47]
	v_mfma_f32_16x16x32_bf16 v[40:43], v[198:201], v[222:225], v[40:43]
	v_mfma_f32_16x16x32_bf16 v[36:39], v[166:169], v[230:233], v[36:39]
	v_mfma_f32_16x16x32_bf16 v[32:35], v[198:201], v[230:233], v[32:35]
	v_mfma_f32_16x16x32_bf16 v[60:63], v[194:197], v[210:213], v[60:63]
	v_mfma_f32_16x16x32_bf16 v[56:59], v[202:205], v[210:213], v[56:59]
	v_mfma_f32_16x16x32_bf16 v[52:55], v[194:197], v[218:221], v[52:55]
	v_mfma_f32_16x16x32_bf16 v[48:51], v[202:205], v[218:221], v[48:51]
	v_mfma_f32_16x16x32_bf16 v[44:47], v[194:197], v[226:229], v[44:47]
	v_mfma_f32_16x16x32_bf16 v[40:43], v[202:205], v[226:229], v[40:43]
	v_mfma_f32_16x16x32_bf16 v[36:39], v[194:197], v[234:237], v[36:39]
	v_mfma_f32_16x16x32_bf16 v[32:35], v[202:205], v[234:237], v[32:35]
	s_setprio 0
	s_barrier
	s_add_i32 s70, s64, s51
	v_lshl_add_u64 v[170:171], s[42:43], 0, v[146:147]
	s_mov_b32 m0, s70
	ds_read_b128 v[206:209], v174 offset:16384
	ds_read_b128 v[210:213], v174 offset:17408
	ds_read_b128 v[214:217], v174 offset:18432
	ds_read_b128 v[218:221], v174 offset:19456
	ds_read_b128 v[222:225], v174 offset:20480
	ds_read_b128 v[226:229], v174 offset:21504
	ds_read_b128 v[230:233], v174 offset:22528
	ds_read_b128 v[234:237], v174 offset:23552
	global_load_lds_dwordx4 v[170:171], off
	s_add_i32 m0, s70, 0x2000
	s_add_u32 s70, s42, 0x40000
	v_lshl_add_u64 v[238:239], s[42:43], 0, v[150:151]
	s_addc_u32 s71, s43, 0
	s_add_i32 s80, s65, s51
	global_load_lds_dwordx4 v[238:239], off
	v_lshl_add_u64 v[240:241], s[70:71], 0, v[146:147]
	s_mov_b32 m0, s80
	s_nop 0
	global_load_lds_dwordx4 v[240:241], off
	v_lshl_add_u64 v[240:241], s[70:71], 0, v[150:151]
	s_add_i32 m0, s80, 0x2000
	s_nop 0
	global_load_lds_dwordx4 v[240:241], off
	s_waitcnt vmcnt(6)
	s_waitcnt lgkmcnt(0)
	s_barrier
; #define PG8_STAGE(bufoff, gbase, voff) do { _Pragma("unroll") for (int _i = 0; _i < 2; ++_i) \
;         __builtin_amdgcn_global_load_lds((const unsigned*)((const char*)(gbase) + (voff)[_i]), (PG8_LAS unsigned*)(lds + (bufoff) + ldsw + _i * 8192), 16, 0, 0); } while (0)
; #define PG8_LDA(dst, b, h) do { _Pragma("unroll") for (int m = 0; m < 4; ++m) _Pragma("unroll") for (int k = 0; k < 2; ++k) dst[m][k] = *(const PG8_LAS bf16x8*)(lds + PG8_SA(b, h) + aoff + m * 2048 + k * 1024); } while (0)
; #define PG8_LDB(dst, b, h) do { _Pragma("unroll") for (int n = 0; n < 2; ++n) _Pragma("unroll") for (int k = 0; k < 2; ++k) dst[n][k] = *(const PG8_LAS bf16x8*)(lds + PG8_SB(b, h) + boff + n * 2048 + k * 1024); } while (0)
; #define PG8_MMA(ai, bj, At, Bt) do { __builtin_amdgcn_s_setprio(1); _Pragma("unroll") for (int m = 0; m < 4; ++m) _Pragma("unroll") for (int n = 0; n < 2; ++n) _Pragma("unroll") for (int k = 0; k < 2; ++k) \
;         acc[ai][bj][m][n] = __builtin_amdgcn_mfma_f32_16x16x32_bf16(Bt[n][k], At[m][k], acc[ai][bj][m][n], 0, 0, 0); __builtin_amdgcn_s_setprio(0); } while (0)
; #define PG8_WAIT_V(n) asm volatile("s_waitcnt vmcnt(" #n ")" ::: "memory")
; #define PG8_WAIT_L(n) asm volatile("s_waitcnt lgkmcnt(" #n ")" ::: "memory")
; #define PG8_BAR __builtin_amdgcn_s_barrier()
; #define PG8_SCHED __builtin_amdgcn_sched_barrier(0)
; template <class Epi, class Sched, bool ALIGN_EPI = false, bool SP2 = false>
; __device__ __forceinline__ void gemm_phase(PG8_LAS unsigned char* lds, const Gemm g, const Sched& S, const Epi& E) {
;     ...
;             PG8_WAIT_V(8); PG8_WAIT_L(0); PG8_BAR; PG8_MMA(1, 0, At, B0); PG8_MMA(1, 1, At, B1); PG8_BAR; PG8_SCHED;
;             PG8_LDB(B0, 1, 0); PG8_LDB(B1, 1, 1); PG8_SCHED; PG8_LDA(At, 1, 0); PG8_STAGE(PG8_SA(0, 1), a2 + hstepA, voffA);
;             PG8_WAIT_V(8); PG8_WAIT_L(0); PG8_BAR; PG8_MMA(0, 0, At, B0); PG8_MMA(0, 1, At, B1); PG8_BAR; PG8_SCHED;
	s_setprio 1
	v_mfma_f32_16x16x32_bf16 v[92:95], v[132:135], v[206:209], v[92:95]
	v_mfma_f32_16x16x32_bf16 v[88:91], v[140:143], v[206:209], v[88:91]
	v_mfma_f32_16x16x32_bf16 v[84:87], v[132:135], v[214:217], v[84:87]
	v_mfma_f32_16x16x32_bf16 v[80:83], v[140:143], v[214:217], v[80:83]
	v_mfma_f32_16x16x32_bf16 v[76:79], v[132:135], v[222:225], v[76:79]
	v_mfma_f32_16x16x32_bf16 v[72:75], v[140:143], v[222:225], v[72:75]
	v_mfma_f32_16x16x32_bf16 v[68:71], v[132:135], v[230:233], v[68:71]
	v_mfma_f32_16x16x32_bf16 v[64:67], v[140:143], v[230:233], v[64:67]
	v_mfma_f32_16x16x32_bf16 v[92:95], v[136:139], v[210:213], v[92:95]
	v_mfma_f32_16x16x32_bf16 v[88:91], v[162:165], v[210:213], v[88:91]
	v_mfma_f32_16x16x32_bf16 v[84:87], v[136:139], v[218:221], v[84:87]
	v_mfma_f32_16x16x32_bf16 v[80:83], v[162:165], v[218:221], v[80:83]
	v_mfma_f32_16x16x32_bf16 v[76:79], v[136:139], v[226:229], v[76:79]
	v_mfma_f32_16x16x32_bf16 v[72:75], v[162:165], v[226:229], v[72:75]
	v_mfma_f32_16x16x32_bf16 v[68:71], v[136:139], v[234:237], v[68:71]
	v_mfma_f32_16x16x32_bf16 v[64:67], v[162:165], v[234:237], v[64:67]
	v_mfma_f32_16x16x32_bf16 v[28:31], v[166:169], v[206:209], v[28:31]
	v_mfma_f32_16x16x32_bf16 v[24:27], v[198:201], v[206:209], v[24:27]
	v_mfma_f32_16x16x32_bf16 v[20:23], v[166:169], v[214:217], v[20:23]
	v_mfma_f32_16x16x32_bf16 v[16:19], v[198:201], v[214:217], v[16:19]
	v_mfma_f32_16x16x32_bf16 v[12:15], v[166:169], v[222:225], v[12:15]
	v_mfma_f32_16x16x32_bf16 v[8:11], v[198:201], v[222:225], v[8:11]
	v_mfma_f32_16x16x32_bf16 v[4:7], v[166:169], v[230:233], v[4:7]
	v_mfma_f32_16x16x32_bf16 v[0:3], v[198:201], v[230:233], v[0:3]
	v_mfma_f32_16x16x32_bf16 v[28:31], v[194:197], v[210:213], v[28:31]
	v_mfma_f32_16x16x32_bf16 v[24:27], v[202:205], v[210:213], v[24:27]
	v_mfma_f32_16x16x32_bf16 v[20:23], v[194:197], v[218:221], v[20:23]
	v_mfma_f32_16x16x32_bf16 v[16:19], v[202:205], v[218:221], v[16:19]
	v_mfma_f32_16x16x32_bf16 v[12:15], v[194:197], v[226:229], v[12:15]
	v_mfma_f32_16x16x32_bf16 v[8:11], v[202:205], v[226:229], v[8:11]
	v_mfma_f32_16x16x32_bf16 v[4:7], v[194:197], v[234:237], v[4:7]
	v_mfma_f32_16x16x32_bf16 v[0:3], v[202:205], v[234:237], v[0:3]
	s_setprio 0
	s_barrier
	s_add_i32 s70, 0, 0x18000
	v_add_u32_e32 v153, s70, v173
	s_add_i32 s71, 0, 0x1c000
	ds_read_b128 v[132:135], v153
	ds_read_b128 v[136:139], v153 offset:1024
	ds_read_b128 v[140:143], v153 offset:2048
	ds_read_b128 v[162:165], v153 offset:3072
	v_add_u32_e32 v153, s71, v173
	ds_read_b128 v[166:169], v153
	ds_read_b128 v[194:197], v153 offset:1024
	ds_read_b128 v[198:201], v153 offset:2048
	ds_read_b128 v[202:205], v153 offset:3072
	v_lshl_add_u64 v[240:241], s[44:45], 0, v[144:145]
	s_mov_b32 m0, s52
	s_nop 0
	global_load_lds_dwordx4 v[240:241], off
	v_lshl_add_u64 v[240:241], s[44:45], 0, v[148:149]
	s_mov_b32 m0, s53
	s_nop 0
	global_load_lds_dwordx4 v[240:241], off
	s_add_u32 s44, s44, 0x40000
	s_addc_u32 s45, s45, 0
	s_mov_b32 m0, s54
	v_lshl_add_u64 v[240:241], s[44:45], 0, v[144:145]
	ds_read_b128 v[206:209], v174 offset:32768
	ds_read_b128 v[210:213], v174 offset:33792
	ds_read_b128 v[214:217], v174 offset:34816
	ds_read_b128 v[218:221], v174 offset:35840
	ds_read_b128 v[222:225], v174 offset:36864
	ds_read_b128 v[226:229], v174 offset:37888
	ds_read_b128 v[230:233], v174 offset:38912
	ds_read_b128 v[234:237], v174 offset:39936
	global_load_lds_dwordx4 v[240:241], off
	v_lshl_add_u64 v[240:241], s[44:45], 0, v[148:149]
	s_mov_b32 m0, s55
	s_nop 0
	global_load_lds_dwordx4 v[240:241], off
	s_waitcnt vmcnt(8)
	s_waitcnt lgkmcnt(0)
	s_barrier
	s_setprio 1
	v_mfma_f32_16x16x32_bf16 v[124:127], v[132:135], v[206:209], v[124:127]
	v_mfma_f32_16x16x32_bf16 v[120:123], v[140:143], v[206:209], v[120:123]
	v_mfma_f32_16x16x32_bf16 v[116:119], v[132:135], v[214:217], v[116:119]
	v_mfma_f32_16x16x32_bf16 v[112:115], v[140:143], v[214:217], v[112:115]
	v_mfma_f32_16x16x32_bf16 v[108:111], v[132:135], v[222:225], v[108:111]
	v_mfma_f32_16x16x32_bf16 v[104:107], v[140:143], v[222:225], v[104:107]
	v_mfma_f32_16x16x32_bf16 v[100:103], v[132:135], v[230:233], v[100:103]
	v_mfma_f32_16x16x32_bf16 v[96:99], v[140:143], v[230:233], v[96:99]
	v_mfma_f32_16x16x32_bf16 v[124:127], v[136:139], v[210:213], v[124:127]
	v_mfma_f32_16x16x32_bf16 v[120:123], v[162:165], v[210:213], v[120:123]
	v_mfma_f32_16x16x32_bf16 v[116:119], v[136:139], v[218:221], v[116:119]
	v_mfma_f32_16x16x32_bf16 v[112:115], v[162:165], v[218:221], v[112:115]
	v_mfma_f32_16x16x32_bf16 v[108:111], v[136:139], v[226:229], v[108:111]
	v_mfma_f32_16x16x32_bf16 v[104:107], v[162:165], v[226:229], v[104:107]
	v_mfma_f32_16x16x32_bf16 v[100:103], v[136:139], v[234:237], v[100:103]
	v_mfma_f32_16x16x32_bf16 v[96:99], v[162:165], v[234:237], v[96:99]
	v_mfma_f32_16x16x32_bf16 v[60:63], v[166:169], v[206:209], v[60:63]
	v_mfma_f32_16x16x32_bf16 v[56:59], v[198:201], v[206:209], v[56:59]
	v_mfma_f32_16x16x32_bf16 v[52:55], v[166:169], v[214:217], v[52:55]
	v_mfma_f32_16x16x32_bf16 v[48:51], v[198:201], v[214:217], v[48:51]
	v_mfma_f32_16x16x32_bf16 v[44:47], v[166:169], v[222:225], v[44:47]
	v_mfma_f32_16x16x32_bf16 v[40:43], v[198:201], v[222:225], v[40:43]
	v_mfma_f32_16x16x32_bf16 v[36:39], v[166:169], v[230:233], v[36:39]
	v_mfma_f32_16x16x32_bf16 v[32:35], v[198:201], v[230:233], v[32:35]
	v_mfma_f32_16x16x32_bf16 v[60:63], v[194:197], v[210:213], v[60:63]
	v_mfma_f32_16x16x32_bf16 v[56:59], v[202:205], v[210:213], v[56:59]
	v_mfma_f32_16x16x32_bf16 v[52:55], v[194:197], v[218:221], v[52:55]
	v_mfma_f32_16x16x32_bf16 v[48:51], v[202:205], v[218:221], v[48:51]
	v_mfma_f32_16x16x32_bf16 v[44:47], v[194:197], v[226:229], v[44:47]
	v_mfma_f32_16x16x32_bf16 v[40:43], v[202:205], v[226:229], v[40:43]
	v_mfma_f32_16x16x32_bf16 v[36:39], v[194:197], v[234:237], v[36:39]
	v_mfma_f32_16x16x32_bf16 v[32:35], v[202:205], v[234:237], v[32:35]
	s_setprio 0
	s_barrier
; #define PG8_STAGE(bufoff, gbase, voff) do { _Pragma("unroll") for (int _i = 0; _i < 2; ++_i) \
;         __builtin_amdgcn_global_load_lds((const unsigned*)((const char*)(gbase) + (voff)[_i]), (PG8_LAS unsigned*)(lds + (bufoff) + ldsw + _i * 8192), 16, 0, 0); } while (0)
; #define PG8_LDA(dst, b, h) do { _Pragma("unroll") for (int m = 0; m < 4; ++m) _Pragma("unroll") for (int k = 0; k < 2; ++k) dst[m][k] = *(const PG8_LAS bf16x8*)(lds + PG8_SA(b, h) + aoff + m * 2048 + k * 1024); } while (0)
; #define PG8_MMA(ai, bj, At, Bt) do { __builtin_amdgcn_s_setprio(1); _Pragma("unroll") for (int m = 0; m < 4; ++m) _Pragma("unroll") for (int n = 0; n < 2; ++n) _Pragma("unroll") for (int k = 0; k < 2; ++k) \
;         acc[ai][bj][m][n] = __builtin_amdgcn_mfma_f32_16x16x32_bf16(Bt[n][k], At[m][k], acc[ai][bj][m][n], 0, 0, 0); __builtin_amdgcn_s_setprio(0); } while (0)
; #define PG8_WAIT_V(n) asm volatile("s_waitcnt vmcnt(" #n ")" ::: "memory")
; #define PG8_WAIT_L(n) asm volatile("s_waitcnt lgkmcnt(" #n ")" ::: "memory")
; #define PG8_BAR __builtin_amdgcn_s_barrier()
; #define PG8_SCHED __builtin_amdgcn_sched_barrier(0)
; template <class Epi, class Sched, bool ALIGN_EPI = false, bool SP2 = false>
; __device__ __forceinline__ void gemm_phase(PG8_LAS unsigned char* lds, const Gemm g, const Sched& S, const Epi& E) {
;     ...
;         for (int t = 0; t < nt; t += 2) {
;     ...
;             PG8_LDA(At, 1, 1); PG8_STAGE(PG8_SB(1, 0), b3, voffB); PG8_STAGE(PG8_SB(1, 1), b3 + hstepB, voffB); PG8_STAGE(PG8_SA(1, 0), a3, voffA);
;             PG8_WAIT_V(8); PG8_WAIT_L(0); PG8_BAR; PG8_MMA(1, 0, At, B0); PG8_MMA(1, 1, At, B1); PG8_BAR; PG8_SCHED;
	s_add_i32 s44, s70, s51
	v_lshl_add_u64 v[170:171], v[170:171], 0, s[18:19]
	s_mov_b32 m0, s44
	ds_read_b128 v[206:209], v174 offset:49152
	ds_read_b128 v[210:213], v174 offset:50176
	ds_read_b128 v[214:217], v174 offset:51200
	ds_read_b128 v[218:221], v174 offset:52224
	ds_read_b128 v[222:225], v174 offset:53248
	ds_read_b128 v[226:229], v174 offset:54272
	ds_read_b128 v[230:233], v174 offset:55296
	ds_read_b128 v[234:237], v174 offset:56320
	global_load_lds_dwordx4 v[170:171], off
	s_add_i32 m0, s44, 0x2000
	s_add_u32 s42, s42, 0x40080
	v_lshl_add_u64 v[170:171], v[238:239], 0, s[18:19]
	s_addc_u32 s43, s43, 0
	s_add_i32 s44, s71, s51
	global_load_lds_dwordx4 v[170:171], off
	v_lshl_add_u64 v[170:171], s[42:43], 0, v[146:147]
	s_mov_b32 m0, s44
	s_nop 0
	global_load_lds_dwordx4 v[170:171], off
	v_lshl_add_u64 v[170:171], s[42:43], 0, v[150:151]
	s_add_i32 m0, s44, 0x2000
	s_nop 0
	global_load_lds_dwordx4 v[170:171], off
	v_lshl_add_u64 v[170:171], s[40:41], 0, v[144:145]
	s_mov_b32 m0, s60
	s_nop 0
	global_load_lds_dwordx4 v[170:171], off
	v_lshl_add_u64 v[170:171], s[40:41], 0, v[148:149]
	s_mov_b32 m0, s61
	s_nop 0
	global_load_lds_dwordx4 v[170:171], off
	s_waitcnt vmcnt(8)
	s_waitcnt lgkmcnt(0)
	s_barrier
	s_setprio 1
	v_mfma_f32_16x16x32_bf16 v[92:95], v[132:135], v[206:209], v[92:95]
	v_mfma_f32_16x16x32_bf16 v[88:91], v[140:143], v[206:209], v[88:91]
	v_mfma_f32_16x16x32_bf16 v[84:87], v[132:135], v[214:217], v[84:87]
	v_mfma_f32_16x16x32_bf16 v[80:83], v[140:143], v[214:217], v[80:83]
	v_mfma_f32_16x16x32_bf16 v[76:79], v[132:135], v[222:225], v[76:79]
	v_mfma_f32_16x16x32_bf16 v[72:75], v[140:143], v[222:225], v[72:75]
	v_mfma_f32_16x16x32_bf16 v[68:71], v[132:135], v[230:233], v[68:71]
	v_mfma_f32_16x16x32_bf16 v[64:67], v[140:143], v[230:233], v[64:67]
	v_mfma_f32_16x16x32_bf16 v[92:95], v[136:139], v[210:213], v[92:95]
	v_mfma_f32_16x16x32_bf16 v[88:91], v[162:165], v[210:213], v[88:91]
	v_mfma_f32_16x16x32_bf16 v[84:87], v[136:139], v[218:221], v[84:87]
	v_mfma_f32_16x16x32_bf16 v[80:83], v[162:165], v[218:221], v[80:83]
	v_mfma_f32_16x16x32_bf16 v[76:79], v[136:139], v[226:229], v[76:79]
	v_mfma_f32_16x16x32_bf16 v[72:75], v[162:165], v[226:229], v[72:75]
	v_mfma_f32_16x16x32_bf16 v[68:71], v[136:139], v[234:237], v[68:71]
	v_mfma_f32_16x16x32_bf16 v[64:67], v[162:165], v[234:237], v[64:67]
	v_mfma_f32_16x16x32_bf16 v[28:31], v[166:169], v[206:209], v[28:31]
	v_mfma_f32_16x16x32_bf16 v[24:27], v[198:201], v[206:209], v[24:27]
	v_mfma_f32_16x16x32_bf16 v[20:23], v[166:169], v[214:217], v[20:23]
	v_mfma_f32_16x16x32_bf16 v[16:19], v[198:201], v[214:217], v[16:19]
	v_mfma_f32_16x16x32_bf16 v[12:15], v[166:169], v[222:225], v[12:15]
	v_mfma_f32_16x16x32_bf16 v[8:11], v[198:201], v[222:225], v[8:11]
	v_mfma_f32_16x16x32_bf16 v[4:7], v[166:169], v[230:233], v[4:7]
	v_mfma_f32_16x16x32_bf16 v[0:3], v[198:201], v[230:233], v[0:3]
	v_mfma_f32_16x16x32_bf16 v[28:31], v[194:197], v[210:213], v[28:31]
	v_mfma_f32_16x16x32_bf16 v[24:27], v[202:205], v[210:213], v[24:27]
	v_mfma_f32_16x16x32_bf16 v[20:23], v[194:197], v[218:221], v[20:23]
	v_mfma_f32_16x16x32_bf16 v[16:19], v[202:205], v[218:221], v[16:19]
	v_mfma_f32_16x16x32_bf16 v[12:15], v[194:197], v[226:229], v[12:15]
	v_mfma_f32_16x16x32_bf16 v[8:11], v[202:205], v[226:229], v[8:11]
	v_mfma_f32_16x16x32_bf16 v[4:7], v[194:197], v[234:237], v[4:7]
	v_mfma_f32_16x16x32_bf16 v[0:3], v[202:205], v[234:237], v[0:3]
	s_setprio 0
	s_barrier
	s_add_i32 s79, s79, 2
	s_add_u32 s38, s38, 0x100
	s_addc_u32 s39, s39, 0
	s_cmp_gt_u32 s79, 13
	s_cbranch_scc0 .LBB0_1841
	s_and_b64 vcc, exec, s[20:21]
	s_cbranch_vccz .LBB0_1844
	s_barrier

; #define PG8_STAGE(bufoff, gbase, voff) do { _Pragma("unroll") for (int _i = 0; _i < 2; ++_i) \
;         __builtin_amdgcn_global_load_lds((const unsigned*)((const char*)(gbase) + (voff)[_i]), (PG8_LAS unsigned*)(lds + (bufoff) + ldsw + _i * 8192), 16, 0, 0); } while (0)
; #define PG8_LDA(dst, b, h) do { _Pragma("unroll") for (int m = 0; m < 4; ++m) _Pragma("unroll") for (int k = 0; k < 2; ++k) dst[m][k] = *(const PG8_LAS bf16x8*)(lds + PG8_SA(b, h) + aoff + m * 2048 + k * 1024); } while (0)
; #define PG8_LDB(dst, b, h) do { _Pragma("unroll") for (int n = 0; n < 2; ++n) _Pragma("unroll") for (int k = 0; k < 2; ++k) dst[n][k] = *(const PG8_LAS bf16x8*)(lds + PG8_SB(b, h) + boff + n * 2048 + k * 1024); } while (0)
; #define PG8_MMA(ai, bj, At, Bt) do { __builtin_amdgcn_s_setprio(1); _Pragma("unroll") for (int m = 0; m < 4; ++m) _Pragma("unroll") for (int n = 0; n < 2; ++n) _Pragma("unroll") for (int k = 0; k < 2; ++k) \
;         acc[ai][bj][m][n] = __builtin_amdgcn_mfma_f32_16x16x32_bf16(Bt[n][k], At[m][k], acc[ai][bj][m][n], 0, 0, 0); __builtin_amdgcn_s_setprio(0); } while (0)
; #define PG8_WAIT_V(n) asm volatile("s_waitcnt vmcnt(" #n ")" ::: "memory")
; #define PG8_BAR __builtin_amdgcn_s_barrier()
; template <class Epi, class Sched, bool ALIGN_EPI = false, bool SP2 = false>
; __device__ __forceinline__ void gemm_phase(PG8_LAS unsigned char* lds, const Gemm g, const Sched& S, const Epi& E) {
;     ...
;         for (int t = 0; t < nt; t += 2) {
;             const bool last = (t == nt - 2);
;             const char* a1 = cA + PG8_AK(t + 1);
;             const char* a2 = last ? nA : cA + PG8_AK(t + 2); const char* b2 = last ? nB : cB + (size_t)(t + 2) * kstep;
;             const char* a3 = last ? nA + PG8_AK(1) : cA + PG8_AK(t + 3); const char* b3 = b2 + kstep;
;             if (last && has_next) S.a_ready(nxt);
;             if constexpr (SP2) {
;             PG8_LDB(B0, 0, 0); PG8_LDB(B1, 0, 1); PG8_SCHED; PG8_LDA(At, 0, 0); PG8_STAGE(PG8_SA(1, 1), a1 + hstepA, voffA);
;             PG8_WAIT_V(8); PG8_WAIT_L(0); PG8_BAR; PG8_MMA(0, 0, At, B0); PG8_MMA(0, 1, At, B1); PG8_BAR; PG8_SCHED;
;             PG8_LDA(At, 0, 1); PG8_STAGE(PG8_SB(0, 0), b2, voffB); PG8_STAGE(PG8_SB(0, 1), b2 + hstepB, voffB); PG8_STAGE(PG8_SA(0, 0), a2, voffA);
;             PG8_WAIT_V(8); PG8_WAIT_L(0); PG8_BAR; PG8_MMA(1, 0, At, B0); PG8_MMA(1, 1, At, B1); PG8_BAR; PG8_SCHED;
.LBB0_2888:
	ds_read_b128 v[124:127], v210
	ds_read_b128 v[128:131], v210 offset:1024
	ds_read_b128 v[132:135], v210 offset:2048
	ds_read_b128 v[144:147], v210 offset:3072
	ds_read_b128 v[148:151], v211
	ds_read_b128 v[170:173], v211 offset:1024
	ds_read_b128 v[174:177], v211 offset:2048
	ds_read_b128 v[178:181], v211 offset:3072
	s_add_u32 s42, s38, s40
	s_addc_u32 s43, s39, s41
	s_add_u32 s46, s42, 0x100
	s_addc_u32 s47, s43, 0
	s_add_u32 s44, s78, s40
	s_addc_u32 s45, s79, s41
	s_add_u32 s42, s42, 0x180
	s_addc_u32 s43, s43, 0
	s_cmpk_eq_i32 s40, 0x1500
	s_cselect_b32 s43, s10, s43
	s_cselect_b32 s42, s3, s42
	s_cselect_b32 s45, s37, s45
	s_cselect_b32 s44, s36, s44
	s_cselect_b32 s47, s9, s47
	s_cselect_b32 s46, s8, s46
	v_lshl_add_u64 v[206:207], v[122:123], 0, s[40:41]
	s_add_i32 m0, s53, 0xc000
	ds_read_b128 v[212:215], v191
	ds_read_b128 v[216:219], v191 offset:1024
	ds_read_b128 v[220:223], v191 offset:2048
	ds_read_b128 v[224:227], v191 offset:3072
	ds_read_b128 v[228:231], v191 offset:4096
	ds_read_b128 v[232:235], v191 offset:5120
	ds_read_b128 v[236:239], v191 offset:6144
	ds_read_b128 v[240:243], v191 offset:7168
	global_load_lds_dwordx4 v[206:207], off
	v_lshl_add_u64 v[206:207], v[120:121], 0, s[40:41]
	s_add_i32 m0, s53, 0xe000
	s_nop 0
	global_load_lds_dwordx4 v[206:207], off
	s_waitcnt vmcnt(8)
	s_waitcnt lgkmcnt(0)
	s_barrier
	s_setprio 1
	v_mfma_f32_16x16x32_bf16 v[140:143], v[124:127], v[212:215], v[140:143]
	v_mfma_f32_16x16x32_bf16 v[136:139], v[132:135], v[212:215], v[136:139]
	v_mfma_f32_16x16x32_bf16 v[116:119], v[124:127], v[220:223], v[116:119]
	v_mfma_f32_16x16x32_bf16 v[112:115], v[132:135], v[220:223], v[112:115]
	v_mfma_f32_16x16x32_bf16 v[108:111], v[124:127], v[228:231], v[108:111]
	v_mfma_f32_16x16x32_bf16 v[104:107], v[132:135], v[228:231], v[104:107]
	v_mfma_f32_16x16x32_bf16 v[100:103], v[124:127], v[236:239], v[100:103]
	v_mfma_f32_16x16x32_bf16 v[96:99], v[132:135], v[236:239], v[96:99]
	v_mfma_f32_16x16x32_bf16 v[140:143], v[128:131], v[216:219], v[140:143]
	v_mfma_f32_16x16x32_bf16 v[136:139], v[144:147], v[216:219], v[136:139]
	v_mfma_f32_16x16x32_bf16 v[116:119], v[128:131], v[224:227], v[116:119]
	v_mfma_f32_16x16x32_bf16 v[112:115], v[144:147], v[224:227], v[112:115]
	v_mfma_f32_16x16x32_bf16 v[108:111], v[128:131], v[232:235], v[108:111]
	v_mfma_f32_16x16x32_bf16 v[104:107], v[144:147], v[232:235], v[104:107]
	v_mfma_f32_16x16x32_bf16 v[100:103], v[128:131], v[240:243], v[100:103]
	v_mfma_f32_16x16x32_bf16 v[96:99], v[144:147], v[240:243], v[96:99]
	v_mfma_f32_16x16x32_bf16 v[60:63], v[148:151], v[212:215], v[60:63]
	v_mfma_f32_16x16x32_bf16 v[56:59], v[174:177], v[212:215], v[56:59]
	v_mfma_f32_16x16x32_bf16 v[52:55], v[148:151], v[220:223], v[52:55]
	v_mfma_f32_16x16x32_bf16 v[48:51], v[174:177], v[220:223], v[48:51]
	v_mfma_f32_16x16x32_bf16 v[44:47], v[148:151], v[228:231], v[44:47]
	v_mfma_f32_16x16x32_bf16 v[40:43], v[174:177], v[228:231], v[40:43]
	v_mfma_f32_16x16x32_bf16 v[36:39], v[148:151], v[236:239], v[36:39]
	v_mfma_f32_16x16x32_bf16 v[32:35], v[174:177], v[236:239], v[32:35]
	v_mfma_f32_16x16x32_bf16 v[60:63], v[170:173], v[216:219], v[60:63]
	v_mfma_f32_16x16x32_bf16 v[56:59], v[178:181], v[216:219], v[56:59]
	v_mfma_f32_16x16x32_bf16 v[52:55], v[170:173], v[224:227], v[52:55]
	v_mfma_f32_16x16x32_bf16 v[48:51], v[178:181], v[224:227], v[48:51]
	v_mfma_f32_16x16x32_bf16 v[44:47], v[170:173], v[232:235], v[44:47]
	v_mfma_f32_16x16x32_bf16 v[40:43], v[178:181], v[232:235], v[40:43]
	v_mfma_f32_16x16x32_bf16 v[36:39], v[170:173], v[240:243], v[36:39]
	v_mfma_f32_16x16x32_bf16 v[32:35], v[178:181], v[240:243], v[32:35]
	s_setprio 0
	s_barrier
	s_add_i32 s70, s69, s52
	v_lshl_add_u64 v[206:207], s[44:45], 0, v[154:155]
	s_mov_b32 m0, s70
	ds_read_b128 v[212:215], v191 offset:16384
	ds_read_b128 v[216:219], v191 offset:17408
	ds_read_b128 v[220:223], v191 offset:18432
	ds_read_b128 v[224:227], v191 offset:19456
	ds_read_b128 v[228:231], v191 offset:20480
	ds_read_b128 v[232:235], v191 offset:21504
	ds_read_b128 v[236:239], v191 offset:22528
	ds_read_b128 v[240:243], v191 offset:23552
	global_load_lds_dwordx4 v[206:207], off
	s_add_i32 m0, s70, 0x2000
	s_add_u32 s70, s44, 0xb0000
	v_lshl_add_u64 v[244:245], s[44:45], 0, v[158:159]
	s_addc_u32 s71, s45, 0
	s_add_i32 s87, s80, s52
	global_load_lds_dwordx4 v[244:245], off
	v_lshl_add_u64 v[246:247], s[70:71], 0, v[154:155]
	s_mov_b32 m0, s87
	s_nop 0
	global_load_lds_dwordx4 v[246:247], off
	v_lshl_add_u64 v[246:247], s[70:71], 0, v[158:159]
	s_add_i32 m0, s87, 0x2000
	s_nop 0
	global_load_lds_dwordx4 v[246:247], off
	s_waitcnt vmcnt(6)
	s_waitcnt lgkmcnt(0)
	s_barrier
; #define PG8_STAGE(bufoff, gbase, voff) do { _Pragma("unroll") for (int _i = 0; _i < 2; ++_i) \
;         __builtin_amdgcn_global_load_lds((const unsigned*)((const char*)(gbase) + (voff)[_i]), (PG8_LAS unsigned*)(lds + (bufoff) + ldsw + _i * 8192), 16, 0, 0); } while (0)
; #define PG8_LDA(dst, b, h) do { _Pragma("unroll") for (int m = 0; m < 4; ++m) _Pragma("unroll") for (int k = 0; k < 2; ++k) dst[m][k] = *(const PG8_LAS bf16x8*)(lds + PG8_SA(b, h) + aoff + m * 2048 + k * 1024); } while (0)
; #define PG8_LDB(dst, b, h) do { _Pragma("unroll") for (int n = 0; n < 2; ++n) _Pragma("unroll") for (int k = 0; k < 2; ++k) dst[n][k] = *(const PG8_LAS bf16x8*)(lds + PG8_SB(b, h) + boff + n * 2048 + k * 1024); } while (0)
; #define PG8_MMA(ai, bj, At, Bt) do { __builtin_amdgcn_s_setprio(1); _Pragma("unroll") for (int m = 0; m < 4; ++m) _Pragma("unroll") for (int n = 0; n < 2; ++n) _Pragma("unroll") for (int k = 0; k < 2; ++k) \
;         acc[ai][bj][m][n] = __builtin_amdgcn_mfma_f32_16x16x32_bf16(Bt[n][k], At[m][k], acc[ai][bj][m][n], 0, 0, 0); __builtin_amdgcn_s_setprio(0); } while (0)
; #define PG8_WAIT_V(n) asm volatile("s_waitcnt vmcnt(" #n ")" ::: "memory")
; #define PG8_WAIT_L(n) asm volatile("s_waitcnt lgkmcnt(" #n ")" ::: "memory")
; #define PG8_BAR __builtin_amdgcn_s_barrier()
; #define PG8_SCHED __builtin_amdgcn_sched_barrier(0)
; template <class Epi, class Sched, bool ALIGN_EPI = false, bool SP2 = false>
; __device__ __forceinline__ void gemm_phase(PG8_LAS unsigned char* lds, const Gemm g, const Sched& S, const Epi& E) {
;     ...
;             PG8_WAIT_V(8); PG8_WAIT_L(0); PG8_BAR; PG8_MMA(1, 0, At, B0); PG8_MMA(1, 1, At, B1); PG8_BAR; PG8_SCHED;
;             PG8_LDB(B0, 1, 0); PG8_LDB(B1, 1, 1); PG8_SCHED; PG8_LDA(At, 1, 0); PG8_STAGE(PG8_SA(0, 1), a2 + hstepA, voffA);
;             PG8_WAIT_V(8); PG8_WAIT_L(0); PG8_BAR; PG8_MMA(0, 0, At, B0); PG8_MMA(0, 1, At, B1); PG8_BAR; PG8_SCHED;
	s_setprio 1
	v_mfma_f32_16x16x32_bf16 v[92:95], v[124:127], v[212:215], v[92:95]
	v_mfma_f32_16x16x32_bf16 v[88:91], v[132:135], v[212:215], v[88:91]
	v_mfma_f32_16x16x32_bf16 v[84:87], v[124:127], v[220:223], v[84:87]
	v_mfma_f32_16x16x32_bf16 v[80:83], v[132:135], v[220:223], v[80:83]
	v_mfma_f32_16x16x32_bf16 v[76:79], v[124:127], v[228:231], v[76:79]
	v_mfma_f32_16x16x32_bf16 v[72:75], v[132:135], v[228:231], v[72:75]
	v_mfma_f32_16x16x32_bf16 v[68:71], v[124:127], v[236:239], v[68:71]
	v_mfma_f32_16x16x32_bf16 v[64:67], v[132:135], v[236:239], v[64:67]
	v_mfma_f32_16x16x32_bf16 v[92:95], v[128:131], v[216:219], v[92:95]
	v_mfma_f32_16x16x32_bf16 v[88:91], v[144:147], v[216:219], v[88:91]
	v_mfma_f32_16x16x32_bf16 v[84:87], v[128:131], v[224:227], v[84:87]
	v_mfma_f32_16x16x32_bf16 v[80:83], v[144:147], v[224:227], v[80:83]
	v_mfma_f32_16x16x32_bf16 v[76:79], v[128:131], v[232:235], v[76:79]
	v_mfma_f32_16x16x32_bf16 v[72:75], v[144:147], v[232:235], v[72:75]
	v_mfma_f32_16x16x32_bf16 v[68:71], v[128:131], v[240:243], v[68:71]
	v_mfma_f32_16x16x32_bf16 v[64:67], v[144:147], v[240:243], v[64:67]
	v_mfma_f32_16x16x32_bf16 v[28:31], v[148:151], v[212:215], v[28:31]
	v_mfma_f32_16x16x32_bf16 v[24:27], v[174:177], v[212:215], v[24:27]
	v_mfma_f32_16x16x32_bf16 v[20:23], v[148:151], v[220:223], v[20:23]
	v_mfma_f32_16x16x32_bf16 v[16:19], v[174:177], v[220:223], v[16:19]
	v_mfma_f32_16x16x32_bf16 v[12:15], v[148:151], v[228:231], v[12:15]
	v_mfma_f32_16x16x32_bf16 v[8:11], v[174:177], v[228:231], v[8:11]
	v_mfma_f32_16x16x32_bf16 v[4:7], v[148:151], v[236:239], v[4:7]
	v_mfma_f32_16x16x32_bf16 v[0:3], v[174:177], v[236:239], v[0:3]
	v_mfma_f32_16x16x32_bf16 v[28:31], v[170:173], v[216:219], v[28:31]
	v_mfma_f32_16x16x32_bf16 v[24:27], v[178:181], v[216:219], v[24:27]
	v_mfma_f32_16x16x32_bf16 v[20:23], v[170:173], v[224:227], v[20:23]
	v_mfma_f32_16x16x32_bf16 v[16:19], v[178:181], v[224:227], v[16:19]
	v_mfma_f32_16x16x32_bf16 v[12:15], v[170:173], v[232:235], v[12:15]
	v_mfma_f32_16x16x32_bf16 v[8:11], v[178:181], v[232:235], v[8:11]
	v_mfma_f32_16x16x32_bf16 v[4:7], v[170:173], v[240:243], v[4:7]
	v_mfma_f32_16x16x32_bf16 v[0:3], v[178:181], v[240:243], v[0:3]
	s_setprio 0
	s_barrier
	s_add_i32 s70, 0, 0x18000
	s_add_i32 s71, 0, 0x1c000
	v_add_u32_e32 v144, s70, v185
	v_add_u32_e32 v161, s71, v185
	ds_read_b128 v[124:127], v144
	ds_read_b128 v[128:131], v144 offset:1024
	ds_read_b128 v[132:135], v144 offset:2048
	ds_read_b128 v[144:147], v144 offset:3072
	ds_read_b128 v[148:151], v161
	ds_read_b128 v[170:173], v161 offset:1024
	ds_read_b128 v[174:177], v161 offset:2048
	ds_read_b128 v[178:181], v161 offset:3072
	v_lshl_add_u64 v[246:247], s[46:47], 0, v[152:153]
	s_mov_b32 m0, s53
	s_nop 0
	global_load_lds_dwordx4 v[246:247], off
	v_lshl_add_u64 v[246:247], s[46:47], 0, v[156:157]
	s_mov_b32 m0, s54
	s_nop 0
	global_load_lds_dwordx4 v[246:247], off
	s_add_u32 s46, s46, 0xb0000
	s_addc_u32 s47, s47, 0
	s_mov_b32 m0, s55
	v_lshl_add_u64 v[246:247], s[46:47], 0, v[152:153]
	ds_read_b128 v[212:215], v191 offset:32768
	ds_read_b128 v[216:219], v191 offset:33792
	ds_read_b128 v[220:223], v191 offset:34816
	ds_read_b128 v[224:227], v191 offset:35840
	ds_read_b128 v[228:231], v191 offset:36864
	ds_read_b128 v[232:235], v191 offset:37888
	ds_read_b128 v[236:239], v191 offset:38912
	ds_read_b128 v[240:243], v191 offset:39936
	global_load_lds_dwordx4 v[246:247], off
	v_lshl_add_u64 v[246:247], s[46:47], 0, v[156:157]
	s_mov_b32 m0, s56
	s_nop 0
	global_load_lds_dwordx4 v[246:247], off
	s_waitcnt vmcnt(8)
	s_waitcnt lgkmcnt(0)
	s_barrier
	s_setprio 1
	v_mfma_f32_16x16x32_bf16 v[140:143], v[124:127], v[212:215], v[140:143]
	v_mfma_f32_16x16x32_bf16 v[136:139], v[132:135], v[212:215], v[136:139]
	v_mfma_f32_16x16x32_bf16 v[116:119], v[124:127], v[220:223], v[116:119]
	v_mfma_f32_16x16x32_bf16 v[112:115], v[132:135], v[220:223], v[112:115]
	v_mfma_f32_16x16x32_bf16 v[108:111], v[124:127], v[228:231], v[108:111]
	v_mfma_f32_16x16x32_bf16 v[104:107], v[132:135], v[228:231], v[104:107]
	v_mfma_f32_16x16x32_bf16 v[100:103], v[124:127], v[236:239], v[100:103]
	v_mfma_f32_16x16x32_bf16 v[96:99], v[132:135], v[236:239], v[96:99]
	v_mfma_f32_16x16x32_bf16 v[140:143], v[128:131], v[216:219], v[140:143]
	v_mfma_f32_16x16x32_bf16 v[136:139], v[144:147], v[216:219], v[136:139]
	v_mfma_f32_16x16x32_bf16 v[116:119], v[128:131], v[224:227], v[116:119]
	v_mfma_f32_16x16x32_bf16 v[112:115], v[144:147], v[224:227], v[112:115]
	v_mfma_f32_16x16x32_bf16 v[108:111], v[128:131], v[232:235], v[108:111]
	v_mfma_f32_16x16x32_bf16 v[104:107], v[144:147], v[232:235], v[104:107]
	v_mfma_f32_16x16x32_bf16 v[100:103], v[128:131], v[240:243], v[100:103]
	v_mfma_f32_16x16x32_bf16 v[96:99], v[144:147], v[240:243], v[96:99]
	v_mfma_f32_16x16x32_bf16 v[60:63], v[148:151], v[212:215], v[60:63]
	v_mfma_f32_16x16x32_bf16 v[56:59], v[174:177], v[212:215], v[56:59]
	v_mfma_f32_16x16x32_bf16 v[52:55], v[148:151], v[220:223], v[52:55]
	v_mfma_f32_16x16x32_bf16 v[48:51], v[174:177], v[220:223], v[48:51]
	v_mfma_f32_16x16x32_bf16 v[44:47], v[148:151], v[228:231], v[44:47]
	v_mfma_f32_16x16x32_bf16 v[40:43], v[174:177], v[228:231], v[40:43]
	v_mfma_f32_16x16x32_bf16 v[36:39], v[148:151], v[236:239], v[36:39]
	v_mfma_f32_16x16x32_bf16 v[32:35], v[174:177], v[236:239], v[32:35]
	v_mfma_f32_16x16x32_bf16 v[60:63], v[170:173], v[216:219], v[60:63]
	v_mfma_f32_16x16x32_bf16 v[56:59], v[178:181], v[216:219], v[56:59]
	v_mfma_f32_16x16x32_bf16 v[52:55], v[170:173], v[224:227], v[52:55]
	v_mfma_f32_16x16x32_bf16 v[48:51], v[178:181], v[224:227], v[48:51]
	v_mfma_f32_16x16x32_bf16 v[44:47], v[170:173], v[232:235], v[44:47]
	v_mfma_f32_16x16x32_bf16 v[40:43], v[178:181], v[232:235], v[40:43]
	v_mfma_f32_16x16x32_bf16 v[36:39], v[170:173], v[240:243], v[36:39]
	v_mfma_f32_16x16x32_bf16 v[32:35], v[178:181], v[240:243], v[32:35]
	s_setprio 0
	s_barrier
; #define PG8_STAGE(bufoff, gbase, voff) do { _Pragma("unroll") for (int _i = 0; _i < 2; ++_i) \
;         __builtin_amdgcn_global_load_lds((const unsigned*)((const char*)(gbase) + (voff)[_i]), (PG8_LAS unsigned*)(lds + (bufoff) + ldsw + _i * 8192), 16, 0, 0); } while (0)
; #define PG8_LDA(dst, b, h) do { _Pragma("unroll") for (int m = 0; m < 4; ++m) _Pragma("unroll") for (int k = 0; k < 2; ++k) dst[m][k] = *(const PG8_LAS bf16x8*)(lds + PG8_SA(b, h) + aoff + m * 2048 + k * 1024); } while (0)
; #define PG8_MMA(ai, bj, At, Bt) do { __builtin_amdgcn_s_setprio(1); _Pragma("unroll") for (int m = 0; m < 4; ++m) _Pragma("unroll") for (int n = 0; n < 2; ++n) _Pragma("unroll") for (int k = 0; k < 2; ++k) \
;         acc[ai][bj][m][n] = __builtin_amdgcn_mfma_f32_16x16x32_bf16(Bt[n][k], At[m][k], acc[ai][bj][m][n], 0, 0, 0); __builtin_amdgcn_s_setprio(0); } while (0)
; #define PG8_WAIT_V(n) asm volatile("s_waitcnt vmcnt(" #n ")" ::: "memory")
; #define PG8_WAIT_L(n) asm volatile("s_waitcnt lgkmcnt(" #n ")" ::: "memory")
; #define PG8_BAR __builtin_amdgcn_s_barrier()
; #define PG8_SCHED __builtin_amdgcn_sched_barrier(0)
; template <class Epi, class Sched, bool ALIGN_EPI = false, bool SP2 = false>
; __device__ __forceinline__ void gemm_phase(PG8_LAS unsigned char* lds, const Gemm g, const Sched& S, const Epi& E) {
;     ...
;         for (int t = 0; t < nt; t += 2) {
;     ...
;             PG8_LDA(At, 1, 1); PG8_STAGE(PG8_SB(1, 0), b3, voffB); PG8_STAGE(PG8_SB(1, 1), b3 + hstepB, voffB); PG8_STAGE(PG8_SA(1, 0), a3, voffA);
;             PG8_WAIT_V(8); PG8_WAIT_L(0); PG8_BAR; PG8_MMA(1, 0, At, B0); PG8_MMA(1, 1, At, B1); PG8_BAR; PG8_SCHED;
	s_add_i32 s46, s70, s52
	v_lshl_add_u64 v[206:207], v[206:207], 0, s[26:27]
	s_mov_b32 m0, s46
	ds_read_b128 v[212:215], v191 offset:49152
	ds_read_b128 v[216:219], v191 offset:50176
	ds_read_b128 v[220:223], v191 offset:51200
	ds_read_b128 v[224:227], v191 offset:52224
	ds_read_b128 v[228:231], v191 offset:53248
	ds_read_b128 v[232:235], v191 offset:54272
	ds_read_b128 v[236:239], v191 offset:55296
	ds_read_b128 v[240:243], v191 offset:56320
	global_load_lds_dwordx4 v[206:207], off
	s_add_i32 m0, s46, 0x2000
	s_add_u32 s44, s44, 0xb0080
	v_lshl_add_u64 v[206:207], v[244:245], 0, s[26:27]
	s_addc_u32 s45, s45, 0
	s_add_i32 s46, s71, s52
	global_load_lds_dwordx4 v[206:207], off
	v_lshl_add_u64 v[206:207], s[44:45], 0, v[154:155]
	s_mov_b32 m0, s46
	s_nop 0
	global_load_lds_dwordx4 v[206:207], off
	v_lshl_add_u64 v[206:207], s[44:45], 0, v[158:159]
	s_add_i32 m0, s46, 0x2000
	s_nop 0
	global_load_lds_dwordx4 v[206:207], off
	v_lshl_add_u64 v[206:207], s[42:43], 0, v[152:153]
	s_mov_b32 m0, s65
	s_nop 0
	global_load_lds_dwordx4 v[206:207], off
	v_lshl_add_u64 v[206:207], s[42:43], 0, v[156:157]
	s_mov_b32 m0, s66
	s_nop 0
	global_load_lds_dwordx4 v[206:207], off
	s_waitcnt vmcnt(8)
	s_waitcnt lgkmcnt(0)
	s_barrier
	s_setprio 1
	v_mfma_f32_16x16x32_bf16 v[92:95], v[124:127], v[212:215], v[92:95]
	v_mfma_f32_16x16x32_bf16 v[88:91], v[132:135], v[212:215], v[88:91]
	v_mfma_f32_16x16x32_bf16 v[84:87], v[124:127], v[220:223], v[84:87]
	v_mfma_f32_16x16x32_bf16 v[80:83], v[132:135], v[220:223], v[80:83]
	v_mfma_f32_16x16x32_bf16 v[76:79], v[124:127], v[228:231], v[76:79]
	v_mfma_f32_16x16x32_bf16 v[72:75], v[132:135], v[228:231], v[72:75]
	v_mfma_f32_16x16x32_bf16 v[68:71], v[124:127], v[236:239], v[68:71]
	v_mfma_f32_16x16x32_bf16 v[64:67], v[132:135], v[236:239], v[64:67]
	v_mfma_f32_16x16x32_bf16 v[92:95], v[128:131], v[216:219], v[92:95]
	v_mfma_f32_16x16x32_bf16 v[88:91], v[144:147], v[216:219], v[88:91]
	v_mfma_f32_16x16x32_bf16 v[84:87], v[128:131], v[224:227], v[84:87]
	v_mfma_f32_16x16x32_bf16 v[80:83], v[144:147], v[224:227], v[80:83]
	v_mfma_f32_16x16x32_bf16 v[76:79], v[128:131], v[232:235], v[76:79]
	v_mfma_f32_16x16x32_bf16 v[72:75], v[144:147], v[232:235], v[72:75]
	v_mfma_f32_16x16x32_bf16 v[68:71], v[128:131], v[240:243], v[68:71]
	v_mfma_f32_16x16x32_bf16 v[64:67], v[144:147], v[240:243], v[64:67]
	v_mfma_f32_16x16x32_bf16 v[28:31], v[148:151], v[212:215], v[28:31]
	v_mfma_f32_16x16x32_bf16 v[24:27], v[174:177], v[212:215], v[24:27]
	v_mfma_f32_16x16x32_bf16 v[20:23], v[148:151], v[220:223], v[20:23]
	v_mfma_f32_16x16x32_bf16 v[16:19], v[174:177], v[220:223], v[16:19]
	v_mfma_f32_16x16x32_bf16 v[12:15], v[148:151], v[228:231], v[12:15]
	v_mfma_f32_16x16x32_bf16 v[8:11], v[174:177], v[228:231], v[8:11]
	v_mfma_f32_16x16x32_bf16 v[4:7], v[148:151], v[236:239], v[4:7]
	v_mfma_f32_16x16x32_bf16 v[0:3], v[174:177], v[236:239], v[0:3]
	v_mfma_f32_16x16x32_bf16 v[28:31], v[170:173], v[216:219], v[28:31]
	v_mfma_f32_16x16x32_bf16 v[24:27], v[178:181], v[216:219], v[24:27]
	v_mfma_f32_16x16x32_bf16 v[20:23], v[170:173], v[224:227], v[20:23]
	v_mfma_f32_16x16x32_bf16 v[16:19], v[178:181], v[224:227], v[16:19]
	v_mfma_f32_16x16x32_bf16 v[12:15], v[170:173], v[232:235], v[12:15]
	v_mfma_f32_16x16x32_bf16 v[8:11], v[178:181], v[232:235], v[8:11]
	v_mfma_f32_16x16x32_bf16 v[4:7], v[170:173], v[240:243], v[4:7]
	v_mfma_f32_16x16x32_bf16 v[0:3], v[178:181], v[240:243], v[0:3]
	s_setprio 0
	s_barrier
	s_add_i32 s86, s86, 2
	s_add_u32 s40, s40, 0x100
	s_addc_u32 s41, s41, 0
	s_cmp_gt_u32 s86, 41
	s_cbranch_scc0 .LBB0_2888
	s_and_b64 vcc, exec, s[28:29]
	s_cbranch_vccz .LBB0_2891
	s_barrier

; #define PG8_STAGE(bufoff, gbase, voff) do { _Pragma("unroll") for (int _i = 0; _i < 2; ++_i) \
;         __builtin_amdgcn_global_load_lds((const unsigned*)((const char*)(gbase) + (voff)[_i]), (PG8_LAS unsigned*)(lds + (bufoff) + ldsw + _i * 8192), 16, 0, 0); } while (0)
; #define PG8_LDA(dst, b, h) do { _Pragma("unroll") for (int m = 0; m < 4; ++m) _Pragma("unroll") for (int k = 0; k < 2; ++k) dst[m][k] = *(const PG8_LAS bf16x8*)(lds + PG8_SA(b, h) + aoff + m * 2048 + k * 1024); } while (0)
; #define PG8_LDB(dst, b, h) do { _Pragma("unroll") for (int n = 0; n < 2; ++n) _Pragma("unroll") for (int k = 0; k < 2; ++k) dst[n][k] = *(const PG8_LAS bf16x8*)(lds + PG8_SB(b, h) + boff + n * 2048 + k * 1024); } while (0)
; #define PG8_MMA(ai, bj, At, Bt) do { __builtin_amdgcn_s_setprio(1); _Pragma("unroll") for (int m = 0; m < 4; ++m) _Pragma("unroll") for (int n = 0; n < 2; ++n) _Pragma("unroll") for (int k = 0; k < 2; ++k) \
;         acc[ai][bj][m][n] = __builtin_amdgcn_mfma_f32_16x16x32_bf16(Bt[n][k], At[m][k], acc[ai][bj][m][n], 0, 0, 0); __builtin_amdgcn_s_setprio(0); } while (0)
; #define PG8_WAIT_V(n) asm volatile("s_waitcnt vmcnt(" #n ")" ::: "memory")
; #define PG8_BAR __builtin_amdgcn_s_barrier()
; template <class Epi, class Sched, bool ALIGN_EPI = false, bool SP2 = false>
; __device__ __forceinline__ void gemm_phase(PG8_LAS unsigned char* lds, const Gemm g, const Sched& S, const Epi& E) {
;     ...
;         for (int t = 0; t < nt; t += 2) {
;             const bool last = (t == nt - 2);
;             const char* a1 = cA + PG8_AK(t + 1);
;             const char* a2 = last ? nA : cA + PG8_AK(t + 2); const char* b2 = last ? nB : cB + (size_t)(t + 2) * kstep;
;             const char* a3 = last ? nA + PG8_AK(1) : cA + PG8_AK(t + 3); const char* b3 = b2 + kstep;
;             if (last && has_next) S.a_ready(nxt);
;             if constexpr (SP2) {
;             PG8_LDB(B0, 0, 0); PG8_LDB(B1, 0, 1); PG8_SCHED; PG8_LDA(At, 0, 0); PG8_STAGE(PG8_SA(1, 1), a1 + hstepA, voffA);
;             PG8_WAIT_V(8); PG8_WAIT_L(0); PG8_BAR; PG8_MMA(0, 0, At, B0); PG8_MMA(0, 1, At, B1); PG8_BAR; PG8_SCHED;
;             PG8_LDA(At, 0, 1); PG8_STAGE(PG8_SB(0, 0), b2, voffB); PG8_STAGE(PG8_SB(0, 1), b2 + hstepB, voffB); PG8_STAGE(PG8_SA(0, 0), a2, voffA);
;             PG8_WAIT_V(8); PG8_WAIT_L(0); PG8_BAR; PG8_MMA(1, 0, At, B0); PG8_MMA(1, 1, At, B1); PG8_BAR; PG8_SCHED;
.LBB0_2980:
	ds_read_b128 v[108:111], v191
	ds_read_b128 v[112:115], v191 offset:1024
	ds_read_b128 v[116:119], v191 offset:2048
	ds_read_b128 v[120:123], v191 offset:3072
	ds_read_b128 v[124:127], v193
	ds_read_b128 v[128:131], v193 offset:1024
	ds_read_b128 v[132:135], v193 offset:2048
	ds_read_b128 v[160:163], v193 offset:3072
	s_add_u32 s42, s38, s40
	s_addc_u32 s43, s39, s41
	s_add_u32 s46, s42, 0x100
	s_addc_u32 s47, s43, 0
	s_add_u32 s44, s80, s40
	s_addc_u32 s45, s81, s41
	s_add_u32 s42, s42, 0x180
	s_addc_u32 s43, s43, 0
	s_cmpk_eq_i32 s40, 0x700
	s_cselect_b32 s43, s79, s43
	s_cselect_b32 s42, s78, s42
	s_cselect_b32 s45, s27, s45
	s_cselect_b32 s44, s69, s44
	s_cselect_b32 s47, s3, s47
	s_cselect_b32 s46, s29, s46
	v_lshl_add_u64 v[242:243], v[106:107], 0, s[40:41]
	s_add_i32 m0, s54, 0xc000
	ds_read_b128 v[164:167], v187
	ds_read_b128 v[168:171], v187 offset:1024
	ds_read_b128 v[218:221], v187 offset:2048
	ds_read_b128 v[222:225], v187 offset:3072
	ds_read_b128 v[226:229], v187 offset:4096
	ds_read_b128 v[230:233], v187 offset:5120
	ds_read_b128 v[234:237], v187 offset:6144
	ds_read_b128 v[238:241], v187 offset:7168
	global_load_lds_dwordx4 v[242:243], off
	v_lshl_add_u64 v[242:243], v[104:105], 0, s[40:41]
	s_add_i32 m0, s54, 0xe000
	s_nop 0
	global_load_lds_dwordx4 v[242:243], off
	s_waitcnt vmcnt(8)
	s_waitcnt lgkmcnt(0)
	s_barrier
	s_setprio 1
	v_mfma_f32_16x16x32_bf16 v[156:159], v[108:111], v[164:167], v[156:159]
	v_mfma_f32_16x16x32_bf16 v[152:155], v[116:119], v[164:167], v[152:155]
	v_mfma_f32_16x16x32_bf16 v[148:151], v[108:111], v[218:221], v[148:151]
	v_mfma_f32_16x16x32_bf16 v[144:147], v[116:119], v[218:221], v[144:147]
	v_mfma_f32_16x16x32_bf16 v[140:143], v[108:111], v[226:229], v[140:143]
	v_mfma_f32_16x16x32_bf16 v[136:139], v[116:119], v[226:229], v[136:139]
	v_mfma_f32_16x16x32_bf16 v[100:103], v[108:111], v[234:237], v[100:103]
	v_mfma_f32_16x16x32_bf16 v[96:99], v[116:119], v[234:237], v[96:99]
	v_mfma_f32_16x16x32_bf16 v[156:159], v[112:115], v[168:171], v[156:159]
	v_mfma_f32_16x16x32_bf16 v[152:155], v[120:123], v[168:171], v[152:155]
	v_mfma_f32_16x16x32_bf16 v[148:151], v[112:115], v[222:225], v[148:151]
	v_mfma_f32_16x16x32_bf16 v[144:147], v[120:123], v[222:225], v[144:147]
	v_mfma_f32_16x16x32_bf16 v[140:143], v[112:115], v[230:233], v[140:143]
	v_mfma_f32_16x16x32_bf16 v[136:139], v[120:123], v[230:233], v[136:139]
	v_mfma_f32_16x16x32_bf16 v[100:103], v[112:115], v[238:241], v[100:103]
	v_mfma_f32_16x16x32_bf16 v[96:99], v[120:123], v[238:241], v[96:99]
	v_mfma_f32_16x16x32_bf16 v[60:63], v[124:127], v[164:167], v[60:63]
	v_mfma_f32_16x16x32_bf16 v[56:59], v[132:135], v[164:167], v[56:59]
	v_mfma_f32_16x16x32_bf16 v[52:55], v[124:127], v[218:221], v[52:55]
	v_mfma_f32_16x16x32_bf16 v[48:51], v[132:135], v[218:221], v[48:51]
	v_mfma_f32_16x16x32_bf16 v[44:47], v[124:127], v[226:229], v[44:47]
	v_mfma_f32_16x16x32_bf16 v[40:43], v[132:135], v[226:229], v[40:43]
	v_mfma_f32_16x16x32_bf16 v[36:39], v[124:127], v[234:237], v[36:39]
	v_mfma_f32_16x16x32_bf16 v[32:35], v[132:135], v[234:237], v[32:35]
	v_mfma_f32_16x16x32_bf16 v[60:63], v[128:131], v[168:171], v[60:63]
	v_mfma_f32_16x16x32_bf16 v[56:59], v[160:163], v[168:171], v[56:59]
	v_mfma_f32_16x16x32_bf16 v[52:55], v[128:131], v[222:225], v[52:55]
	v_mfma_f32_16x16x32_bf16 v[48:51], v[160:163], v[222:225], v[48:51]
	v_mfma_f32_16x16x32_bf16 v[44:47], v[128:131], v[230:233], v[44:47]
	v_mfma_f32_16x16x32_bf16 v[40:43], v[160:163], v[230:233], v[40:43]
	v_mfma_f32_16x16x32_bf16 v[36:39], v[128:131], v[238:241], v[36:39]
	v_mfma_f32_16x16x32_bf16 v[32:35], v[160:163], v[238:241], v[32:35]
	s_setprio 0
	s_barrier
	s_add_i32 s70, s66, s53
	v_lshl_add_u64 v[242:243], s[44:45], 0, v[174:175]
	s_mov_b32 m0, s70
	ds_read_b128 v[164:167], v187 offset:16384
	ds_read_b128 v[168:171], v187 offset:17408
	ds_read_b128 v[218:221], v187 offset:18432
	ds_read_b128 v[222:225], v187 offset:19456
	ds_read_b128 v[226:229], v187 offset:20480
	ds_read_b128 v[230:233], v187 offset:21504
	ds_read_b128 v[234:237], v187 offset:22528
	ds_read_b128 v[238:241], v187 offset:23552
	global_load_lds_dwordx4 v[242:243], off
	s_add_i32 m0, s70, 0x2000
	s_add_u32 s70, s44, 0x40000
	v_lshl_add_u64 v[244:245], s[44:45], 0, v[178:179]
	s_addc_u32 s71, s45, 0
	s_add_i32 s83, s67, s53
	global_load_lds_dwordx4 v[244:245], off
	v_lshl_add_u64 v[246:247], s[70:71], 0, v[174:175]
	s_mov_b32 m0, s83
	s_nop 0
	global_load_lds_dwordx4 v[246:247], off
	v_lshl_add_u64 v[246:247], s[70:71], 0, v[178:179]
	s_add_i32 m0, s83, 0x2000
	s_nop 0
	global_load_lds_dwordx4 v[246:247], off
	s_waitcnt vmcnt(6)
	s_waitcnt lgkmcnt(0)
	s_barrier
; #define PG8_STAGE(bufoff, gbase, voff) do { _Pragma("unroll") for (int _i = 0; _i < 2; ++_i) \
;         __builtin_amdgcn_global_load_lds((const unsigned*)((const char*)(gbase) + (voff)[_i]), (PG8_LAS unsigned*)(lds + (bufoff) + ldsw + _i * 8192), 16, 0, 0); } while (0)
; #define PG8_LDA(dst, b, h) do { _Pragma("unroll") for (int m = 0; m < 4; ++m) _Pragma("unroll") for (int k = 0; k < 2; ++k) dst[m][k] = *(const PG8_LAS bf16x8*)(lds + PG8_SA(b, h) + aoff + m * 2048 + k * 1024); } while (0)
; #define PG8_LDB(dst, b, h) do { _Pragma("unroll") for (int n = 0; n < 2; ++n) _Pragma("unroll") for (int k = 0; k < 2; ++k) dst[n][k] = *(const PG8_LAS bf16x8*)(lds + PG8_SB(b, h) + boff + n * 2048 + k * 1024); } while (0)
; #define PG8_MMA(ai, bj, At, Bt) do { __builtin_amdgcn_s_setprio(1); _Pragma("unroll") for (int m = 0; m < 4; ++m) _Pragma("unroll") for (int n = 0; n < 2; ++n) _Pragma("unroll") for (int k = 0; k < 2; ++k) \
;         acc[ai][bj][m][n] = __builtin_amdgcn_mfma_f32_16x16x32_bf16(Bt[n][k], At[m][k], acc[ai][bj][m][n], 0, 0, 0); __builtin_amdgcn_s_setprio(0); } while (0)
; #define PG8_WAIT_V(n) asm volatile("s_waitcnt vmcnt(" #n ")" ::: "memory")
; #define PG8_WAIT_L(n) asm volatile("s_waitcnt lgkmcnt(" #n ")" ::: "memory")
; #define PG8_BAR __builtin_amdgcn_s_barrier()
; #define PG8_SCHED __builtin_amdgcn_sched_barrier(0)
; template <class Epi, class Sched, bool ALIGN_EPI = false, bool SP2 = false>
; __device__ __forceinline__ void gemm_phase(PG8_LAS unsigned char* lds, const Gemm g, const Sched& S, const Epi& E) {
;     ...
;             PG8_WAIT_V(8); PG8_WAIT_L(0); PG8_BAR; PG8_MMA(1, 0, At, B0); PG8_MMA(1, 1, At, B1); PG8_BAR; PG8_SCHED;
;             PG8_LDB(B0, 1, 0); PG8_LDB(B1, 1, 1); PG8_SCHED; PG8_LDA(At, 1, 0); PG8_STAGE(PG8_SA(0, 1), a2 + hstepA, voffA);
;             PG8_WAIT_V(8); PG8_WAIT_L(0); PG8_BAR; PG8_MMA(0, 0, At, B0); PG8_MMA(0, 1, At, B1); PG8_BAR; PG8_SCHED;
	s_setprio 1
	v_mfma_f32_16x16x32_bf16 v[92:95], v[108:111], v[164:167], v[92:95]
	v_mfma_f32_16x16x32_bf16 v[88:91], v[116:119], v[164:167], v[88:91]
	v_mfma_f32_16x16x32_bf16 v[84:87], v[108:111], v[218:221], v[84:87]
	v_mfma_f32_16x16x32_bf16 v[80:83], v[116:119], v[218:221], v[80:83]
	v_mfma_f32_16x16x32_bf16 v[76:79], v[108:111], v[226:229], v[76:79]
	v_mfma_f32_16x16x32_bf16 v[72:75], v[116:119], v[226:229], v[72:75]
	v_mfma_f32_16x16x32_bf16 v[68:71], v[108:111], v[234:237], v[68:71]
	v_mfma_f32_16x16x32_bf16 v[64:67], v[116:119], v[234:237], v[64:67]
	v_mfma_f32_16x16x32_bf16 v[92:95], v[112:115], v[168:171], v[92:95]
	v_mfma_f32_16x16x32_bf16 v[88:91], v[120:123], v[168:171], v[88:91]
	v_mfma_f32_16x16x32_bf16 v[84:87], v[112:115], v[222:225], v[84:87]
	v_mfma_f32_16x16x32_bf16 v[80:83], v[120:123], v[222:225], v[80:83]
	v_mfma_f32_16x16x32_bf16 v[76:79], v[112:115], v[230:233], v[76:79]
	v_mfma_f32_16x16x32_bf16 v[72:75], v[120:123], v[230:233], v[72:75]
	v_mfma_f32_16x16x32_bf16 v[68:71], v[112:115], v[238:241], v[68:71]
	v_mfma_f32_16x16x32_bf16 v[64:67], v[120:123], v[238:241], v[64:67]
	v_mfma_f32_16x16x32_bf16 v[28:31], v[124:127], v[164:167], v[28:31]
	v_mfma_f32_16x16x32_bf16 v[24:27], v[132:135], v[164:167], v[24:27]
	v_mfma_f32_16x16x32_bf16 v[20:23], v[124:127], v[218:221], v[20:23]
	v_mfma_f32_16x16x32_bf16 v[16:19], v[132:135], v[218:221], v[16:19]
	v_mfma_f32_16x16x32_bf16 v[12:15], v[124:127], v[226:229], v[12:15]
	v_mfma_f32_16x16x32_bf16 v[8:11], v[132:135], v[226:229], v[8:11]
	v_mfma_f32_16x16x32_bf16 v[4:7], v[124:127], v[234:237], v[4:7]
	v_mfma_f32_16x16x32_bf16 v[0:3], v[132:135], v[234:237], v[0:3]
	v_mfma_f32_16x16x32_bf16 v[28:31], v[128:131], v[168:171], v[28:31]
	v_mfma_f32_16x16x32_bf16 v[24:27], v[160:163], v[168:171], v[24:27]
	v_mfma_f32_16x16x32_bf16 v[20:23], v[128:131], v[222:225], v[20:23]
	v_mfma_f32_16x16x32_bf16 v[16:19], v[160:163], v[222:225], v[16:19]
	v_mfma_f32_16x16x32_bf16 v[12:15], v[128:131], v[230:233], v[12:15]
	v_mfma_f32_16x16x32_bf16 v[8:11], v[160:163], v[230:233], v[8:11]
	v_mfma_f32_16x16x32_bf16 v[4:7], v[128:131], v[238:241], v[4:7]
	v_mfma_f32_16x16x32_bf16 v[0:3], v[160:163], v[238:241], v[0:3]
	s_setprio 0
	s_barrier
	s_add_i32 s70, 0, 0x18000
	s_add_i32 s71, 0, 0x1c000
	v_add_u32_e32 v120, s70, v181
	v_add_u32_e32 v160, s71, v181
	ds_read_b128 v[108:111], v120
	ds_read_b128 v[112:115], v120 offset:1024
	ds_read_b128 v[116:119], v120 offset:2048
	ds_read_b128 v[120:123], v120 offset:3072
	ds_read_b128 v[124:127], v160
	ds_read_b128 v[128:131], v160 offset:1024
	ds_read_b128 v[132:135], v160 offset:2048
	ds_read_b128 v[160:163], v160 offset:3072
	v_lshl_add_u64 v[246:247], s[46:47], 0, v[172:173]
	s_mov_b32 m0, s54
	s_nop 0
	global_load_lds_dwordx4 v[246:247], off
	v_lshl_add_u64 v[246:247], s[46:47], 0, v[176:177]
	s_mov_b32 m0, s55
	s_nop 0
	global_load_lds_dwordx4 v[246:247], off
	s_add_u32 s46, s46, 0x40000
	s_addc_u32 s47, s47, 0
	s_mov_b32 m0, s56
	v_lshl_add_u64 v[246:247], s[46:47], 0, v[172:173]
	ds_read_b128 v[164:167], v187 offset:32768
	ds_read_b128 v[168:171], v187 offset:33792
	ds_read_b128 v[218:221], v187 offset:34816
	ds_read_b128 v[222:225], v187 offset:35840
	ds_read_b128 v[226:229], v187 offset:36864
	ds_read_b128 v[230:233], v187 offset:37888
	ds_read_b128 v[234:237], v187 offset:38912
	ds_read_b128 v[238:241], v187 offset:39936
	global_load_lds_dwordx4 v[246:247], off
	v_lshl_add_u64 v[246:247], s[46:47], 0, v[176:177]
	s_mov_b32 m0, s57
	s_nop 0
	global_load_lds_dwordx4 v[246:247], off
	s_waitcnt vmcnt(8)
	s_waitcnt lgkmcnt(0)
	s_barrier
	s_setprio 1
	v_mfma_f32_16x16x32_bf16 v[156:159], v[108:111], v[164:167], v[156:159]
	v_mfma_f32_16x16x32_bf16 v[152:155], v[116:119], v[164:167], v[152:155]
	v_mfma_f32_16x16x32_bf16 v[148:151], v[108:111], v[218:221], v[148:151]
	v_mfma_f32_16x16x32_bf16 v[144:147], v[116:119], v[218:221], v[144:147]
	v_mfma_f32_16x16x32_bf16 v[140:143], v[108:111], v[226:229], v[140:143]
	v_mfma_f32_16x16x32_bf16 v[136:139], v[116:119], v[226:229], v[136:139]
	v_mfma_f32_16x16x32_bf16 v[100:103], v[108:111], v[234:237], v[100:103]
	v_mfma_f32_16x16x32_bf16 v[96:99], v[116:119], v[234:237], v[96:99]
	v_mfma_f32_16x16x32_bf16 v[156:159], v[112:115], v[168:171], v[156:159]
	v_mfma_f32_16x16x32_bf16 v[152:155], v[120:123], v[168:171], v[152:155]
	v_mfma_f32_16x16x32_bf16 v[148:151], v[112:115], v[222:225], v[148:151]
	v_mfma_f32_16x16x32_bf16 v[144:147], v[120:123], v[222:225], v[144:147]
	v_mfma_f32_16x16x32_bf16 v[140:143], v[112:115], v[230:233], v[140:143]
	v_mfma_f32_16x16x32_bf16 v[136:139], v[120:123], v[230:233], v[136:139]
	v_mfma_f32_16x16x32_bf16 v[100:103], v[112:115], v[238:241], v[100:103]
	v_mfma_f32_16x16x32_bf16 v[96:99], v[120:123], v[238:241], v[96:99]
	v_mfma_f32_16x16x32_bf16 v[60:63], v[124:127], v[164:167], v[60:63]
	v_mfma_f32_16x16x32_bf16 v[56:59], v[132:135], v[164:167], v[56:59]
	v_mfma_f32_16x16x32_bf16 v[52:55], v[124:127], v[218:221], v[52:55]
	v_mfma_f32_16x16x32_bf16 v[48:51], v[132:135], v[218:221], v[48:51]
	v_mfma_f32_16x16x32_bf16 v[44:47], v[124:127], v[226:229], v[44:47]
	v_mfma_f32_16x16x32_bf16 v[40:43], v[132:135], v[226:229], v[40:43]
	v_mfma_f32_16x16x32_bf16 v[36:39], v[124:127], v[234:237], v[36:39]
	v_mfma_f32_16x16x32_bf16 v[32:35], v[132:135], v[234:237], v[32:35]
	v_mfma_f32_16x16x32_bf16 v[60:63], v[128:131], v[168:171], v[60:63]
	v_mfma_f32_16x16x32_bf16 v[56:59], v[160:163], v[168:171], v[56:59]
	v_mfma_f32_16x16x32_bf16 v[52:55], v[128:131], v[222:225], v[52:55]
	v_mfma_f32_16x16x32_bf16 v[48:51], v[160:163], v[222:225], v[48:51]
	v_mfma_f32_16x16x32_bf16 v[44:47], v[128:131], v[230:233], v[44:47]
	v_mfma_f32_16x16x32_bf16 v[40:43], v[160:163], v[230:233], v[40:43]
	v_mfma_f32_16x16x32_bf16 v[36:39], v[128:131], v[238:241], v[36:39]
	v_mfma_f32_16x16x32_bf16 v[32:35], v[160:163], v[238:241], v[32:35]
	s_setprio 0
	s_barrier
; #define PG8_STAGE(bufoff, gbase, voff) do { _Pragma("unroll") for (int _i = 0; _i < 2; ++_i) \
;         __builtin_amdgcn_global_load_lds((const unsigned*)((const char*)(gbase) + (voff)[_i]), (PG8_LAS unsigned*)(lds + (bufoff) + ldsw + _i * 8192), 16, 0, 0); } while (0)
; #define PG8_LDA(dst, b, h) do { _Pragma("unroll") for (int m = 0; m < 4; ++m) _Pragma("unroll") for (int k = 0; k < 2; ++k) dst[m][k] = *(const PG8_LAS bf16x8*)(lds + PG8_SA(b, h) + aoff + m * 2048 + k * 1024); } while (0)
; #define PG8_MMA(ai, bj, At, Bt) do { __builtin_amdgcn_s_setprio(1); _Pragma("unroll") for (int m = 0; m < 4; ++m) _Pragma("unroll") for (int n = 0; n < 2; ++n) _Pragma("unroll") for (int k = 0; k < 2; ++k) \
;         acc[ai][bj][m][n] = __builtin_amdgcn_mfma_f32_16x16x32_bf16(Bt[n][k], At[m][k], acc[ai][bj][m][n], 0, 0, 0); __builtin_amdgcn_s_setprio(0); } while (0)
; #define PG8_WAIT_V(n) asm volatile("s_waitcnt vmcnt(" #n ")" ::: "memory")
; #define PG8_WAIT_L(n) asm volatile("s_waitcnt lgkmcnt(" #n ")" ::: "memory")
; #define PG8_BAR __builtin_amdgcn_s_barrier()
; #define PG8_SCHED __builtin_amdgcn_sched_barrier(0)
; template <class Epi, class Sched, bool ALIGN_EPI = false, bool SP2 = false>
; __device__ __forceinline__ void gemm_phase(PG8_LAS unsigned char* lds, const Gemm g, const Sched& S, const Epi& E) {
;     ...
;         for (int t = 0; t < nt; t += 2) {
;     ...
;             PG8_LDA(At, 1, 1); PG8_STAGE(PG8_SB(1, 0), b3, voffB); PG8_STAGE(PG8_SB(1, 1), b3 + hstepB, voffB); PG8_STAGE(PG8_SA(1, 0), a3, voffA);
;             PG8_WAIT_V(8); PG8_WAIT_L(0); PG8_BAR; PG8_MMA(1, 0, At, B0); PG8_MMA(1, 1, At, B1); PG8_BAR; PG8_SCHED;
	s_add_i32 s46, s70, s53
	v_lshl_add_u64 v[242:243], v[242:243], 0, s[6:7]
	s_mov_b32 m0, s46
	ds_read_b128 v[164:167], v187 offset:49152
	ds_read_b128 v[168:171], v187 offset:50176
	ds_read_b128 v[218:221], v187 offset:51200
	ds_read_b128 v[222:225], v187 offset:52224
	ds_read_b128 v[226:229], v187 offset:53248
	ds_read_b128 v[230:233], v187 offset:54272
	ds_read_b128 v[234:237], v187 offset:55296
	ds_read_b128 v[238:241], v187 offset:56320
	global_load_lds_dwordx4 v[242:243], off
	s_add_i32 m0, s46, 0x2000
	s_add_u32 s44, s44, 0x40080
	v_lshl_add_u64 v[242:243], v[244:245], 0, s[6:7]
	s_addc_u32 s45, s45, 0
	s_add_i32 s46, s71, s53
	global_load_lds_dwordx4 v[242:243], off
	v_lshl_add_u64 v[242:243], s[44:45], 0, v[174:175]
	s_mov_b32 m0, s46
	s_nop 0
	global_load_lds_dwordx4 v[242:243], off
	v_lshl_add_u64 v[242:243], s[44:45], 0, v[178:179]
	s_add_i32 m0, s46, 0x2000
	s_nop 0
	global_load_lds_dwordx4 v[242:243], off
	v_lshl_add_u64 v[242:243], s[42:43], 0, v[172:173]
	s_mov_b32 m0, s63
	s_nop 0
	global_load_lds_dwordx4 v[242:243], off
	v_lshl_add_u64 v[242:243], s[42:43], 0, v[176:177]
	s_mov_b32 m0, s64
	s_nop 0
	global_load_lds_dwordx4 v[242:243], off
	s_waitcnt vmcnt(8)
	s_waitcnt lgkmcnt(0)
	s_barrier
	s_setprio 1
	v_mfma_f32_16x16x32_bf16 v[92:95], v[108:111], v[164:167], v[92:95]
	v_mfma_f32_16x16x32_bf16 v[88:91], v[116:119], v[164:167], v[88:91]
	v_mfma_f32_16x16x32_bf16 v[84:87], v[108:111], v[218:221], v[84:87]
	v_mfma_f32_16x16x32_bf16 v[80:83], v[116:119], v[218:221], v[80:83]
	v_mfma_f32_16x16x32_bf16 v[76:79], v[108:111], v[226:229], v[76:79]
	v_mfma_f32_16x16x32_bf16 v[72:75], v[116:119], v[226:229], v[72:75]
	v_mfma_f32_16x16x32_bf16 v[68:71], v[108:111], v[234:237], v[68:71]
	v_mfma_f32_16x16x32_bf16 v[64:67], v[116:119], v[234:237], v[64:67]
	v_mfma_f32_16x16x32_bf16 v[92:95], v[112:115], v[168:171], v[92:95]
	v_mfma_f32_16x16x32_bf16 v[88:91], v[120:123], v[168:171], v[88:91]
	v_mfma_f32_16x16x32_bf16 v[84:87], v[112:115], v[222:225], v[84:87]
	v_mfma_f32_16x16x32_bf16 v[80:83], v[120:123], v[222:225], v[80:83]
	v_mfma_f32_16x16x32_bf16 v[76:79], v[112:115], v[230:233], v[76:79]
	v_mfma_f32_16x16x32_bf16 v[72:75], v[120:123], v[230:233], v[72:75]
	v_mfma_f32_16x16x32_bf16 v[68:71], v[112:115], v[238:241], v[68:71]
	v_mfma_f32_16x16x32_bf16 v[64:67], v[120:123], v[238:241], v[64:67]
	v_mfma_f32_16x16x32_bf16 v[28:31], v[124:127], v[164:167], v[28:31]
	v_mfma_f32_16x16x32_bf16 v[24:27], v[132:135], v[164:167], v[24:27]
	v_mfma_f32_16x16x32_bf16 v[20:23], v[124:127], v[218:221], v[20:23]
	v_mfma_f32_16x16x32_bf16 v[16:19], v[132:135], v[218:221], v[16:19]
	v_mfma_f32_16x16x32_bf16 v[12:15], v[124:127], v[226:229], v[12:15]
	v_mfma_f32_16x16x32_bf16 v[8:11], v[132:135], v[226:229], v[8:11]
	v_mfma_f32_16x16x32_bf16 v[4:7], v[124:127], v[234:237], v[4:7]
	v_mfma_f32_16x16x32_bf16 v[0:3], v[132:135], v[234:237], v[0:3]
	v_mfma_f32_16x16x32_bf16 v[28:31], v[128:131], v[168:171], v[28:31]
	v_mfma_f32_16x16x32_bf16 v[24:27], v[160:163], v[168:171], v[24:27]
	v_mfma_f32_16x16x32_bf16 v[20:23], v[128:131], v[222:225], v[20:23]
	v_mfma_f32_16x16x32_bf16 v[16:19], v[160:163], v[222:225], v[16:19]
	v_mfma_f32_16x16x32_bf16 v[12:15], v[128:131], v[230:233], v[12:15]
	v_mfma_f32_16x16x32_bf16 v[8:11], v[160:163], v[230:233], v[8:11]
	v_mfma_f32_16x16x32_bf16 v[4:7], v[128:131], v[238:241], v[4:7]
	v_mfma_f32_16x16x32_bf16 v[0:3], v[160:163], v[238:241], v[0:3]
	s_setprio 0
	s_barrier
	s_add_i32 s82, s82, 2
	s_add_u32 s40, s40, 0x100
	s_addc_u32 s41, s41, 0
	s_cmp_gt_u32 s82, 13
	s_cbranch_scc0 .LBB0_2980
	s_and_b64 vcc, exec, s[22:23]
	s_cbranch_vccz .LBB0_2983
	s_barrier
